# v26 + all loop headers (targets of backward branches) aligned to 64 bytes with s_nop padding
# speedup vs baseline: 1.0009x; 1.0009x over previous
.LBB0_2:
	s_or_b64 exec, exec, s[2:3]
	s_add_u32 s2, s88, 0x4100000
	s_addc_u32 s3, s89, 0
	v_writelane_b32 v237, s2, 3
	s_cmp_lg_u32 s24, 0
	s_nop 0
	v_writelane_b32 v237, s3, 4
	s_cbranch_scc1 .LBB0_10
	v_sub_u32_e32 v1, 0xd7f, v128
	v_lshrrev_b32_e32 v2, 8, v1
	v_add_u32_e32 v1, 2, v2
	v_add_u32_e32 v129, 0x100, v128
	s_mov_b32 s2, 0
	v_and_b32_e32 v3, 30, v1
	v_mov_b32_e32 v1, v2
	s_mov_b32 s3, 1
	s_mov_b64 s[6:7], 0
	v_mov_b32_e32 v5, 0
	s_mov_b32 s8, s2
	v_mov_b64_e32 v[6:7], v[128:129]
	s_branch .LBB0_5
	.p2alignl 6, 3212836864

.LBB0_22:
	s_or_b64 exec, exec, s[2:3]
	s_load_dwordx16 s[60:75], s[0:1], 0x80
	v_mov_b32_e32 v30, v128
	s_cmpk_gt_i32 s24, 0x27f
	s_cbranch_scc1 .LBB0_25
	v_ashrrev_i32_e32 v1, 4, v30
	s_movk_i32 s2, 0xa00
	v_add_u32_e32 v2, 16, v1
	v_mad_i64_i32 v[22:23], s[0:1], v2, s2, 0
	v_add_u32_e32 v2, 32, v1
	v_mad_i64_i32 v[24:25], s[0:1], v2, s2, 0
	v_add_u32_e32 v2, 48, v1
	v_mad_i64_i32 v[20:21], s[0:1], v1, s2, 0
	v_mad_i64_i32 v[26:27], s[0:1], v2, s2, 0
	s_mul_hi_i32 s0, s24, 0x66666667
	s_lshr_b32 s1, s0, 31
	s_ashr_i32 s0, s0, 8
	s_add_i32 s0, s0, s1
	s_mul_i32 s2, s0, 0xa00000
	s_mul_hi_i32 s1, s0, 0xa00000
	s_add_u32 s2, s40, s2
	s_mulk_i32 s0, 0xfd80
	s_addc_u32 s1, s41, s1
	s_add_i32 s0, s0, s24
	s_mul_hi_i32 s3, s0, 0x66666667
	s_lshr_b32 s4, s3, 31
	s_ashr_i32 s3, s3, 4
	s_add_i32 s3, s3, s4
	s_lshl_b32 s4, s3, 6
	s_mul_i32 s5, s3, 0xa0000
	s_mul_hi_i32 s4, s4, 0x2800
	s_add_u32 s2, s2, s5
	s_addc_u32 s4, s1, s4
	s_mul_i32 s1, s3, 0xffffffd8
	s_add_i32 s1, s1, s0
	s_lshl_b32 s0, s1, 6
	s_ashr_i32 s1, s0, 31
	s_lshl_b64 s[0:1], s[0:1], 2
	v_and_b32_e32 v28, 15, v30
	s_add_u32 s0, s2, s0
	v_mov_b32_e32 v19, 0
	s_addc_u32 s1, s4, s1
	v_lshlrev_b32_e32 v18, 4, v28
	v_lshl_add_u64 v[10:11], s[0:1], 0, v[18:19]
	v_lshl_add_u64 v[2:3], v[26:27], 2, v[10:11]
	v_lshl_add_u64 v[6:7], v[24:25], 2, v[10:11]
	v_lshl_add_u64 v[12:13], v[22:23], 2, v[10:11]
	v_lshl_add_u64 v[14:15], v[20:21], 2, v[10:11]
	global_load_dwordx4 v[2:5], v[2:3], off nt
	s_nop 0
	global_load_dwordx4 v[6:9], v[6:7], off nt
	s_nop 0
	global_load_dwordx4 v[10:13], v[12:13], off nt
	s_nop 0
	global_load_dwordx4 v[14:17], v[14:15], off nt
	v_lshlrev_b32_e32 v18, 2, v28
	v_mul_u32_u24_e32 v28, 0x120, v28
	v_lshlrev_b32_e32 v28, 1, v28
	v_lshl_add_u32 v1, v1, 1, v28
	v_lshlrev_b32_e32 v28, 3, v30
	v_and_b32_e32 v32, 56, v28
	v_lshlrev_b32_e32 v36, 1, v32
	v_ashrrev_i32_e32 v34, 3, v30
	s_movk_i32 s2, 0x90
	v_mad_u64_u32 v[28:29], s[0:1], v34, s2, v[36:37]
	v_add_u32_e32 v29, 0x100, v30
	v_ashrrev_i32_e32 v29, 3, v29
	v_mad_u64_u32 v[30:31], s[0:1], v29, s2, v[36:37]
	v_lshlrev_b32_e32 v18, 2, v18
	v_lshlrev_b32_e32 v32, 1, v32
	v_mov_b32_e32 v33, v19
	s_mov_b32 s0, s24
	.p2alignl 6, 3212836864

.LBB0_25:
	s_add_u32 s10, s88, 0x500000
	s_addc_u32 s11, s89, 0
	v_mov_b32_e32 v30, v128
	s_cmpk_gt_i32 s24, 0x7f
	s_cbranch_scc1 .LBB0_28
	s_ashr_i32 s0, s24, 31
	s_lshr_b32 s0, s0, 25
	s_add_i32 s2, s24, s0
	s_ashr_i32 s0, s2, 7
	s_ashr_i32 s1, s0, 31
	v_readlane_b32 s44, v237, 5
	s_lshl_b64 s[0:1], s[0:1], 21
	v_readlane_b32 s52, v237, 13
	v_readlane_b32 s53, v237, 14
	s_add_u32 s3, s52, s0
	s_addc_u32 s4, s53, s1
	s_and_b32 s0, s2, 0xffffff80
	s_sub_i32 s2, s24, s0
	s_ashr_i32 s0, s2, 31
	s_lshr_b32 s0, s0, 28
	s_add_i32 s0, s2, s0
	s_ashr_i32 s5, s0, 4
	s_lshl_b32 s0, s5, 6
	s_ashr_i32 s1, s0, 31
	s_lshl_b64 s[0:1], s[0:1], 12
	s_add_u32 s3, s3, s0
	s_addc_u32 s4, s4, s1
	s_lshl_b32 s0, s5, 10
	s_lshl_b32 s1, s2, 6
	s_sub_i32 s0, s1, s0
	s_ashr_i32 s1, s0, 31
	v_ashrrev_i32_e32 v28, 4, v30
	s_lshl_b64 s[0:1], s[0:1], 2
	v_and_b32_e32 v1, 15, v30
	v_add_u32_e32 v22, 16, v28
	v_add_u32_e32 v24, 32, v28
	v_add_u32_e32 v26, 48, v28
	s_add_u32 s0, s3, s0
	v_mov_b32_e32 v19, 0
	v_ashrrev_i32_e32 v29, 31, v28
	v_ashrrev_i32_e32 v23, 31, v22
	v_ashrrev_i32_e32 v25, 31, v24
	v_ashrrev_i32_e32 v27, 31, v26
	s_addc_u32 s1, s4, s1
	v_lshlrev_b32_e32 v18, 4, v1
	v_lshl_add_u64 v[10:11], s[0:1], 0, v[18:19]
	v_lshlrev_b64 v[2:3], 12, v[26:27]
	v_lshlrev_b64 v[4:5], 12, v[24:25]
	v_lshlrev_b64 v[12:13], 12, v[22:23]
	v_lshlrev_b64 v[14:15], 12, v[28:29]
	v_lshl_add_u64 v[2:3], v[10:11], 0, v[2:3]
	v_lshl_add_u64 v[6:7], v[10:11], 0, v[4:5]
	v_lshl_add_u64 v[12:13], v[10:11], 0, v[12:13]
	v_lshl_add_u64 v[14:15], v[10:11], 0, v[14:15]
	global_load_dwordx4 v[2:5], v[2:3], off nt
	s_nop 0
	global_load_dwordx4 v[6:9], v[6:7], off nt
	s_nop 0
	global_load_dwordx4 v[10:13], v[12:13], off nt
	s_nop 0
	global_load_dwordx4 v[14:17], v[14:15], off nt
	v_lshlrev_b32_e32 v18, 2, v1
	v_mul_u32_u24_e32 v1, 0x120, v1
	v_lshlrev_b32_e32 v1, 1, v1
	v_lshlrev_b64 v[20:21], 10, v[28:29]
	v_lshl_add_u32 v1, v28, 1, v1
	v_lshlrev_b32_e32 v28, 3, v30
	v_and_b32_e32 v32, 56, v28
	v_lshlrev_b32_e32 v36, 1, v32
	v_ashrrev_i32_e32 v34, 3, v30
	s_movk_i32 s2, 0x90
	v_mad_u64_u32 v[28:29], s[0:1], v34, s2, v[36:37]
	v_add_u32_e32 v29, 0x100, v30
	v_ashrrev_i32_e32 v29, 3, v29
	v_mad_u64_u32 v[30:31], s[0:1], v29, s2, v[36:37]
	v_lshlrev_b64 v[22:23], 10, v[22:23]
	v_lshlrev_b64 v[24:25], 10, v[24:25]
	v_lshlrev_b64 v[26:27], 10, v[26:27]
	v_and_b32_e32 v31, 31, v34
	v_and_b32_e32 v35, 31, v29
	s_lshl_b32 s2, s24, 6
	s_lshl_b32 s3, s90, 6
	v_lshlrev_b32_e32 v18, 2, v18
	v_lshlrev_b32_e32 v32, 1, v32
	v_mov_b32_e32 v33, v19
	s_movk_i32 s4, 0x200
	v_mov_b32_e32 v36, 0xfffffe00
	s_mov_b32 s6, s24
	v_readlane_b32 s45, v237, 6
	v_readlane_b32 s46, v237, 7
	v_readlane_b32 s47, v237, 8
	v_readlane_b32 s48, v237, 9
	v_readlane_b32 s49, v237, 10
	v_readlane_b32 s50, v237, 11
	v_readlane_b32 s51, v237, 12
	v_readlane_b32 s54, v237, 15
	v_readlane_b32 s55, v237, 16
	v_readlane_b32 s56, v237, 17
	v_readlane_b32 s57, v237, 18
	v_readlane_b32 s58, v237, 19
	v_readlane_b32 s59, v237, 20
	.p2alignl 6, 3212836864

.LBB0_28:
	s_add_u32 s8, s88, 0x600000
	s_addc_u32 s9, s89, 0
	s_cmpk_lt_i32 s24, 0x100
	v_mov_b32_e32 v30, v128
	s_cselect_b64 s[0:1], -1, 0
	s_cmpk_gt_i32 s24, 0xff
	s_cbranch_scc1 .LBB0_31
	s_ashr_i32 s2, s24, 31
	s_lshr_b32 s2, s2, 24
	s_add_i32 s4, s24, s2
	s_ashr_i32 s2, s4, 8
	v_readlane_b32 s44, v237, 5
	s_ashr_i32 s3, s2, 31
	v_readlane_b32 s54, v237, 15
	v_readlane_b32 s55, v237, 16
	s_lshl_b64 s[2:3], s[2:3], 22
	s_mov_b64 s[26:27], s[54:55]
	s_add_u32 s5, s26, s2
	s_addc_u32 s6, s27, s3
	s_and_b32 s2, s4, 0xffffff00
	s_sub_i32 s4, s24, s2
	s_ashr_i32 s2, s4, 31
	s_lshr_b32 s2, s2, 28
	s_add_i32 s2, s4, s2
	s_ashr_i32 s7, s2, 4
	s_lshl_b32 s2, s7, 6
	s_ashr_i32 s3, s2, 31
	s_lshl_b64 s[2:3], s[2:3], 12
	s_add_u32 s5, s5, s2
	s_addc_u32 s6, s6, s3
	s_lshl_b32 s2, s7, 10
	s_lshl_b32 s3, s4, 6
	s_sub_i32 s2, s3, s2
	s_ashr_i32 s3, s2, 31
	v_ashrrev_i32_e32 v28, 4, v30
	s_lshl_b64 s[2:3], s[2:3], 2
	v_and_b32_e32 v1, 15, v30
	v_add_u32_e32 v22, 16, v28
	v_add_u32_e32 v24, 32, v28
	v_add_u32_e32 v26, 48, v28
	s_add_u32 s2, s5, s2
	v_mov_b32_e32 v19, 0
	v_ashrrev_i32_e32 v29, 31, v28
	v_ashrrev_i32_e32 v23, 31, v22
	v_ashrrev_i32_e32 v25, 31, v24
	v_ashrrev_i32_e32 v27, 31, v26
	s_addc_u32 s3, s6, s3
	v_lshlrev_b32_e32 v18, 4, v1
	v_lshl_add_u64 v[10:11], s[2:3], 0, v[18:19]
	v_lshlrev_b64 v[2:3], 12, v[26:27]
	v_lshlrev_b64 v[4:5], 12, v[24:25]
	v_lshlrev_b64 v[12:13], 12, v[22:23]
	v_lshlrev_b64 v[14:15], 12, v[28:29]
	v_lshl_add_u64 v[2:3], v[10:11], 0, v[2:3]
	v_lshl_add_u64 v[6:7], v[10:11], 0, v[4:5]
	v_lshl_add_u64 v[12:13], v[10:11], 0, v[12:13]
	v_lshl_add_u64 v[14:15], v[10:11], 0, v[14:15]
	global_load_dwordx4 v[2:5], v[2:3], off nt
	s_nop 0
	global_load_dwordx4 v[6:9], v[6:7], off nt
	s_nop 0
	global_load_dwordx4 v[10:13], v[12:13], off nt
	s_nop 0
	global_load_dwordx4 v[14:17], v[14:15], off nt
	v_lshlrev_b32_e32 v18, 2, v1
	v_mul_u32_u24_e32 v1, 0x120, v1
	v_lshlrev_b32_e32 v1, 1, v1
	v_lshlrev_b64 v[20:21], 10, v[28:29]
	v_lshl_add_u32 v1, v28, 1, v1
	v_lshlrev_b32_e32 v28, 3, v30
	v_and_b32_e32 v32, 56, v28
	v_lshlrev_b32_e32 v36, 1, v32
	v_ashrrev_i32_e32 v34, 3, v30
	s_movk_i32 s4, 0x90
	v_mad_u64_u32 v[28:29], s[2:3], v34, s4, v[36:37]
	v_add_u32_e32 v29, 0x100, v30
	v_ashrrev_i32_e32 v29, 3, v29
	v_lshlrev_b64 v[22:23], 10, v[22:23]
	v_lshlrev_b64 v[24:25], 10, v[24:25]
	v_lshlrev_b64 v[26:27], 10, v[26:27]
	v_mad_u64_u32 v[30:31], s[2:3], v29, s4, v[36:37]
	s_lshl_b32 s4, s24, 6
	s_lshl_b32 s5, s90, 6
	v_lshlrev_b32_e32 v18, 2, v18
	v_lshlrev_b32_e32 v32, 1, v32
	v_mov_b32_e32 v33, v19
	s_mov_b32 s6, s24
	v_readlane_b32 s45, v237, 6
	v_readlane_b32 s46, v237, 7
	v_readlane_b32 s47, v237, 8
	v_readlane_b32 s48, v237, 9
	v_readlane_b32 s49, v237, 10
	v_readlane_b32 s50, v237, 11
	v_readlane_b32 s51, v237, 12
	v_readlane_b32 s52, v237, 13
	v_readlane_b32 s53, v237, 14
	v_readlane_b32 s56, v237, 17
	v_readlane_b32 s57, v237, 18
	v_readlane_b32 s58, v237, 19
	v_readlane_b32 s59, v237, 20
	.p2alignl 6, 3212836864

.LBB0_31:
	s_add_u32 s2, s88, 0x800000
	s_addc_u32 s3, s89, 0
	v_writelane_b32 v237, s2, 21
	v_mov_b32_e32 v30, v128
	s_cmpk_gt_i32 s24, 0x17f
	v_writelane_b32 v237, s3, 22
	s_cbranch_scc1 .LBB0_34
	v_ashrrev_i32_e32 v1, 4, v30
	s_movk_i32 s4, 0x600
	v_add_u32_e32 v2, 16, v1
	v_mad_i64_i32 v[22:23], s[2:3], v2, s4, 0
	v_add_u32_e32 v2, 32, v1
	v_mad_i64_i32 v[24:25], s[2:3], v2, s4, 0
	v_add_u32_e32 v2, 48, v1
	v_mad_i64_i32 v[20:21], s[2:3], v1, s4, 0
	v_mad_i64_i32 v[26:27], s[2:3], v2, s4, 0
	s_mul_hi_i32 s2, s24, 0x2aaaaaab
	s_lshr_b32 s3, s2, 31
	s_ashr_i32 s2, s2, 6
	v_readlane_b32 s44, v237, 5
	s_add_i32 s2, s2, s3
	v_readlane_b32 s56, v237, 17
	v_readlane_b32 s57, v237, 18
	s_mul_i32 s4, s2, 0x600000
	v_readlane_b32 s58, v237, 19
	v_readlane_b32 s59, v237, 20
	s_mov_b64 s[28:29], s[56:57]
	s_mul_hi_i32 s3, s2, 0x600000
	s_add_u32 s4, s28, s4
	s_mulk_i32 s2, 0xfe80
	s_addc_u32 s3, s29, s3
	s_add_i32 s2, s2, s24
	s_mul_hi_i32 s5, s2, 0x2aaaaaab
	s_lshr_b32 s6, s5, 31
	s_ashr_i32 s5, s5, 2
	s_add_i32 s5, s5, s6
	s_lshl_b32 s6, s5, 6
	s_mul_i32 s7, s5, 0x60000
	s_mul_hi_i32 s6, s6, 0x1800
	s_add_u32 s4, s4, s7
	s_addc_u32 s6, s3, s6
	s_mul_i32 s3, s5, 0xffffffe8
	s_add_i32 s3, s3, s2
	s_lshl_b32 s2, s3, 6
	s_ashr_i32 s3, s2, 31
	s_lshl_b64 s[2:3], s[2:3], 2
	v_and_b32_e32 v28, 15, v30
	s_add_u32 s2, s4, s2
	v_mov_b32_e32 v19, 0
	s_addc_u32 s3, s6, s3
	v_lshlrev_b32_e32 v18, 4, v28
	v_lshl_add_u64 v[10:11], s[2:3], 0, v[18:19]
	v_lshl_add_u64 v[2:3], v[26:27], 2, v[10:11]
	v_lshl_add_u64 v[6:7], v[24:25], 2, v[10:11]
	v_lshl_add_u64 v[12:13], v[22:23], 2, v[10:11]
	v_lshl_add_u64 v[14:15], v[20:21], 2, v[10:11]
	global_load_dwordx4 v[2:5], v[2:3], off nt
	s_nop 0
	global_load_dwordx4 v[6:9], v[6:7], off nt
	s_nop 0
	global_load_dwordx4 v[10:13], v[12:13], off nt
	s_nop 0
	global_load_dwordx4 v[14:17], v[14:15], off nt
	v_lshlrev_b32_e32 v18, 2, v28
	v_mul_u32_u24_e32 v28, 0x120, v28
	v_lshlrev_b32_e32 v28, 1, v28
	v_lshl_add_u32 v1, v1, 1, v28
	v_lshlrev_b32_e32 v28, 3, v30
	v_and_b32_e32 v32, 56, v28
	v_lshlrev_b32_e32 v36, 1, v32
	v_ashrrev_i32_e32 v34, 3, v30
	s_movk_i32 s4, 0x90
	v_mad_u64_u32 v[28:29], s[2:3], v34, s4, v[36:37]
	v_add_u32_e32 v29, 0x100, v30
	v_ashrrev_i32_e32 v29, 3, v29
	v_mad_u64_u32 v[30:31], s[2:3], v29, s4, v[36:37]
	v_readlane_b32 s18, v237, 21
	v_lshlrev_b32_e32 v18, 2, v18
	v_lshlrev_b32_e32 v32, 1, v32
	v_mov_b32_e32 v33, v19
	s_mov_b32 s2, s24
	v_readlane_b32 s19, v237, 22
	v_readlane_b32 s45, v237, 6
	v_readlane_b32 s46, v237, 7
	v_readlane_b32 s47, v237, 8
	v_readlane_b32 s48, v237, 9
	v_readlane_b32 s49, v237, 10
	v_readlane_b32 s50, v237, 11
	v_readlane_b32 s51, v237, 12
	v_readlane_b32 s52, v237, 13
	v_readlane_b32 s53, v237, 14
	v_readlane_b32 s54, v237, 15
	v_readlane_b32 s55, v237, 16
	s_mov_b64 s[30:31], s[58:59]
	.p2alignl 6, 3212836864

.LBB0_34:
	s_add_u32 s2, s88, 0xb00000
	s_addc_u32 s3, s89, 0
	v_writelane_b32 v237, s2, 23
	v_mov_b32_e32 v30, v128
	s_andn2_b64 vcc, exec, s[0:1]
	v_writelane_b32 v237, s3, 24
	s_cbranch_vccnz .LBB0_37
	s_ashr_i32 s0, s24, 31
	s_lshr_b32 s0, s0, 24
	s_add_i32 s2, s24, s0
	s_ashr_i32 s0, s2, 8
	s_ashr_i32 s1, s0, 31
	s_lshl_b64 s[0:1], s[0:1], 22
	s_waitcnt lgkmcnt(0)
	s_add_u32 s3, s60, s0
	s_addc_u32 s4, s61, s1
	s_and_b32 s0, s2, 0xffffff00
	s_sub_i32 s2, s24, s0
	s_ashr_i32 s0, s2, 31
	s_lshr_b32 s0, s0, 28
	s_add_i32 s0, s2, s0
	s_ashr_i32 s5, s0, 4
	s_lshl_b32 s0, s5, 6
	s_ashr_i32 s1, s0, 31
	s_lshl_b64 s[0:1], s[0:1], 12
	s_add_u32 s3, s3, s0
	s_addc_u32 s4, s4, s1
	s_lshl_b32 s0, s5, 10
	s_lshl_b32 s1, s2, 6
	s_sub_i32 s0, s1, s0
	s_ashr_i32 s1, s0, 31
	v_ashrrev_i32_e32 v28, 4, v30
	s_lshl_b64 s[0:1], s[0:1], 2
	v_and_b32_e32 v1, 15, v30
	v_add_u32_e32 v22, 16, v28
	v_add_u32_e32 v24, 32, v28
	v_add_u32_e32 v26, 48, v28
	s_add_u32 s0, s3, s0
	v_mov_b32_e32 v19, 0
	v_ashrrev_i32_e32 v29, 31, v28
	v_ashrrev_i32_e32 v23, 31, v22
	v_ashrrev_i32_e32 v25, 31, v24
	v_ashrrev_i32_e32 v27, 31, v26
	s_addc_u32 s1, s4, s1
	v_lshlrev_b32_e32 v18, 4, v1
	v_lshl_add_u64 v[10:11], s[0:1], 0, v[18:19]
	v_lshlrev_b64 v[2:3], 12, v[26:27]
	v_lshlrev_b64 v[4:5], 12, v[24:25]
	v_lshlrev_b64 v[12:13], 12, v[22:23]
	v_lshlrev_b64 v[14:15], 12, v[28:29]
	v_lshl_add_u64 v[2:3], v[10:11], 0, v[2:3]
	v_lshl_add_u64 v[6:7], v[10:11], 0, v[4:5]
	v_lshl_add_u64 v[12:13], v[10:11], 0, v[12:13]
	v_lshl_add_u64 v[14:15], v[10:11], 0, v[14:15]
	global_load_dwordx4 v[2:5], v[2:3], off nt
	s_nop 0
	global_load_dwordx4 v[6:9], v[6:7], off nt
	s_nop 0
	global_load_dwordx4 v[10:13], v[12:13], off nt
	s_nop 0
	global_load_dwordx4 v[14:17], v[14:15], off nt
	v_lshlrev_b32_e32 v18, 2, v1
	v_mul_u32_u24_e32 v1, 0x120, v1
	v_lshlrev_b32_e32 v1, 1, v1
	v_lshlrev_b64 v[20:21], 10, v[28:29]
	v_lshl_add_u32 v1, v28, 1, v1
	v_lshlrev_b32_e32 v28, 3, v30
	v_and_b32_e32 v32, 56, v28
	v_lshlrev_b32_e32 v36, 1, v32
	v_ashrrev_i32_e32 v34, 3, v30
	s_movk_i32 s2, 0x90
	v_mad_u64_u32 v[28:29], s[0:1], v34, s2, v[36:37]
	v_add_u32_e32 v29, 0x100, v30
	v_ashrrev_i32_e32 v29, 3, v29
	v_readlane_b32 s18, v237, 23
	v_lshlrev_b64 v[22:23], 10, v[22:23]
	v_lshlrev_b64 v[24:25], 10, v[24:25]
	v_lshlrev_b64 v[26:27], 10, v[26:27]
	v_mad_u64_u32 v[30:31], s[0:1], v29, s2, v[36:37]
	s_lshl_b32 s2, s24, 6
	s_lshl_b32 s3, s90, 6
	v_lshlrev_b32_e32 v18, 2, v18
	v_lshlrev_b32_e32 v32, 1, v32
	v_mov_b32_e32 v33, v19
	s_mov_b32 s4, s24
	v_readlane_b32 s19, v237, 24
	.p2alignl 6, 3212836864

.LBB0_37:
	s_add_u32 s20, s88, 0xd00000
	s_addc_u32 s21, s89, 0
	s_cmpk_lt_i32 s24, 0x1000
	v_mov_b32_e32 v30, v128
	s_cselect_b64 s[2:3], -1, 0
	s_cmpk_gt_i32 s24, 0xfff
	s_cbranch_scc1 .LBB0_40
	s_ashr_i32 s0, s24, 31
	s_lshr_b32 s0, s0, 25
	s_add_i32 s4, s24, s0
	s_ashr_i32 s0, s4, 7
	s_ashr_i32 s1, s0, 31
	s_lshl_b64 s[0:1], s[0:1], 21
	s_waitcnt lgkmcnt(0)
	s_add_u32 s5, s74, s0
	s_addc_u32 s6, s75, s1
	s_and_b32 s0, s4, 0xffffff80
	s_sub_i32 s4, s24, s0
	s_ashr_i32 s0, s4, 31
	s_lshr_b32 s0, s0, 29
	s_add_i32 s0, s4, s0
	s_ashr_i32 s7, s0, 3
	s_lshl_b32 s0, s7, 6
	s_ashr_i32 s1, s0, 31
	s_lshl_b64 s[0:1], s[0:1], 11
	s_add_u32 s5, s5, s0
	s_addc_u32 s6, s6, s1
	s_lshl_b32 s0, s7, 9
	s_lshl_b32 s1, s4, 6
	s_sub_i32 s0, s1, s0
	s_ashr_i32 s1, s0, 31
	v_ashrrev_i32_e32 v28, 4, v30
	s_lshl_b64 s[0:1], s[0:1], 2
	v_and_b32_e32 v1, 15, v30
	v_add_u32_e32 v22, 16, v28
	v_add_u32_e32 v24, 32, v28
	v_add_u32_e32 v26, 48, v28
	s_add_u32 s0, s5, s0
	v_mov_b32_e32 v19, 0
	v_ashrrev_i32_e32 v29, 31, v28
	v_ashrrev_i32_e32 v23, 31, v22
	v_ashrrev_i32_e32 v25, 31, v24
	v_ashrrev_i32_e32 v27, 31, v26
	s_addc_u32 s1, s6, s1
	v_lshlrev_b32_e32 v18, 4, v1
	v_lshl_add_u64 v[10:11], s[0:1], 0, v[18:19]
	v_lshlrev_b64 v[2:3], 11, v[26:27]
	v_lshlrev_b64 v[4:5], 11, v[24:25]
	v_lshlrev_b64 v[12:13], 11, v[22:23]
	v_lshlrev_b64 v[14:15], 11, v[28:29]
	v_lshl_add_u64 v[2:3], v[10:11], 0, v[2:3]
	v_lshl_add_u64 v[6:7], v[10:11], 0, v[4:5]
	v_lshl_add_u64 v[12:13], v[10:11], 0, v[12:13]
	v_lshl_add_u64 v[14:15], v[10:11], 0, v[14:15]
	global_load_dwordx4 v[2:5], v[2:3], off nt
	s_nop 0
	global_load_dwordx4 v[6:9], v[6:7], off nt
	s_nop 0
	global_load_dwordx4 v[10:13], v[12:13], off nt
	s_nop 0
	global_load_dwordx4 v[14:17], v[14:15], off nt
	v_lshlrev_b32_e32 v18, 2, v1
	v_mul_u32_u24_e32 v1, 0x120, v1
	v_lshlrev_b32_e32 v1, 1, v1
	v_lshlrev_b64 v[20:21], 9, v[28:29]
	v_lshl_add_u32 v1, v28, 1, v1
	v_lshlrev_b32_e32 v28, 3, v30
	v_and_b32_e32 v32, 56, v28
	v_lshlrev_b32_e32 v36, 1, v32
	v_ashrrev_i32_e32 v34, 3, v30
	s_movk_i32 s5, 0x90
	v_mad_u64_u32 v[28:29], s[0:1], v34, s5, v[36:37]
	v_add_u32_e32 v29, 0x100, v30
	v_ashrrev_i32_e32 v29, 3, v29
	v_mad_u64_u32 v[30:31], s[0:1], v29, s5, v[36:37]
	v_lshlrev_b64 v[22:23], 9, v[22:23]
	v_lshlrev_b64 v[24:25], 9, v[24:25]
	v_lshlrev_b64 v[26:27], 9, v[26:27]
	s_movk_i32 s4, 0x100
	v_and_b32_e32 v31, 31, v34
	v_and_b32_e32 v35, 31, v29
	s_lshl_b32 s5, s24, 6
	s_lshl_b32 s6, s90, 6
	v_lshlrev_b32_e32 v18, 2, v18
	v_lshlrev_b32_e32 v32, 1, v32
	v_mov_b32_e32 v33, v19
	v_mov_b32_e32 v36, 0xffffff00
	s_mov_b32 s14, s24
	.p2alignl 6, 3212836864

.LBB0_40:
	s_add_u32 s22, s88, 0x2d00000
	s_addc_u32 s23, s89, 0
	s_cmpk_lt_i32 s24, 0x800
	v_writelane_b32 v237, s20, 25
	v_mov_b32_e32 v30, v128
	s_cselect_b64 s[0:1], -1, 0
	s_cmpk_gt_i32 s24, 0x7ff
	v_writelane_b32 v237, s21, 26
	s_cbranch_scc1 .LBB0_43
	s_ashr_i32 s4, s24, 31
	s_lshr_b32 s4, s4, 26
	s_add_i32 s6, s24, s4
	s_ashr_i32 s4, s6, 6
	s_ashr_i32 s5, s4, 31
	s_lshl_b64 s[4:5], s[4:5], 20
	s_add_u32 s7, s80, s4
	s_addc_u32 s14, s81, s5
	s_andn2_b32 s6, s6, 63
	s_sub_i32 s6, s24, s6
	s_ashr_i32 s4, s6, 31
	s_lshr_b32 s4, s4, 28
	s_add_i32 s4, s6, s4
	s_ashr_i32 s15, s4, 4
	s_lshl_b32 s4, s15, 6
	s_ashr_i32 s5, s4, 31
	s_lshl_b64 s[4:5], s[4:5], 12
	s_add_u32 s7, s7, s4
	s_addc_u32 s14, s14, s5
	s_lshl_b32 s4, s15, 10
	s_lshl_b32 s5, s6, 6
	s_sub_i32 s4, s5, s4
	s_ashr_i32 s5, s4, 31
	v_ashrrev_i32_e32 v28, 4, v30
	s_lshl_b64 s[4:5], s[4:5], 2
	v_and_b32_e32 v1, 15, v30
	v_add_u32_e32 v22, 16, v28
	v_add_u32_e32 v24, 32, v28
	v_add_u32_e32 v26, 48, v28
	s_add_u32 s4, s7, s4
	v_mov_b32_e32 v19, 0
	v_ashrrev_i32_e32 v29, 31, v28
	v_ashrrev_i32_e32 v23, 31, v22
	v_ashrrev_i32_e32 v25, 31, v24
	v_ashrrev_i32_e32 v27, 31, v26
	s_addc_u32 s5, s14, s5
	v_lshlrev_b32_e32 v18, 4, v1
	v_lshl_add_u64 v[10:11], s[4:5], 0, v[18:19]
	v_lshlrev_b64 v[2:3], 12, v[26:27]
	v_lshlrev_b64 v[4:5], 12, v[24:25]
	v_lshlrev_b64 v[12:13], 12, v[22:23]
	v_lshlrev_b64 v[14:15], 12, v[28:29]
	v_lshl_add_u64 v[2:3], v[10:11], 0, v[2:3]
	v_lshl_add_u64 v[6:7], v[10:11], 0, v[4:5]
	v_lshl_add_u64 v[12:13], v[10:11], 0, v[12:13]
	v_lshl_add_u64 v[14:15], v[10:11], 0, v[14:15]
	global_load_dwordx4 v[2:5], v[2:3], off nt
	s_nop 0
	global_load_dwordx4 v[6:9], v[6:7], off nt
	s_nop 0
	global_load_dwordx4 v[10:13], v[12:13], off nt
	s_nop 0
	global_load_dwordx4 v[14:17], v[14:15], off nt
	v_lshlrev_b32_e32 v18, 2, v1
	v_mul_u32_u24_e32 v1, 0x120, v1
	v_lshlrev_b32_e32 v1, 1, v1
	v_lshlrev_b64 v[20:21], 10, v[28:29]
	v_lshl_add_u32 v1, v28, 1, v1
	v_lshlrev_b32_e32 v28, 3, v30
	v_and_b32_e32 v32, 56, v28
	v_lshlrev_b32_e32 v36, 1, v32
	v_ashrrev_i32_e32 v34, 3, v30
	s_movk_i32 s6, 0x90
	v_mad_u64_u32 v[28:29], s[4:5], v34, s6, v[36:37]
	v_add_u32_e32 v29, 0x100, v30
	v_ashrrev_i32_e32 v29, 3, v29
	v_mad_u64_u32 v[30:31], s[4:5], v29, s6, v[36:37]
	v_lshlrev_b64 v[22:23], 10, v[22:23]
	v_lshlrev_b64 v[24:25], 10, v[24:25]
	v_lshlrev_b64 v[26:27], 10, v[26:27]
	s_lshl_b32 s4, s24, 6
	s_lshl_b32 s5, s90, 6
	v_lshlrev_b32_e32 v18, 2, v18
	v_lshlrev_b32_e32 v32, 1, v32
	v_mov_b32_e32 v33, v19
	s_mov_b32 s14, s24
	.p2alignl 6, 3212836864

.LBB0_43:
	v_writelane_b32 v237, s22, 27
	s_mov_b32 s25, 0
	s_lshl_b64 s[4:5], s[24:25], 8
	v_writelane_b32 v237, s23, 28
	v_mov_b32_e32 v6, v128
	v_writelane_b32 v237, s4, 29
	v_ashrrev_i32_e32 v7, 31, v6
	s_nop 0
	v_writelane_b32 v237, s5, 30
	v_lshl_add_u64 v[2:3], s[4:5], 0, v[6:7]
	s_mov_b64 s[4:5], 0x400000
	v_cmp_gt_u64_e32 vcc, s[4:5], v[2:3]
	s_and_saveexec_b64 s[6:7], vcc
	s_cbranch_execz .LBB0_46
	s_mov_b32 s4, s90
	s_mov_b32 s5, s25
	s_lshl_b64 s[14:15], s[4:5], 8
	s_lshl_b64 s[16:17], s[24:25], 12
	s_add_u32 s16, s88, s16
	s_addc_u32 s17, s89, s17
	v_lshl_add_u64 v[4:5], v[6:7], 4, s[16:17]
	s_mov_b64 s[16:17], 0xe500000
	v_lshl_add_u64 v[4:5], v[4:5], 0, s[16:17]
	s_lshl_b64 s[16:17], s[4:5], 12
	s_lshl_b64 s[18:19], s[24:25], 13
	s_add_u32 s18, s36, s18
	v_lshlrev_b64 v[6:7], 5, v[6:7]
	s_addc_u32 s19, s37, s19
	v_lshl_add_u64 v[6:7], s[18:19], 0, v[6:7]
	v_lshl_add_u64 v[6:7], v[6:7], 0, 16
	s_lshl_b64 s[18:19], s[4:5], 13
	s_mov_b64 s[20:21], 0
	s_mov_b64 s[22:23], 0x3fffff
	.p2alignl 6, 3212836864

.Lmy_prep_tail:
	v_cmp_ge_u64_e32 vcc, s[22:23], v[2:3]
	s_and_b64 exec, exec, vcc
	s_cbranch_execz .LBB0_46
	.p2alignl 6, 3212836864

.LBB0_52:
	s_or_b64 exec, exec, s[14:15]
	v_mov_b32_e32 v0, 0
	global_load_dword v2, v0, s[12:13] offset:32 sc1
	v_and_b32_e32 v1, 0xffff0000, v1
	s_waitcnt vmcnt(0)
	v_and_b32_e32 v2, 0xffff0000, v2
	v_cmp_eq_u32_e32 vcc, v2, v1
	s_and_b64 exec, exec, vcc
	s_cbranch_execz .LBB0_55
	s_mov_b64 s[14:15], 0
	.p2alignl 6, 3212836864

.LBB0_59:
	s_or_b64 exec, exec, s[6:7]
	s_add_u32 s58, s88, 0xe500000
	s_addc_u32 s59, s89, 0
	s_add_u32 s76, s88, 0x4500000
	s_addc_u32 s77, s89, 0
	v_readlane_b32 s4, v237, 31
	v_mov_b32_e32 v0, v128
	s_cmpk_gt_i32 s4, 0x13ff
	v_readlane_b32 s5, v237, 32
	s_cbranch_scc1 .LBB0_90
	v_lshlrev_b32_e32 v0, 7, v0
	v_and_b32_e32 v129, 0xfffffc00, v0
	v_readlane_b32 s4, v237, 31
	s_lshl_b32 s20, s90, 17
	s_mov_b64 s[14:15], -1
	v_lshl_add_u32 v0, s4, 17, v129
	v_add_u32_e32 v134, 0x18100, v0
	v_add_u32_e32 v135, 0x10100, v0
	v_add_u32_e32 v136, 0x8100, v0
	v_or_b32_e32 v137, 0x100, v0
	v_add_u32_e32 v138, 0x180c0, v0
	v_add_u32_e32 v139, 0x100c0, v0
	v_add_u32_e32 v140, 0x80c0, v0
	v_or_b32_e32 v141, 0xc0, v0
	s_movk_i32 s21, 0x50
	s_movk_i32 s22, 0x1400
	v_mov_b32_e32 v131, 0
	s_movk_i32 s23, 0xffc0
	s_movk_i32 s24, 0xa0
	s_movk_i32 s25, 0x110
	s_mov_b32 s7, 0
	s_mov_b32 s16, s4
	v_readlane_b32 s5, v237, 32
	s_branch .LBB0_62
	.p2alignl 6, 3212836864

.LBB0_66:
	s_add_i32 s28, s16, s90
	s_cmpk_gt_i32 s28, 0x13ff
	s_cselect_b64 s[12:13], -1, 0
	s_cmpk_lt_i32 s28, 0x1400
	s_cselect_b64 s[14:15], -1, 0
	s_and_b64 s[4:5], s[14:15], exec
	s_cselect_b32 s4, s28, s16
	s_mul_hi_i32 s5, s4, 0x66666667
	s_lshr_b32 s16, s5, 31
	s_ashr_i32 s5, s5, 3
	s_add_i32 s5, s5, s16
	v_and_b32_e32 v66, 15, v142
	v_bfe_u32 v144, v142, 4, 2
	v_lshlrev_b32_e32 v67, 1, v143
	v_ashrrev_i32_e32 v68, 1, v142
	s_mul_i32 s16, s5, 0x7fec
	v_lshl_add_u32 v146, v72, 1, v67
	v_lshl_add_u32 v147, v69, 1, v67
	v_lshl_add_u32 v148, v70, 1, v67
	v_lshl_add_u32 v149, v71, 1, v67
	v_or_b32_e32 v67, 0x3c0, v143
	v_and_or_b32 v145, v68, s23, v66
	v_lshlrev_b32_e32 v66, 4, v144
	v_and_b32_e32 v68, 0x4f, v142
	s_add_i32 s16, s16, s4
	s_lshl_b32 s29, s5, 17
	v_mad_u64_u32 v[132:133], s[4:5], v145, s24, v[66:67]
	v_mul_u32_u24_e32 v68, 0x50, v68
	v_lshl_add_u32 v133, v68, 1, v66
	v_add_u32_e32 v152, v67, v64
	v_add_u32_e32 v153, v67, v65
	s_mul_i32 s4, s6, 0x280000
	v_mov_b32_e32 v64, 0
	s_lshl_b32 s30, s16, 17
	v_add_u32_e32 v150, 0xf000, v133
	v_add_u32_e32 v151, 0xf040, v133
	v_add_u32_e32 v154, 0x8000, v152
	v_add_u32_e32 v155, 0x8000, v153
	v_add_u32_e32 v156, 0x10000, v152
	v_add_u32_e32 v157, 0x10000, v153
	v_add_u32_e32 v158, 0x18000, v152
	v_add_u32_e32 v159, 0x18000, v153
	v_add_u32_e32 v160, v129, v143
	v_subrev_u32_e32 v161, s4, v134
	v_subrev_u32_e32 v162, s4, v135
	v_subrev_u32_e32 v163, s4, v136
	v_subrev_u32_e32 v164, s4, v137
	v_subrev_u32_e32 v165, s4, v138
	v_subrev_u32_e32 v166, s4, v139
	v_subrev_u32_e32 v167, s4, v140
	v_subrev_u32_e32 v168, s4, v141
	s_mov_b32 s31, 0
	v_mov_b32_e32 v65, v64
	v_mov_b32_e32 v66, v64
	v_mov_b32_e32 v67, v64
	v_mov_b32_e32 v68, v64
	v_mov_b32_e32 v69, v64
	v_mov_b32_e32 v70, v64
	v_mov_b32_e32 v71, v64
	v_mov_b32_e32 v72, v64
	v_mov_b32_e32 v73, v64
	v_mov_b32_e32 v74, v64
	v_mov_b32_e32 v75, v64
	v_mov_b32_e32 v76, v64
	v_mov_b32_e32 v77, v64
	v_mov_b32_e32 v78, v64
	v_mov_b32_e32 v79, v64
	v_mov_b32_e32 v80, v64
	v_mov_b32_e32 v81, v64
	v_mov_b32_e32 v82, v64
	v_mov_b32_e32 v83, v64
	v_mov_b32_e32 v84, v64
	v_mov_b32_e32 v85, v64
	v_mov_b32_e32 v86, v64
	v_mov_b32_e32 v87, v64
	v_mov_b32_e32 v88, v64
	v_mov_b32_e32 v89, v64
	v_mov_b32_e32 v90, v64
	v_mov_b32_e32 v91, v64
	v_mov_b32_e32 v92, v64
	v_mov_b32_e32 v93, v64
	v_mov_b32_e32 v94, v64
	v_mov_b32_e32 v95, v64
	v_mov_b32_e32 v96, v64
	v_mov_b32_e32 v97, v64
	v_mov_b32_e32 v98, v64
	v_mov_b32_e32 v99, v64
	v_mov_b32_e32 v100, v64
	v_mov_b32_e32 v101, v64
	v_mov_b32_e32 v102, v64
	v_mov_b32_e32 v103, v64
	v_mov_b32_e32 v104, v64
	v_mov_b32_e32 v105, v64
	v_mov_b32_e32 v106, v64
	v_mov_b32_e32 v107, v64
	v_mov_b32_e32 v108, v64
	v_mov_b32_e32 v109, v64
	v_mov_b32_e32 v110, v64
	v_mov_b32_e32 v111, v64
	v_mov_b32_e32 v112, v64
	v_mov_b32_e32 v113, v64
	v_mov_b32_e32 v114, v64
	v_mov_b32_e32 v115, v64
	v_mov_b32_e32 v116, v64
	v_mov_b32_e32 v117, v64
	v_mov_b32_e32 v118, v64
	v_mov_b32_e32 v119, v64
	v_mov_b32_e32 v120, v64
	v_mov_b32_e32 v121, v64
	v_mov_b32_e32 v122, v64
	v_mov_b32_e32 v123, v64
	v_mov_b32_e32 v124, v64
	v_mov_b32_e32 v125, v64
	v_mov_b32_e32 v126, v64
	v_mov_b32_e32 v127, v64
	s_branch .LBB0_68
	.p2alignl 6, 3212836864

.LBB0_90:
	s_waitcnt vmcnt(0)
	s_barrier
	s_mov_b64 s[6:7], exec
	v_readlane_b32 s4, v237, 1
	v_readlane_b32 s5, v237, 2
	s_and_b64 s[4:5], s[6:7], s[4:5]
	s_mov_b64 exec, s[4:5]
	s_cbranch_execz .LBB0_142
	v_mov_b32_e32 v0, 0x13ff0
	s_waitcnt vmcnt(0) expcnt(0) lgkmcnt(0)
	ds_read_b32 v2, v0
	v_mov_b32_e32 v0, 0x13ff4
	ds_read_b32 v0, v0
	s_waitcnt lgkmcnt(1)
	v_cmp_ne_u32_e32 vcc, 0, v2
	s_cbranch_vccnz .LBB0_106
	s_add_u32 s12, s88, 0x4100200
	s_addc_u32 s13, s89, 0
	s_add_u32 s14, s88, 0x4100400
	s_addc_u32 s15, s89, 0
	s_add_u32 s16, s88, 0x4100500
	s_addc_u32 s17, s89, 0
	s_add_u32 s18, s88, 0x4100600
	s_addc_u32 s19, s89, 0
	s_add_u32 s20, s88, 0x4100700
	s_addc_u32 s21, s89, 0
	s_add_u32 s22, s88, 0x4100800
	s_addc_u32 s23, s89, 0
	s_add_u32 s24, s88, 0x4100900
	s_addc_u32 s25, s89, 0
	s_add_u32 s26, s88, 0x4100a00
	s_addc_u32 s27, s89, 0
	s_add_u32 s28, s88, 0x4100b00
	s_addc_u32 s29, s89, 0
	s_add_u32 s30, s88, 0x4100c00
	s_addc_u32 s31, s89, 0
	s_add_u32 s34, s88, 0x4100d00
	s_addc_u32 s35, s89, 0
	s_add_u32 s38, s88, 0x4100e00
	s_addc_u32 s39, s89, 0
	s_add_u32 s40, s88, 0x4100f00
	s_addc_u32 s41, s89, 0
	s_add_u32 s44, s88, 0x4101000
	s_addc_u32 s45, s89, 0
	s_add_u32 s46, s88, 0x4101100
	s_addc_u32 s47, s89, 0
	s_add_u32 s48, s88, 0x4101200
	v_readlane_b32 s4, v237, 0
	s_addc_u32 s49, s89, 0
	s_mul_i32 s4, s91, s4
	s_add_u32 s50, s88, 0x4101300
	s_mul_i32 s4, s4, s90
	s_addc_u32 s51, s89, 0
	s_mov_b32 s5, 1
	v_mov_b32_e32 v16, 0
	s_branch .LBB0_94
	.p2alignl 6, 3212836864

.LBB0_94:
	global_load_dword v15, v16, s[14:15] sc1
	s_waitcnt lgkmcnt(0)
	global_load_dword v0, v16, s[16:17] sc1
	global_load_dword v1, v16, s[18:19] sc1
	global_load_dword v2, v16, s[20:21] sc1
	global_load_dword v3, v16, s[22:23] sc1
	global_load_dword v4, v16, s[24:25] sc1
	global_load_dword v5, v16, s[26:27] sc1
	global_load_dword v6, v16, s[28:29] sc1
	global_load_dword v7, v16, s[30:31] sc1
	global_load_dword v8, v16, s[34:35] sc1
	global_load_dword v9, v16, s[38:39] sc1
	global_load_dword v10, v16, s[40:41] sc1
	global_load_dword v11, v16, s[44:45] sc1
	global_load_dword v12, v16, s[46:47] sc1
	global_load_dword v13, v16, s[48:49] sc1
	global_load_dword v14, v16, s[50:51] sc1
	s_mov_b64 s[52:53], -1
	s_mov_b64 s[54:55], -1
	s_waitcnt vmcnt(14)
	v_add_u32_e32 v17, v0, v15
	s_waitcnt vmcnt(13)
	v_add_u32_e32 v17, v17, v1
	s_waitcnt vmcnt(12)
	v_add_u32_e32 v17, v17, v2
	s_waitcnt vmcnt(11)
	v_add_u32_e32 v17, v17, v3
	s_waitcnt vmcnt(10)
	v_add_u32_e32 v17, v17, v4
	s_waitcnt vmcnt(9)
	v_add_u32_e32 v17, v17, v5
	s_waitcnt vmcnt(8)
	v_add_u32_e32 v17, v17, v6
	s_waitcnt vmcnt(7)
	v_add_u32_e32 v17, v17, v7
	s_waitcnt vmcnt(6)
	v_add_u32_e32 v17, v17, v8
	s_waitcnt vmcnt(5)
	v_add_u32_e32 v17, v17, v9
	s_waitcnt vmcnt(4)
	v_add_u32_e32 v17, v17, v10
	s_waitcnt vmcnt(3)
	v_add_u32_e32 v17, v17, v11
	s_waitcnt vmcnt(2)
	v_add_u32_e32 v17, v17, v12
	s_waitcnt vmcnt(1)
	v_add_u32_e32 v17, v17, v13
	s_waitcnt vmcnt(0)
	v_add_u32_e32 v17, v17, v14
	v_cmp_eq_u32_e32 vcc, s4, v17
	s_cbranch_vccnz .LBB0_93
	s_and_b32 s33, s5, 0xff
	s_cmp_eq_u32 s33, 0
	s_mov_b64 s[56:57], -1
	s_sleep 1
	s_cbranch_scc1 .LBB0_98
	s_and_b64 vcc, exec, s[56:57]
	s_cbranch_vccz .LBB0_93
	.p2alignl 6, 3212836864

.Lmy_xb0_poll:
	s_mov_b32 s100, 0
	.p2alignl 6, 3212836864

.LBB0_142:
	s_or_b64 exec, exec, s[6:7]
	s_waitcnt lgkmcnt(0)
	v_cndmask_b32_e64 v0, 0, 1, s[0:1]
	v_cmp_ne_u32_e64 s[4:5], 1, v0
	s_andn2_b64 vcc, exec, s[0:1]
	s_nop 0
	v_writelane_b32 v237, s4, 34
	s_barrier
	s_nop 0
	v_writelane_b32 v237, s5, 35
	s_cbranch_vccnz .LBB0_149
	s_add_u32 s12, s88, 0x3d01000
	s_addc_u32 s13, s89, 0
	s_add_u32 s18, s88, 0x1d500000
	v_readlane_b32 s16, v237, 31
	s_addc_u32 s19, s89, 0
	s_lshl_b32 s20, s16, 6
	s_lshl_b32 s21, s90, 6
	s_movk_i32 s22, 0x7f
	s_movk_i32 s23, 0x1400
	v_mov_b32_e32 v1, 0
	s_movk_i32 s24, 0xa0
	s_mov_b32 s25, 0x800000
	s_mov_b32 s26, 0x3f317217
	s_mov_b32 s27, 0x7f800000
	v_mov_b32_e32 v38, 0x41b17218
	s_mov_b64 s[14:15], 0x60
	v_readlane_b32 s17, v237, 32
	s_branch .LBB0_145
	.p2alignl 6, 3212836864

.LBB0_157:
	s_or_b64 exec, exec, s[6:7]
	s_add_u32 s12, s88, 0x3d02000
	v_cndmask_b32_e64 v32, 0, 1, s[2:3]
	s_addc_u32 s13, s89, 0
	v_cmp_ne_u32_e64 s[60:61], 1, v32
	s_andn2_b64 vcc, exec, s[2:3]
	s_cbranch_vccnz .LBB0_176
	v_or_b32_e32 v32, v39, v38
	v_ashrrev_i32_e32 v33, 31, v32
	v_lshl_add_u64 v[32:33], v[32:33], 3, s[12:13]
	global_load_dwordx2 v[48:49], v[32:33], off
	s_add_u32 s14, s88, 0x1c500000
	v_readlane_b32 s0, v237, 31
	v_mov_b32_e32 v51, 0
	s_movk_i32 s15, 0x1400
	s_movk_i32 s16, 0x2100
	s_addc_u32 s17, s89, 0
	s_mov_b32 s18, s0
	v_readlane_b32 s1, v237, 32
	s_waitcnt vmcnt(0)
	v_mov_b32_e32 v52, v49
	v_mov_b32_e32 v53, v48
	.p2alignl 6, 3212836864

.LBB0_167:
	s_or_b64 exec, exec, s[6:7]
	v_mul_lo_u32 v57, v61, s16
	s_waitcnt vmcnt(0)
	v_mfma_f32_16x16x32_bf16 v[62:65], v[44:47], v[4:7], 0
	v_mul_u32_u24_e32 v50, 0x210, v60
	v_lshl_or_b32 v55, v55, 2, v57
	v_lshl_add_u32 v50, v50, 2, v55
	v_mfma_f32_16x16x32_bf16 v[66:69], v[44:47], v[8:11], 0
	v_add_u32_e32 v56, 0x400, v50
	s_barrier
	v_mfma_f32_16x16x32_bf16 v[70:73], v[44:47], v[0:3], 0
	v_mfma_f32_16x16x32_bf16 v[74:77], v[44:47], v[12:15], 0
	s_nop 3
	ds_write2_b32 v50, v62, v66 offset1:16
	ds_write2_b32 v50, v63, v67 offset0:132 offset1:148
	ds_write2_b32 v56, v64, v68 offset0:8 offset1:24
	v_mfma_f32_16x16x32_bf16 v[60:63], v[44:47], v[16:19], 0
	ds_write2_b32 v56, v65, v69 offset0:140 offset1:156
	ds_write2_b32 v50, v70, v74 offset0:32 offset1:48
	ds_write2_b32 v50, v71, v75 offset0:164 offset1:180
	s_mov_b32 s0, 0
	v_mfma_f32_16x16x32_bf16 v[64:67], v[44:47], v[24:27], 0
	ds_write2_b32 v56, v72, v76 offset0:40 offset1:56
	ds_write2_b32 v56, v73, v77 offset0:172 offset1:188
	s_nop 5
	ds_write2_b32 v50, v60, v64 offset0:64 offset1:80
	ds_write2_b32 v50, v61, v65 offset0:196 offset1:212
	ds_write2_b32 v56, v62, v66 offset0:72 offset1:88
	ds_write2_b32 v56, v63, v67 offset0:204 offset1:220
	v_mfma_f32_16x16x32_bf16 v[68:71], v[44:47], v[20:23], 0
	v_mfma_f32_16x16x32_bf16 v[44:47], v[44:47], v[28:31], 0
	s_nop 7
	ds_write2_b32 v50, v68, v44 offset0:96 offset1:112
	ds_write2_b32 v50, v69, v45 offset0:228 offset1:244
	ds_write2_b32 v56, v70, v46 offset0:104 offset1:120
	ds_write2_b32 v56, v71, v47 offset0:236 offset1:252
	v_lshl_or_b32 v45, v58, 2, v57
	v_mov_b32_e32 v44, 0
	.p2alignl 6, 3212836864
.LBB0_168:
	v_add_u32_e32 v57, s0, v45
	ds_read2st64_b32 v[60:61], v57 offset1:1
	v_pk_mul_f32 v[46:47], v[44:45], v[52:53] op_sel_hi:[0,1]
	v_pk_fma_f32 v[62:63], v[54:55], v[48:49], v[46:47] neg_lo:[0,0,1] neg_hi:[0,0,1]
	v_pk_fma_f32 v[46:47], v[54:55], v[48:49], v[46:47] op_sel_hi:[0,1,1]
	ds_read2_b32 v[54:55], v57 offset0:132 offset1:196
	v_mov_b32_e32 v63, v47
	s_waitcnt lgkmcnt(1)
	v_pk_add_f32 v[60:61], v[62:63], v[60:61]
	v_add_u32_e32 v44, 32, v57
	v_pk_mul_f32 v[62:63], v[60:61], v[52:53] op_sel:[1,0]
	v_add_u32_e32 v57, 48, v57
	v_pk_fma_f32 v[66:67], v[60:61], v[48:49], v[62:63] neg_lo:[0,0,1] neg_hi:[0,0,1]
	v_pk_fma_f32 v[60:61], v[60:61], v[48:49], v[62:63] op_sel_hi:[0,1,1]
	v_mov_b32_e32 v67, v61
	ds_read2st64_b32 v[46:47], v44 offset0:4 offset1:5
	ds_read2st64_b32 v[64:65], v57 offset0:6 offset1:7
	s_waitcnt lgkmcnt(2)
	v_pk_add_f32 v[54:55], v[66:67], v[54:55]
	s_addk_i32 s0, 0x840
	v_pk_mul_f32 v[60:61], v[54:55], v[52:53] op_sel:[1,0]
	s_cmpk_eq_i32 s0, 0x2100
	v_pk_fma_f32 v[62:63], v[54:55], v[48:49], v[60:61] neg_lo:[0,0,1] neg_hi:[0,0,1]
	v_pk_fma_f32 v[54:55], v[54:55], v[48:49], v[60:61] op_sel_hi:[0,1,1]
	v_mov_b32_e32 v63, v55
	s_waitcnt lgkmcnt(1)
	v_pk_add_f32 v[46:47], v[62:63], v[46:47]
	s_nop 0
	v_pk_mul_f32 v[54:55], v[46:47], v[52:53] op_sel:[1,0]
	s_nop 0
	v_pk_fma_f32 v[60:61], v[46:47], v[48:49], v[54:55] neg_lo:[0,0,1] neg_hi:[0,0,1]
	v_pk_fma_f32 v[46:47], v[46:47], v[48:49], v[54:55] op_sel_hi:[0,1,1]
	v_mov_b32_e32 v61, v47
	s_waitcnt lgkmcnt(0)
	v_pk_add_f32 v[54:55], v[60:61], v[64:65]
	s_nop 0
	v_mov_b32_e32 v44, v55
	s_cbranch_scc0 .LBB0_168
	v_mfma_f32_16x16x32_bf16 v[60:63], v[40:43], v[4:7], 0
	s_mov_b32 s0, 0
	v_mfma_f32_16x16x32_bf16 v[64:67], v[40:43], v[8:11], 0
	s_nop 7
	ds_write2_b32 v50, v60, v64 offset1:16
	ds_write2_b32 v50, v61, v65 offset0:132 offset1:148
	ds_write2_b32 v56, v62, v66 offset0:8 offset1:24
	v_mfma_f32_16x16x32_bf16 v[68:71], v[40:43], v[0:3], 0
	v_mfma_f32_16x16x32_bf16 v[72:75], v[40:43], v[12:15], 0
	ds_write2_b32 v56, v63, v67 offset0:140 offset1:156
	s_nop 6
	ds_write2_b32 v50, v68, v72 offset0:32 offset1:48
	ds_write2_b32 v50, v69, v73 offset0:164 offset1:180
	v_mfma_f32_16x16x32_bf16 v[76:79], v[40:43], v[16:19], 0
	v_mfma_f32_16x16x32_bf16 v[60:63], v[40:43], v[24:27], 0
	ds_write2_b32 v56, v70, v74 offset0:40 offset1:56
	ds_write2_b32 v56, v71, v75 offset0:172 offset1:188
	s_nop 5
	ds_write2_b32 v50, v76, v60 offset0:64 offset1:80
	ds_write2_b32 v50, v77, v61 offset0:196 offset1:212
	ds_write2_b32 v56, v78, v62 offset0:72 offset1:88
	ds_write2_b32 v56, v79, v63 offset0:204 offset1:220
	v_mfma_f32_16x16x32_bf16 v[64:67], v[40:43], v[20:23], 0
	v_mfma_f32_16x16x32_bf16 v[40:43], v[40:43], v[28:31], 0
	s_nop 7
	ds_write2_b32 v50, v64, v40 offset0:96 offset1:112
	ds_write2_b32 v50, v65, v41 offset0:228 offset1:244
	ds_write2_b32 v56, v66, v42 offset0:104 offset1:120
	ds_write2_b32 v56, v67, v43 offset0:236 offset1:252
	.p2alignl 6, 3212836864
.LBB0_170:
	v_add_u32_e32 v44, s0, v45
	ds_read2st64_b32 v[42:43], v44 offset1:1
	v_pk_mul_f32 v[40:41], v[54:55], v[52:53] op_sel:[1,0]
	s_addk_i32 s0, 0x840
	v_pk_fma_f32 v[46:47], v[54:55], v[48:49], v[40:41] neg_lo:[0,0,1] neg_hi:[0,0,1]
	v_pk_fma_f32 v[40:41], v[54:55], v[48:49], v[40:41] op_sel_hi:[0,1,1]
	ds_read2_b32 v[54:55], v44 offset0:132 offset1:196
	v_mov_b32_e32 v47, v41
	s_waitcnt lgkmcnt(1)
	v_pk_add_f32 v[42:43], v[46:47], v[42:43]
	v_add_u32_e32 v40, 32, v44
	v_pk_mul_f32 v[46:47], v[42:43], v[52:53] op_sel:[1,0]
	v_add_u32_e32 v44, 48, v44
	v_pk_fma_f32 v[62:63], v[42:43], v[48:49], v[46:47] neg_lo:[0,0,1] neg_hi:[0,0,1]
	v_pk_fma_f32 v[42:43], v[42:43], v[48:49], v[46:47] op_sel_hi:[0,1,1]
	v_mov_b32_e32 v63, v43
	ds_read2st64_b32 v[40:41], v40 offset0:4 offset1:5
	ds_read2st64_b32 v[60:61], v44 offset0:6 offset1:7
	s_waitcnt lgkmcnt(2)
	v_pk_add_f32 v[42:43], v[62:63], v[54:55]
	s_cmpk_lg_i32 s0, 0x2100
	v_pk_mul_f32 v[46:47], v[42:43], v[52:53] op_sel:[1,0]
	s_nop 0
	v_pk_fma_f32 v[54:55], v[42:43], v[48:49], v[46:47] neg_lo:[0,0,1] neg_hi:[0,0,1]
	v_pk_fma_f32 v[42:43], v[42:43], v[48:49], v[46:47] op_sel_hi:[0,1,1]
	v_mov_b32_e32 v55, v43
	s_waitcnt lgkmcnt(1)
	v_pk_add_f32 v[40:41], v[54:55], v[40:41]
	s_nop 0
	v_pk_mul_f32 v[42:43], v[40:41], v[52:53] op_sel:[1,0]
	s_nop 0
	v_pk_fma_f32 v[46:47], v[40:41], v[48:49], v[42:43] neg_lo:[0,0,1] neg_hi:[0,0,1]
	v_pk_fma_f32 v[40:41], v[40:41], v[48:49], v[42:43] op_sel_hi:[0,1,1]
	v_mov_b32_e32 v47, v41
	s_waitcnt lgkmcnt(0)
	v_pk_add_f32 v[54:55], v[46:47], v[60:61]
	s_cbranch_scc1 .LBB0_170
	v_mfma_f32_16x16x32_bf16 v[40:43], v[36:39], v[4:7], 0
	s_mov_b32 s0, 0
	v_mfma_f32_16x16x32_bf16 v[60:63], v[36:39], v[8:11], 0
	s_nop 7
	ds_write2_b32 v50, v40, v60 offset1:16
	ds_write2_b32 v50, v41, v61 offset0:132 offset1:148
	ds_write2_b32 v56, v42, v62 offset0:8 offset1:24
	v_mfma_f32_16x16x32_bf16 v[64:67], v[36:39], v[0:3], 0
	v_mfma_f32_16x16x32_bf16 v[68:71], v[36:39], v[12:15], 0
	ds_write2_b32 v56, v43, v63 offset0:140 offset1:156
	s_nop 6
	ds_write2_b32 v50, v64, v68 offset0:32 offset1:48
	ds_write2_b32 v50, v65, v69 offset0:164 offset1:180
	v_mfma_f32_16x16x32_bf16 v[72:75], v[36:39], v[16:19], 0
	v_mfma_f32_16x16x32_bf16 v[40:43], v[36:39], v[24:27], 0
	ds_write2_b32 v56, v66, v70 offset0:40 offset1:56
	ds_write2_b32 v56, v67, v71 offset0:172 offset1:188
	s_nop 5
	ds_write2_b32 v50, v72, v40 offset0:64 offset1:80
	ds_write2_b32 v50, v73, v41 offset0:196 offset1:212
	ds_write2_b32 v56, v74, v42 offset0:72 offset1:88
	ds_write2_b32 v56, v75, v43 offset0:204 offset1:220
	v_mfma_f32_16x16x32_bf16 v[60:63], v[36:39], v[20:23], 0
	v_mfma_f32_16x16x32_bf16 v[36:39], v[36:39], v[28:31], 0
	s_nop 7
	ds_write2_b32 v50, v60, v36 offset0:96 offset1:112
	ds_write2_b32 v50, v61, v37 offset0:228 offset1:244
	ds_write2_b32 v56, v62, v38 offset0:104 offset1:120
	ds_write2_b32 v56, v63, v39 offset0:236 offset1:252
	.p2alignl 6, 3212836864
.LBB0_172:
	v_add_u32_e32 v44, s0, v45
	ds_read2st64_b32 v[38:39], v44 offset1:1
	v_pk_mul_f32 v[36:37], v[54:55], v[52:53] op_sel:[1,0]
	ds_read2_b32 v[42:43], v44 offset0:132 offset1:196
	v_pk_fma_f32 v[40:41], v[54:55], v[48:49], v[36:37] neg_lo:[0,0,1] neg_hi:[0,0,1]
	v_pk_fma_f32 v[36:37], v[54:55], v[48:49], v[36:37] op_sel_hi:[0,1,1]
	v_mov_b32_e32 v41, v37
	s_waitcnt lgkmcnt(1)
	v_pk_add_f32 v[38:39], v[40:41], v[38:39]
	v_add_u32_e32 v36, 32, v44
	v_pk_mul_f32 v[40:41], v[38:39], v[52:53] op_sel:[1,0]
	v_add_u32_e32 v44, 48, v44
	v_pk_fma_f32 v[54:55], v[38:39], v[48:49], v[40:41] neg_lo:[0,0,1] neg_hi:[0,0,1]
	v_pk_fma_f32 v[38:39], v[38:39], v[48:49], v[40:41] op_sel_hi:[0,1,1]
	v_mov_b32_e32 v55, v39
	ds_read2st64_b32 v[36:37], v36 offset0:4 offset1:5
	ds_read2st64_b32 v[46:47], v44 offset0:6 offset1:7
	s_waitcnt lgkmcnt(2)
	v_pk_add_f32 v[38:39], v[54:55], v[42:43]
	s_addk_i32 s0, 0x840
	v_pk_mul_f32 v[40:41], v[38:39], v[52:53] op_sel:[1,0]
	s_cmpk_lg_i32 s0, 0x2100
	v_pk_fma_f32 v[42:43], v[38:39], v[48:49], v[40:41] neg_lo:[0,0,1] neg_hi:[0,0,1]
	v_pk_fma_f32 v[38:39], v[38:39], v[48:49], v[40:41] op_sel_hi:[0,1,1]
	v_mov_b32_e32 v43, v39
	s_waitcnt lgkmcnt(1)
	v_pk_add_f32 v[36:37], v[42:43], v[36:37]
	s_nop 0
	v_pk_mul_f32 v[38:39], v[36:37], v[52:53] op_sel:[1,0]
	s_nop 0
	v_pk_fma_f32 v[40:41], v[36:37], v[48:49], v[38:39] neg_lo:[0,0,1] neg_hi:[0,0,1]
	v_pk_fma_f32 v[36:37], v[36:37], v[48:49], v[38:39] op_sel_hi:[0,1,1]
	v_mov_b32_e32 v41, v37
	s_waitcnt lgkmcnt(0)
	v_pk_add_f32 v[54:55], v[40:41], v[46:47]
	s_cbranch_scc1 .LBB0_172
	v_mfma_f32_16x16x32_bf16 v[36:39], v[32:35], v[4:7], 0
	s_mov_b32 s0, 0
	v_mfma_f32_16x16x32_bf16 v[40:43], v[32:35], v[8:11], 0
	s_nop 7
	ds_write2_b32 v50, v36, v40 offset1:16
	ds_write2_b32 v50, v37, v41 offset0:132 offset1:148
	ds_write2_b32 v56, v38, v42 offset0:8 offset1:24
	v_mfma_f32_16x16x32_bf16 v[60:63], v[32:35], v[0:3], 0
	v_mfma_f32_16x16x32_bf16 v[64:67], v[32:35], v[12:15], 0
	ds_write2_b32 v56, v39, v43 offset0:140 offset1:156
	s_nop 6
	ds_write2_b32 v50, v60, v64 offset0:32 offset1:48
	ds_write2_b32 v50, v61, v65 offset0:164 offset1:180
	v_mfma_f32_16x16x32_bf16 v[68:71], v[32:35], v[16:19], 0
	v_mfma_f32_16x16x32_bf16 v[36:39], v[32:35], v[24:27], 0
	ds_write2_b32 v56, v62, v66 offset0:40 offset1:56
	ds_write2_b32 v56, v63, v67 offset0:172 offset1:188
	s_nop 5
	ds_write2_b32 v50, v68, v36 offset0:64 offset1:80
	ds_write2_b32 v50, v69, v37 offset0:196 offset1:212
	ds_write2_b32 v56, v70, v38 offset0:72 offset1:88
	ds_write2_b32 v56, v71, v39 offset0:204 offset1:220
	v_mfma_f32_16x16x32_bf16 v[40:43], v[32:35], v[20:23], 0
	v_mfma_f32_16x16x32_bf16 v[32:35], v[32:35], v[28:31], 0
	s_nop 7
	ds_write2_b32 v50, v40, v32 offset0:96 offset1:112
	ds_write2_b32 v50, v41, v33 offset0:228 offset1:244
	ds_write2_b32 v56, v42, v34 offset0:104 offset1:120
	ds_write2_b32 v56, v43, v35 offset0:236 offset1:252
	.p2alignl 6, 3212836864

.LBB0_176:
	s_waitcnt vmcnt(0)
	s_barrier
	s_mov_b64 s[0:1], exec
	v_readlane_b32 s2, v237, 1
	v_readlane_b32 s3, v237, 2
	s_and_b64 s[2:3], s[0:1], s[2:3]
	s_mov_b64 exec, s[2:3]
	s_cbranch_execz .LBB0_228
	v_mov_b32_e32 v0, 0x13ff0
	s_waitcnt vmcnt(0) expcnt(0) lgkmcnt(0)
	ds_read_b32 v2, v0
	v_mov_b32_e32 v0, 0x13ff4
	ds_read_b32 v0, v0
	s_waitcnt lgkmcnt(1)
	v_cmp_ne_u32_e32 vcc, 0, v2
	s_cbranch_vccnz .LBB0_192
	v_readlane_b32 s2, v237, 0
	s_mul_i32 s4, s91, s2
	s_add_u32 s2, s88, 0x4100200
	s_addc_u32 s3, s89, 0
	s_add_u32 s6, s88, 0x4100400
	s_addc_u32 s7, s89, 0
	s_add_u32 s14, s88, 0x4100500
	s_addc_u32 s15, s89, 0
	s_add_u32 s16, s88, 0x4100600
	s_addc_u32 s17, s89, 0
	s_add_u32 s18, s88, 0x4100700
	s_addc_u32 s19, s89, 0
	s_add_u32 s20, s88, 0x4100800
	s_addc_u32 s21, s89, 0
	s_add_u32 s22, s88, 0x4100900
	s_addc_u32 s23, s89, 0
	s_add_u32 s24, s88, 0x4100a00
	s_addc_u32 s25, s89, 0
	s_add_u32 s26, s88, 0x4100b00
	s_addc_u32 s27, s89, 0
	s_add_u32 s28, s88, 0x4100c00
	s_addc_u32 s29, s89, 0
	s_add_u32 s30, s88, 0x4100d00
	s_addc_u32 s31, s89, 0
	s_add_u32 s34, s88, 0x4100e00
	s_addc_u32 s35, s89, 0
	s_add_u32 s38, s88, 0x4100f00
	s_addc_u32 s39, s89, 0
	s_add_u32 s40, s88, 0x4101000
	s_addc_u32 s41, s89, 0
	s_add_u32 s44, s88, 0x4101100
	s_addc_u32 s45, s89, 0
	s_add_u32 s46, s88, 0x4101200
	s_addc_u32 s47, s89, 0
	s_add_u32 s48, s88, 0x4101300
	s_mul_i32 s4, s4, s90
	s_addc_u32 s49, s89, 0
	s_mov_b32 s5, 1
	v_mov_b32_e32 v16, 0
	s_branch .LBB0_180
	.p2alignl 6, 3212836864

.LBB0_180:
	global_load_dword v15, v16, s[6:7] sc1
	s_waitcnt lgkmcnt(0)
	global_load_dword v0, v16, s[14:15] sc1
	global_load_dword v1, v16, s[16:17] sc1
	global_load_dword v2, v16, s[18:19] sc1
	global_load_dword v3, v16, s[20:21] sc1
	global_load_dword v4, v16, s[22:23] sc1
	global_load_dword v5, v16, s[24:25] sc1
	global_load_dword v6, v16, s[26:27] sc1
	global_load_dword v7, v16, s[28:29] sc1
	global_load_dword v8, v16, s[30:31] sc1
	global_load_dword v9, v16, s[34:35] sc1
	global_load_dword v10, v16, s[38:39] sc1
	global_load_dword v11, v16, s[40:41] sc1
	global_load_dword v12, v16, s[44:45] sc1
	global_load_dword v13, v16, s[46:47] sc1
	global_load_dword v14, v16, s[48:49] sc1
	s_mov_b64 s[50:51], -1
	s_mov_b64 s[52:53], -1
	s_waitcnt vmcnt(14)
	v_add_u32_e32 v17, v0, v15
	s_waitcnt vmcnt(13)
	v_add_u32_e32 v17, v17, v1
	s_waitcnt vmcnt(12)
	v_add_u32_e32 v17, v17, v2
	s_waitcnt vmcnt(11)
	v_add_u32_e32 v17, v17, v3
	s_waitcnt vmcnt(10)
	v_add_u32_e32 v17, v17, v4
	s_waitcnt vmcnt(9)
	v_add_u32_e32 v17, v17, v5
	s_waitcnt vmcnt(8)
	v_add_u32_e32 v17, v17, v6
	s_waitcnt vmcnt(7)
	v_add_u32_e32 v17, v17, v7
	s_waitcnt vmcnt(6)
	v_add_u32_e32 v17, v17, v8
	s_waitcnt vmcnt(5)
	v_add_u32_e32 v17, v17, v9
	s_waitcnt vmcnt(4)
	v_add_u32_e32 v17, v17, v10
	s_waitcnt vmcnt(3)
	v_add_u32_e32 v17, v17, v11
	s_waitcnt vmcnt(2)
	v_add_u32_e32 v17, v17, v12
	s_waitcnt vmcnt(1)
	v_add_u32_e32 v17, v17, v13
	s_waitcnt vmcnt(0)
	v_add_u32_e32 v17, v17, v14
	v_cmp_eq_u32_e32 vcc, s4, v17
	s_cbranch_vccnz .LBB0_179
	s_and_b32 s33, s5, 0xff
	s_cmp_eq_u32 s33, 0
	s_mov_b64 s[54:55], -1
	s_sleep 1
	s_cbranch_scc1 .LBB0_184
	s_and_b64 vcc, exec, s[54:55]
	s_cbranch_vccz .LBB0_179
	.p2alignl 6, 3212836864

.LBB0_232:
	s_andn2_b64 vcc, exec, s[0:1]
	s_cbranch_vccnz .LBB0_251
	v_readlane_b32 s6, v237, 31
	v_mov_b32_e32 v36, v128
	s_lshl_b32 s0, s6, 4
	s_and_b32 s0, s0, 0x70
	v_ashrrev_i32_e32 v0, 4, v36
	s_lshl_b32 s1, s6, 12
	v_add_u32_e32 v0, s0, v0
	s_and_b32 s2, s1, 0x38000
	s_mov_b32 s3, 0
	v_ashrrev_i32_e32 v1, 31, v0
	v_lshlrev_b32_e32 v2, 3, v36
	s_lshl_b32 s1, s2, 2
	v_lshl_add_u64 v[0:1], v[0:1], 0, s[2:3]
	v_and_b32_e32 v2, 0x78, v2
	s_add_u32 s4, s88, s1
	v_lshlrev_b64 v[108:109], 8, v[0:1]
	s_addc_u32 s5, s89, 0
	v_lshlrev_b32_e32 v110, 2, v2
	v_mov_b32_e32 v111, 0
	v_lshl_or_b32 v0, v2, 1, v108
	v_lshl_add_u64 v[2:3], s[4:5], 0, v[110:111]
	s_mov_b64 s[4:5], 0x1d500000
	s_mov_b32 s1, 0x1d500000
	v_mov_b32_e32 v1, v109
	v_lshl_add_u64 v[8:9], v[2:3], 0, s[4:5]
	v_add_co_u32_e32 v2, vcc, s1, v2
	v_lshl_add_u64 v[0:1], s[58:59], 0, v[0:1]
	s_nop 0
	v_addc_co_u32_e32 v3, vcc, 0, v3, vcc
	s_mov_b32 s1, 0x8000
	v_add_co_u32_e32 v4, vcc, s1, v0
	s_mov_b32 s1, 0x10000
	s_nop 0
	v_addc_co_u32_e32 v5, vcc, 0, v1, vcc
	global_load_dwordx4 v[68:71], v[0:1], off
	global_load_dwordx4 v[64:67], v[8:9], off offset:16
	global_load_dwordx4 v[72:75], v[2:3], off
	global_load_dwordx4 v[96:99], v[4:5], off
	global_load_dwordx4 v[100:103], v[8:9], off offset:528
	global_load_dwordx4 v[104:107], v[8:9], off offset:512
	v_add_co_u32_e32 v2, vcc, s1, v0
	s_mov_b32 s1, 0x18000
	s_nop 0
	v_addc_co_u32_e32 v3, vcc, 0, v1, vcc
	v_add_co_u32_e32 v4, vcc, s1, v0
	s_mov_b32 s1, 0x20000
	s_nop 0
	v_addc_co_u32_e32 v5, vcc, 0, v1, vcc
	global_load_dwordx4 v[84:87], v[8:9], off offset:1040
	global_load_dwordx4 v[88:91], v[8:9], off offset:1024
	global_load_dwordx4 v[92:95], v[2:3], off
	global_load_dwordx4 v[60:63], v[4:5], off
	v_add_co_u32_e32 v2, vcc, s1, v0
	s_mov_b32 s1, 0x28000
	s_nop 0
	v_addc_co_u32_e32 v3, vcc, 0, v1, vcc
	v_add_co_u32_e32 v4, vcc, s1, v0
	s_mov_b32 s1, 0x30000
	s_nop 0
	v_addc_co_u32_e32 v5, vcc, 0, v1, vcc
	global_load_dwordx4 v[48:51], v[2:3], off
	global_load_dwordx4 v[24:27], v[4:5], off
	global_load_dwordx4 v[76:79], v[8:9], off offset:1552
	global_load_dwordx4 v[80:83], v[8:9], off offset:1536
	global_load_dwordx4 v[52:55], v[8:9], off offset:2064
	global_load_dwordx4 v[56:59], v[8:9], off offset:2048
	global_load_dwordx4 v[28:31], v[8:9], off offset:2576
	global_load_dwordx4 v[32:35], v[8:9], off offset:2560
	v_add_co_u32_e32 v2, vcc, s1, v0
	s_mov_b32 s0, 0x38000
	s_nop 0
	v_addc_co_u32_e32 v3, vcc, 0, v1, vcc
	v_add_co_u32_e32 v0, vcc, s0, v0
	global_load_dwordx4 v[12:15], v[8:9], off offset:3088
	global_load_dwordx4 v[16:19], v[8:9], off offset:3072
	v_addc_co_u32_e32 v1, vcc, 0, v1, vcc
	global_load_dwordx4 v[20:23], v[2:3], off
	s_nop 0
	global_load_dwordx4 v[0:3], v[0:1], off
	s_nop 0
	global_load_dwordx4 v[4:7], v[8:9], off offset:3600
	s_nop 0
	global_load_dwordx4 v[8:11], v[8:9], off offset:3584
	s_lshl_b32 s0, s6, 14
	v_readlane_b32 s7, v237, 32
	v_and_b32_e32 v36, 15, v36
	s_and_b32 s0, s0, 0xe0000
	v_lshl_or_b32 v108, v36, 4, v108
	v_lshl_or_b32 v110, v36, 5, s0
	s_mov_b64 s[6:7], 0x1d501000
	s_mov_b64 s[14:15], 0x1d501200
	s_mov_b64 s[16:17], 0x1d501400
	s_mov_b64 s[18:19], 0x1d501600
	s_mov_b64 s[20:21], 0x1d501800
	s_mov_b64 s[22:23], 0x1d501a00
	s_mov_b64 s[24:25], 0x1d501c00
	s_mov_b64 s[26:27], 0x1d501e00
	s_mov_b64 s[28:29], 0x40000
	s_mov_b64 s[30:31], 0x1000
	v_mov_b32_e32 v116, v111
	v_mov_b32_e32 v117, v111
	v_mov_b32_e32 v118, v111
	v_mov_b32_e32 v119, v111
	v_mov_b32_e32 v120, v111
	v_mov_b32_e32 v121, v111
	v_mov_b32_e32 v122, v111
	v_mov_b32_e32 v123, v111
	s_branch .LBB0_235
	.p2alignl 6, 3212836864

.LBB0_303:
	s_or_b64 exec, exec, s[0:1]
	v_readlane_b32 s0, v237, 34
	v_readlane_b32 s1, v237, 35
	s_and_b64 vcc, exec, s[0:1]
	s_waitcnt lgkmcnt(0)
	s_barrier
	s_cbranch_vccnz .LBB0_308
	s_add_u32 s15, s88, 0x12500000
	s_addc_u32 s20, s89, 0
	s_add_u32 s2, s88, 0x3d01000
	s_addc_u32 s3, s89, 0
	s_add_u32 s21, s88, 0x18500000
	v_readlane_b32 s16, v237, 31
	s_mov_b32 s0, 0x358637bd
	s_addc_u32 s22, s89, 0
	s_lshl_b32 s23, s16, 6
	s_lshl_b32 s24, s90, 6
	s_movk_i32 s25, 0x1400
	s_mov_b32 s7, 0
	v_mov_b32_e32 v49, 0
	s_movk_i32 s26, 0x120
	s_movk_i32 s27, 0x7f
	s_mov_b32 s28, 0x800000
	s_mov_b32 s29, 0x3f317217
	s_mov_b32 s30, 0x7f800000
	v_mov_b32_e32 v73, 0x41b17218
	s_movk_i32 s31, 0x1200
	s_movk_i32 s33, 0xa0
	s_brev_b32 s14, 60
	v_mov_b64_e32 v[50:51], s[0:1]
	v_readlane_b32 s17, v237, 32
	s_branch .LBB0_306
	.p2alignl 6, 3212836864

.LBB0_316:
	s_or_b64 exec, exec, s[2:3]
	s_and_b64 vcc, exec, s[60:61]
	s_cbranch_vccnz .LBB0_335
	v_readlane_b32 s16, v237, 5
	v_ashrrev_i32_e32 v33, 31, v32
	v_readlane_b32 s18, v237, 7
	v_readlane_b32 s19, v237, 8
	s_waitcnt vmcnt(1)
	v_lshlrev_b64 v[54:55], 12, v[32:33]
	s_mov_b64 s[2:3], s[18:19]
	v_readlane_b32 s20, v237, 9
	v_readlane_b32 s21, v237, 10
	v_lshl_add_u64 v[36:37], s[2:3], 0, v[54:55]
	v_lshlrev_b32_e32 v64, 8, v40
	v_mov_b32_e32 v65, 0
	v_readlane_b32 s22, v237, 11
	v_readlane_b32 s23, v237, 12
	s_mov_b64 s[4:5], s[20:21]
	v_lshl_add_u64 v[36:37], v[36:37], 0, v[64:65]
	v_mov_b32_e32 v35, v65
	v_lshl_add_u64 v[50:51], v[36:37], 0, v[34:35]
	v_or_b32_e32 v36, v42, v41
	v_lshl_add_u64 v[54:55], s[4:5], 0, v[54:55]
	v_ashrrev_i32_e32 v37, 31, v36
	v_lshl_add_u64 v[54:55], v[54:55], 0, v[64:65]
	s_mov_b64 s[6:7], s[22:23]
	v_lshl_add_u64 v[36:37], v[36:37], 3, s[12:13]
	v_lshl_add_u64 v[34:35], v[54:55], 0, v[34:35]
	v_lshl_or_b32 v32, v32, 4, v40
	global_load_dwordx2 v[66:67], v[36:37], off
	s_nop 0
	global_load_dwordx4 v[36:39], v[50:51], off
	global_load_dwordx4 v[42:45], v[50:51], off offset:16
	global_load_dwordx4 v[46:49], v[50:51], off offset:144
	s_nop 0
	global_load_dwordx4 v[50:53], v[50:51], off offset:128
	s_nop 0
	global_load_dwordx4 v[54:57], v[34:35], off
	global_load_dwordx4 v[58:61], v[34:35], off offset:16
	global_load_dwordx4 v[72:75], v[34:35], off offset:128
	global_load_dwordx4 v[80:83], v[34:35], off offset:144
	v_mov_b32_e32 v34, s6
	v_mov_b32_e32 v35, s7
	v_ashrrev_i32_e32 v33, 31, v32
	v_lshl_add_u64 v[32:33], v[32:33], 2, v[34:35]
	global_load_dword v79, v[32:33], off
	v_readlane_b32 s25, v237, 14
	s_add_u32 s16, s88, 0x1cd00000
	s_addc_u32 s25, s89, 0
	v_readlane_b32 s17, v237, 6
	v_readlane_b32 s24, v237, 13
	v_readlane_b32 s26, v237, 15
	s_add_u32 s2, s88, 0x16500000
	v_readlane_b32 s0, v237, 31
	s_movk_i32 s17, 0x1400
	s_movk_i32 s18, 0x1000
	s_movk_i32 s19, 0x2100
	s_movk_i32 s20, 0x2000
	s_movk_i32 s21, 0x3000
	s_movk_i32 s22, 0x4000
	s_movk_i32 s23, 0x1200
	s_movk_i32 s24, 0xf100
	v_mov_b64_e32 v[68:69], s[76:77]
	s_addc_u32 s3, s89, 0
	s_mov_b32 s26, s0
	v_readlane_b32 s27, v237, 16
	v_readlane_b32 s28, v237, 17
	v_readlane_b32 s29, v237, 18
	v_readlane_b32 s30, v237, 19
	v_readlane_b32 s31, v237, 20
	v_readlane_b32 s1, v237, 32
	s_waitcnt vmcnt(9)
	v_pk_mov_b32 v[70:71], v[66:67], v[66:67] op_sel:[1,0]
	s_waitcnt vmcnt(8)
	v_cvt_pk_bf16_f32 v32, v36, v37
	v_cvt_pk_bf16_f32 v33, v38, v39
	s_waitcnt vmcnt(7)
	v_cvt_pk_bf16_f32 v34, v42, v43
	v_cvt_pk_bf16_f32 v35, v44, v45
	s_waitcnt vmcnt(5)
	v_cvt_pk_bf16_f32 v36, v50, v51
	v_cvt_pk_bf16_f32 v37, v52, v53
	v_cvt_pk_bf16_f32 v38, v46, v47
	v_cvt_pk_bf16_f32 v39, v48, v49
	s_waitcnt vmcnt(4)
	v_pk_add_f32 v[40:41], v[54:55], 0 neg_lo:[1,1] neg_hi:[1,1]
	v_pk_add_f32 v[42:43], v[56:57], 0 neg_lo:[1,1] neg_hi:[1,1]
	s_waitcnt vmcnt(3)
	v_pk_add_f32 v[44:45], v[58:59], 0 neg_lo:[1,1] neg_hi:[1,1]
	v_pk_add_f32 v[46:47], v[60:61], 0 neg_lo:[1,1] neg_hi:[1,1]
	s_waitcnt vmcnt(2)
	v_pk_add_f32 v[48:49], v[72:73], 0 neg_lo:[1,1] neg_hi:[1,1]
	v_pk_add_f32 v[50:51], v[74:75], 0 neg_lo:[1,1] neg_hi:[1,1]
	s_waitcnt vmcnt(1)
	v_pk_add_f32 v[52:53], v[80:81], 0 neg_lo:[1,1] neg_hi:[1,1]
	v_pk_add_f32 v[54:55], v[82:83], 0 neg_lo:[1,1] neg_hi:[1,1]
	v_cvt_pk_bf16_f32 v40, v40, v41
	v_cvt_pk_bf16_f32 v41, v42, v43
	v_cvt_pk_bf16_f32 v42, v44, v45
	v_cvt_pk_bf16_f32 v43, v46, v47
	v_cvt_pk_bf16_f32 v44, v48, v49
	v_cvt_pk_bf16_f32 v45, v50, v51
	v_cvt_pk_bf16_f32 v46, v52, v53
	v_cvt_pk_bf16_f32 v47, v54, v55
	.p2alignl 6, 3212836864

.LBB0_326:
	s_or_b64 exec, exec, s[14:15]
	s_ashr_i32 s13, s12, 31
	s_lshl_b64 s[0:1], s[12:13], 14
	v_lshl_or_b32 v76, v72, 6, v81
	s_add_u32 s0, s16, s0
	v_lshlrev_b32_e32 v64, 2, v73
	v_ashrrev_i32_e32 v77, 31, v76
	s_addc_u32 s1, s25, s1
	v_or_b32_e32 v72, s4, v64
	v_lshl_add_u64 v[76:77], v[76:77], 3, s[0:1]
	v_mad_u64_u32 v[82:83], s[0:1], v72, s17, v[68:69]
	v_add_u32_e32 v83, s6, v83
	v_lshlrev_b32_e32 v64, 1, v78
	v_lshl_add_u64 v[82:83], v[74:75], 1, v[82:83]
	v_lshl_add_u64 v[82:83], v[82:83], 0, v[64:65]
	v_add_co_u32_e32 v86, vcc, s18, v82
	global_load_dwordx2 v[76:77], v[76:77], off
	s_nop 0
	v_addc_co_u32_e32 v87, vcc, 0, v83, vcc
	v_add_co_u32_e32 v90, vcc, s20, v82
	s_nop 1
	v_addc_co_u32_e32 v91, vcc, 0, v83, vcc
	v_add_co_u32_e32 v92, vcc, s21, v82
	s_barrier
	s_nop 0
	v_addc_co_u32_e32 v93, vcc, 0, v83, vcc
	v_add_co_u32_e32 v82, vcc, s22, v82
	s_nop 1
	v_addc_co_u32_e32 v83, vcc, 0, v83, vcc
	global_load_ushort v88, v[86:87], off
	s_nop 0
	global_load_ushort v86, v[90:91], off offset:1024
	global_load_ushort v87, v[92:93], off offset:2048
	global_load_ushort v89, v[82:83], off offset:3072
	v_mul_lo_u32 v64, v85, s19
	s_waitcnt vmcnt(5)
	v_mfma_f32_16x16x32_bf16 v[92:95], v[60:63], v[8:11], 0
	v_mul_u32_u24_e32 v73, 0x210, v73
	v_lshl_or_b32 v80, v78, 2, v64
	v_lshl_add_u32 v82, v73, 2, v80
	v_mfma_f32_16x16x32_bf16 v[96:99], v[60:63], v[4:7], 0
	v_add_u32_e32 v83, 0x400, v82
	v_mfma_f32_16x16x32_bf16 v[100:103], v[60:63], v[12:15], 0
	v_lshl_or_b32 v80, v81, 2, v64
	s_nop 4
	ds_write2_b32 v82, v92, v96 offset1:16
	ds_write2_b32 v82, v93, v97 offset0:132 offset1:148
	v_mfma_f32_16x16x32_bf16 v[104:107], v[60:63], v[0:3], 0
	ds_write2_b32 v83, v94, v98 offset0:8 offset1:24
	ds_write2_b32 v83, v95, v99 offset0:140 offset1:156
	s_nop 5
	ds_write2_b32 v82, v100, v104 offset0:32 offset1:48
	ds_write2_b32 v82, v101, v105 offset0:164 offset1:180
	v_mfma_f32_16x16x32_bf16 v[108:111], v[60:63], v[20:23], 0
	v_mul_u32_u24_e32 v90, 0x120, v78
	v_mov_b32_e32 v73, s7
	s_mov_b32 s0, 0
	v_mfma_f32_16x16x32_bf16 v[92:95], v[60:63], v[16:19], 0
	ds_write2_b32 v83, v102, v106 offset0:40 offset1:56
	ds_write2_b32 v83, v103, v107 offset0:172 offset1:188
	s_nop 5
	ds_write2_b32 v82, v108, v92 offset0:64 offset1:80
	ds_write2_b32 v82, v109, v93 offset0:196 offset1:212
	ds_write2_b32 v83, v110, v94 offset0:72 offset1:88
	ds_write2_b32 v83, v111, v95 offset0:204 offset1:220
	v_mfma_f32_16x16x32_bf16 v[96:99], v[60:63], v[28:31], 0
	v_mfma_f32_16x16x32_bf16 v[60:63], v[60:63], v[24:27], 0
	s_nop 7
	ds_write2_b32 v82, v96, v60 offset0:96 offset1:112
	ds_write2_b32 v82, v97, v61 offset0:228 offset1:244
	ds_write2_b32 v83, v98, v62 offset0:104 offset1:120
	ds_write2_b32 v83, v99, v63 offset0:236 offset1:252
	v_mul_lo_u32 v60, v85, s23
	v_lshl_or_b32 v60, v81, 1, v60
	v_add_u32_e32 v81, 0x8400, v60
	v_mov_b32_e32 v60, v80
	.p2alignl 6, 3212836864
.LBB0_327:
	ds_read2st64_b32 v[62:63], v60 offset1:1
	s_waitcnt vmcnt(4)
	v_pk_mul_f32 v[92:93], v[76:77], v[70:71] op_sel:[1,0]
	ds_read2_b32 v[94:95], v60 offset0:132 offset1:196
	v_pk_fma_f32 v[96:97], v[76:77], v[66:67], v[92:93] neg_lo:[0,0,1] neg_hi:[0,0,1]
	v_pk_fma_f32 v[76:77], v[76:77], v[66:67], v[92:93] op_sel_hi:[0,1,1]
	v_mov_b32_e32 v97, v77
	v_add_u32_e32 v61, s0, v81
	v_add_u32_e32 v91, 32, v60
	v_add_u32_e32 v98, 48, v60
	s_addk_i32 s0, 0x480
	s_waitcnt lgkmcnt(1)
	v_pk_add_f32 v[62:63], v[96:97], v[62:63]
	ds_read2st64_b32 v[92:93], v91 offset0:4 offset1:5
	ds_read2st64_b32 v[98:99], v98 offset0:6 offset1:7
	v_cvt_pk_bf16_f32 v91, v62, s0
	v_cvt_pk_bf16_f32 v96, v63, s0
	v_pk_mul_f32 v[76:77], v[62:63], v[70:71] op_sel:[1,0]
	ds_write_b16 v61, v91
	ds_write_b16 v61, v96 offset:128
	v_pk_fma_f32 v[96:97], v[62:63], v[66:67], v[76:77] neg_lo:[0,0,1] neg_hi:[0,0,1]
	v_pk_fma_f32 v[62:63], v[62:63], v[66:67], v[76:77] op_sel_hi:[0,1,1]
	v_mov_b32_e32 v97, v63
	s_waitcnt lgkmcnt(4)
	v_pk_add_f32 v[62:63], v[96:97], v[94:95]
	v_add_u32_e32 v60, 0x840, v60
	v_cvt_pk_bf16_f32 v91, v62, s0
	v_cvt_pk_bf16_f32 v94, v63, s0
	v_pk_mul_f32 v[76:77], v[62:63], v[70:71] op_sel:[1,0]
	ds_write_b16 v61, v91 offset:288
	ds_write_b16 v61, v94 offset:416
	v_pk_fma_f32 v[94:95], v[62:63], v[66:67], v[76:77] neg_lo:[0,0,1] neg_hi:[0,0,1]
	v_pk_fma_f32 v[62:63], v[62:63], v[66:67], v[76:77] op_sel_hi:[0,1,1]
	v_mov_b32_e32 v95, v63
	s_waitcnt lgkmcnt(5)
	v_pk_add_f32 v[62:63], v[94:95], v[92:93]
	s_cmpk_eq_i32 s0, 0x1200
	v_cvt_pk_bf16_f32 v91, v62, s0
	v_cvt_pk_bf16_f32 v92, v63, s0
	v_pk_mul_f32 v[76:77], v[62:63], v[70:71] op_sel:[1,0]
	ds_write_b16 v61, v91 offset:576
	ds_write_b16 v61, v92 offset:704
	v_pk_fma_f32 v[92:93], v[62:63], v[66:67], v[76:77] neg_lo:[0,0,1] neg_hi:[0,0,1]
	v_pk_fma_f32 v[62:63], v[62:63], v[66:67], v[76:77] op_sel_hi:[0,1,1]
	v_mov_b32_e32 v93, v63
	s_waitcnt lgkmcnt(6)
	v_pk_add_f32 v[76:77], v[92:93], v[98:99]
	s_nop 0
	v_cvt_pk_bf16_f32 v62, v76, s0
	v_cvt_pk_bf16_f32 v63, v77, s0
	ds_write_b16 v61, v62 offset:864
	ds_write_b16 v61, v63 offset:992
	s_cbranch_scc0 .LBB0_327
	v_mul_lo_u32 v60, v85, s24
	v_and_b32_e32 v61, 48, v84
	v_add3_u32 v60, v64, v60, v90
	v_add_u32_e32 v84, v60, v61
	ds_read_b128 v[60:63], v84 offset:33792
	ds_read_b128 v[90:93], v84 offset:33856
	s_waitcnt lgkmcnt(1)
	v_mfma_f32_16x16x32_bf16 v[60:63], v[60:63], v[32:35], 0
	ds_read_b128 v[94:97], v84 offset:33920
	ds_read_b128 v[98:101], v84 offset:33984
	v_lshlrev_b32_e32 v64, 1, v78
	s_waitcnt vmcnt(3)
	v_lshlrev_b32_e32 v78, 16, v88
	s_waitcnt lgkmcnt(2)
	v_mfma_f32_16x16x32_bf16 v[60:63], v[90:93], v[36:39], v[60:63]
	s_waitcnt vmcnt(2)
	v_lshlrev_b32_e32 v85, 16, v86
	s_waitcnt vmcnt(1)
	v_lshlrev_b32_e32 v92, 16, v87
	s_waitcnt vmcnt(0)
	v_lshlrev_b32_e32 v93, 16, v89
	s_waitcnt lgkmcnt(1)
	v_mfma_f32_16x16x32_bf16 v[60:63], v[94:97], v[40:43], v[60:63]
	v_lshlrev_b64 v[90:91], 1, v[74:75]
	s_waitcnt lgkmcnt(0)
	v_mfma_f32_16x16x32_bf16 v[86:89], v[98:101], v[44:47], v[60:63]
	v_mfma_f32_16x16x32_bf16 v[104:107], v[56:59], v[20:23], 0
	s_nop 3
	v_lshlrev_b64 v[62:63], 10, v[72:73]
	s_nop 1
	v_fma_f32 v78, v79, v78, v86
	v_fma_f32 v85, v79, v85, v87
	v_mul_f32_e32 v60, 0x3d372713, v78
	v_mul_f32_e32 v61, 0x3d372713, v85
	v_mul_f32_e32 v60, v78, v60
	v_mul_f32_e32 v61, v85, v61
	v_fma_f32 v60, v78, v60, v78
	v_fma_f32 v61, v85, v61, v85
	v_mul_f32_e32 v60, 0xbfcc422a, v60
	v_mul_f32_e32 v61, 0xbfcc422a, v61
	v_mul_f32_e32 v60, 0x3fb8aa3b, v60
	v_mul_f32_e32 v61, 0x3fb8aa3b, v61
	v_exp_f32_e32 v86, v60
	v_exp_f32_e32 v87, v61
	v_lshl_add_u64 v[60:61], s[2:3], 0, v[90:91]
	v_lshl_add_u64 v[60:61], v[60:61], 0, v[64:65]
	v_add_f32_e32 v73, 1.0, v86
	v_add_f32_e32 v86, 1.0, v87
	v_rcp_f32_e32 v73, v73
	v_rcp_f32_e32 v86, v86
	v_lshl_add_u64 v[62:63], v[60:61], 0, v[62:63]
	v_fmac_f32_e32 v89, v79, v93
	v_mul_f32_e32 v73, v78, v73
	v_mul_f32_e32 v78, v85, v86
	v_cvt_pk_bf16_f32 v73, v73, s0
	global_store_short v[62:63], v73, off
	v_cvt_pk_bf16_f32 v73, v78, s0
	v_or_b32_e32 v62, 1, v72
	v_mov_b32_e32 v63, s7
	v_fma_f32 v78, v79, v92, v88
	v_mul_f32_e32 v85, 0x3d372713, v78
	v_lshlrev_b64 v[86:87], 10, v[62:63]
	v_mul_f32_e32 v85, v78, v85
	v_lshl_add_u64 v[86:87], v[60:61], 0, v[86:87]
	v_fma_f32 v85, v78, v85, v78
	global_store_short v[86:87], v73, off
	v_mul_f32_e32 v73, 0x3d372713, v89
	v_mul_f32_e32 v85, 0xbfcc422a, v85
	v_mul_f32_e32 v73, v89, v73
	v_mul_f32_e32 v85, 0x3fb8aa3b, v85
	v_fma_f32 v73, v89, v73, v89
	v_exp_f32_e32 v85, v85
	v_mul_f32_e32 v73, 0xbfcc422a, v73
	v_mul_f32_e32 v73, 0x3fb8aa3b, v73
	v_exp_f32_e32 v73, v73
	v_add_f32_e32 v62, 1.0, v85
	v_rcp_f32_e32 v62, v62
	v_mfma_f32_16x16x32_bf16 v[92:95], v[56:59], v[4:7], 0
	v_add_f32_e32 v73, 1.0, v73
	v_rcp_f32_e32 v73, v73
	v_mul_f32_e32 v62, v78, v62
	v_cvt_pk_bf16_f32 v78, v62, s0
	v_or_b32_e32 v62, 2, v72
	v_lshlrev_b64 v[86:87], 10, v[62:63]
	v_mul_f32_e32 v62, v89, v73
	v_lshl_add_u64 v[86:87], v[60:61], 0, v[86:87]
	v_cvt_pk_bf16_f32 v73, v62, s0
	v_or_b32_e32 v62, 3, v72
	global_store_short v[86:87], v78, off
	v_lshlrev_b64 v[86:87], 10, v[62:63]
	v_lshl_add_u64 v[86:87], v[60:61], 0, v[86:87]
	global_store_short v[86:87], v73, off
	v_or_b32_e32 v62, 16, v72
	v_mov_b64_e32 v[86:87], s[76:77]
	v_mad_u64_u32 v[86:87], s[0:1], v62, s17, v[86:87]
	v_add_u32_e32 v87, s6, v87
	v_lshl_add_u64 v[86:87], v[86:87], 0, v[90:91]
	v_lshl_add_u64 v[86:87], v[86:87], 0, v[64:65]
	v_add_co_u32_e32 v96, vcc, s18, v86
	v_mfma_f32_16x16x32_bf16 v[88:91], v[56:59], v[8:11], 0
	s_nop 0
	v_addc_co_u32_e32 v97, vcc, 0, v87, vcc
	v_add_co_u32_e32 v98, vcc, s20, v86
	s_mov_b32 s0, 0
	s_nop 0
	v_addc_co_u32_e32 v99, vcc, 0, v87, vcc
	v_add_co_u32_e32 v100, vcc, s21, v86
	s_nop 1
	v_addc_co_u32_e32 v101, vcc, 0, v87, vcc
	v_add_co_u32_e32 v102, vcc, s22, v86
	s_nop 1
	v_addc_co_u32_e32 v103, vcc, 0, v87, vcc
	global_load_ushort v78, v[96:97], off
	global_load_ushort v85, v[98:99], off offset:1024
	global_load_ushort v86, v[100:101], off offset:2048
	global_load_ushort v73, v[102:103], off offset:3072
	v_mfma_f32_16x16x32_bf16 v[96:99], v[56:59], v[12:15], 0
	ds_write2_b32 v82, v88, v92 offset1:16
	ds_write2_b32 v82, v89, v93 offset0:132 offset1:148
	ds_write2_b32 v83, v90, v94 offset0:8 offset1:24
	v_mfma_f32_16x16x32_bf16 v[100:103], v[56:59], v[0:3], 0
	ds_write2_b32 v83, v91, v95 offset0:140 offset1:156
	s_nop 6
	ds_write2_b32 v82, v96, v100 offset0:32 offset1:48
	ds_write2_b32 v82, v97, v101 offset0:164 offset1:180
	v_mfma_f32_16x16x32_bf16 v[88:91], v[56:59], v[16:19], 0
	ds_write2_b32 v83, v98, v102 offset0:40 offset1:56
	ds_write2_b32 v83, v99, v103 offset0:172 offset1:188
	s_nop 5
	ds_write2_b32 v82, v104, v88 offset0:64 offset1:80
	ds_write2_b32 v82, v105, v89 offset0:196 offset1:212
	ds_write2_b32 v83, v106, v90 offset0:72 offset1:88
	ds_write2_b32 v83, v107, v91 offset0:204 offset1:220
	v_mfma_f32_16x16x32_bf16 v[92:95], v[56:59], v[28:31], 0
	v_mfma_f32_16x16x32_bf16 v[56:59], v[56:59], v[24:27], 0
	s_nop 7
	ds_write2_b32 v82, v92, v56 offset0:96 offset1:112
	ds_write2_b32 v82, v93, v57 offset0:228 offset1:244
	ds_write2_b32 v83, v94, v58 offset0:104 offset1:120
	ds_write2_b32 v83, v95, v59 offset0:236 offset1:252
	v_mov_b32_e32 v56, v80
	.p2alignl 6, 3212836864
.LBB0_329:
	ds_read2st64_b32 v[58:59], v56 offset1:1
	v_pk_mul_f32 v[88:89], v[76:77], v[70:71] op_sel:[1,0]
	ds_read2_b32 v[90:91], v56 offset0:132 offset1:196
	v_pk_fma_f32 v[92:93], v[76:77], v[66:67], v[88:89] neg_lo:[0,0,1] neg_hi:[0,0,1]
	v_pk_fma_f32 v[76:77], v[76:77], v[66:67], v[88:89] op_sel_hi:[0,1,1]
	v_mov_b32_e32 v93, v77
	v_add_u32_e32 v57, s0, v81
	v_add_u32_e32 v87, 32, v56
	v_add_u32_e32 v94, 48, v56
	s_addk_i32 s0, 0x480
	s_waitcnt lgkmcnt(1)
	v_pk_add_f32 v[58:59], v[92:93], v[58:59]
	ds_read2st64_b32 v[88:89], v87 offset0:4 offset1:5
	ds_read2st64_b32 v[94:95], v94 offset0:6 offset1:7
	v_cvt_pk_bf16_f32 v87, v58, s0
	v_cvt_pk_bf16_f32 v92, v59, s0
	v_pk_mul_f32 v[76:77], v[58:59], v[70:71] op_sel:[1,0]
	ds_write_b16 v57, v87
	ds_write_b16 v57, v92 offset:128
	v_pk_fma_f32 v[92:93], v[58:59], v[66:67], v[76:77] neg_lo:[0,0,1] neg_hi:[0,0,1]
	v_pk_fma_f32 v[58:59], v[58:59], v[66:67], v[76:77] op_sel_hi:[0,1,1]
	v_mov_b32_e32 v93, v59
	s_waitcnt lgkmcnt(4)
	v_pk_add_f32 v[58:59], v[92:93], v[90:91]
	v_add_u32_e32 v56, 0x840, v56
	v_cvt_pk_bf16_f32 v87, v58, s0
	v_cvt_pk_bf16_f32 v90, v59, s0
	v_pk_mul_f32 v[76:77], v[58:59], v[70:71] op_sel:[1,0]
	ds_write_b16 v57, v87 offset:288
	ds_write_b16 v57, v90 offset:416
	v_pk_fma_f32 v[90:91], v[58:59], v[66:67], v[76:77] neg_lo:[0,0,1] neg_hi:[0,0,1]
	v_pk_fma_f32 v[58:59], v[58:59], v[66:67], v[76:77] op_sel_hi:[0,1,1]
	v_mov_b32_e32 v91, v59
	s_waitcnt lgkmcnt(5)
	v_pk_add_f32 v[58:59], v[90:91], v[88:89]
	s_cmpk_lg_i32 s0, 0x1200
	v_cvt_pk_bf16_f32 v87, v58, s0
	v_cvt_pk_bf16_f32 v88, v59, s0
	v_pk_mul_f32 v[76:77], v[58:59], v[70:71] op_sel:[1,0]
	ds_write_b16 v57, v87 offset:576
	ds_write_b16 v57, v88 offset:704
	v_pk_fma_f32 v[88:89], v[58:59], v[66:67], v[76:77] neg_lo:[0,0,1] neg_hi:[0,0,1]
	v_pk_fma_f32 v[58:59], v[58:59], v[66:67], v[76:77] op_sel_hi:[0,1,1]
	v_mov_b32_e32 v89, v59
	s_waitcnt lgkmcnt(6)
	v_pk_add_f32 v[76:77], v[88:89], v[94:95]
	s_nop 0
	v_cvt_pk_bf16_f32 v58, v76, s0
	v_cvt_pk_bf16_f32 v59, v77, s0
	ds_write_b16 v57, v58 offset:864
	ds_write_b16 v57, v59 offset:992
	s_cbranch_scc1 .LBB0_329
	ds_read_b128 v[56:59], v84 offset:33792
	ds_read_b128 v[88:91], v84 offset:33856
	ds_read_b128 v[92:95], v84 offset:33920
	ds_read_b128 v[96:99], v84 offset:33984
	s_waitcnt lgkmcnt(3)
	v_mfma_f32_16x16x32_bf16 v[56:59], v[56:59], v[32:35], 0
	s_waitcnt vmcnt(3)
	v_lshlrev_b32_e32 v78, 16, v78
	s_waitcnt vmcnt(2)
	v_lshlrev_b32_e32 v85, 16, v85
	s_waitcnt vmcnt(0)
	v_lshlrev_b32_e32 v73, 16, v73
	s_waitcnt lgkmcnt(2)
	v_mfma_f32_16x16x32_bf16 v[56:59], v[88:91], v[36:39], v[56:59]
	v_lshlrev_b32_e32 v90, 16, v86
	s_waitcnt lgkmcnt(1)
	v_mfma_f32_16x16x32_bf16 v[86:89], v[92:95], v[40:43], v[56:59]
	s_waitcnt lgkmcnt(0)
	v_mfma_f32_16x16x32_bf16 v[86:89], v[96:99], v[44:47], v[86:89]
	s_nop 2
	v_lshlrev_b64 v[58:59], 10, v[62:63]
	v_lshl_add_u64 v[58:59], v[60:61], 0, v[58:59]
	v_or_b32_e32 v56, 17, v72
	v_mfma_f32_16x16x32_bf16 v[102:105], v[52:55], v[20:23], 0
	s_nop 0
	v_fma_f32 v62, v79, v78, v86
	v_mul_f32_e32 v57, 0x3d372713, v62
	v_mul_f32_e32 v57, v62, v57
	v_fma_f32 v57, v62, v57, v62
	v_mul_f32_e32 v57, 0xbfcc422a, v57
	v_mul_f32_e32 v57, 0x3fb8aa3b, v57
	v_fma_f32 v63, v79, v85, v87
	v_exp_f32_e32 v85, v57
	v_mul_f32_e32 v78, 0x3d372713, v63
	v_mul_f32_e32 v78, v63, v78
	v_fma_f32 v78, v63, v78, v63
	v_mul_f32_e32 v78, 0xbfcc422a, v78
	v_add_f32_e32 v85, 1.0, v85
	v_mul_f32_e32 v78, 0x3fb8aa3b, v78
	v_rcp_f32_e32 v85, v85
	v_exp_f32_e32 v78, v78
	v_fma_f32 v86, v79, v90, v88
	v_mul_f32_e32 v87, 0x3d372713, v86
	v_mul_f32_e32 v62, v62, v85
	v_add_f32_e32 v78, 1.0, v78
	v_cvt_pk_bf16_f32 v62, v62, s0
	v_rcp_f32_e32 v78, v78
	global_store_short v[58:59], v62, off
	v_mul_f32_e32 v58, v86, v87
	v_fma_f32 v58, v86, v58, v86
	v_mul_f32_e32 v58, 0xbfcc422a, v58
	v_mov_b32_e32 v57, s7
	v_mul_f32_e32 v58, 0x3fb8aa3b, v58
	v_mul_f32_e32 v63, v63, v78
	v_exp_f32_e32 v62, v58
	v_lshlrev_b64 v[58:59], 10, v[56:57]
	v_cvt_pk_bf16_f32 v63, v63, s0
	v_lshl_add_u64 v[58:59], v[60:61], 0, v[58:59]
	v_fmac_f32_e32 v89, v79, v73
	global_store_short v[58:59], v63, off
	v_mul_f32_e32 v58, 0x3d372713, v89
	v_mul_f32_e32 v58, v89, v58
	v_fma_f32 v58, v89, v58, v89
	v_mul_f32_e32 v58, 0xbfcc422a, v58
	v_mul_f32_e32 v58, 0x3fb8aa3b, v58
	v_exp_f32_e32 v58, v58
	v_add_f32_e32 v56, 1.0, v62
	v_rcp_f32_e32 v56, v56
	v_mfma_f32_16x16x32_bf16 v[90:93], v[52:55], v[4:7], 0
	v_add_f32_e32 v58, 1.0, v58
	v_rcp_f32_e32 v63, v58
	v_mul_f32_e32 v56, v86, v56
	v_cvt_pk_bf16_f32 v62, v56, s0
	v_or_b32_e32 v56, 18, v72
	v_lshlrev_b64 v[58:59], 10, v[56:57]
	v_lshl_add_u64 v[58:59], v[60:61], 0, v[58:59]
	v_mul_f32_e32 v56, v89, v63
	global_store_short v[58:59], v62, off
	v_cvt_pk_bf16_f32 v62, v56, s0
	v_or_b32_e32 v56, 19, v72
	v_lshlrev_b64 v[58:59], 10, v[56:57]
	v_lshl_add_u64 v[58:59], v[60:61], 0, v[58:59]
	global_store_short v[58:59], v62, off
	v_or_b32_e32 v56, 32, v72
	v_mov_b64_e32 v[58:59], s[76:77]
	v_mad_u64_u32 v[58:59], s[0:1], v56, s17, v[58:59]
	v_add_u32_e32 v59, s6, v59
	v_lshl_add_u64 v[58:59], v[74:75], 1, v[58:59]
	v_lshl_add_u64 v[58:59], v[58:59], 0, v[64:65]
	v_add_co_u32_e32 v62, vcc, s18, v58
	v_mfma_f32_16x16x32_bf16 v[86:89], v[52:55], v[8:11], 0
	s_nop 0
	v_addc_co_u32_e32 v63, vcc, 0, v59, vcc
	v_add_co_u32_e32 v94, vcc, s20, v58
	s_mov_b32 s0, 0
	s_nop 0
	v_addc_co_u32_e32 v95, vcc, 0, v59, vcc
	v_add_co_u32_e32 v96, vcc, s21, v58
	s_nop 1
	v_addc_co_u32_e32 v97, vcc, 0, v59, vcc
	v_add_co_u32_e32 v98, vcc, s22, v58
	s_nop 1
	v_addc_co_u32_e32 v99, vcc, 0, v59, vcc
	global_load_ushort v59, v[62:63], off
	s_nop 0
	global_load_ushort v62, v[94:95], off offset:1024
	global_load_ushort v63, v[96:97], off offset:2048
	global_load_ushort v58, v[98:99], off offset:3072
	v_mfma_f32_16x16x32_bf16 v[94:97], v[52:55], v[12:15], 0
	ds_write2_b32 v82, v86, v90 offset1:16
	ds_write2_b32 v82, v87, v91 offset0:132 offset1:148
	ds_write2_b32 v83, v88, v92 offset0:8 offset1:24
	v_mfma_f32_16x16x32_bf16 v[98:101], v[52:55], v[0:3], 0
	ds_write2_b32 v83, v89, v93 offset0:140 offset1:156
	s_nop 6
	ds_write2_b32 v82, v94, v98 offset0:32 offset1:48
	ds_write2_b32 v82, v95, v99 offset0:164 offset1:180
	v_mfma_f32_16x16x32_bf16 v[86:89], v[52:55], v[16:19], 0
	ds_write2_b32 v83, v96, v100 offset0:40 offset1:56
	ds_write2_b32 v83, v97, v101 offset0:172 offset1:188
	s_nop 5
	ds_write2_b32 v82, v102, v86 offset0:64 offset1:80
	ds_write2_b32 v82, v103, v87 offset0:196 offset1:212
	ds_write2_b32 v83, v104, v88 offset0:72 offset1:88
	ds_write2_b32 v83, v105, v89 offset0:204 offset1:220
	v_mfma_f32_16x16x32_bf16 v[90:93], v[52:55], v[28:31], 0
	v_mfma_f32_16x16x32_bf16 v[52:55], v[52:55], v[24:27], 0
	s_nop 7
	ds_write2_b32 v82, v90, v52 offset0:96 offset1:112
	ds_write2_b32 v82, v91, v53 offset0:228 offset1:244
	ds_write2_b32 v83, v92, v54 offset0:104 offset1:120
	ds_write2_b32 v83, v93, v55 offset0:236 offset1:252
	v_mov_b32_e32 v52, v80
	.p2alignl 6, 3212836864
.LBB0_331:
	ds_read2st64_b32 v[54:55], v52 offset1:1
	v_pk_mul_f32 v[86:87], v[76:77], v[70:71] op_sel:[1,0]
	ds_read2_b32 v[88:89], v52 offset0:132 offset1:196
	v_pk_fma_f32 v[90:91], v[76:77], v[66:67], v[86:87] neg_lo:[0,0,1] neg_hi:[0,0,1]
	v_pk_fma_f32 v[76:77], v[76:77], v[66:67], v[86:87] op_sel_hi:[0,1,1]
	v_mov_b32_e32 v91, v77
	s_waitcnt lgkmcnt(1)
	v_pk_add_f32 v[54:55], v[90:91], v[54:55]
	v_add_u32_e32 v53, s0, v81
	v_add_u32_e32 v73, 32, v52
	v_add_u32_e32 v78, 48, v52
	s_addk_i32 s0, 0x480
	v_pk_mul_f32 v[76:77], v[54:55], v[70:71] op_sel:[1,0]
	ds_read2st64_b32 v[86:87], v73 offset0:4 offset1:5
	ds_read2st64_b32 v[92:93], v78 offset0:6 offset1:7
	v_cvt_pk_bf16_f32 v73, v54, s0
	v_cvt_pk_bf16_f32 v78, v55, s0
	v_pk_fma_f32 v[90:91], v[54:55], v[66:67], v[76:77] neg_lo:[0,0,1] neg_hi:[0,0,1]
	v_pk_fma_f32 v[54:55], v[54:55], v[66:67], v[76:77] op_sel_hi:[0,1,1]
	v_mov_b32_e32 v91, v55
	s_waitcnt lgkmcnt(2)
	v_pk_add_f32 v[54:55], v[90:91], v[88:89]
	ds_write_b16 v53, v73
	ds_write_b16 v53, v78 offset:128
	v_pk_mul_f32 v[76:77], v[54:55], v[70:71] op_sel:[1,0]
	v_cvt_pk_bf16_f32 v73, v54, s0
	v_cvt_pk_bf16_f32 v78, v55, s0
	v_pk_fma_f32 v[88:89], v[54:55], v[66:67], v[76:77] neg_lo:[0,0,1] neg_hi:[0,0,1]
	v_pk_fma_f32 v[54:55], v[54:55], v[66:67], v[76:77] op_sel_hi:[0,1,1]
	v_mov_b32_e32 v89, v55
	s_waitcnt lgkmcnt(3)
	v_pk_add_f32 v[54:55], v[88:89], v[86:87]
	ds_write_b16 v53, v73 offset:288
	ds_write_b16 v53, v78 offset:416
	v_pk_mul_f32 v[76:77], v[54:55], v[70:71] op_sel:[1,0]
	v_cvt_pk_bf16_f32 v73, v54, s0
	v_cvt_pk_bf16_f32 v78, v55, s0
	v_pk_fma_f32 v[86:87], v[54:55], v[66:67], v[76:77] neg_lo:[0,0,1] neg_hi:[0,0,1]
	v_pk_fma_f32 v[54:55], v[54:55], v[66:67], v[76:77] op_sel_hi:[0,1,1]
	v_mov_b32_e32 v87, v55
	s_waitcnt lgkmcnt(4)
	v_pk_add_f32 v[76:77], v[86:87], v[92:93]
	v_add_u32_e32 v52, 0x840, v52
	s_cmpk_lg_i32 s0, 0x1200
	v_cvt_pk_bf16_f32 v54, v76, s0
	ds_write_b16 v53, v73 offset:576
	ds_write_b16 v53, v78 offset:704
	v_cvt_pk_bf16_f32 v55, v77, s0
	ds_write_b16 v53, v54 offset:864
	ds_write_b16 v53, v55 offset:992
	s_cbranch_scc1 .LBB0_331
	ds_read_b128 v[52:55], v84 offset:33792
	ds_read_b128 v[86:89], v84 offset:33856
	ds_read_b128 v[90:93], v84 offset:33920
	ds_read_b128 v[94:97], v84 offset:33984
	s_waitcnt lgkmcnt(3)
	v_mfma_f32_16x16x32_bf16 v[52:55], v[52:55], v[32:35], 0
	s_waitcnt vmcnt(3)
	v_lshlrev_b32_e32 v73, 16, v59
	s_waitcnt vmcnt(0)
	v_lshlrev_b32_e32 v78, 16, v58
	v_lshlrev_b64 v[58:59], 10, v[56:57]
	s_waitcnt lgkmcnt(2)
	v_mfma_f32_16x16x32_bf16 v[52:55], v[86:89], v[36:39], v[52:55]
	v_lshlrev_b32_e32 v62, 16, v62
	v_lshlrev_b32_e32 v63, 16, v63
	s_waitcnt lgkmcnt(1)
	v_mfma_f32_16x16x32_bf16 v[86:89], v[90:93], v[40:43], v[52:55]
	s_waitcnt lgkmcnt(0)
	v_mfma_f32_16x16x32_bf16 v[54:57], v[94:97], v[44:47], v[86:89]
	s_nop 1
	v_or_b32_e32 v52, 33, v72
	v_mfma_f32_16x16x32_bf16 v[90:93], v[48:51], v[4:7], 0
	v_mfma_f32_16x16x32_bf16 v[94:97], v[48:51], v[12:15], 0
	s_nop 2
	v_fma_f32 v73, v79, v73, v54
	v_mul_f32_e32 v53, 0x3d372713, v73
	v_mul_f32_e32 v53, v73, v53
	v_fma_f32 v53, v73, v53, v73
	v_fma_f32 v62, v79, v62, v55
	v_mul_f32_e32 v53, 0xbfcc422a, v53
	v_mul_f32_e32 v54, 0x3d372713, v62
	v_mul_f32_e32 v53, 0x3fb8aa3b, v53
	v_mul_f32_e32 v54, v62, v54
	v_exp_f32_e32 v85, v53
	v_fma_f32 v54, v62, v54, v62
	v_mul_f32_e32 v54, 0xbfcc422a, v54
	v_mul_f32_e32 v54, 0x3fb8aa3b, v54
	v_exp_f32_e32 v86, v54
	v_lshl_add_u64 v[54:55], v[60:61], 0, v[58:59]
	v_add_f32_e32 v58, 1.0, v85
	v_rcp_f32_e32 v58, v58
	v_fma_f32 v56, v79, v63, v56
	v_add_f32_e32 v59, 1.0, v86
	v_mul_f32_e32 v63, 0x3d372713, v56
	v_mul_f32_e32 v58, v73, v58
	v_cvt_pk_bf16_f32 v58, v58, s0
	v_rcp_f32_e32 v59, v59
	global_store_short v[54:55], v58, off
	v_mul_f32_e32 v54, v56, v63
	v_fma_f32 v54, v56, v54, v56
	v_mul_f32_e32 v54, 0xbfcc422a, v54
	v_mov_b32_e32 v53, s7
	v_mul_f32_e32 v54, 0x3fb8aa3b, v54
	v_mul_f32_e32 v59, v62, v59
	v_exp_f32_e32 v58, v54
	v_lshlrev_b64 v[54:55], 10, v[52:53]
	v_cvt_pk_bf16_f32 v59, v59, s0
	v_lshl_add_u64 v[54:55], v[60:61], 0, v[54:55]
	v_fmac_f32_e32 v57, v79, v78
	global_store_short v[54:55], v59, off
	v_mul_f32_e32 v54, 0x3d372713, v57
	v_mul_f32_e32 v54, v57, v54
	v_fma_f32 v54, v57, v54, v57
	v_mul_f32_e32 v54, 0xbfcc422a, v54
	v_mul_f32_e32 v54, 0x3fb8aa3b, v54
	v_exp_f32_e32 v54, v54
	v_add_f32_e32 v52, 1.0, v58
	v_rcp_f32_e32 v52, v52
	v_mfma_f32_16x16x32_bf16 v[86:89], v[48:51], v[8:11], 0
	v_add_f32_e32 v54, 1.0, v54
	v_rcp_f32_e32 v58, v54
	v_mul_f32_e32 v52, v56, v52
	v_cvt_pk_bf16_f32 v56, v52, s0
	v_or_b32_e32 v52, 34, v72
	v_lshlrev_b64 v[54:55], 10, v[52:53]
	v_lshl_add_u64 v[54:55], v[60:61], 0, v[54:55]
	v_mul_f32_e32 v52, v57, v58
	global_store_short v[54:55], v56, off
	v_cvt_pk_bf16_f32 v56, v52, s0
	v_or_b32_e32 v52, 35, v72
	v_lshlrev_b64 v[54:55], 10, v[52:53]
	v_lshl_add_u64 v[54:55], v[60:61], 0, v[54:55]
	global_store_short v[54:55], v56, off
	v_or_b32_e32 v52, 48, v72
	v_mov_b64_e32 v[54:55], s[76:77]
	v_mad_u64_u32 v[54:55], s[0:1], v52, s17, v[54:55]
	v_add_u32_e32 v55, s6, v55
	v_lshl_add_u64 v[54:55], v[74:75], 1, v[54:55]
	v_lshl_add_u64 v[54:55], v[54:55], 0, v[64:65]
	v_add_co_u32_e32 v56, vcc, s18, v54
	v_mfma_f32_16x16x32_bf16 v[98:101], v[48:51], v[0:3], 0
	s_nop 0
	v_addc_co_u32_e32 v57, vcc, 0, v55, vcc
	v_add_co_u32_e32 v58, vcc, s20, v54
	v_mfma_f32_16x16x32_bf16 v[102:105], v[48:51], v[20:23], 0
	s_nop 0
	v_addc_co_u32_e32 v59, vcc, 0, v55, vcc
	v_add_co_u32_e32 v62, vcc, s21, v54
	s_mov_b32 s0, 0
	s_nop 0
	v_addc_co_u32_e32 v63, vcc, 0, v55, vcc
	v_add_co_u32_e32 v74, vcc, s22, v54
	s_nop 1
	v_addc_co_u32_e32 v75, vcc, 0, v55, vcc
	global_load_ushort v54, v[56:57], off
	global_load_ushort v55, v[58:59], off offset:1024
	s_nop 0
	global_load_ushort v56, v[62:63], off offset:2048
	global_load_ushort v57, v[74:75], off offset:3072
	ds_write2_b32 v82, v86, v90 offset1:16
	ds_write2_b32 v82, v87, v91 offset0:132 offset1:148
	ds_write2_b32 v83, v88, v92 offset0:8 offset1:24
	ds_write2_b32 v83, v89, v93 offset0:140 offset1:156
	ds_write2_b32 v82, v94, v98 offset0:32 offset1:48
	ds_write2_b32 v82, v95, v99 offset0:164 offset1:180
	v_mfma_f32_16x16x32_bf16 v[86:89], v[48:51], v[16:19], 0
	ds_write2_b32 v83, v96, v100 offset0:40 offset1:56
	ds_write2_b32 v83, v97, v101 offset0:172 offset1:188
	s_nop 5
	ds_write2_b32 v82, v102, v86 offset0:64 offset1:80
	ds_write2_b32 v82, v103, v87 offset0:196 offset1:212
	ds_write2_b32 v83, v104, v88 offset0:72 offset1:88
	ds_write2_b32 v83, v105, v89 offset0:204 offset1:220
	v_mfma_f32_16x16x32_bf16 v[90:93], v[48:51], v[28:31], 0
	v_mfma_f32_16x16x32_bf16 v[48:51], v[48:51], v[24:27], 0
	s_nop 7
	ds_write2_b32 v82, v90, v48 offset0:96 offset1:112
	ds_write2_b32 v82, v91, v49 offset0:228 offset1:244
	ds_write2_b32 v83, v92, v50 offset0:104 offset1:120
	ds_write2_b32 v83, v93, v51 offset0:236 offset1:252
	.p2alignl 6, 3212836864

.LBB0_335:
	s_waitcnt vmcnt(0)
	s_barrier
	s_mov_b64 s[0:1], exec
	v_readlane_b32 s2, v237, 1
	v_readlane_b32 s3, v237, 2
	s_and_b64 s[2:3], s[0:1], s[2:3]
	s_mov_b64 exec, s[2:3]
	s_cbranch_execz .LBB0_387
	v_mov_b32_e32 v0, 0x13ff0
	s_waitcnt vmcnt(0) expcnt(0) lgkmcnt(0)
	ds_read_b32 v2, v0
	v_mov_b32_e32 v0, 0x13ff4
	ds_read_b32 v0, v0
	s_waitcnt lgkmcnt(1)
	v_cmp_ne_u32_e32 vcc, 0, v2
	s_cbranch_vccnz .LBB0_351
	v_readlane_b32 s2, v237, 0
	s_mul_i32 s4, s91, s2
	s_add_u32 s2, s88, 0x4100200
	s_addc_u32 s3, s89, 0
	s_add_u32 s6, s88, 0x4100400
	s_addc_u32 s7, s89, 0
	s_add_u32 s12, s88, 0x4100500
	s_addc_u32 s13, s89, 0
	s_add_u32 s14, s88, 0x4100600
	s_addc_u32 s15, s89, 0
	s_add_u32 s16, s88, 0x4100700
	s_addc_u32 s17, s89, 0
	s_add_u32 s18, s88, 0x4100800
	s_addc_u32 s19, s89, 0
	s_add_u32 s20, s88, 0x4100900
	s_addc_u32 s21, s89, 0
	s_add_u32 s22, s88, 0x4100a00
	s_addc_u32 s23, s89, 0
	s_add_u32 s24, s88, 0x4100b00
	s_addc_u32 s25, s89, 0
	s_add_u32 s26, s88, 0x4100c00
	s_addc_u32 s27, s89, 0
	s_add_u32 s28, s88, 0x4100d00
	s_addc_u32 s29, s89, 0
	s_add_u32 s30, s88, 0x4100e00
	s_addc_u32 s31, s89, 0
	s_add_u32 s34, s88, 0x4100f00
	s_addc_u32 s35, s89, 0
	s_add_u32 s38, s88, 0x4101000
	s_addc_u32 s39, s89, 0
	s_add_u32 s40, s88, 0x4101100
	s_addc_u32 s41, s89, 0
	s_add_u32 s42, s88, 0x4101200
	s_addc_u32 s43, s89, 0
	s_add_u32 s44, s88, 0x4101300
	s_mul_i32 s4, s4, s90
	s_addc_u32 s45, s89, 0
	s_mov_b32 s5, 1
	v_mov_b32_e32 v16, 0
	s_branch .LBB0_339
	.p2alignl 6, 3212836864

.LBB0_339:
	global_load_dword v15, v16, s[6:7] sc1
	s_waitcnt lgkmcnt(0)
	global_load_dword v0, v16, s[12:13] sc1
	global_load_dword v1, v16, s[14:15] sc1
	global_load_dword v2, v16, s[16:17] sc1
	global_load_dword v3, v16, s[18:19] sc1
	global_load_dword v4, v16, s[20:21] sc1
	global_load_dword v5, v16, s[22:23] sc1
	global_load_dword v6, v16, s[24:25] sc1
	global_load_dword v7, v16, s[26:27] sc1
	global_load_dword v8, v16, s[28:29] sc1
	global_load_dword v9, v16, s[30:31] sc1
	global_load_dword v10, v16, s[34:35] sc1
	global_load_dword v11, v16, s[38:39] sc1
	global_load_dword v12, v16, s[40:41] sc1
	global_load_dword v13, v16, s[42:43] sc1
	global_load_dword v14, v16, s[44:45] sc1
	s_mov_b64 s[46:47], -1
	s_mov_b64 s[48:49], -1
	s_waitcnt vmcnt(14)
	v_add_u32_e32 v17, v0, v15
	s_waitcnt vmcnt(13)
	v_add_u32_e32 v17, v17, v1
	s_waitcnt vmcnt(12)
	v_add_u32_e32 v17, v17, v2
	s_waitcnt vmcnt(11)
	v_add_u32_e32 v17, v17, v3
	s_waitcnt vmcnt(10)
	v_add_u32_e32 v17, v17, v4
	s_waitcnt vmcnt(9)
	v_add_u32_e32 v17, v17, v5
	s_waitcnt vmcnt(8)
	v_add_u32_e32 v17, v17, v6
	s_waitcnt vmcnt(7)
	v_add_u32_e32 v17, v17, v7
	s_waitcnt vmcnt(6)
	v_add_u32_e32 v17, v17, v8
	s_waitcnt vmcnt(5)
	v_add_u32_e32 v17, v17, v9
	s_waitcnt vmcnt(4)
	v_add_u32_e32 v17, v17, v10
	s_waitcnt vmcnt(3)
	v_add_u32_e32 v17, v17, v11
	s_waitcnt vmcnt(2)
	v_add_u32_e32 v17, v17, v12
	s_waitcnt vmcnt(1)
	v_add_u32_e32 v17, v17, v13
	s_waitcnt vmcnt(0)
	v_add_u32_e32 v17, v17, v14
	v_cmp_eq_u32_e32 vcc, s4, v17
	s_cbranch_vccnz .LBB0_338
	s_and_b32 s33, s5, 0xff
	s_cmp_eq_u32 s33, 0
	s_mov_b64 s[50:51], -1
	s_sleep 1
	s_cbranch_scc1 .LBB0_343
	s_and_b64 vcc, exec, s[50:51]
	s_cbranch_vccz .LBB0_338
	.p2alignl 6, 3212836864

.LBB0_387:
	v_writelane_b32 v237, s60, 37
	s_nop 1
	v_writelane_b32 v237, s61, 38
	v_writelane_b32 v237, s78, 39
	v_writelane_b32 v237, s58, 40
	s_nop 1
	v_writelane_b32 v237, s59, 41
	s_or_b64 exec, exec, s[0:1]
	s_add_u32 s80, s88, 0x16500000
	s_addc_u32 s81, s89, 0
	v_readlane_b32 s0, v237, 34
	s_add_u32 s78, s88, 0x18500000
	v_readlane_b32 s1, v237, 35
	s_addc_u32 s79, s89, 0
	s_waitcnt lgkmcnt(0)
	v_mov_b32_e32 v0, v128
	s_and_b64 vcc, exec, s[0:1]
	s_barrier
	s_cbranch_vccnz .LBB0_414
	v_ashrrev_i32_e32 v129, 3, v0
	v_readlane_b32 s0, v237, 31
	v_lshlrev_b32_e32 v136, 9, v129
	s_mov_b64 s[2:3], -1
	s_movk_i32 s14, 0x50
	v_mov_b32_e32 v131, 0
	s_movk_i32 s15, 0xffc0
	s_movk_i32 s16, 0xa0
	s_mov_b32 s17, s0
	s_mov_b32 s6, s0
	v_readlane_b32 s1, v237, 32
	s_branch .LBB0_390
	.p2alignl 6, 3212836864

.LBB0_394:
	s_and_b32 s98, s17, 7
	s_lshl_b32 s98, s98, 5
	s_bfe_u32 s99, s17, 0x50005
	s_or_b32 s98, s98, s99
	s_lshl_b32 s98, s98, 3
	s_lshr_b32 s99, s17, 10
	s_lshl_b32 s99, s99, 2
	s_or_b32 s98, s98, s99
	s_bfe_u32 s99, s17, 0x20003
	s_or_b32 s98, s98, s99
	s_and_b32 s0, s98, 7
	s_add_i32 s20, s6, s90
	s_cmpk_gt_i32 s20, 0x7ff
	v_lshl_add_u32 v142, s0, 16, v136
	s_cselect_b64 s[0:1], -1, 0
	s_cmpk_lt_i32 s20, 0x800
	s_cselect_b64 s[2:3], -1, 0
	s_and_b64 s[4:5], s[2:3], exec
	v_lshlrev_b32_e32 v10, 1, v138
	s_cselect_b32 s4, s20, s6
	s_and_b32 s98, s4, 7
	s_lshl_b32 s98, s98, 5
	s_bfe_u32 s99, s4, 0x50005
	s_or_b32 s98, s98, s99
	s_lshl_b32 s98, s98, 3
	s_lshr_b32 s99, s4, 10
	s_lshl_b32 s99, s99, 2
	s_or_b32 s98, s98, s99
	s_bfe_u32 s99, s4, 0x20003
	s_or_b32 s4, s98, s99
	v_bfe_u32 v139, v64, 6, 1
	v_and_b32_e32 v9, 15, v64
	v_lshl_add_u32 v145, v71, 1, v10
	v_lshl_add_u32 v146, v68, 1, v10
	v_lshl_add_u32 v147, v69, 1, v10
	v_lshl_add_u32 v148, v70, 1, v10
	v_ashrrev_i32_e32 v10, 1, v64
	s_lshl_b32 s5, s4, 4
	s_lshl_b32 s4, s4, 7
	v_bfe_u32 v140, v64, 4, 2
	v_and_or_b32 v141, v10, s15, v9
	v_lshl_or_b32 v9, v139, 6, v9
	s_and_b32 s5, s5, 0x7fff80
	s_and_b32 s4, s4, 0x380
	v_lshlrev_b32_e32 v10, 4, v140
	v_mul_u32_u24_e32 v9, 0x50, v9
	v_add_lshl_u32 v143, s5, v129, 9
	v_add_lshl_u32 v144, s4, v129, 9
	v_mad_u64_u32 v[134:135], s[4:5], v141, s16, v[10:11]
	v_lshlrev_b32_e32 v9, 1, v9
	v_or_b32_e32 v66, 0x1c0, v138
	v_add_u32_e32 v135, v10, v9
	v_or_b32_e32 v64, 0xf000, v10
	v_add_u32_e32 v67, 0x1400, v9
	v_add_u32_e32 v9, 0x1e00, v9
	v_add_u32_e32 v149, v64, v67
	v_add_u32_e32 v150, v64, v9
	v_or_b32_e32 v10, 0xf040, v10
	v_add_u32_e32 v153, v66, v137
	v_add_u32_e32 v154, v66, v65
	v_mov_b32_e32 v64, 0
	v_add_u32_e32 v151, v10, v67
	v_add_u32_e32 v152, v10, v9
	v_add_u32_e32 v155, 0x4000, v153
	v_add_u32_e32 v156, 0x4000, v154
	v_add_u32_e32 v157, 0x8000, v153
	v_add_u32_e32 v158, 0x8000, v154
	v_add_u32_e32 v159, 0xc000, v153
	v_add_u32_e32 v160, 0xc000, v154
	s_mov_b32 s21, 0
	v_mov_b32_e32 v65, v64
	v_mov_b32_e32 v66, v64
	v_mov_b32_e32 v67, v64
	v_mov_b32_e32 v72, v64
	v_mov_b32_e32 v73, v64
	v_mov_b32_e32 v74, v64
	v_mov_b32_e32 v75, v64
	v_mov_b32_e32 v80, v64
	v_mov_b32_e32 v81, v64
	v_mov_b32_e32 v82, v64
	v_mov_b32_e32 v83, v64
	v_mov_b32_e32 v88, v64
	v_mov_b32_e32 v89, v64
	v_mov_b32_e32 v90, v64
	v_mov_b32_e32 v91, v64
	v_mov_b32_e32 v96, v64
	v_mov_b32_e32 v97, v64
	v_mov_b32_e32 v98, v64
	v_mov_b32_e32 v99, v64
	v_mov_b32_e32 v104, v64
	v_mov_b32_e32 v105, v64
	v_mov_b32_e32 v106, v64
	v_mov_b32_e32 v107, v64
	v_mov_b32_e32 v112, v64
	v_mov_b32_e32 v113, v64
	v_mov_b32_e32 v114, v64
	v_mov_b32_e32 v115, v64
	v_mov_b32_e32 v120, v64
	v_mov_b32_e32 v121, v64
	v_mov_b32_e32 v122, v64
	v_mov_b32_e32 v123, v64
	v_mov_b32_e32 v68, v64
	v_mov_b32_e32 v69, v64
	v_mov_b32_e32 v70, v64
	v_mov_b32_e32 v71, v64
	v_mov_b32_e32 v76, v64
	v_mov_b32_e32 v77, v64
	v_mov_b32_e32 v78, v64
	v_mov_b32_e32 v79, v64
	v_mov_b32_e32 v84, v64
	v_mov_b32_e32 v85, v64
	v_mov_b32_e32 v86, v64
	v_mov_b32_e32 v87, v64
	v_mov_b32_e32 v92, v64
	v_mov_b32_e32 v93, v64
	v_mov_b32_e32 v94, v64
	v_mov_b32_e32 v95, v64
	v_mov_b32_e32 v100, v64
	v_mov_b32_e32 v101, v64
	v_mov_b32_e32 v102, v64
	v_mov_b32_e32 v103, v64
	v_mov_b32_e32 v108, v64
	v_mov_b32_e32 v109, v64
	v_mov_b32_e32 v110, v64
	v_mov_b32_e32 v111, v64
	v_mov_b32_e32 v116, v64
	v_mov_b32_e32 v117, v64
	v_mov_b32_e32 v118, v64
	v_mov_b32_e32 v119, v64
	v_mov_b32_e32 v124, v64
	v_mov_b32_e32 v125, v64
	v_mov_b32_e32 v126, v64
	v_mov_b32_e32 v127, v64
	v_mov_b32_e32 v9, v132
	v_mov_b32_e32 v10, v133
	s_branch .LBB0_396
	.p2alignl 6, 3212836864

.LBB0_414:
	s_waitcnt vmcnt(0)
	s_barrier
	s_mov_b64 s[0:1], exec
	v_readlane_b32 s2, v237, 1
	v_readlane_b32 s3, v237, 2
	s_and_b64 s[2:3], s[0:1], s[2:3]
	s_mov_b64 exec, s[2:3]
	s_cbranch_execz .LBB0_466
	v_mov_b32_e32 v0, 0x13ff0
	s_waitcnt vmcnt(0) expcnt(0) lgkmcnt(0)
	ds_read_b32 v2, v0
	v_mov_b32_e32 v0, 0x13ff4
	ds_read_b32 v0, v0
	s_waitcnt lgkmcnt(1)
	v_cmp_ne_u32_e32 vcc, 0, v2
	s_cbranch_vccnz .LBB0_430
	v_readlane_b32 s2, v237, 0
	s_mul_i32 s4, s91, s2
	s_add_u32 s2, s88, 0x4100200
	s_addc_u32 s3, s89, 0
	s_add_u32 s6, s88, 0x4100400
	s_addc_u32 s7, s89, 0
	s_add_u32 s10, s88, 0x4100500
	s_addc_u32 s11, s89, 0
	s_add_u32 s12, s88, 0x4100600
	s_addc_u32 s13, s89, 0
	s_add_u32 s14, s88, 0x4100700
	s_addc_u32 s15, s89, 0
	s_add_u32 s16, s88, 0x4100800
	s_addc_u32 s17, s89, 0
	s_add_u32 s18, s88, 0x4100900
	s_addc_u32 s19, s89, 0
	s_add_u32 s20, s88, 0x4100a00
	s_addc_u32 s21, s89, 0
	s_add_u32 s22, s88, 0x4100b00
	s_addc_u32 s23, s89, 0
	s_add_u32 s24, s88, 0x4100c00
	s_addc_u32 s25, s89, 0
	s_add_u32 s26, s88, 0x4100d00
	s_addc_u32 s27, s89, 0
	s_add_u32 s28, s88, 0x4100e00
	s_addc_u32 s29, s89, 0
	s_add_u32 s30, s88, 0x4100f00
	s_addc_u32 s31, s89, 0
	s_add_u32 s34, s88, 0x4101000
	s_addc_u32 s35, s89, 0
	s_add_u32 s38, s88, 0x4101100
	s_addc_u32 s39, s89, 0
	s_add_u32 s40, s88, 0x4101200
	s_addc_u32 s41, s89, 0
	s_add_u32 s42, s88, 0x4101300
	s_mul_i32 s4, s4, s90
	s_addc_u32 s43, s89, 0
	s_mov_b32 s5, 1
	v_mov_b32_e32 v16, 0
	s_branch .LBB0_418
	.p2alignl 6, 3212836864

.LBB0_418:
	global_load_dword v15, v16, s[6:7] sc1
	s_waitcnt lgkmcnt(0)
	global_load_dword v0, v16, s[10:11] sc1
	global_load_dword v1, v16, s[12:13] sc1
	global_load_dword v2, v16, s[14:15] sc1
	global_load_dword v3, v16, s[16:17] sc1
	global_load_dword v4, v16, s[18:19] sc1
	global_load_dword v5, v16, s[20:21] sc1
	global_load_dword v6, v16, s[22:23] sc1
	global_load_dword v7, v16, s[24:25] sc1
	global_load_dword v8, v16, s[26:27] sc1
	global_load_dword v9, v16, s[28:29] sc1
	global_load_dword v10, v16, s[30:31] sc1
	global_load_dword v11, v16, s[34:35] sc1
	global_load_dword v12, v16, s[38:39] sc1
	global_load_dword v13, v16, s[40:41] sc1
	global_load_dword v14, v16, s[42:43] sc1
	s_mov_b64 s[44:45], -1
	s_mov_b64 s[46:47], -1
	s_waitcnt vmcnt(14)
	v_add_u32_e32 v17, v0, v15
	s_waitcnt vmcnt(13)
	v_add_u32_e32 v17, v17, v1
	s_waitcnt vmcnt(12)
	v_add_u32_e32 v17, v17, v2
	s_waitcnt vmcnt(11)
	v_add_u32_e32 v17, v17, v3
	s_waitcnt vmcnt(10)
	v_add_u32_e32 v17, v17, v4
	s_waitcnt vmcnt(9)
	v_add_u32_e32 v17, v17, v5
	s_waitcnt vmcnt(8)
	v_add_u32_e32 v17, v17, v6
	s_waitcnt vmcnt(7)
	v_add_u32_e32 v17, v17, v7
	s_waitcnt vmcnt(6)
	v_add_u32_e32 v17, v17, v8
	s_waitcnt vmcnt(5)
	v_add_u32_e32 v17, v17, v9
	s_waitcnt vmcnt(4)
	v_add_u32_e32 v17, v17, v10
	s_waitcnt vmcnt(3)
	v_add_u32_e32 v17, v17, v11
	s_waitcnt vmcnt(2)
	v_add_u32_e32 v17, v17, v12
	s_waitcnt vmcnt(1)
	v_add_u32_e32 v17, v17, v13
	s_waitcnt vmcnt(0)
	v_add_u32_e32 v17, v17, v14
	v_cmp_eq_u32_e32 vcc, s4, v17
	s_cbranch_vccnz .LBB0_417
	s_and_b32 s33, s5, 0xff
	s_cmp_eq_u32 s33, 0
	s_mov_b64 s[48:49], -1
	s_sleep 1
	s_cbranch_scc1 .LBB0_422
	s_and_b64 vcc, exec, s[48:49]
	s_cbranch_vccz .LBB0_417
	.p2alignl 6, 3212836864

.LBB0_466:
	s_or_b64 exec, exec, s[0:1]
	v_readlane_b32 s0, v237, 34
	v_readlane_b32 s1, v237, 35
	s_waitcnt lgkmcnt(0)
	v_mov_b32_e32 v0, v128
	s_and_b64 vcc, exec, s[0:1]
	s_barrier
	s_cbranch_vccnz .LBB0_493
	v_ashrrev_i32_e32 v129, 3, v0
	v_readlane_b32 s0, v237, 31
	v_lshlrev_b32_e32 v136, 10, v129
	s_mov_b64 s[2:3], -1
	s_movk_i32 s12, 0x50
	v_mov_b32_e32 v131, 0
	s_movk_i32 s13, 0xffc0
	s_movk_i32 s14, 0xa0
	s_mov_b32 s15, s0
	s_mov_b32 s6, s0
	v_readlane_b32 s1, v237, 32
	s_branch .LBB0_469
	.p2alignl 6, 3212836864

.LBB0_473:
	s_and_b32 s98, s15, 7
	s_lshl_b32 s98, s98, 5
	s_bfe_u32 s99, s15, 0x50005
	s_or_b32 s98, s98, s99
	s_lshl_b32 s98, s98, 3
	s_lshr_b32 s99, s15, 10
	s_lshl_b32 s99, s99, 2
	s_or_b32 s98, s98, s99
	s_bfe_u32 s99, s15, 0x20003
	s_or_b32 s98, s98, s99
	s_and_b32 s0, s98, 7
	s_add_i32 s18, s6, s90
	s_cmpk_gt_i32 s18, 0x7ff
	v_lshl_add_u32 v140, s0, 17, v136
	s_cselect_b64 s[0:1], -1, 0
	s_cmpk_lt_i32 s18, 0x800
	s_cselect_b64 s[2:3], -1, 0
	s_and_b64 s[4:5], s[2:3], exec
	s_cselect_b32 s4, s18, s6
	s_and_b32 s98, s4, 7
	s_lshl_b32 s98, s98, 5
	s_bfe_u32 s99, s4, 0x50005
	s_or_b32 s98, s98, s99
	s_lshl_b32 s98, s98, 3
	s_lshr_b32 s99, s4, 10
	s_lshl_b32 s99, s99, 2
	s_or_b32 s98, s98, s99
	s_bfe_u32 s99, s4, 0x20003
	s_or_b32 s4, s98, s99
	v_lshlrev_b32_e32 v10, 1, v139
	s_lshl_b32 s5, s4, 4
	s_lshl_b32 s4, s4, 7
	v_and_b32_e32 v9, 15, v137
	v_bfe_u32 v141, v137, 4, 2
	v_lshl_add_u32 v144, v70, 1, v10
	v_lshl_add_u32 v145, v67, 1, v10
	v_lshl_add_u32 v146, v68, 1, v10
	v_lshl_add_u32 v147, v69, 1, v10
	v_ashrrev_i32_e32 v10, 1, v137
	s_and_b32 s5, s5, 0x3fff80
	s_and_b32 s4, s4, 0x380
	v_and_or_b32 v148, v10, s13, v9
	v_lshlrev_b32_e32 v10, 4, v141
	v_and_b32_e32 v9, 0x4f, v137
	v_add_lshl_u32 v142, s5, v129, 10
	v_add_lshl_u32 v143, s4, v129, 10
	v_or_b32_e32 v65, 0x3c0, v139
	v_mad_u64_u32 v[134:135], s[4:5], v148, s14, v[10:11]
	v_mul_u32_u24_e32 v9, 0x50, v9
	v_lshl_add_u32 v135, v9, 1, v10
	v_add_u32_e32 v151, v65, v138
	v_add_u32_e32 v152, v65, v64
	v_mov_b32_e32 v64, 0
	v_add_u32_e32 v149, 0xf000, v135
	v_add_u32_e32 v150, 0xf040, v135
	v_add_u32_e32 v153, 0x8000, v151
	v_add_u32_e32 v154, 0x8000, v152
	v_add_u32_e32 v155, 0x10000, v151
	v_add_u32_e32 v156, 0x10000, v152
	v_add_u32_e32 v157, 0x18000, v151
	v_add_u32_e32 v158, 0x18000, v152
	s_mov_b32 s19, 0
	v_mov_b32_e32 v65, v64
	v_mov_b32_e32 v66, v64
	v_mov_b32_e32 v67, v64
	v_mov_b32_e32 v68, v64
	v_mov_b32_e32 v69, v64
	v_mov_b32_e32 v70, v64
	v_mov_b32_e32 v71, v64
	v_mov_b32_e32 v72, v64
	v_mov_b32_e32 v73, v64
	v_mov_b32_e32 v74, v64
	v_mov_b32_e32 v75, v64
	v_mov_b32_e32 v76, v64
	v_mov_b32_e32 v77, v64
	v_mov_b32_e32 v78, v64
	v_mov_b32_e32 v79, v64
	v_mov_b32_e32 v80, v64
	v_mov_b32_e32 v81, v64
	v_mov_b32_e32 v82, v64
	v_mov_b32_e32 v83, v64
	v_mov_b32_e32 v84, v64
	v_mov_b32_e32 v85, v64
	v_mov_b32_e32 v86, v64
	v_mov_b32_e32 v87, v64
	v_mov_b32_e32 v88, v64
	v_mov_b32_e32 v89, v64
	v_mov_b32_e32 v90, v64
	v_mov_b32_e32 v91, v64
	v_mov_b32_e32 v92, v64
	v_mov_b32_e32 v93, v64
	v_mov_b32_e32 v94, v64
	v_mov_b32_e32 v95, v64
	v_mov_b32_e32 v96, v64
	v_mov_b32_e32 v97, v64
	v_mov_b32_e32 v98, v64
	v_mov_b32_e32 v99, v64
	v_mov_b32_e32 v100, v64
	v_mov_b32_e32 v101, v64
	v_mov_b32_e32 v102, v64
	v_mov_b32_e32 v103, v64
	v_mov_b32_e32 v104, v64
	v_mov_b32_e32 v105, v64
	v_mov_b32_e32 v106, v64
	v_mov_b32_e32 v107, v64
	v_mov_b32_e32 v108, v64
	v_mov_b32_e32 v109, v64
	v_mov_b32_e32 v110, v64
	v_mov_b32_e32 v111, v64
	v_mov_b32_e32 v112, v64
	v_mov_b32_e32 v113, v64
	v_mov_b32_e32 v114, v64
	v_mov_b32_e32 v115, v64
	v_mov_b32_e32 v116, v64
	v_mov_b32_e32 v117, v64
	v_mov_b32_e32 v118, v64
	v_mov_b32_e32 v119, v64
	v_mov_b32_e32 v120, v64
	v_mov_b32_e32 v121, v64
	v_mov_b32_e32 v122, v64
	v_mov_b32_e32 v123, v64
	v_mov_b32_e32 v124, v64
	v_mov_b32_e32 v125, v64
	v_mov_b32_e32 v126, v64
	v_mov_b32_e32 v127, v64
	v_mov_b32_e32 v9, v132
	v_mov_b32_e32 v10, v133
	s_branch .LBB0_475
	.p2alignl 6, 3212836864

.LBB0_493:
	s_waitcnt vmcnt(0)
	s_barrier
	s_mov_b64 s[0:1], exec
	v_readlane_b32 s2, v237, 1
	v_readlane_b32 s3, v237, 2
	s_and_b64 s[2:3], s[0:1], s[2:3]
	s_mov_b64 exec, s[2:3]
	s_cbranch_execz .LBB0_545
	v_mov_b32_e32 v0, 0x13ff0
	s_waitcnt vmcnt(0) expcnt(0) lgkmcnt(0)
	ds_read_b32 v2, v0
	v_mov_b32_e32 v0, 0x13ff4
	ds_read_b32 v0, v0
	s_waitcnt lgkmcnt(1)
	v_cmp_ne_u32_e32 vcc, 0, v2
	s_cbranch_vccnz .LBB0_509
	v_readlane_b32 s2, v237, 0
	s_mul_i32 s4, s91, s2
	s_add_u32 s2, s88, 0x4100200
	s_addc_u32 s3, s89, 0
	s_add_u32 s6, s88, 0x4100400
	s_addc_u32 s7, s89, 0
	s_add_u32 s8, s88, 0x4100500
	s_addc_u32 s9, s89, 0
	s_add_u32 s10, s88, 0x4100600
	s_addc_u32 s11, s89, 0
	s_add_u32 s12, s88, 0x4100700
	s_addc_u32 s13, s89, 0
	s_add_u32 s14, s88, 0x4100800
	s_addc_u32 s15, s89, 0
	s_add_u32 s16, s88, 0x4100900
	s_addc_u32 s17, s89, 0
	s_add_u32 s18, s88, 0x4100a00
	s_addc_u32 s19, s89, 0
	s_add_u32 s20, s88, 0x4100b00
	s_addc_u32 s21, s89, 0
	s_add_u32 s22, s88, 0x4100c00
	s_addc_u32 s23, s89, 0
	s_add_u32 s24, s88, 0x4100d00
	s_addc_u32 s25, s89, 0
	s_add_u32 s26, s88, 0x4100e00
	s_addc_u32 s27, s89, 0
	s_add_u32 s28, s88, 0x4100f00
	s_addc_u32 s29, s89, 0
	s_add_u32 s30, s88, 0x4101000
	s_addc_u32 s31, s89, 0
	s_add_u32 s34, s88, 0x4101100
	s_addc_u32 s35, s89, 0
	s_add_u32 s38, s88, 0x4101200
	s_addc_u32 s39, s89, 0
	s_add_u32 s40, s88, 0x4101300
	s_mul_i32 s4, s4, s90
	s_addc_u32 s41, s89, 0
	s_mov_b32 s5, 1
	v_mov_b32_e32 v16, 0
	s_branch .LBB0_497
	.p2alignl 6, 3212836864

.LBB0_497:
	global_load_dword v15, v16, s[6:7] sc1
	s_waitcnt lgkmcnt(0)
	global_load_dword v0, v16, s[8:9] sc1
	global_load_dword v1, v16, s[10:11] sc1
	global_load_dword v2, v16, s[12:13] sc1
	global_load_dword v3, v16, s[14:15] sc1
	global_load_dword v4, v16, s[16:17] sc1
	global_load_dword v5, v16, s[18:19] sc1
	global_load_dword v6, v16, s[20:21] sc1
	global_load_dword v7, v16, s[22:23] sc1
	global_load_dword v8, v16, s[24:25] sc1
	global_load_dword v9, v16, s[26:27] sc1
	global_load_dword v10, v16, s[28:29] sc1
	global_load_dword v11, v16, s[30:31] sc1
	global_load_dword v12, v16, s[34:35] sc1
	global_load_dword v13, v16, s[38:39] sc1
	global_load_dword v14, v16, s[40:41] sc1
	s_mov_b64 s[42:43], -1
	s_mov_b64 s[44:45], -1
	s_waitcnt vmcnt(14)
	v_add_u32_e32 v17, v0, v15
	s_waitcnt vmcnt(13)
	v_add_u32_e32 v17, v17, v1
	s_waitcnt vmcnt(12)
	v_add_u32_e32 v17, v17, v2
	s_waitcnt vmcnt(11)
	v_add_u32_e32 v17, v17, v3
	s_waitcnt vmcnt(10)
	v_add_u32_e32 v17, v17, v4
	s_waitcnt vmcnt(9)
	v_add_u32_e32 v17, v17, v5
	s_waitcnt vmcnt(8)
	v_add_u32_e32 v17, v17, v6
	s_waitcnt vmcnt(7)
	v_add_u32_e32 v17, v17, v7
	s_waitcnt vmcnt(6)
	v_add_u32_e32 v17, v17, v8
	s_waitcnt vmcnt(5)
	v_add_u32_e32 v17, v17, v9
	s_waitcnt vmcnt(4)
	v_add_u32_e32 v17, v17, v10
	s_waitcnt vmcnt(3)
	v_add_u32_e32 v17, v17, v11
	s_waitcnt vmcnt(2)
	v_add_u32_e32 v17, v17, v12
	s_waitcnt vmcnt(1)
	v_add_u32_e32 v17, v17, v13
	s_waitcnt vmcnt(0)
	v_add_u32_e32 v17, v17, v14
	v_cmp_eq_u32_e32 vcc, s4, v17
	s_cbranch_vccnz .LBB0_496
	s_and_b32 s33, s5, 0xff
	s_cmp_eq_u32 s33, 0
	s_mov_b64 s[46:47], -1
	s_sleep 1
	s_cbranch_scc1 .LBB0_501
	s_and_b64 vcc, exec, s[46:47]
	s_cbranch_vccz .LBB0_496
	.p2alignl 6, 3212836864

.LBB0_545:
	s_or_b64 exec, exec, s[0:1]
	s_waitcnt vmcnt(1)
	v_mov_b32_e32 v56, v128
	s_waitcnt lgkmcnt(0)
	s_barrier
	s_nop 0
	v_add_u32_e32 v66, 0x100, v56
	v_ashrrev_i32_e32 v57, 31, v56
	v_ashrrev_i32_e32 v67, 31, v66
	v_lshl_add_u64 v[0:1], v[56:57], 4, s[70:71]
	v_lshl_add_u64 v[4:5], v[66:67], 4, s[70:71]
	v_add_u32_e32 v68, 0x200, v56
	v_add_u32_e32 v70, 0x300, v56
	s_barrier
	global_load_dwordx4 v[0:3], v[0:1], off
	s_nop 0
	global_load_dwordx4 v[4:7], v[4:5], off
	v_ashrrev_i32_e32 v69, 31, v68
	v_ashrrev_i32_e32 v71, 31, v70
	v_lshl_add_u64 v[8:9], v[68:69], 4, s[70:71]
	v_lshl_add_u64 v[12:13], v[70:71], 4, s[70:71]
	v_add_u32_e32 v72, 0x400, v56
	global_load_dwordx4 v[8:11], v[8:9], off
	v_ashrrev_i32_e32 v73, 31, v72
	global_load_dwordx4 v[12:15], v[12:13], off nt
	v_lshl_add_u64 v[16:17], v[72:73], 4, s[70:71]
	v_add_u32_e32 v74, 0x500, v56
	global_load_dwordx4 v[16:19], v[16:17], off
	v_ashrrev_i32_e32 v75, 31, v74
	v_lshl_add_u64 v[20:21], v[74:75], 4, s[70:71]
	v_add_u32_e32 v76, 0x600, v56
	global_load_dwordx4 v[20:23], v[20:21], off
	v_ashrrev_i32_e32 v77, 31, v76
	v_lshl_add_u64 v[24:25], v[76:77], 4, s[70:71]
	v_add_u32_e32 v78, 0x700, v56
	global_load_dwordx4 v[24:27], v[24:25], off
	v_ashrrev_i32_e32 v79, 31, v78
	v_lshl_add_u64 v[28:29], v[78:79], 4, s[70:71]
	v_add_u32_e32 v80, 0x800, v56
	global_load_dwordx4 v[28:31], v[28:29], off
	v_ashrrev_i32_e32 v81, 31, v80
	v_lshl_add_u64 v[32:33], v[80:81], 4, s[70:71]
	v_add_u32_e32 v82, 0x900, v56
	global_load_dwordx4 v[32:35], v[32:33], off
	v_ashrrev_i32_e32 v83, 31, v82
	v_lshl_add_u64 v[36:37], v[82:83], 4, s[70:71]
	v_add_u32_e32 v84, 0xa00, v56
	global_load_dwordx4 v[36:39], v[36:37], off
	v_ashrrev_i32_e32 v85, 31, v84
	v_lshl_add_u64 v[40:41], v[84:85], 4, s[70:71]
	v_add_u32_e32 v86, 0xb00, v56
	global_load_dwordx4 v[40:43], v[40:41], off
	v_ashrrev_i32_e32 v87, 31, v86
	v_lshl_add_u64 v[44:45], v[86:87], 4, s[70:71]
	v_add_u32_e32 v88, 0xc00, v56
	global_load_dwordx4 v[44:47], v[44:45], off
	v_ashrrev_i32_e32 v89, 31, v88
	v_lshl_add_u64 v[48:49], v[88:89], 4, s[70:71]
	v_add_u32_e32 v90, 0xd00, v56
	global_load_dwordx4 v[48:51], v[48:49], off
	v_ashrrev_i32_e32 v91, 31, v90
	v_lshl_add_u64 v[52:53], v[90:91], 4, s[70:71]
	v_add_u32_e32 v92, 0xe00, v56
	global_load_dwordx4 v[52:55], v[52:53], off
	v_ashrrev_i32_e32 v93, 31, v92
	v_lshl_add_u64 v[58:59], v[92:93], 4, s[70:71]
	v_add_u32_e32 v94, 0xf00, v56
	global_load_dwordx4 v[58:61], v[58:59], off
	v_ashrrev_i32_e32 v95, 31, v94
	s_waitcnt vmcnt(15)
	v_lshl_add_u64 v[62:63], v[94:95], 4, s[70:71]
	global_load_dwordx4 v[62:65], v[62:63], off
	v_lshlrev_b32_e32 v67, 14, v56
	v_and_b32_e32 v69, -4, v56
	v_and_b32_e32 v67, 0xc000, v67
	v_and_b32_e32 v66, -4, v66
	v_and_b32_e32 v68, -4, v68
	v_add_u32_e32 v69, v67, v69
	v_add_u32_e32 v66, v67, v66
	v_add_u32_e32 v68, v67, v68
	s_add_u32 s0, s88, 0x3e00000
	s_addc_u32 s1, s89, 0
	v_writelane_b32 v237, s0, 42
	s_waitcnt vmcnt(15)
	ds_write2st64_b32 v69, v0, v1 offset1:16
	ds_write2st64_b32 v69, v2, v3 offset0:32 offset1:48
	s_waitcnt vmcnt(14)
	ds_write2st64_b32 v66, v4, v5 offset1:16
	ds_write2st64_b32 v66, v6, v7 offset0:32 offset1:48
	s_waitcnt vmcnt(13)
	ds_write2st64_b32 v68, v8, v9 offset1:16
	ds_write2st64_b32 v68, v10, v11 offset0:32 offset1:48
	v_and_b32_e32 v0, -4, v70
	v_add_u32_e32 v0, v67, v0
	s_waitcnt vmcnt(12)
	ds_write2st64_b32 v0, v12, v13 offset1:16
	ds_write2st64_b32 v0, v14, v15 offset0:32 offset1:48
	v_and_b32_e32 v0, -4, v72
	v_add_u32_e32 v0, v67, v0
	s_waitcnt vmcnt(11)
	ds_write2st64_b32 v0, v16, v17 offset1:16
	ds_write2st64_b32 v0, v18, v19 offset0:32 offset1:48
	v_and_b32_e32 v0, -4, v74
	v_add_u32_e32 v0, v67, v0
	v_writelane_b32 v237, s1, 43
	s_waitcnt vmcnt(10)
	ds_write2st64_b32 v0, v20, v21 offset1:16
	ds_write2st64_b32 v0, v22, v23 offset0:32 offset1:48
	v_and_b32_e32 v0, -4, v76
	s_add_u32 s0, s88, 0x3d80000
	v_add_u32_e32 v0, v67, v0
	s_addc_u32 s1, s89, 0
	s_waitcnt vmcnt(9)
	ds_write2st64_b32 v0, v24, v25 offset1:16
	ds_write2st64_b32 v0, v26, v27 offset0:32 offset1:48
	v_and_b32_e32 v0, -4, v78
	v_writelane_b32 v237, s0, 44
	v_add_u32_e32 v0, v67, v0
	s_waitcnt vmcnt(8)
	ds_write2st64_b32 v0, v28, v29 offset1:16
	ds_write2st64_b32 v0, v30, v31 offset0:32 offset1:48
	v_writelane_b32 v237, s1, 45
	v_and_b32_e32 v0, -4, v80
	v_readlane_b32 s0, v237, 31
	v_add_u32_e32 v0, v67, v0
	s_cmpk_lt_i32 s0, 0x200
	s_waitcnt vmcnt(7)
	ds_write2st64_b32 v0, v32, v33 offset1:16
	ds_write2st64_b32 v0, v34, v35 offset0:32 offset1:48
	v_and_b32_e32 v0, -4, v82
	s_cselect_b64 s[2:3], -1, 0
	v_add_u32_e32 v0, v67, v0
	v_readlane_b32 s1, v237, 32
	v_writelane_b32 v237, s2, 46
	s_waitcnt vmcnt(6)
	ds_write2st64_b32 v0, v36, v37 offset1:16
	ds_write2st64_b32 v0, v38, v39 offset0:32 offset1:48
	v_and_b32_e32 v0, -4, v84
	v_writelane_b32 v237, s3, 47
	v_add_u32_e32 v0, v67, v0
	v_writelane_b32 v237, s80, 48
	s_waitcnt vmcnt(5)
	ds_write2st64_b32 v0, v40, v41 offset1:16
	ds_write2st64_b32 v0, v42, v43 offset0:32 offset1:48
	v_and_b32_e32 v0, -4, v86
	v_writelane_b32 v237, s81, 49
	v_add_u32_e32 v0, v67, v0
	v_writelane_b32 v237, s82, 50
	s_waitcnt vmcnt(4)
	ds_write2st64_b32 v0, v44, v45 offset1:16
	ds_write2st64_b32 v0, v46, v47 offset0:32 offset1:48
	v_and_b32_e32 v0, -4, v88
	v_writelane_b32 v237, s83, 51
	v_add_u32_e32 v0, v67, v0
	v_writelane_b32 v237, s84, 52
	s_waitcnt vmcnt(3)
	ds_write2st64_b32 v0, v48, v49 offset1:16
	ds_write2st64_b32 v0, v50, v51 offset0:32 offset1:48
	v_and_b32_e32 v0, -4, v90
	v_writelane_b32 v237, s85, 53
	v_add_u32_e32 v0, v67, v0
	v_writelane_b32 v237, s86, 54
	s_waitcnt vmcnt(2)
	ds_write2st64_b32 v0, v52, v53 offset1:16
	ds_write2st64_b32 v0, v54, v55 offset0:32 offset1:48
	v_and_b32_e32 v0, -4, v92
	v_writelane_b32 v237, s87, 55
	v_add_u32_e32 v0, v67, v0
	v_writelane_b32 v237, s88, 56
	s_waitcnt vmcnt(1)
	ds_write2st64_b32 v0, v58, v59 offset1:16
	ds_write2st64_b32 v0, v60, v61 offset0:32 offset1:48
	v_and_b32_e32 v0, -4, v94
	v_writelane_b32 v237, s89, 57
	v_add_u32_e32 v0, v67, v0
	s_cmpk_gt_i32 s0, 0x1ff
	v_writelane_b32 v237, s90, 58
	s_waitcnt vmcnt(0)
	ds_write2st64_b32 v0, v62, v63 offset1:16
	ds_write2st64_b32 v0, v64, v65 offset0:32 offset1:48
	s_waitcnt lgkmcnt(0)
	s_barrier
	v_writelane_b32 v237, s91, 59
	s_cbranch_scc1 .LBB0_594
	v_and_b32_e32 v5, 63, v56
	v_mov_b32_e32 v61, 0
	v_readlane_b32 s0, v237, 40
	v_lshlrev_b32_e32 v0, 3, v5
	v_mov_b32_e32 v1, v61
	v_readlane_b32 s1, v237, 41
	v_lshl_add_u64 v[2:3], v[56:57], 2, s[88:89]
	v_ashrrev_i32_e32 v4, 2, v56
	v_lshl_add_u64 v[64:65], s[0:1], 0, v[0:1]
	s_mov_b64 s[0:1], 0x3d00000
	v_lshl_add_u64 v[70:71], v[2:3], 0, s[0:1]
	v_lshlrev_b32_e32 v2, 6, v5
	v_mov_b32_e32 v3, v61
	v_lshl_add_u64 v[72:73], s[66:67], 0, v[2:3]
	s_mov_b64 s[0:1], 0x1000
	v_lshl_add_u64 v[74:75], v[72:73], 0, s[0:1]
	s_mov_b64 s[0:1], 0x2000
	v_lshl_add_u64 v[76:77], v[72:73], 0, s[0:1]
	s_mov_b64 s[0:1], 0x3000
	v_lshl_add_u64 v[78:79], v[72:73], 0, s[0:1]
	v_readlane_b32 s4, v237, 31
	s_lshl_b32 s0, s90, 6
	v_cmp_gt_i32_e64 s[6:7], 24, v56
	v_lshlrev_b32_e32 v6, 2, v56
	v_and_b32_e32 v58, -16, v4
	v_lshlrev_b32_e32 v60, 4, v5
	v_cmp_gt_i32_e64 s[8:9], 64, v56
	v_readlane_b32 s5, v237, 32
	s_lshl_b32 s12, s4, 6
	v_writelane_b32 v237, s0, 60
	v_mov_b32_e32 v2, 0x10000
	v_lshl_add_u64 v[0:1], s[88:89], 0, v[0:1]
	s_mov_b64 s[0:1], 0x4500400
	v_add_u32_e32 v99, 0x10100, v6
	v_ashrrev_i32_e32 v59, 31, v58
	v_lshl_add_u64 v[62:63], s[36:37], 0, v[60:61]
	v_lshl_add_u64 v[66:67], s[62:63], 0, v[60:61]
	v_lshl_add_u64 v[68:69], s[64:65], 0, v[60:61]
	v_lshrrev_b32_e32 v250, 6, v56
	v_lshlrev_b32_e32 v250, 10, v250
	v_mov_b32_e32 v251, 0
	v_lshl_add_u64 v[252:253], v[66:67], 0, v[250:251]
	global_load_dwordx4 v[186:189], v[252:253], off
	v_lshl_add_u64 v[252:253], v[68:69], 0, v[250:251]
	global_load_dwordx4 v[190:193], v[252:253], off
	v_lshlrev_b32_e32 v250, 4, v56
	v_add_u32_e32 v250, 0x10400, v250
	s_waitcnt vmcnt(0)
	ds_write_b128 v250, v[186:189]
	ds_write_b128 v250, v[190:193] offset:4096
	v_add_u32_e32 v234, 0x10400, v60
	s_waitcnt lgkmcnt(0)
	s_mov_b32 s3, 0
	v_cmp_eq_u32_e64 s[10:11], 0, v5
	v_add_u32_e32 v112, 0x10000, v6
	v_add_u32_e32 v113, 0x10200, v6
	v_add_u32_e32 v57, 0x10180, v6
	v_add_u32_e32 v114, s12, v4
	v_lshl_add_u32 v115, v4, 2, v2
	v_lshl_add_u64 v[80:81], v[0:1], 0, s[0:1]
	s_mov_b32 s22, 0x3fb504f3
	v_mov_b32_e32 v116, 0x3727c5ac
	v_mov_b32_e32 v117, 1
	v_mov_b32_e32 v118, 0xff61b1e6
	v_mov_b32_e32 v119, 0x10100
	v_mov_b32_e32 v120, 0x10180
	s_mov_b32 s2, s4
	v_writelane_b32 v237, s6, 62
	v_writelane_b32 v236, s8, 0
	s_nop 0
	v_writelane_b32 v237, s7, 63
	v_writelane_b32 v236, s9, 1
	s_branch .LBB0_548
	.p2alignl 6, 3212836864

.LBB0_548:
	s_barrier
	s_and_saveexec_b64 s[0:1], s[6:7]
	ds_write_b32 v99, v61
	s_or_b64 exec, exec, s[0:1]
	s_lshl_b32 s4, s2, 6
	s_ashr_i32 s5, s4, 31
	v_lshl_add_u64 v[82:83], s[4:5], 0, v[58:59]
	v_lshlrev_b64 v[0:1], 12, v[82:83]
	v_lshl_add_u64 v[0:1], v[62:63], 0, v[0:1]
	v_lshlrev_b64 v[2:3], 11, v[82:83]
	v_lshl_add_u64 v[2:3], v[64:65], 0, v[2:3]
	global_load_dwordx4 v[28:31], v[0:1], off
	global_load_dwordx4 v[20:23], v[0:1], off offset:1024
	global_load_dwordx4 v[24:27], v[0:1], off offset:2048
	global_load_dwordx4 v[16:19], v[0:1], off offset:3072
	global_load_dwordx2 v[84:85], v[2:3], off
	global_load_dwordx2 v[88:89], v[2:3], off offset:512
	global_load_dwordx2 v[90:91], v[2:3], off offset:1024
	global_load_dwordx2 v[92:93], v[2:3], off offset:1536
	global_load_dwordx4 v[182:185], v[72:73], off
	global_load_dwordx4 v[186:189], v[72:73], off offset:16
	global_load_dwordx4 v[190:193], v[72:73], off offset:32
	global_load_dwordx4 v[194:197], v[72:73], off offset:48
	global_load_dwordx4 v[198:201], v[74:75], off
	global_load_dwordx4 v[202:205], v[74:75], off offset:16
	global_load_dwordx4 v[206:209], v[74:75], off offset:32
	global_load_dwordx4 v[210:213], v[74:75], off offset:48
	global_load_dwordx4 v[214:217], v[76:77], off
	global_load_dwordx4 v[218:221], v[76:77], off offset:16
	global_load_dwordx4 v[222:225], v[76:77], off offset:32
	global_load_dwordx4 v[226:229], v[76:77], off offset:48
	global_load_dwordx4 v[230:233], v[78:79], off
	global_load_dwordx4 v[238:241], v[78:79], off offset:16
	global_load_dwordx4 v[242:245], v[78:79], off offset:32
	global_load_dwordx4 v[246:249], v[78:79], off offset:48
	global_load_dword v162, v61, s[72:73] offset:0
	global_load_dword v163, v61, s[72:73] offset:4
	global_load_dword v164, v61, s[72:73] offset:8
	global_load_dword v165, v61, s[72:73] offset:12
	global_load_dword v166, v61, s[72:73] offset:16
	global_load_dword v167, v61, s[72:73] offset:20
	global_load_dword v168, v61, s[72:73] offset:24
	global_load_dword v169, v61, s[72:73] offset:28
	global_load_dword v170, v61, s[72:73] offset:32
	global_load_dword v171, v61, s[72:73] offset:36
	global_load_dword v172, v61, s[72:73] offset:40
	global_load_dword v173, v61, s[72:73] offset:44
	global_load_dword v174, v61, s[72:73] offset:48
	global_load_dword v175, v61, s[72:73] offset:52
	global_load_dword v176, v61, s[72:73] offset:56
	global_load_dword v177, v61, s[72:73] offset:60
	global_load_dwordx4 v[178:181], v61, s[68:69] offset:0
	v_writelane_b32 v236, s2, 2
	s_mov_b32 s0, s4
	s_ashr_i32 s13, s12, 31
	v_writelane_b32 v236, s0, 4
	v_lshl_add_u64 v[0:1], v[58:59], 0, s[12:13]
	v_lshlrev_b64 v[0:1], 11, v[0:1]
	v_writelane_b32 v236, s1, 5
	s_mov_b32 s0, s12
	v_writelane_b32 v236, s0, 6
	v_lshl_add_u64 v[86:87], v[80:81], 0, v[0:1]
	s_mov_b32 s7, 0
	v_mov_b32_e32 v121, v115
	v_writelane_b32 v236, s1, 7
	s_branch .LBB0_552
	.p2alignl 6, 3212836864

.LBB0_552:
	s_add_i32 s23, s7, 1
	s_waitcnt vmcnt(0)
	v_mov_b64_e32 v[38:39], v[84:85]
	v_mov_b64_e32 v[32:33], v[92:93]
	v_mov_b64_e32 v[34:35], v[90:91]
	v_mov_b64_e32 v[36:37], v[88:89]
	v_mov_b32_e32 v0, s23
	v_min_u32_e32 v0, 15, v0
	v_mov_b32_e32 v1, 0
	v_lshl_add_u64 v[0:1], v[82:83], 0, v[0:1]
	v_lshlrev_b64 v[2:3], 12, v[0:1]
	v_lshlrev_b64 v[0:1], 11, v[0:1]
	v_lshl_add_u64 v[12:13], v[62:63], 0, v[2:3]
	v_lshl_add_u64 v[92:93], v[64:65], 0, v[0:1]
	global_load_dwordx4 v[0:3], v[12:13], off nt
	global_load_dwordx2 v[84:85], v[92:93], off nt
	global_load_dwordx4 v[4:7], v[12:13], off offset:1024 nt
	global_load_dwordx2 v[88:89], v[92:93], off offset:512 nt
	global_load_dwordx4 v[8:11], v[12:13], off offset:2048 nt
	global_load_dwordx2 v[90:91], v[92:93], off offset:1024 nt
	s_nop 0
	global_load_dwordx4 v[12:15], v[12:13], off offset:3072 nt
	s_nop 0
	global_load_dwordx2 v[92:93], v[92:93], off offset:1536 nt
	v_lshlrev_b32_e32 v40, 16, v38
	v_and_b32_e32 v41, 0xffff0000, v38
	v_lshlrev_b32_e32 v38, 16, v39
	v_and_b32_e32 v39, 0xffff0000, v39
	v_lshlrev_b32_e32 v54, 16, v36
	v_and_b32_e32 v55, 0xffff0000, v36
	v_lshlrev_b32_e32 v94, 16, v37
	v_and_b32_e32 v95, 0xffff0000, v37
	v_lshlrev_b32_e32 v96, 16, v34
	v_and_b32_e32 v97, 0xffff0000, v34
	v_lshlrev_b32_e32 v100, 16, v35
	v_and_b32_e32 v101, 0xffff0000, v35
	v_lshlrev_b32_e32 v102, 16, v32
	v_and_b32_e32 v103, 0xffff0000, v32
	v_lshlrev_b32_e32 v104, 16, v33
	v_and_b32_e32 v105, 0xffff0000, v33
	v_pk_fma_f32 v[106:107], v[30:31], s[22:23], v[38:39] op_sel_hi:[1,0,1]
	ds_read_b128 v[30:33], v234
	ds_read_b128 v[34:37], v234 offset:4096
	v_pk_fma_f32 v[28:29], v[28:29], s[22:23], v[40:41] op_sel_hi:[1,0,1]
	v_pk_fma_f32 v[20:21], v[20:21], s[22:23], v[54:55] op_sel_hi:[1,0,1]
	v_add_f32_e32 v38, v28, v29
	v_add_f32_e32 v38, v38, v106
	v_pk_fma_f32 v[22:23], v[22:23], s[22:23], v[94:95] op_sel_hi:[1,0,1]
	v_add_f32_e32 v54, v20, v21
	v_pk_fma_f32 v[24:25], v[24:25], s[22:23], v[96:97] op_sel_hi:[1,0,1]
	v_add_f32_e32 v38, v107, v38
	v_add_f32_e32 v54, v54, v22
	v_pk_fma_f32 v[26:27], v[26:27], s[22:23], v[100:101] op_sel_hi:[1,0,1]
	v_add_f32_e32 v55, v24, v25
	v_add_f32_e32 v98, 0, v38
	v_add_f32_e32 v54, v23, v54
	v_add_f32_e32 v55, v55, v26
	v_add_f32_e32 v54, v98, v54
	v_add_f32_e32 v55, v27, v55
	v_pk_fma_f32 v[16:17], v[16:17], s[22:23], v[102:103] op_sel_hi:[1,0,1]
	v_add_f32_e32 v54, v54, v55
	v_pk_fma_f32 v[18:19], v[18:19], s[22:23], v[104:105] op_sel_hi:[1,0,1]
	v_add_f32_e32 v55, v16, v17
	v_add_f32_e32 v55, v55, v18
	v_add_f32_e32 v55, v19, v55
	v_add_f32_e32 v54, v54, v55
	ds_read_b128 v[38:41], v60
	ds_read_b128 v[42:45], v60 offset:4096
	ds_read_b128 v[46:49], v60 offset:8192
	ds_read_b128 v[50:53], v60 offset:12288
	ds_read_b128 v[108:111], v60 offset:16384
	ds_read_b128 v[122:125], v60 offset:20480
	ds_read_b128 v[130:133], v60 offset:24576
	ds_read_b128 v[134:137], v60 offset:28672
	ds_read_b128 v[138:141], v60 offset:32768
	ds_read_b128 v[142:145], v60 offset:36864
	ds_read_b128 v[146:149], v60 offset:40960
	ds_read_b128 v[150:153], v60 offset:45056
	ds_read_b128 v[154:157], v60 offset:49152
	v_add_f32_dpp v54, v54, v54 quad_perm:[1,0,3,2] row_mask:0xf bank_mask:0xf bound_ctrl:1
	s_nop 1
	v_add_f32_dpp v54, v54, v54 quad_perm:[2,3,0,1] row_mask:0xf bank_mask:0xf bound_ctrl:1
	s_nop 1
	v_add_f32_dpp v54, v54, v54 row_half_mirror row_mask:0xf bank_mask:0xf bound_ctrl:1
	s_nop 1
	v_add_f32_dpp v54, v54, v54 row_mirror row_mask:0xf bank_mask:0xf bound_ctrl:1
	s_nop 0
	v_readlane_b32 s2, v54, 16
	v_readlane_b32 s4, v54, 48
	v_readlane_b32 s0, v54, 0
	v_readlane_b32 s1, v54, 32
	v_mov_b32_e32 v54, s2
	v_mov_b32_e32 v55, s4
	v_pk_add_f32 v[54:55], s[0:1], v[54:55]
	s_nop 0
	v_add_f32_e32 v54, v54, v55
	v_mul_f32_e32 v54, 0x3a800000, v54
	v_pk_add_f32 v[28:29], v[28:29], v[54:55] op_sel_hi:[1,0] neg_lo:[0,1] neg_hi:[0,1]
	v_pk_add_f32 v[126:127], v[106:107], v[54:55] op_sel_hi:[1,0] neg_lo:[0,1] neg_hi:[0,1]
	v_pk_mul_f32 v[104:105], v[28:29], v[28:29]
	v_pk_mul_f32 v[106:107], v[126:127], v[126:127]
	v_pk_add_f32 v[158:159], v[20:21], v[54:55] op_sel_hi:[1,0] neg_lo:[0,1] neg_hi:[0,1]
	v_pk_add_f32 v[160:161], v[22:23], v[54:55] op_sel_hi:[1,0] neg_lo:[0,1] neg_hi:[0,1]
	v_pk_add_f32 v[100:101], v[24:25], v[54:55] op_sel_hi:[1,0] neg_lo:[0,1] neg_hi:[0,1]
	v_pk_add_f32 v[102:103], v[26:27], v[54:55] op_sel_hi:[1,0] neg_lo:[0,1] neg_hi:[0,1]
	v_pk_add_f32 v[94:95], v[16:17], v[54:55] op_sel_hi:[1,0] neg_lo:[0,1] neg_hi:[0,1]
	v_pk_add_f32 v[96:97], v[18:19], v[54:55] op_sel_hi:[1,0] neg_lo:[0,1] neg_hi:[0,1]
	v_add_f32_e32 v54, v104, v105
	v_add_f32_e32 v54, v106, v54
	v_pk_mul_f32 v[20:21], v[158:159], v[158:159]
	v_add_f32_e32 v54, v107, v54
	v_add_f32_e32 v20, v20, v54
	v_pk_mul_f32 v[22:23], v[160:161], v[160:161]
	v_add_f32_e32 v20, v21, v20
	v_add_f32_e32 v20, v22, v20
	v_pk_mul_f32 v[24:25], v[100:101], v[100:101]
	v_add_f32_e32 v20, v23, v20
	v_add_f32_e32 v20, v24, v20
	v_pk_mul_f32 v[26:27], v[102:103], v[102:103]
	v_add_f32_e32 v20, v25, v20
	v_add_f32_e32 v20, v26, v20
	v_pk_mul_f32 v[16:17], v[94:95], v[94:95]
	v_add_f32_e32 v20, v27, v20
	v_add_f32_e32 v16, v16, v20
	v_pk_mul_f32 v[18:19], v[96:97], v[96:97]
	v_add_f32_e32 v16, v17, v16
	v_add_f32_e32 v16, v18, v16
	v_add_f32_e32 v16, v19, v16
	s_nop 1
	v_add_f32_dpp v16, v16, v16 quad_perm:[1,0,3,2] row_mask:0xf bank_mask:0xf bound_ctrl:1
	s_nop 1
	v_add_f32_dpp v16, v16, v16 quad_perm:[2,3,0,1] row_mask:0xf bank_mask:0xf bound_ctrl:1
	s_nop 1
	v_add_f32_dpp v16, v16, v16 row_half_mirror row_mask:0xf bank_mask:0xf bound_ctrl:1
	s_nop 1
	v_add_f32_dpp v16, v16, v16 row_mirror row_mask:0xf bank_mask:0xf bound_ctrl:1
	s_nop 0
	v_readlane_b32 s2, v16, 16
	v_readlane_b32 s4, v16, 48
	v_readlane_b32 s0, v16, 0
	v_readlane_b32 s1, v16, 32
	v_mov_b32_e32 v16, s2
	v_mov_b32_e32 v17, s4
	v_pk_add_f32 v[16:17], s[0:1], v[16:17]
	s_mov_b32 s0, 0x800000
	v_add_f32_e32 v16, v16, v17
	v_fmamk_f32 v16, v16, 0x3a800000, v116
	v_cmp_gt_f32_e32 vcc, s0, v16
	v_mul_f32_e32 v17, 0x4b800000, v16
	s_nop 0
	v_cndmask_b32_e32 v16, v16, v17, vcc
	v_rsq_f32_e32 v54, v16
	ds_read_b128 v[16:19], v60 offset:53248
	s_waitcnt lgkmcnt(15)
	ds_read_b128 v[20:23], v60 offset:57344
	s_waitcnt lgkmcnt(15)
	ds_read_b128 v[24:27], v60 offset:61440
	s_waitcnt lgkmcnt(15)
	v_mul_f32_e32 v55, 0x45800000, v54
	v_cndmask_b32_e32 v98, v54, v55, vcc
	v_pk_mul_f32 v[28:29], v[28:29], v[98:99] op_sel_hi:[1,0]
	v_pk_fma_f32 v[106:107], v[30:31], v[28:29], v[34:35]
	v_pk_mul_f32 v[28:29], v[126:127], v[98:99] op_sel_hi:[1,0]
	s_waitcnt lgkmcnt(2)
	v_mul_f32_e32 v17, v107, v17
	v_pk_fma_f32 v[104:105], v[32:33], v[28:29], v[36:37]
	v_cvt_pk_bf16_f32 v28, v106, v107
	v_cvt_pk_bf16_f32 v29, v104, v105
	global_store_dwordx2 v[86:87], v[28:29], off offset:-1024
	v_mul_f32_e32 v54, v39, v107
	v_fmac_f32_e32 v54, v38, v106
	ds_read_b128 v[32:35], v234 offset:1024
	ds_read_b128 v[36:39], v234 offset:5120
	v_fmac_f32_e32 v54, v104, v40
	v_fmac_f32_e32 v54, v105, v41
	v_mul_f32_e32 v55, v107, v43
	v_fmac_f32_e32 v55, v106, v42
	v_fmac_f32_e32 v55, v104, v44
	v_fmac_f32_e32 v55, v105, v45
	v_mul_f32_e32 v28, v107, v47
	v_fmac_f32_e32 v28, v106, v46
	v_fmac_f32_e32 v28, v104, v48
	v_fmac_f32_e32 v28, v105, v49
	v_add_f32_e32 v46, 0, v28
	v_mul_f32_e32 v45, v107, v51
	v_fmac_f32_e32 v45, v106, v50
	v_fmac_f32_e32 v45, v104, v52
	v_fmac_f32_e32 v45, v105, v53
	v_mul_f32_e32 v44, v107, v109
	v_fmac_f32_e32 v44, v106, v108
	v_fmac_f32_e32 v44, v104, v110
	v_fmac_f32_e32 v44, v105, v111
	v_mul_f32_e32 v53, v107, v123
	v_fmac_f32_e32 v53, v106, v122
	v_fmac_f32_e32 v53, v104, v124
	v_fmac_f32_e32 v53, v105, v125
	v_mul_f32_e32 v52, v107, v131
	v_fmac_f32_e32 v52, v106, v130
	v_fmac_f32_e32 v52, v104, v132
	v_fmac_f32_e32 v52, v105, v133
	v_mul_f32_e32 v51, v107, v135
	v_fmac_f32_e32 v51, v106, v134
	v_fmac_f32_e32 v51, v104, v136
	v_fmac_f32_e32 v51, v105, v137
	v_mul_f32_e32 v50, v107, v139
	v_fmac_f32_e32 v50, v106, v138
	v_fmac_f32_e32 v50, v104, v140
	v_fmac_f32_e32 v50, v105, v141
	v_mul_f32_e32 v49, v107, v143
	v_fmac_f32_e32 v49, v106, v142
	v_fmac_f32_e32 v49, v104, v144
	v_fmac_f32_e32 v49, v105, v145
	v_mul_f32_e32 v48, v107, v147
	v_fmac_f32_e32 v48, v106, v146
	v_fmac_f32_e32 v48, v104, v148
	v_fmac_f32_e32 v48, v105, v149
	v_mul_f32_e32 v131, v107, v151
	v_fmac_f32_e32 v17, v106, v16
	s_waitcnt lgkmcnt(3)
	v_mul_f32_e32 v122, v107, v21
	v_fmac_f32_e32 v131, v106, v150
	v_fmac_f32_e32 v122, v106, v20
	v_fmac_f32_e32 v131, v104, v152
	v_fmac_f32_e32 v122, v104, v22
	v_fmac_f32_e32 v131, v105, v153
	v_fmac_f32_e32 v122, v105, v23
	v_mul_f32_e32 v125, v107, v155
	s_waitcnt lgkmcnt(2)
	v_mul_f32_e32 v123, v107, v25
	v_fmac_f32_e32 v125, v106, v154
	v_fmac_f32_e32 v123, v106, v24
	v_fmac_f32_e32 v125, v104, v156
	v_fmac_f32_e32 v17, v104, v18
	v_fmac_f32_e32 v123, v104, v26
	v_fmac_f32_e32 v125, v105, v157
	v_fmac_f32_e32 v17, v105, v19
	v_fmac_f32_e32 v123, v105, v27
	v_pk_mul_f32 v[40:41], v[158:159], v[98:99] op_sel_hi:[1,0]
	v_add_f32_e32 v124, 0, v17
	s_waitcnt lgkmcnt(0)
	v_pk_fma_f32 v[108:109], v[40:41], v[32:33], v[36:37]
	ds_read_b128 v[40:43], v60 offset:1024
	ds_read_b128 v[134:137], v60 offset:21504
	v_pk_mul_f32 v[32:33], v[160:161], v[98:99] op_sel_hi:[1,0]
	ds_read_b128 v[142:145], v60 offset:29696
	v_pk_fma_f32 v[110:111], v[32:33], v[34:35], v[38:39]
	s_waitcnt lgkmcnt(2)
	v_fma_f32 v126, v109, v41, v54
	v_cvt_pk_bf16_f32 v32, v108, v109
	v_cvt_pk_bf16_f32 v33, v110, v111
	v_fmac_f32_e32 v126, v108, v40
	global_store_dwordx2 v[86:87], v[32:33], off offset:-512
	ds_read_b128 v[32:35], v60 offset:5120
	v_fmac_f32_e32 v126, v110, v42
	v_fmac_f32_e32 v126, v111, v43
	s_waitcnt lgkmcnt(2)
	v_fma_f32 v133, v109, v135, v53
	s_waitcnt lgkmcnt(1)
	v_fma_f32 v135, v109, v143, v51
	v_fmac_f32_e32 v135, v108, v142
	v_fmac_f32_e32 v135, v110, v144
	v_fmac_f32_e32 v135, v111, v145
	ds_read_b128 v[144:147], v60 offset:50176
	s_waitcnt lgkmcnt(1)
	v_fma_f32 v127, v109, v33, v55
	v_fmac_f32_e32 v127, v108, v32
	v_fmac_f32_e32 v127, v110, v34
	v_fmac_f32_e32 v127, v111, v35
	ds_read_b128 v[36:39], v60 offset:9216
	ds_read_b128 v[32:35], v60 offset:13312
	ds_read_b128 v[40:43], v60 offset:17408
	ds_read_b128 v[138:141], v60 offset:25600
	v_fmac_f32_e32 v133, v108, v134
	v_fmac_f32_e32 v133, v110, v136
	s_waitcnt lgkmcnt(3)
	v_fma_f32 v129, v109, v37, v46
	s_waitcnt lgkmcnt(2)
	v_fma_f32 v130, v109, v33, v45
	v_fmac_f32_e32 v133, v111, v137
	v_fmac_f32_e32 v129, v108, v36
	v_fmac_f32_e32 v130, v108, v32
	s_waitcnt lgkmcnt(0)
	v_fma_f32 v134, v109, v139, v52
	v_fmac_f32_e32 v129, v110, v38
	v_fmac_f32_e32 v130, v110, v34
	v_fma_f32 v132, v109, v41, v44
	v_fmac_f32_e32 v134, v108, v138
	v_fmac_f32_e32 v129, v111, v39
	v_fmac_f32_e32 v130, v111, v35
	v_fmac_f32_e32 v132, v108, v40
	v_fmac_f32_e32 v134, v110, v140
	v_fmac_f32_e32 v132, v110, v42
	v_fmac_f32_e32 v134, v111, v141
	v_fmac_f32_e32 v132, v111, v43
	ds_read_b128 v[52:55], v60 offset:33792
	ds_read_b128 v[138:141], v60 offset:37888
	s_waitcnt lgkmcnt(1)
	v_fma_f32 v136, v109, v53, v50
	v_fmac_f32_e32 v136, v108, v52
	v_fmac_f32_e32 v136, v110, v54
	v_fmac_f32_e32 v136, v111, v55
	ds_read_b128 v[50:53], v60 offset:41984
	s_waitcnt lgkmcnt(1)
	v_fma_f32 v137, v109, v139, v49
	v_fmac_f32_e32 v137, v108, v138
	v_fmac_f32_e32 v137, v110, v140
	v_fmac_f32_e32 v137, v111, v141
	ds_read_b128 v[140:143], v60 offset:46080
	s_waitcnt lgkmcnt(1)
	v_fma_f32 v138, v109, v51, v48
	v_fmac_f32_e32 v138, v108, v50
	v_fmac_f32_e32 v138, v110, v52
	v_fmac_f32_e32 v138, v111, v53
	ds_read_b128 v[48:51], v234 offset:2048
	ds_read_b128 v[52:55], v234 offset:6144
	s_waitcnt lgkmcnt(2)
	v_fma_f32 v131, v109, v141, v131
	v_fmac_f32_e32 v131, v108, v140
	v_fmac_f32_e32 v131, v110, v142
	v_fmac_f32_e32 v131, v111, v143
	ds_read_b128 v[140:143], v60 offset:54272
	v_fma_f32 v139, v109, v145, v125
	v_fmac_f32_e32 v139, v108, v144
	v_fmac_f32_e32 v139, v110, v146
	v_fmac_f32_e32 v139, v111, v147
	ds_read_b128 v[144:147], v60 offset:58368
	s_waitcnt lgkmcnt(1)
	v_fma_f32 v148, v109, v141, v124
	v_fmac_f32_e32 v148, v108, v140
	v_fmac_f32_e32 v148, v110, v142
	v_fmac_f32_e32 v148, v111, v143
	ds_read_b128 v[140:143], v60 offset:62464
	s_waitcnt lgkmcnt(1)
	v_mul_f32_e32 v124, v109, v145
	v_fmac_f32_e32 v124, v108, v144
	v_fmac_f32_e32 v124, v110, v146
	v_fmac_f32_e32 v124, v111, v147
	v_add_f32_e32 v144, v122, v124
	s_waitcnt lgkmcnt(0)
	v_mul_f32_e32 v122, v109, v141
	v_fmac_f32_e32 v122, v108, v140
	v_fmac_f32_e32 v122, v110, v142
	v_fmac_f32_e32 v122, v111, v143
	v_add_f32_e32 v142, v123, v122
	v_mov_b32_e32 v122, v106
	v_mov_b32_e32 v123, v108
	v_mov_b32_e32 v108, v107
	v_mov_b32_e32 v106, v186
	v_mov_b32_e32 v124, v182
	v_mov_b32_e32 v140, v190
	v_mov_b32_e32 v125, v198
	v_mov_b32_e32 v107, v202
	v_pk_mul_f32 v[106:107], v[108:109], v[106:107]
	v_mov_b32_e32 v36, v187
	v_pk_fma_f32 v[106:107], v[122:123], v[124:125], v[106:107]
	v_mov_b32_e32 v124, v104
	v_mov_b32_e32 v125, v110
	v_mov_b32_e32 v110, v105
	v_mov_b32_e32 v104, v194
	v_mov_b32_e32 v141, v206
	v_pk_fma_f32 v[106:107], v[124:125], v[140:141], v[106:107]
	v_mov_b32_e32 v105, v210
	v_mov_b32_e32 v32, v183
	v_mov_b32_e32 v37, v203
	v_pk_mul_f32 v[24:25], v[108:109], v[36:37]
	v_pk_fma_f32 v[104:105], v[110:111], v[104:105], v[106:107]
	v_mov_b32_e32 v33, v199
	v_pk_fma_f32 v[24:25], v[122:123], v[32:33], v[24:25]
	v_mov_b32_e32 v40, v191
	v_add_f32_e32 v16, 0, v104
	v_mov_b32_e32 v41, v207
	v_pk_fma_f32 v[20:21], v[124:125], v[40:41], v[24:25]
	v_mov_b32_e32 v44, v195
	v_add_f32_e32 v107, v16, v105
	v_mov_b32_e32 v45, v211
	v_pk_fma_f32 v[16:17], v[110:111], v[44:45], v[20:21]
	v_mov_b32_e32 v20, v188
	v_add_f32_e32 v16, 0, v16
	v_mov_b32_e32 v21, v204
	v_add_f32_e32 v105, v16, v17
	v_mov_b32_e32 v16, v184
	v_mov_b32_e32 v17, v200
	v_pk_mul_f32 v[20:21], v[108:109], v[20:21]
	v_mov_b32_e32 v38, v189
	v_pk_fma_f32 v[16:17], v[122:123], v[16:17], v[20:21]
	v_mov_b32_e32 v20, v192
	v_mov_b32_e32 v21, v208
	v_pk_fma_f32 v[16:17], v[124:125], v[20:21], v[16:17]
	v_mov_b32_e32 v20, v196
	v_mov_b32_e32 v21, v212
	v_pk_fma_f32 v[16:17], v[110:111], v[20:21], v[16:17]
	v_mov_b32_e32 v34, v185
	v_add_f32_e32 v16, 0, v16
	v_add_f32_e32 v106, v16, v17
	v_mov_b32_e32 v39, v205
	v_pk_mul_f32 v[16:17], v[108:109], v[38:39]
	v_mov_b32_e32 v42, v193
	v_mov_b32_e32 v35, v201
	v_pk_fma_f32 v[16:17], v[122:123], v[34:35], v[16:17]
	v_mov_b32_e32 v46, v197
	v_mov_b32_e32 v43, v209
	v_pk_fma_f32 v[16:17], v[124:125], v[42:43], v[16:17]
	v_pk_mul_f32 v[20:21], v[102:103], v[98:99] op_sel_hi:[1,0]
	v_mov_b32_e32 v47, v213
	v_pk_fma_f32 v[16:17], v[110:111], v[46:47], v[16:17]
	v_pk_fma_f32 v[50:51], v[20:21], v[50:51], v[54:55]
	v_add_f32_e32 v16, 0, v16
	v_add_f32_e32 v104, v16, v17
	v_pk_mul_f32 v[16:17], v[100:101], v[98:99] op_sel_hi:[1,0]
	v_cvt_pk_bf16_f32 v21, v50, v51
	v_pk_fma_f32 v[48:49], v[16:17], v[48:49], v[52:53]
	ds_read_b128 v[16:19], v60 offset:2048
	v_cvt_pk_bf16_f32 v20, v48, v49
	global_store_dwordx2 v[86:87], v[20:21], off
	ds_read_b128 v[20:23], v60 offset:6144
	v_pk_mul_f32 v[46:47], v[94:95], v[98:99] op_sel_hi:[1,0]
	s_waitcnt lgkmcnt(1)
	v_fma_f32 v42, v49, v17, v126
	v_fmac_f32_e32 v42, v48, v16
	v_fmac_f32_e32 v42, v50, v18
	v_fmac_f32_e32 v42, v51, v19
	ds_read_b128 v[16:19], v60 offset:10240
	s_waitcnt lgkmcnt(1)
	v_fma_f32 v41, v49, v21, v127
	v_fmac_f32_e32 v41, v48, v20
	v_fmac_f32_e32 v41, v50, v22
	v_fmac_f32_e32 v41, v51, v23
	ds_read_b128 v[20:23], v60 offset:14336
	s_waitcnt lgkmcnt(1)
	v_fma_f32 v40, v49, v17, v129
	v_fmac_f32_e32 v40, v48, v16
	v_fmac_f32_e32 v40, v50, v18
	v_fmac_f32_e32 v40, v51, v19
	ds_read_b128 v[16:19], v60 offset:18432
	ds_read_b128 v[32:35], v234 offset:3072
	ds_read_b128 v[36:39], v234 offset:7168
	s_waitcnt lgkmcnt(3)
	v_fma_f32 v45, v49, v21, v130
	v_fmac_f32_e32 v45, v48, v20
	v_fmac_f32_e32 v45, v50, v22
	v_fmac_f32_e32 v45, v51, v23
	ds_read_b128 v[20:23], v60 offset:22528
	s_waitcnt lgkmcnt(3)
	v_fma_f32 v44, v49, v17, v132
	v_fmac_f32_e32 v44, v48, v16
	v_fmac_f32_e32 v44, v50, v18
	v_fmac_f32_e32 v44, v51, v19
	ds_read_b128 v[16:19], v60 offset:26624
	s_waitcnt lgkmcnt(1)
	v_fma_f32 v124, v49, v21, v133
	v_fmac_f32_e32 v124, v48, v20
	v_fmac_f32_e32 v124, v50, v22
	v_fmac_f32_e32 v124, v51, v23
	ds_read_b128 v[20:23], v60 offset:30720
	s_waitcnt lgkmcnt(1)
	v_fma_f32 v123, v49, v17, v134
	v_fmac_f32_e32 v123, v48, v16
	v_fmac_f32_e32 v123, v50, v18
	v_fmac_f32_e32 v123, v51, v19
	s_waitcnt lgkmcnt(0)
	v_fma_f32 v122, v49, v21, v135
	v_fmac_f32_e32 v122, v48, v20
	v_fmac_f32_e32 v122, v50, v22
	ds_read_b128 v[16:19], v60 offset:34816
	v_fmac_f32_e32 v122, v51, v23
	ds_read_b128 v[20:23], v60 offset:38912
	s_waitcnt lgkmcnt(1)
	v_fma_f32 v111, v49, v17, v136
	v_fmac_f32_e32 v111, v48, v16
	v_fmac_f32_e32 v111, v50, v18
	s_waitcnt lgkmcnt(0)
	v_fma_f32 v110, v49, v21, v137
	v_fmac_f32_e32 v110, v48, v20
	v_fmac_f32_e32 v111, v51, v19
	v_fmac_f32_e32 v110, v50, v22
	ds_read_b128 v[16:19], v60 offset:43008
	v_fmac_f32_e32 v110, v51, v23
	ds_read_b128 v[20:23], v60 offset:47104
	s_waitcnt lgkmcnt(1)
	v_fma_f32 v109, v49, v17, v138
	v_fmac_f32_e32 v109, v48, v16
	v_fmac_f32_e32 v109, v50, v18
	s_waitcnt lgkmcnt(0)
	v_fma_f32 v108, v49, v21, v131
	v_fmac_f32_e32 v108, v48, v20
	v_fmac_f32_e32 v109, v51, v19
	v_fmac_f32_e32 v108, v50, v22
	ds_read_b128 v[16:19], v60 offset:51200
	v_fmac_f32_e32 v108, v51, v23
	ds_read_b128 v[20:23], v60 offset:55296
	s_waitcnt lgkmcnt(1)
	v_fma_f32 v103, v49, v17, v139
	v_fmac_f32_e32 v103, v48, v16
	v_fmac_f32_e32 v103, v50, v18
	s_waitcnt lgkmcnt(0)
	v_fma_f32 v102, v49, v21, v148
	v_fmac_f32_e32 v102, v48, v20
	v_fmac_f32_e32 v103, v51, v19
	v_fmac_f32_e32 v102, v50, v22
	ds_read_b128 v[16:19], v60 offset:59392
	v_fmac_f32_e32 v102, v51, v23
	ds_read_b128 v[20:23], v60 offset:63488
	s_waitcnt lgkmcnt(1)
	v_fma_f32 v100, v49, v17, v144
	v_fmac_f32_e32 v100, v48, v16
	v_fmac_f32_e32 v100, v50, v18
	s_waitcnt lgkmcnt(0)
	v_fma_f32 v101, v49, v21, v142
	v_fmac_f32_e32 v101, v48, v20
	v_fmac_f32_e32 v101, v50, v22
	v_fmac_f32_e32 v100, v51, v19
	v_fmac_f32_e32 v101, v51, v23
	v_pk_fma_f32 v[52:53], v[46:47], v[32:33], v[36:37]
	v_pk_mul_f32 v[32:33], v[96:97], v[98:99] op_sel_hi:[1,0]
	ds_read_b128 v[94:97], v60 offset:3072
	v_pk_fma_f32 v[54:55], v[32:33], v[34:35], v[38:39]
	v_cvt_pk_bf16_f32 v32, v52, v53
	v_cvt_pk_bf16_f32 v33, v54, v55
	global_store_dwordx2 v[86:87], v[32:33], off offset:512
	ds_read_b128 v[32:35], v60 offset:7168
	s_waitcnt lgkmcnt(1)
	v_mul_f32_e32 v36, v53, v95
	v_fmac_f32_e32 v36, v52, v94
	v_fmac_f32_e32 v36, v54, v96
	v_fmac_f32_e32 v36, v55, v97
	v_add_f32_e32 v94, v42, v36
	ds_read_b128 v[36:39], v60 offset:11264
	ds_read_b128 v[130:133], v60 offset:15360
	s_waitcnt lgkmcnt(2)
	v_fma_f32 v95, v53, v33, v41
	v_fmac_f32_e32 v95, v52, v32
	v_fmac_f32_e32 v95, v54, v34
	s_waitcnt lgkmcnt(1)
	v_fma_f32 v96, v53, v37, v40
	v_fmac_f32_e32 v96, v52, v36
	v_fmac_f32_e32 v96, v54, v38
	v_fmac_f32_e32 v95, v55, v35
	v_fmac_f32_e32 v96, v55, v39
	ds_read_b128 v[40:43], v60 offset:19456
	s_waitcnt lgkmcnt(1)
	v_fma_f32 v97, v53, v131, v45
	v_fmac_f32_e32 v97, v52, v130
	v_fmac_f32_e32 v97, v54, v132
	v_fmac_f32_e32 v97, v55, v133
	ds_read_b128 v[130:133], v60 offset:23552
	s_waitcnt lgkmcnt(1)
	v_fma_f32 v125, v53, v41, v44
	v_fmac_f32_e32 v125, v52, v40
	v_fmac_f32_e32 v125, v54, v42
	v_fmac_f32_e32 v125, v55, v43
	ds_read_b128 v[134:137], v60 offset:27648
	s_waitcnt lgkmcnt(1)
	v_fma_f32 v124, v53, v131, v124
	v_fmac_f32_e32 v124, v52, v130
	v_fmac_f32_e32 v124, v54, v132
	v_fmac_f32_e32 v124, v55, v133
	ds_read_b128 v[130:133], v60 offset:31744
	s_waitcnt lgkmcnt(1)
	v_fma_f32 v98, v53, v135, v123
	v_fmac_f32_e32 v98, v52, v134
	v_fmac_f32_e32 v98, v54, v136
	v_fmac_f32_e32 v98, v55, v137
	ds_read_b128 v[134:137], v60 offset:35840
	s_waitcnt lgkmcnt(1)
	v_fma_f32 v122, v53, v131, v122
	v_fmac_f32_e32 v122, v52, v130
	v_fmac_f32_e32 v122, v54, v132
	v_fmac_f32_e32 v122, v55, v133
	ds_read_b128 v[130:133], v60 offset:39936
	s_waitcnt lgkmcnt(1)
	v_fma_f32 v111, v53, v135, v111
	v_fmac_f32_e32 v111, v52, v134
	v_fmac_f32_e32 v111, v54, v136
	v_fmac_f32_e32 v111, v55, v137
	ds_read_b128 v[134:137], v60 offset:44032
	s_waitcnt lgkmcnt(1)
	v_fma_f32 v110, v53, v131, v110
	v_fmac_f32_e32 v110, v52, v130
	v_fmac_f32_e32 v110, v54, v132
	v_fmac_f32_e32 v110, v55, v133
	ds_read_b128 v[130:133], v60 offset:48128
	s_waitcnt lgkmcnt(1)
	v_fma_f32 v109, v53, v135, v109
	v_fmac_f32_e32 v109, v52, v134
	v_fmac_f32_e32 v109, v54, v136
	v_fmac_f32_e32 v109, v55, v137
	ds_read_b128 v[134:137], v60 offset:52224
	s_waitcnt lgkmcnt(1)
	v_fma_f32 v108, v53, v131, v108
	v_fmac_f32_e32 v108, v52, v130
	v_fmac_f32_e32 v108, v54, v132
	v_fmac_f32_e32 v108, v55, v133
	ds_read_b128 v[130:133], v60 offset:56320
	s_waitcnt lgkmcnt(1)
	v_fma_f32 v103, v53, v135, v103
	v_fmac_f32_e32 v103, v52, v134
	v_fmac_f32_e32 v103, v54, v136
	v_fmac_f32_e32 v103, v55, v137
	ds_read_b128 v[134:137], v60 offset:60416
	s_waitcnt lgkmcnt(1)
	v_fma_f32 v102, v53, v131, v102
	v_fmac_f32_e32 v102, v52, v130
	v_fmac_f32_e32 v102, v54, v132
	v_fmac_f32_e32 v102, v55, v133
	ds_read_b128 v[130:133], v60 offset:64512
	s_waitcnt lgkmcnt(1)
	v_fma_f32 v123, v53, v135, v100
	v_fmac_f32_e32 v123, v52, v134
	v_fmac_f32_e32 v123, v54, v136
	v_fmac_f32_e32 v123, v55, v137
	s_waitcnt lgkmcnt(0)
	v_fma_f32 v129, v53, v131, v101
	v_fmac_f32_e32 v129, v52, v130
	v_fmac_f32_e32 v129, v54, v132
	v_fmac_f32_e32 v129, v55, v133
	v_mov_b32_e32 v100, v48
	v_mov_b32_e32 v101, v52
	v_mov_b32_e32 v52, v49
	v_mov_b32_e32 v48, v218
	v_mov_b32_e32 v126, v214
	v_mov_b32_e32 v130, v222
	v_mov_b32_e32 v127, v230
	v_mov_b32_e32 v49, v238
	v_pk_mul_f32 v[48:49], v[52:53], v[48:49]
	v_mov_b32_e32 v36, v219
	v_pk_fma_f32 v[48:49], v[100:101], v[126:127], v[48:49]
	v_mov_b32_e32 v126, v50
	v_mov_b32_e32 v127, v54
	v_mov_b32_e32 v131, v242
	v_pk_fma_f32 v[48:49], v[126:127], v[130:131], v[48:49]
	v_mov_b32_e32 v54, v51
	v_mov_b32_e32 v50, v226
	v_mov_b32_e32 v51, v246
	v_mov_b32_e32 v32, v215
	v_mov_b32_e32 v37, v239
	v_pk_mul_f32 v[24:25], v[52:53], v[36:37]
	v_pk_fma_f32 v[48:49], v[54:55], v[50:51], v[48:49]
	v_mov_b32_e32 v33, v231
	v_pk_fma_f32 v[24:25], v[100:101], v[32:33], v[24:25]
	v_mov_b32_e32 v40, v223
	v_add_f32_e32 v16, v107, v48
	v_mov_b32_e32 v41, v243
	v_pk_fma_f32 v[20:21], v[126:127], v[40:41], v[24:25]
	v_mov_b32_e32 v44, v227
	v_add_f32_e32 v28, v16, v49
	v_mov_b32_e32 v45, v247
	v_pk_fma_f32 v[16:17], v[54:55], v[44:45], v[20:21]
	v_mov_b32_e32 v20, v220
	v_add_f32_e32 v16, v105, v16
	v_mov_b32_e32 v21, v240
	v_add_f32_e32 v24, v16, v17
	v_mov_b32_e32 v16, v216
	v_mov_b32_e32 v17, v232
	v_pk_mul_f32 v[20:21], v[52:53], v[20:21]
	v_mov_b32_e32 v38, v221
	v_pk_fma_f32 v[16:17], v[100:101], v[16:17], v[20:21]
	v_mov_b32_e32 v20, v224
	v_mov_b32_e32 v21, v244
	v_pk_fma_f32 v[16:17], v[126:127], v[20:21], v[16:17]
	v_mov_b32_e32 v20, v228
	v_mov_b32_e32 v21, v248
	v_pk_fma_f32 v[16:17], v[54:55], v[20:21], v[16:17]
	v_mov_b32_e32 v34, v217
	v_add_f32_e32 v16, v106, v16
	v_add_f32_e32 v20, v16, v17
	v_mov_b32_e32 v39, v241
	v_pk_mul_f32 v[16:17], v[52:53], v[38:39]
	v_mov_b32_e32 v42, v225
	v_mov_b32_e32 v35, v233
	v_pk_fma_f32 v[16:17], v[100:101], v[34:35], v[16:17]
	v_mov_b32_e32 v46, v229
	v_mov_b32_e32 v43, v245
	v_pk_fma_f32 v[16:17], v[126:127], v[42:43], v[16:17]
	v_mov_b32_e32 v47, v249
	v_pk_fma_f32 v[16:17], v[54:55], v[46:47], v[16:17]
	v_add_f32_e32 v16, v104, v16
	v_add_f32_e32 v22, v16, v17
	v_add_f32_dpp v250, v24, v24 row_mirror row_mask:0xf bank_mask:0xf bound_ctrl:1
	v_add_f32_dpp v94, v94, v94 row_mirror row_mask:0xf bank_mask:0xf bound_ctrl:1
	v_add_f32_dpp v125, v125, v125 row_mirror row_mask:0xf bank_mask:0xf bound_ctrl:1
	v_add_f32_dpp v111, v111, v111 row_mirror row_mask:0xf bank_mask:0xf bound_ctrl:1
	v_add_f32_dpp v103, v103, v103 row_mirror row_mask:0xf bank_mask:0xf bound_ctrl:1
	v_add_f32_dpp v250, v20, v20 row_mirror row_mask:0xf bank_mask:0xc bound_ctrl:1
	v_add_f32_dpp v94, v95, v95 row_mirror row_mask:0xf bank_mask:0xc bound_ctrl:1
	v_add_f32_dpp v125, v124, v124 row_mirror row_mask:0xf bank_mask:0xc bound_ctrl:1
	v_add_f32_dpp v111, v110, v110 row_mirror row_mask:0xf bank_mask:0xc bound_ctrl:1
	v_add_f32_dpp v103, v102, v102 row_mirror row_mask:0xf bank_mask:0xc bound_ctrl:1
	v_add_f32_dpp v251, v28, v28 row_mirror row_mask:0xf bank_mask:0xf bound_ctrl:1
	v_add_f32_dpp v96, v96, v96 row_mirror row_mask:0xf bank_mask:0xf bound_ctrl:1
	v_add_f32_dpp v98, v98, v98 row_mirror row_mask:0xf bank_mask:0xf bound_ctrl:1
	v_add_f32_dpp v109, v109, v109 row_mirror row_mask:0xf bank_mask:0xf bound_ctrl:1
	v_add_f32_dpp v123, v123, v123 row_mirror row_mask:0xf bank_mask:0xf bound_ctrl:1
	v_add_f32_dpp v251, v22, v22 row_mirror row_mask:0xf bank_mask:0xc bound_ctrl:1
	v_add_f32_dpp v96, v97, v97 row_mirror row_mask:0xf bank_mask:0xc bound_ctrl:1
	v_add_f32_dpp v98, v122, v122 row_mirror row_mask:0xf bank_mask:0xc bound_ctrl:1
	v_add_f32_dpp v109, v108, v108 row_mirror row_mask:0xf bank_mask:0xc bound_ctrl:1
	v_add_f32_dpp v123, v129, v129 row_mirror row_mask:0xf bank_mask:0xc bound_ctrl:1
	v_add_f32_dpp v250, v250, v250 row_half_mirror row_mask:0xf bank_mask:0xf bound_ctrl:1
	v_add_f32_dpp v94, v94, v94 row_half_mirror row_mask:0xf bank_mask:0xf bound_ctrl:1
	v_add_f32_dpp v125, v125, v125 row_half_mirror row_mask:0xf bank_mask:0xf bound_ctrl:1
	v_add_f32_dpp v111, v111, v111 row_half_mirror row_mask:0xf bank_mask:0xf bound_ctrl:1
	v_add_f32_dpp v103, v103, v103 row_half_mirror row_mask:0xf bank_mask:0xf bound_ctrl:1
	v_add_f32_dpp v250, v251, v251 row_half_mirror row_mask:0xf bank_mask:0xa bound_ctrl:1
	v_add_f32_dpp v94, v96, v96 row_half_mirror row_mask:0xf bank_mask:0xa bound_ctrl:1
	v_add_f32_dpp v125, v98, v98 row_half_mirror row_mask:0xf bank_mask:0xa bound_ctrl:1
	v_add_f32_dpp v111, v109, v109 row_half_mirror row_mask:0xf bank_mask:0xa bound_ctrl:1
	v_add_f32_dpp v103, v123, v123 row_half_mirror row_mask:0xf bank_mask:0xa bound_ctrl:1
	v_add_f32_dpp v250, v250, v250 quad_perm:[1,0,3,2] row_mask:0xf bank_mask:0xf bound_ctrl:1
	v_add_f32_dpp v94, v94, v94 quad_perm:[1,0,3,2] row_mask:0xf bank_mask:0xf bound_ctrl:1
	v_add_f32_dpp v125, v125, v125 quad_perm:[1,0,3,2] row_mask:0xf bank_mask:0xf bound_ctrl:1
	v_add_f32_dpp v111, v111, v111 quad_perm:[1,0,3,2] row_mask:0xf bank_mask:0xf bound_ctrl:1
	v_add_f32_dpp v103, v103, v103 quad_perm:[1,0,3,2] row_mask:0xf bank_mask:0xf bound_ctrl:1
	v_add_f32_dpp v250, v250, v250 quad_perm:[2,3,0,1] row_mask:0xf bank_mask:0xf bound_ctrl:1
	v_add_f32_dpp v94, v94, v94 quad_perm:[2,3,0,1] row_mask:0xf bank_mask:0xf bound_ctrl:1
	v_add_f32_dpp v125, v125, v125 quad_perm:[2,3,0,1] row_mask:0xf bank_mask:0xf bound_ctrl:1
	v_add_f32_dpp v111, v111, v111 quad_perm:[2,3,0,1] row_mask:0xf bank_mask:0xf bound_ctrl:1
	v_add_f32_dpp v103, v103, v103 quad_perm:[2,3,0,1] row_mask:0xf bank_mask:0xf bound_ctrl:1
	v_readlane_b32 s2, v250, 20
	v_readlane_b32 s4, v250, 52
	v_readlane_b32 s0, v250, 4
	v_readlane_b32 s1, v250, 36
	v_mov_b32_e32 v16, s2
	v_mov_b32_e32 v17, s4
	v_readlane_b32 s2, v250, 16
	v_readlane_b32 s4, v250, 48
	v_pk_add_f32 v[16:17], s[0:1], v[16:17]
	v_readlane_b32 s0, v250, 0
	v_readlane_b32 s1, v250, 32
	v_mov_b32_e32 v18, s2
	v_mov_b32_e32 v19, s4
	v_readlane_b32 s2, v250, 24
	v_readlane_b32 s4, v250, 56
	v_pk_add_f32 v[18:19], s[0:1], v[18:19]
	v_readlane_b32 s0, v250, 8
	v_readlane_b32 s1, v250, 40
	v_mov_b32_e32 v20, s2
	v_mov_b32_e32 v21, s4
	v_pk_add_f32 v[20:21], s[0:1], v[20:21]
	v_mov_b32_e32 v25, v18
	v_add_f32_e32 v26, v20, v21
	v_mov_b32_e32 v18, v17
	v_readlane_b32 s2, v250, 28
	v_readlane_b32 s4, v250, 60
	v_readlane_b32 s0, v250, 12
	v_readlane_b32 s1, v250, 44
	v_mov_b32_e32 v20, s2
	v_mov_b32_e32 v21, s4
	v_pk_add_f32 v[20:21], s[0:1], v[20:21]
	v_add_f32_e32 v27, v20, v21
	v_readlane_b32 s20, v94, 0
	v_readlane_b32 s4, v94, 16
	v_readlane_b32 s21, v94, 32
	v_readlane_b32 s5, v94, 48
	v_readlane_b32 s91, v94, 8
	v_readlane_b32 s95, v94, 24
	v_readlane_b32 s94, v94, 40
	v_readlane_b32 s92, v94, 56
	v_readlane_b32 s6, v94, 4
	v_readlane_b32 s75, v94, 20
	v_readlane_b32 s74, v94, 36
	v_readlane_b32 s84, v94, 52
	v_readlane_b32 s97, v94, 12
	v_readlane_b32 s9, v94, 28
	v_readlane_b32 s8, v94, 44
	v_readlane_b32 s12, v94, 60
	v_readlane_b32 s59, v125, 0
	v_readlane_b32 s61, v125, 16
	v_readlane_b32 s60, v125, 32
	v_readlane_b32 s82, v125, 48
	v_readlane_b32 s52, v125, 8
	v_readlane_b32 s54, v125, 24
	v_readlane_b32 s53, v125, 40
	v_readlane_b32 s93, v125, 56
	v_readlane_b32 s85, v125, 4
	v_readlane_b32 s87, v125, 20
	v_readlane_b32 s86, v125, 36
	v_readlane_b32 s90, v125, 52
	v_readlane_b32 s13, v125, 12
	v_readlane_b32 s24, v125, 28
	v_readlane_b32 s16, v125, 44
	v_readlane_b32 s17, v125, 60
	v_readlane_b32 s83, v111, 0
	v_readlane_b32 s89, v111, 16
	v_readlane_b32 s88, v111, 32
	v_readlane_b32 s96, v111, 48
	v_readlane_b32 s55, v111, 8
	v_readlane_b32 s57, v111, 24
	v_readlane_b32 s56, v111, 40
	v_readlane_b32 s58, v111, 56
	v_readlane_b32 s46, v111, 4
	v_readlane_b32 s48, v111, 20
	v_readlane_b32 s47, v111, 36
	v_readlane_b32 s49, v111, 52
	v_readlane_b32 s38, v111, 12
	v_readlane_b32 s40, v111, 28
	v_readlane_b32 s39, v111, 44
	v_readlane_b32 s41, v111, 60
	v_readlane_b32 s34, v103, 0
	v_readlane_b32 s36, v103, 16
	v_readlane_b32 s35, v103, 32
	v_readlane_b32 s37, v103, 48
	v_readlane_b32 s29, v103, 8
	v_readlane_b32 s31, v103, 24
	v_readlane_b32 s30, v103, 40
	v_readlane_b32 s33, v103, 56
	v_readlane_b32 s25, v103, 4
	v_readlane_b32 s28, v103, 20
	v_readlane_b32 s50, v103, 36
	v_readlane_b32 s51, v103, 52
	v_mov_b32_e32 v24, v16
	v_pk_add_f32 v[16:17], v[24:25], v[18:19]
	v_mov_b32_e32 v20, v178
	v_mov_b32_e32 v21, v179
	v_mov_b32_e32 v22, v180
	v_mov_b32_e32 v23, v181
	v_add_f32_e32 v19, v26, v22
	v_pk_add_f32 v[16:17], v[16:17], v[20:21]
	v_add_f32_e32 v18, v27, v23
	v_cmp_gt_f32_e32 vcc, v17, v16
	v_mov_b32_e32 v22, 0
	v_readlane_b32 s42, v103, 12
	v_cndmask_b32_e32 v20, v16, v17, vcc
	v_cmp_gt_f32_e64 s[18:19], v19, v20
	v_cndmask_b32_e64 v21, 0, 1, vcc
	s_and_b64 s[14:15], s[18:19], exec
	v_cndmask_b32_e64 v20, v20, v19, s[18:19]
	v_cmp_ngt_f32_e64 s[0:1], v18, v20
	v_readfirstlane_b32 s2, v21
	s_cselect_b32 s2, 2, s2
	s_and_b64 s[14:15], s[0:1], exec
	s_cselect_b32 s2, s2, 3
	s_cmp_eq_u32 s2, 0
	s_cselect_b64 s[26:27], -1, 0
	s_cmp_lg_u32 s2, 0
	v_mov_b32_e32 v21, 0
	v_readlane_b32 s44, v103, 28
	v_readlane_b32 s43, v103, 44
	v_readlane_b32 s45, v103, 60
	v_cmp_gt_f32_e64 s[14:15], v18, v20
	s_waitcnt lgkmcnt(0)
	s_cbranch_scc0 .LBB0_560
	v_cndmask_b32_e64 v23, 0, 1, s[26:27]
	v_cmp_ne_u32_e64 s[20:21], 1, v23
	s_andn2_b64 vcc, exec, s[26:27]
	s_cbranch_vccz .LBB0_561
	.p2alignl 6, 3212836864
.LBB0_554:
	v_mov_b32_e32 v23, 0
	s_and_b64 vcc, exec, s[20:21]
	v_mov_b32_e32 v24, 0
	s_cbranch_vccz .LBB0_562
	.p2alignl 6, 3212836864
.LBB0_555:
	s_and_b64 vcc, exec, s[20:21]
	s_cbranch_vccz .LBB0_563
	.p2alignl 6, 3212836864
.LBB0_556:
	s_cmp_eq_u32 s2, 1
	s_cselect_b64 s[26:27], -1, 0
	s_cmp_lg_u32 s2, 1
	s_cbranch_scc1 .LBB0_564
	.p2alignl 6, 3212836864
.LBB0_557:
	v_mov_b32_e32 v22, s61
	v_mov_b32_e32 v25, s82
	v_add_f32_e32 v22, s59, v22
	v_add_f32_e32 v25, s60, v25
	v_add_f32_e32 v22, v22, v25
	v_mov_b32_e32 v25, v166
	v_add_f32_e32 v22, v22, v25
	v_cndmask_b32_e64 v25, 0, 1, s[26:27]
	v_cmp_ne_u32_e64 s[20:21], 1, v25
	s_andn2_b64 vcc, exec, s[26:27]
	s_cbranch_vccz .LBB0_565
	.p2alignl 6, 3212836864
.LBB0_558:
	s_and_b64 vcc, exec, s[20:21]
	s_cbranch_vccnz .LBB0_566
	.p2alignl 6, 3212836864

.LBB0_572:
	v_readlane_b32 s88, v237, 56
	s_and_b64 vcc, exec, s[18:19]
	v_readlane_b32 s52, v237, 48
	v_readlane_b32 s89, v237, 57
	v_readlane_b32 s90, v237, 58
	v_readlane_b32 s91, v237, 59
	v_readlane_b32 s53, v237, 49
	v_readlane_b32 s54, v237, 50
	v_readlane_b32 s55, v237, 51
	v_readlane_b32 s56, v237, 52
	v_readlane_b32 s57, v237, 53
	v_readlane_b32 s58, v237, 54
	v_readlane_b32 s59, v237, 55
	s_cbranch_vccnz .LBB0_579
	v_mov_b32_e32 v24, s48
	v_mov_b32_e32 v25, s49
	v_add_f32_e32 v24, s46, v24
	v_add_f32_e32 v25, s47, v25
	v_add_f32_e32 v24, v24, v25
	v_mov_b32_e32 v25, v172
	v_add_f32_e32 v24, v24, v25
	s_and_b64 vcc, exec, s[18:19]
	s_cbranch_vccz .LBB0_580
	.p2alignl 6, 3212836864
.LBB0_574:
	v_cndmask_b32_e64 v25, 0, 1, s[14:15]
	v_cmp_ne_u32_e64 s[18:19], 1, v25
	s_andn2_b64 vcc, exec, s[14:15]
	s_cbranch_vccnz .LBB0_581
	.p2alignl 6, 3212836864
.LBB0_575:
	v_mov_b32_e32 v22, v174
	v_mov_b32_e32 v25, s36
	v_mov_b32_e32 v26, s37
	v_add_f32_e32 v25, s34, v25
	v_add_f32_e32 v26, s35, v26
	v_add_f32_e32 v25, v25, v26
	v_add_f32_e32 v22, v25, v22
	s_and_b64 vcc, exec, s[18:19]
	s_cbranch_vccz .LBB0_582
	.p2alignl 6, 3212836864
.LBB0_576:
	s_and_b64 vcc, exec, s[18:19]
	s_cbranch_vccnz .LBB0_583
	.p2alignl 6, 3212836864
.LBB0_577:
	v_mov_b32_e32 v24, v176
	v_mov_b32_e32 v25, s28
	v_mov_b32_e32 v26, s51
	v_add_f32_e32 v25, s25, v25
	v_add_f32_e32 v26, s50, v26
	v_add_f32_e32 v25, v25, v26
	v_add_f32_e32 v24, v25, v24
	s_and_b64 vcc, exec, s[18:19]
	s_cbranch_vccz .LBB0_584
	.p2alignl 6, 3212836864

.LBB0_594:
	s_waitcnt vmcnt(0)
	s_barrier
	s_mov_b64 s[0:1], exec
	v_readlane_b32 s2, v237, 1
	v_readlane_b32 s3, v237, 2
	s_and_b64 s[2:3], s[0:1], s[2:3]
	s_mov_b64 exec, s[2:3]
	s_cbranch_execz .LBB0_646
	v_mov_b32_e32 v0, 0x13ff0
	s_waitcnt vmcnt(0) expcnt(0) lgkmcnt(0)
	ds_read_b32 v2, v0
	v_mov_b32_e32 v0, 0x13ff4
	ds_read_b32 v0, v0
	s_waitcnt lgkmcnt(1)
	v_cmp_ne_u32_e32 vcc, 0, v2
	s_cbranch_vccnz .LBB0_610
	v_readlane_b32 s2, v237, 0
	s_mul_i32 s4, s91, s2
	s_add_u32 s2, s88, 0x4100200
	s_addc_u32 s3, s89, 0
	s_add_u32 s6, s88, 0x4100400
	s_addc_u32 s7, s89, 0
	s_add_u32 s8, s88, 0x4100500
	s_addc_u32 s9, s89, 0
	s_add_u32 s10, s88, 0x4100600
	s_addc_u32 s11, s89, 0
	s_add_u32 s12, s88, 0x4100700
	s_addc_u32 s13, s89, 0
	s_add_u32 s14, s88, 0x4100800
	s_addc_u32 s15, s89, 0
	s_add_u32 s18, s88, 0x4100900
	s_addc_u32 s19, s89, 0
	s_add_u32 s20, s88, 0x4100a00
	s_addc_u32 s21, s89, 0
	s_add_u32 s22, s88, 0x4100b00
	s_addc_u32 s23, s89, 0
	s_add_u32 s24, s88, 0x4100c00
	s_addc_u32 s25, s89, 0
	s_add_u32 s26, s88, 0x4100d00
	s_addc_u32 s27, s89, 0
	s_add_u32 s28, s88, 0x4100e00
	s_addc_u32 s29, s89, 0
	s_add_u32 s30, s88, 0x4100f00
	s_addc_u32 s31, s89, 0
	s_add_u32 s34, s88, 0x4101000
	s_addc_u32 s35, s89, 0
	s_add_u32 s36, s88, 0x4101100
	s_addc_u32 s37, s89, 0
	s_add_u32 s38, s88, 0x4101200
	s_addc_u32 s39, s89, 0
	s_add_u32 s40, s88, 0x4101300
	s_mul_i32 s4, s4, s90
	s_addc_u32 s41, s89, 0
	s_mov_b32 s5, 1
	v_mov_b32_e32 v16, 0
	s_branch .LBB0_598
	.p2alignl 6, 3212836864

.LBB0_598:
	global_load_dword v15, v16, s[6:7] sc1
	s_waitcnt lgkmcnt(0)
	global_load_dword v0, v16, s[8:9] sc1
	global_load_dword v1, v16, s[10:11] sc1
	global_load_dword v2, v16, s[12:13] sc1
	global_load_dword v3, v16, s[14:15] sc1
	global_load_dword v4, v16, s[18:19] sc1
	global_load_dword v5, v16, s[20:21] sc1
	global_load_dword v6, v16, s[22:23] sc1
	global_load_dword v7, v16, s[24:25] sc1
	global_load_dword v8, v16, s[26:27] sc1
	global_load_dword v9, v16, s[28:29] sc1
	global_load_dword v10, v16, s[30:31] sc1
	global_load_dword v11, v16, s[34:35] sc1
	global_load_dword v12, v16, s[36:37] sc1
	global_load_dword v13, v16, s[38:39] sc1
	global_load_dword v14, v16, s[40:41] sc1
	s_mov_b64 s[42:43], -1
	s_mov_b64 s[44:45], -1
	s_waitcnt vmcnt(14)
	v_add_u32_e32 v17, v0, v15
	s_waitcnt vmcnt(13)
	v_add_u32_e32 v17, v17, v1
	s_waitcnt vmcnt(12)
	v_add_u32_e32 v17, v17, v2
	s_waitcnt vmcnt(11)
	v_add_u32_e32 v17, v17, v3
	s_waitcnt vmcnt(10)
	v_add_u32_e32 v17, v17, v4
	s_waitcnt vmcnt(9)
	v_add_u32_e32 v17, v17, v5
	s_waitcnt vmcnt(8)
	v_add_u32_e32 v17, v17, v6
	s_waitcnt vmcnt(7)
	v_add_u32_e32 v17, v17, v7
	s_waitcnt vmcnt(6)
	v_add_u32_e32 v17, v17, v8
	s_waitcnt vmcnt(5)
	v_add_u32_e32 v17, v17, v9
	s_waitcnt vmcnt(4)
	v_add_u32_e32 v17, v17, v10
	s_waitcnt vmcnt(3)
	v_add_u32_e32 v17, v17, v11
	s_waitcnt vmcnt(2)
	v_add_u32_e32 v17, v17, v12
	s_waitcnt vmcnt(1)
	v_add_u32_e32 v17, v17, v13
	s_waitcnt vmcnt(0)
	v_add_u32_e32 v17, v17, v14
	v_cmp_eq_u32_e32 vcc, s4, v17
	s_cbranch_vccnz .LBB0_597
	s_and_b32 s16, s5, 0xff
	s_cmp_eq_u32 s16, 0
	s_mov_b64 s[46:47], -1
	s_sleep 1
	s_cbranch_scc1 .LBB0_602
	s_and_b64 vcc, exec, s[46:47]
	s_cbranch_vccz .LBB0_597
	.p2alignl 6, 3212836864

.LBB0_672:
	v_ashrrev_i32_e32 v144, 3, v12
	v_add_u32_e32 v8, v139, v144
	v_cmp_lt_i32_e32 vcc, v8, v142
	v_add_u32_e32 v4, 32, v8
	v_add_u32_e32 v6, 64, v8
	v_cndmask_b32_e32 v2, 0, v8, vcc
	v_cmp_lt_i32_e32 vcc, v4, v142
	v_add_u32_e32 v8, 0x60, v8
	v_readlane_b32 s0, v237, 42
	v_cndmask_b32_e32 v4, 0, v4, vcc
	v_cmp_lt_i32_e32 vcc, v6, v142
	v_lshlrev_b64 v[0:1], 17, v[130:131]
	v_readlane_b32 s1, v237, 43
	v_cndmask_b32_e32 v6, 0, v6, vcc
	v_cmp_lt_i32_e32 vcc, v8, v142
	v_lshl_add_u64 v[0:1], s[0:1], 0, v[0:1]
	v_ashrrev_i32_e32 v3, 31, v2
	v_cndmask_b32_e32 v8, 0, v8, vcc
	v_ashrrev_i32_e32 v5, 31, v4
	v_ashrrev_i32_e32 v7, 31, v6
	v_ashrrev_i32_e32 v9, 31, v8
	v_lshl_add_u64 v[2:3], v[2:3], 2, v[0:1]
	v_lshl_add_u64 v[4:5], v[4:5], 2, v[0:1]
	v_lshl_add_u64 v[6:7], v[6:7], 2, v[0:1]
	v_lshl_add_u64 v[0:1], v[8:9], 2, v[0:1]
	global_load_dword v2, v[2:3], off
	s_nop 0
	global_load_dword v3, v[4:5], off
	s_nop 0
	global_load_dword v4, v[6:7], off
	s_nop 0
	global_load_dword v0, v[0:1], off
	s_movk_i32 s1, 0xab
	v_mul_lo_u32 v1, v130, s1
	v_bfe_u32 v1, v1, 10, 6
	v_mul_lo_u32 v5, v1, -6
	v_readlane_b32 s4, v237, 31
	v_add_u32_e32 v5, v5, v130
	s_and_b32 s0, s4, 7
	v_cmp_gt_i32_e32 vcc, 5, v5
	v_min_i32_e32 v8, 4, v5
	s_cmp_lt_u32 s0, 4
	v_cndmask_b32_e64 v6, 2, 1, vcc
	v_add_u32_e32 v7, 1, v5
	v_add_u32_e32 v8, -1, v8
	v_cmp_gt_i32_e32 vcc, 3, v5
	v_lshlrev_b32_e32 v1, 2, v1
	s_mov_b32 s3, 0
	v_cndmask_b32_e64 v5, v6, 0, vcc
	v_cndmask_b32_e32 v6, v8, v7, vcc
	s_cselect_b64 vcc, -1, 0
	s_lshl_b32 s0, s4, 7
	v_or_b32_e32 v5, v5, v1
	v_add_u32_e32 v1, v6, v1
	s_and_b32 s0, s0, 0x180
	v_cndmask_b32_e32 v1, v1, v5, vcc
	v_add_lshl_u32 v5, v144, s0, 10
	s_mov_b64 s[6:7], -1
	s_movk_i32 s33, 0xfcc0
	s_movk_i32 s96, 0xc0
	s_movk_i32 s97, 0xfd00
	s_movk_i32 s16, 0x100
	v_mov_b32_e32 v132, v130
	v_lshl_add_u32 v149, v1, 19, v5
	s_mov_b32 s82, s4
	v_readlane_b32 s5, v237, 32
	s_waitcnt vmcnt(3)
	v_lshlrev_b32_e32 v148, 10, v2
	s_waitcnt vmcnt(2)
	v_lshlrev_b32_e32 v147, 10, v3
	s_waitcnt vmcnt(1)
	v_lshlrev_b32_e32 v146, 10, v4
	s_waitcnt vmcnt(0)
	v_lshlrev_b32_e32 v145, 10, v0
	s_branch .LBB0_674
	.p2alignl 6, 3212836864

.LBB0_703:
	s_movk_i32 s0, 0xab
	v_mul_lo_u32 v69, v134, s0
	v_bfe_u32 v69, v69, 10, 6
	v_mul_lo_u32 v70, v69, -6
	v_add_u32_e32 v70, v70, v134
	v_cmp_gt_i32_e32 vcc, 5, v70
	v_min_i32_e32 v77, 4, v70
	s_and_b32 s0, s83, 7
	v_cndmask_b32_e64 v71, 2, 1, vcc
	v_add_u32_e32 v76, 1, v70
	v_add_u32_e32 v77, -1, v77
	v_cmp_gt_i32_e32 vcc, 3, v70
	s_cmp_lt_u32 s0, 4
	v_lshlrev_b32_e32 v69, 2, v69
	v_cndmask_b32_e64 v70, v71, 0, vcc
	v_cndmask_b32_e32 v71, v77, v76, vcc
	s_cselect_b64 vcc, -1, 0
	s_lshl_b32 s0, s83, 7
	v_or_b32_e32 v70, v70, v69
	v_add_u32_e32 v69, v71, v69
	s_and_b32 s0, s0, 0x180
	s_waitcnt vmcnt(3)
	v_lshlrev_b32_e32 v135, 10, v64
	s_waitcnt vmcnt(2)
	v_lshlrev_b32_e32 v153, 10, v65
	v_cndmask_b32_e32 v64, v69, v70, vcc
	v_add_lshl_u32 v65, s0, v144, 10
	v_lshl_add_u32 v156, v64, 19, v65
	v_lshlrev_b32_e32 v64, 1, v133
	v_bfe_u32 v138, v66, 6, 1
	v_and_b32_e32 v65, 15, v66
	v_bfe_u32 v140, v66, 4, 2
	v_lshl_add_u32 v141, v75, 1, v64
	v_lshl_add_u32 v158, v72, 1, v64
	v_lshl_add_u32 v159, v73, 1, v64
	v_lshl_add_u32 v160, v74, 1, v64
	v_ashrrev_i32_e32 v64, 1, v66
	s_movk_i32 s0, 0xffc0
	v_and_or_b32 v157, v64, s0, v65
	v_lshlrev_b32_e32 v64, 4, v140
	v_lshl_or_b32 v65, v138, 6, v65
	s_movk_i32 s0, 0xa0
	v_mad_u64_u32 v[136:137], s[0:1], v157, s0, v[64:65]
	v_mul_u32_u24_e32 v65, 0x50, v65
	v_lshlrev_b32_e32 v65, 1, v65
	s_waitcnt vmcnt(1)
	v_lshlrev_b32_e32 v154, 10, v67
	s_waitcnt vmcnt(0)
	v_lshlrev_b32_e32 v155, 10, v68
	v_or_b32_e32 v67, 0x3c0, v133
	v_add_u32_e32 v137, v64, v65
	v_or_b32_e32 v66, 0xf000, v64
	v_add_u32_e32 v68, 0x1400, v65
	v_add_u32_e32 v65, 0x1e00, v65
	v_or_b32_e32 v64, 0xf040, v64
	v_add_u32_e32 v163, v64, v68
	v_add_u32_e32 v164, v64, v65
	v_add_u32_e32 v166, v67, v149
	v_mov_b32_e32 v64, 0
	s_mov_b32 s2, 0
	v_add_u32_e32 v161, v66, v68
	v_add_u32_e32 v162, v66, v65
	v_add_u32_e32 v165, v67, v148
	v_add_u32_e32 v167, v67, v147
	v_add_u32_e32 v168, 0x8000, v166
	v_add_u32_e32 v169, v67, v146
	v_add_u32_e32 v170, 0x10000, v166
	v_add_u32_e32 v171, v67, v145
	v_add_u32_e32 v172, 0x18000, v166
	v_mov_b32_e32 v173, v148
	v_mov_b32_e32 v174, v149
	v_mov_b32_e32 v175, v147
	v_mov_b32_e32 v176, v146
	v_mov_b32_e32 v177, v145
	v_mov_b32_e32 v178, v135
	v_mov_b32_e32 v179, v156
	v_mov_b32_e32 v180, v153
	v_mov_b32_e32 v181, v154
	v_mov_b32_e32 v182, v155
	v_mov_b32_e32 v65, v64
	v_mov_b32_e32 v66, v64
	v_mov_b32_e32 v67, v64
	v_mov_b32_e32 v80, v64
	v_mov_b32_e32 v81, v64
	v_mov_b32_e32 v82, v64
	v_mov_b32_e32 v83, v64
	v_mov_b32_e32 v96, v64
	v_mov_b32_e32 v97, v64
	v_mov_b32_e32 v98, v64
	v_mov_b32_e32 v99, v64
	v_mov_b32_e32 v112, v64
	v_mov_b32_e32 v113, v64
	v_mov_b32_e32 v114, v64
	v_mov_b32_e32 v115, v64
	v_mov_b32_e32 v72, v64
	v_mov_b32_e32 v73, v64
	v_mov_b32_e32 v74, v64
	v_mov_b32_e32 v75, v64
	v_mov_b32_e32 v88, v64
	v_mov_b32_e32 v89, v64
	v_mov_b32_e32 v90, v64
	v_mov_b32_e32 v91, v64
	v_mov_b32_e32 v104, v64
	v_mov_b32_e32 v105, v64
	v_mov_b32_e32 v106, v64
	v_mov_b32_e32 v107, v64
	v_mov_b32_e32 v120, v64
	v_mov_b32_e32 v121, v64
	v_mov_b32_e32 v122, v64
	v_mov_b32_e32 v123, v64
	v_mov_b32_e32 v68, v64
	v_mov_b32_e32 v69, v64
	v_mov_b32_e32 v70, v64
	v_mov_b32_e32 v71, v64
	v_mov_b32_e32 v84, v64
	v_mov_b32_e32 v85, v64
	v_mov_b32_e32 v86, v64
	v_mov_b32_e32 v87, v64
	v_mov_b32_e32 v100, v64
	v_mov_b32_e32 v101, v64
	v_mov_b32_e32 v102, v64
	v_mov_b32_e32 v103, v64
	v_mov_b32_e32 v116, v64
	v_mov_b32_e32 v117, v64
	v_mov_b32_e32 v118, v64
	v_mov_b32_e32 v119, v64
	v_mov_b32_e32 v76, v64
	v_mov_b32_e32 v77, v64
	v_mov_b32_e32 v78, v64
	v_mov_b32_e32 v79, v64
	v_mov_b32_e32 v92, v64
	v_mov_b32_e32 v93, v64
	v_mov_b32_e32 v94, v64
	v_mov_b32_e32 v95, v64
	v_mov_b32_e32 v108, v64
	v_mov_b32_e32 v109, v64
	v_mov_b32_e32 v110, v64
	v_mov_b32_e32 v111, v64
	v_mov_b32_e32 v124, v64
	v_mov_b32_e32 v125, v64
	v_mov_b32_e32 v126, v64
	v_mov_b32_e32 v127, v64
	s_branch .LBB0_705
	.p2alignl 6, 3212836864

.LBB0_734:
	s_waitcnt vmcnt(0)
	s_barrier
	s_mov_b64 s[0:1], exec
	v_readlane_b32 s2, v237, 1
	v_readlane_b32 s3, v237, 2
	s_and_b64 s[2:3], s[0:1], s[2:3]
	s_mov_b64 exec, s[2:3]
	s_cbranch_execz .LBB0_786
	s_waitcnt vmcnt(8)
	v_mov_b32_e32 v0, 0x13ff0
	s_waitcnt vmcnt(0) expcnt(0) lgkmcnt(0)
	ds_read_b32 v2, v0
	v_mov_b32_e32 v0, 0x13ff4
	ds_read_b32 v0, v0
	s_waitcnt lgkmcnt(1)
	v_cmp_ne_u32_e32 vcc, 0, v2
	s_cbranch_vccnz .LBB0_750
	v_readlane_b32 s40, v237, 56
	v_readlane_b32 s43, v237, 59
	v_readlane_b32 s2, v237, 0
	v_readlane_b32 s41, v237, 57
	s_mul_i32 s16, s43, s2
	s_add_u32 s2, s40, 0x4100200
	s_addc_u32 s3, s41, 0
	s_add_u32 s4, s40, 0x4100400
	s_addc_u32 s5, s41, 0
	s_add_u32 s6, s40, 0x4100500
	s_addc_u32 s7, s41, 0
	s_add_u32 s8, s40, 0x4100600
	s_addc_u32 s9, s41, 0
	s_add_u32 s10, s40, 0x4100700
	s_addc_u32 s11, s41, 0
	s_add_u32 s12, s40, 0x4100800
	s_addc_u32 s13, s41, 0
	s_add_u32 s14, s40, 0x4100900
	s_addc_u32 s15, s41, 0
	s_add_u32 s18, s40, 0x4100a00
	s_addc_u32 s19, s41, 0
	s_add_u32 s20, s40, 0x4100b00
	s_addc_u32 s21, s41, 0
	s_add_u32 s22, s40, 0x4100c00
	s_addc_u32 s23, s41, 0
	s_add_u32 s24, s40, 0x4100d00
	s_addc_u32 s25, s41, 0
	s_add_u32 s26, s40, 0x4100e00
	s_addc_u32 s27, s41, 0
	s_add_u32 s28, s40, 0x4100f00
	s_addc_u32 s29, s41, 0
	s_add_u32 s30, s40, 0x4101000
	s_addc_u32 s31, s41, 0
	s_add_u32 s34, s40, 0x4101100
	s_addc_u32 s35, s41, 0
	s_add_u32 s36, s40, 0x4101200
	s_addc_u32 s37, s41, 0
	v_readlane_b32 s42, v237, 58
	s_add_u32 s38, s40, 0x4101300
	s_mul_i32 s16, s16, s42
	s_addc_u32 s39, s41, 0
	s_mov_b32 s17, 1
	v_mov_b32_e32 v16, 0
	s_branch .LBB0_738
	.p2alignl 6, 3212836864

.LBB0_738:
	global_load_dword v15, v16, s[4:5] sc1
	s_waitcnt lgkmcnt(0)
	global_load_dword v0, v16, s[6:7] sc1
	global_load_dword v1, v16, s[8:9] sc1
	global_load_dword v2, v16, s[10:11] sc1
	global_load_dword v3, v16, s[12:13] sc1
	global_load_dword v4, v16, s[14:15] sc1
	global_load_dword v5, v16, s[18:19] sc1
	global_load_dword v6, v16, s[20:21] sc1
	global_load_dword v7, v16, s[22:23] sc1
	global_load_dword v8, v16, s[24:25] sc1
	global_load_dword v9, v16, s[26:27] sc1
	global_load_dword v10, v16, s[28:29] sc1
	global_load_dword v11, v16, s[30:31] sc1
	global_load_dword v12, v16, s[34:35] sc1
	global_load_dword v13, v16, s[36:37] sc1
	global_load_dword v14, v16, s[38:39] sc1
	s_mov_b64 s[40:41], -1
	s_mov_b64 s[42:43], -1
	s_waitcnt vmcnt(14)
	v_add_u32_e32 v17, v0, v15
	s_waitcnt vmcnt(13)
	v_add_u32_e32 v17, v17, v1
	s_waitcnt vmcnt(12)
	v_add_u32_e32 v17, v17, v2
	s_waitcnt vmcnt(11)
	v_add_u32_e32 v17, v17, v3
	s_waitcnt vmcnt(10)
	v_add_u32_e32 v17, v17, v4
	s_waitcnt vmcnt(9)
	v_add_u32_e32 v17, v17, v5
	s_waitcnt vmcnt(8)
	v_add_u32_e32 v17, v17, v6
	s_waitcnt vmcnt(7)
	v_add_u32_e32 v17, v17, v7
	s_waitcnt vmcnt(6)
	v_add_u32_e32 v17, v17, v8
	s_waitcnt vmcnt(5)
	v_add_u32_e32 v17, v17, v9
	s_waitcnt vmcnt(4)
	v_add_u32_e32 v17, v17, v10
	s_waitcnt vmcnt(3)
	v_add_u32_e32 v17, v17, v11
	s_waitcnt vmcnt(2)
	v_add_u32_e32 v17, v17, v12
	s_waitcnt vmcnt(1)
	v_add_u32_e32 v17, v17, v13
	s_waitcnt vmcnt(0)
	v_add_u32_e32 v17, v17, v14
	v_cmp_eq_u32_e32 vcc, s16, v17
	s_cbranch_vccnz .LBB0_737
	s_and_b32 s33, s17, 0xff
	s_cmp_eq_u32 s33, 0
	s_mov_b64 s[44:45], -1
	s_sleep 1
	s_cbranch_scc1 .LBB0_742
	s_and_b64 vcc, exec, s[44:45]
	s_cbranch_vccz .LBB0_737
	.p2alignl 6, 3212836864

.LBB0_812:
	s_movk_i32 s6, 0xab
	v_mul_lo_u32 v1, v130, s6
	v_bfe_u32 v1, v1, 10, 6
	v_mul_lo_u32 v2, v1, -6
	v_add_u32_e32 v2, v2, v130
	v_cmp_gt_i32_e32 vcc, 5, v2
	v_ashrrev_i32_e32 v140, 3, v8
	v_add_u32_e32 v4, 1, v2
	v_cndmask_b32_e64 v3, 2, 1, vcc
	v_cmp_gt_i32_e32 vcc, 3, v2
	v_min_i32_e32 v5, 4, v2
	v_add_u32_e32 v0, v0, v138
	v_cndmask_b32_e64 v2, v3, 0, vcc
	v_readlane_b32 s8, v237, 31
	v_add_lshl_u32 v142, v0, v140, 9
	s_lshl_b32 s0, s8, 15
	v_lshlrev_b32_e32 v0, 20, v1
	v_lshlrev_b32_e32 v1, 18, v2
	v_add_u32_e32 v5, -1, v5
	s_and_b32 s0, s0, 0x38000
	v_or_b32_e32 v0, v1, v0
	v_cndmask_b32_e32 v3, v5, v4, vcc
	v_lshlrev_b32_e32 v141, 8, v140
	v_or_b32_e32 v0, s0, v0
	v_add_u32_e32 v144, v0, v141
	v_sub_u32_e32 v0, v3, v2
	s_mov_b32 s3, 0
	v_lshlrev_b32_e32 v143, 18, v0
	s_mov_b64 s[4:5], -1
	s_movk_i32 s7, 0x50
	s_mov_b32 s16, s8
	v_readlane_b32 s9, v237, 32
	s_branch .LBB0_814
	.p2alignl 6, 3212836864

.LBB0_843:
	v_lshlrev_b32_e32 v65, 1, v136
	v_lshl_add_u32 v155, v74, 1, v65
	v_lshl_add_u32 v156, v71, 1, v65
	v_lshl_add_u32 v157, v72, 1, v65
	v_lshl_add_u32 v158, v73, 1, v65
	v_or_b32_e32 v65, 0xc0, v136
	s_waitcnt lgkmcnt(0)
	s_barrier
	s_waitcnt vmcnt(15)
	ds_write_b128 v155, v[0:3] offset:40960
	s_waitcnt vmcnt(14)
	ds_write_b128 v155, v[8:11] offset:61440
	s_waitcnt vmcnt(13)
	ds_write_b128 v156, v[16:19] offset:40960
	s_waitcnt vmcnt(12)
	ds_write_b128 v156, v[24:27] offset:61440
	s_waitcnt vmcnt(11)
	ds_write_b128 v157, v[28:31] offset:40960
	s_waitcnt vmcnt(10)
	ds_write_b128 v157, v[36:39] offset:61440
	s_waitcnt vmcnt(9)
	ds_write_b128 v158, v[44:47] offset:40960
	s_waitcnt vmcnt(8)
	ds_write_b128 v158, v[56:59] offset:61440
	v_add_u32_e32 v44, v65, v142
	v_mov_b32_e32 v132, v44
	v_mul_lo_u32 v66, v146, s6
	v_lshl_add_u64 v[0:1], v[132:133], 1, s[88:89]
	v_add_u32_e32 v132, v65, v144
	global_load_dwordx4 v[0:3], v[0:1], off
	v_bfe_u32 v66, v66, 10, 6
	v_lshl_add_u64 v[8:9], v[132:133], 1, s[18:19]
	v_add_u32_e32 v132, 0x4000, v44
	global_load_dwordx4 v[8:11], v[8:9], off
	v_mul_lo_u32 v67, v66, -6
	v_lshl_add_u64 v[16:17], v[132:133], 1, s[88:89]
	v_add_u32_e32 v132, v65, v137
	global_load_dwordx4 v[16:19], v[16:17], off
	v_add_u32_e32 v151, v67, v146
	v_lshl_add_u64 v[24:25], v[132:133], 1, s[18:19]
	v_add_u32_e32 v132, 0x8000, v44
	global_load_dwordx4 v[24:27], v[24:25], off
	v_cmp_gt_i32_e32 vcc, 5, v151
	v_lshl_add_u64 v[28:29], v[132:133], 1, s[88:89]
	v_add_u32_e32 v132, v65, v148
	global_load_dwordx4 v[28:31], v[28:29], off
	v_cndmask_b32_e64 v67, 2, 1, vcc
	v_lshl_add_u64 v[36:37], v[132:133], 1, s[18:19]
	v_add_u32_e32 v132, 0xc000, v44
	global_load_dwordx4 v[36:39], v[36:37], off
	v_cmp_gt_i32_e64 s[12:13], 3, v151
	v_lshl_add_u64 v[44:45], v[132:133], 1, s[88:89]
	v_add_u32_e32 v132, v65, v149
	global_load_dwordx4 v[44:47], v[44:45], off
	v_cndmask_b32_e64 v152, v67, 0, s[12:13]
	v_lshl_add_u64 v[56:57], v[132:133], 1, s[18:19]
	global_load_dwordx4 v[56:59], v[56:57], off
	v_add_u32_e32 v64, v64, v145
	v_add_lshl_u32 v150, v64, v140, 9
	s_lshl_b32 s0, s33, 15
	v_lshlrev_b32_e32 v64, 20, v66
	v_lshlrev_b32_e32 v66, 18, v152
	s_and_b32 s0, s0, 0x38000
	v_or_b32_e32 v64, v66, v64
	v_or_b32_e32 v64, s0, v64
	v_add_u32_e32 v153, v64, v141
	v_and_b32_e32 v64, 15, v131
	v_bfe_u32 v159, v131, 4, 2
	v_ashrrev_i32_e32 v66, 1, v131
	s_movk_i32 s0, 0xffc0
	v_and_or_b32 v154, v66, s0, v64
	v_lshlrev_b32_e32 v64, 4, v159
	v_and_b32_e32 v66, 0x4f, v131
	s_movk_i32 s0, 0xa0
	v_mad_u64_u32 v[134:135], s[0:1], v154, s0, v[64:65]
	v_mul_u32_u24_e32 v66, 0x50, v66
	v_lshl_add_u32 v135, v66, 1, v64
	v_add_u32_e32 v64, v144, v143
	v_add_u32_e32 v164, v65, v64
	v_add_u32_e32 v166, v136, v64
	ds_read_b128 v[64:67], v134
	ds_read_b128 v[68:71], v134 offset:2560
	ds_read_b128 v[72:75], v135 offset:20480
	ds_read_b128 v[76:79], v135 offset:23040
	ds_read_b128 v[80:83], v134 offset:5120
	ds_read_b128 v[84:87], v134 offset:7680
	ds_read_b128 v[88:91], v135 offset:25600
	ds_read_b128 v[92:95], v135 offset:28160
	v_add_u32_e32 v162, v142, v136
	s_mov_b32 s2, 2
	s_mov_b32 s14, 0
	v_add_u32_e32 v160, 0xf000, v135
	v_add_u32_e32 v161, 0xf040, v135
	v_add_u32_e32 v163, 0x1c0, v162
	v_add_u32_e32 v165, 0x41c0, v162
	v_add_u32_e32 v167, 0x20c0, v166
	v_add_u32_e32 v168, 0x81c0, v162
	v_add_u32_e32 v169, 0x40c0, v166
	v_add_u32_e32 v170, 0xc1c0, v162
	v_add_u32_e32 v171, 0x60c0, v166
	v_add_u32_e32 v172, 0x2000, v153
	v_add_u32_e32 v173, 0x4000, v153
	v_add_u32_e32 v174, 0x6000, v153
	s_setprio 1
	s_waitcnt lgkmcnt(5)
	v_mfma_f32_16x16x32_bf16 v[96:99], v[72:75], v[64:67], 0
	v_mfma_f32_16x16x32_bf16 v[100:103], v[72:75], v[68:71], 0
	s_waitcnt lgkmcnt(3)
	v_mfma_f32_16x16x32_bf16 v[104:107], v[72:75], v[80:83], 0
	s_waitcnt lgkmcnt(2)
	v_mfma_f32_16x16x32_bf16 v[72:75], v[72:75], v[84:87], 0
	v_mfma_f32_16x16x32_bf16 v[108:111], v[76:79], v[64:67], 0
	v_mfma_f32_16x16x32_bf16 v[112:115], v[76:79], v[68:71], 0
	v_mfma_f32_16x16x32_bf16 v[116:119], v[76:79], v[80:83], 0
	v_mfma_f32_16x16x32_bf16 v[76:79], v[76:79], v[84:87], 0
	s_waitcnt lgkmcnt(1)
	v_mfma_f32_16x16x32_bf16 v[120:123], v[88:91], v[64:67], 0
	v_mfma_f32_16x16x32_bf16 v[124:127], v[88:91], v[68:71], 0
	v_mfma_f32_16x16x32_bf16 v[176:179], v[88:91], v[80:83], 0
	v_mfma_f32_16x16x32_bf16 v[88:91], v[88:91], v[84:87], 0
	s_waitcnt lgkmcnt(0)
	v_mfma_f32_16x16x32_bf16 v[64:67], v[92:95], v[64:67], 0
	v_mfma_f32_16x16x32_bf16 v[68:71], v[92:95], v[68:71], 0
	v_mfma_f32_16x16x32_bf16 v[80:83], v[92:95], v[80:83], 0
	v_mfma_f32_16x16x32_bf16 v[84:87], v[92:95], v[84:87], 0
	s_setprio 0
	ds_read_b128 v[92:95], v134 offset:64
	ds_read_b128 v[180:183], v134 offset:2624
	ds_read_b128 v[184:187], v135 offset:20544
	ds_read_b128 v[188:191], v135 offset:23104
	ds_read_b128 v[192:195], v134 offset:5184
	ds_read_b128 v[196:199], v134 offset:7744
	ds_read_b128 v[200:203], v135 offset:25664
	ds_read_b128 v[204:207], v135 offset:28224
	s_setprio 1
	s_waitcnt lgkmcnt(5)
	v_mfma_f32_16x16x32_bf16 v[96:99], v[184:187], v[92:95], v[96:99]
	v_mfma_f32_16x16x32_bf16 v[100:103], v[184:187], v[180:183], v[100:103]
	s_waitcnt lgkmcnt(3)
	v_mfma_f32_16x16x32_bf16 v[104:107], v[184:187], v[192:195], v[104:107]
	s_waitcnt lgkmcnt(2)
	v_mfma_f32_16x16x32_bf16 v[72:75], v[184:187], v[196:199], v[72:75]
	v_mfma_f32_16x16x32_bf16 v[108:111], v[188:191], v[92:95], v[108:111]
	v_mfma_f32_16x16x32_bf16 v[112:115], v[188:191], v[180:183], v[112:115]
	v_mfma_f32_16x16x32_bf16 v[116:119], v[188:191], v[192:195], v[116:119]
	v_mfma_f32_16x16x32_bf16 v[76:79], v[188:191], v[196:199], v[76:79]
	s_waitcnt lgkmcnt(1)
	v_mfma_f32_16x16x32_bf16 v[120:123], v[200:203], v[92:95], v[120:123]
	v_mfma_f32_16x16x32_bf16 v[124:127], v[200:203], v[180:183], v[124:127]
	v_mfma_f32_16x16x32_bf16 v[88:91], v[200:203], v[196:199], v[88:91]
	s_waitcnt lgkmcnt(0)
	v_mfma_f32_16x16x32_bf16 v[64:67], v[204:207], v[92:95], v[64:67]
	v_mfma_f32_16x16x32_bf16 v[68:71], v[204:207], v[180:183], v[68:71]
	v_mfma_f32_16x16x32_bf16 v[80:83], v[204:207], v[192:195], v[80:83]
	v_mfma_f32_16x16x32_bf16 v[84:87], v[204:207], v[196:199], v[84:87]
	v_mfma_f32_16x16x32_bf16 v[176:179], v[200:203], v[192:195], v[176:179]
	s_setprio 0
	v_add_u32_e32 v132, 0x100, v162
	s_barrier
	s_waitcnt vmcnt(15)
	ds_write_b128 v155, v[4:7]
	s_waitcnt vmcnt(14)
	ds_write_b128 v155, v[12:15] offset:20480
	s_waitcnt vmcnt(13)
	ds_write_b128 v156, v[20:23]
	s_waitcnt vmcnt(12)
	ds_write_b128 v156, v[32:35] offset:20480
	s_waitcnt vmcnt(11)
	ds_write_b128 v157, v[40:43]
	s_waitcnt vmcnt(10)
	ds_write_b128 v157, v[48:51] offset:20480
	s_waitcnt vmcnt(9)
	ds_write_b128 v158, v[52:55]
	s_waitcnt vmcnt(8)
	ds_write_b128 v158, v[60:63] offset:20480
	s_nop 0
	v_lshl_add_u64 v[4:5], v[132:133], 1, s[88:89]
	v_mov_b32_e32 v132, v166
	global_load_dwordx4 v[4:7], v[4:5], off
	s_nop 0
	v_lshl_add_u64 v[12:13], v[132:133], 1, s[18:19]
	v_add_u32_e32 v132, 0x4100, v162
	global_load_dwordx4 v[12:15], v[12:13], off
	s_nop 0
	v_lshl_add_u64 v[20:21], v[132:133], 1, s[88:89]
	v_add_u32_e32 v132, 0x2000, v166
	global_load_dwordx4 v[20:23], v[20:21], off
	s_nop 0
	v_lshl_add_u64 v[32:33], v[132:133], 1, s[18:19]
	v_add_u32_e32 v132, 0x8100, v162
	global_load_dwordx4 v[32:35], v[32:33], off
	s_nop 0
	v_lshl_add_u64 v[40:41], v[132:133], 1, s[88:89]
	v_add_u32_e32 v132, 0x4000, v166
	global_load_dwordx4 v[40:43], v[40:41], off
	s_nop 0
	v_lshl_add_u64 v[48:49], v[132:133], 1, s[18:19]
	v_add_u32_e32 v132, 0xc100, v162
	global_load_dwordx4 v[48:51], v[48:49], off
	s_nop 0
	v_lshl_add_u64 v[52:53], v[132:133], 1, s[88:89]
	v_add_u32_e32 v132, 0x6000, v166
	global_load_dwordx4 v[52:55], v[52:53], off
	s_nop 0
	v_lshl_add_u64 v[60:61], v[132:133], 1, s[18:19]
	global_load_dwordx4 v[60:63], v[60:61], off
	ds_read_b128 v[92:95], v134 offset:40960
	ds_read_b128 v[180:183], v134 offset:43520
	ds_read_b128 v[184:187], v135 offset:61440
	ds_read_b128 v[188:191], v135 offset:64000
	ds_read_b128 v[192:195], v134 offset:46080
	ds_read_b128 v[196:199], v134 offset:48640
	ds_read_b128 v[200:203], v160 offset:5120
	ds_read_b128 v[204:207], v160 offset:7680
	s_setprio 1
	s_waitcnt lgkmcnt(5)
	v_mfma_f32_16x16x32_bf16 v[96:99], v[184:187], v[92:95], v[96:99]
	v_mfma_f32_16x16x32_bf16 v[100:103], v[184:187], v[180:183], v[100:103]
	s_waitcnt lgkmcnt(3)
	v_mfma_f32_16x16x32_bf16 v[104:107], v[184:187], v[192:195], v[104:107]
	s_waitcnt lgkmcnt(2)
	v_mfma_f32_16x16x32_bf16 v[72:75], v[184:187], v[196:199], v[72:75]
	v_mfma_f32_16x16x32_bf16 v[112:115], v[188:191], v[180:183], v[112:115]
	v_mfma_f32_16x16x32_bf16 v[116:119], v[188:191], v[192:195], v[116:119]
	s_waitcnt lgkmcnt(0)
	v_mfma_f32_16x16x32_bf16 v[64:67], v[204:207], v[92:95], v[64:67]
	v_mfma_f32_16x16x32_bf16 v[80:83], v[204:207], v[192:195], v[80:83]
	v_mfma_f32_16x16x32_bf16 v[184:187], v[188:191], v[92:95], v[108:111]
	v_mfma_f32_16x16x32_bf16 v[188:191], v[188:191], v[196:199], v[76:79]
	v_mfma_f32_16x16x32_bf16 v[208:211], v[200:203], v[92:95], v[120:123]
	v_mfma_f32_16x16x32_bf16 v[212:215], v[200:203], v[180:183], v[124:127]
	v_mfma_f32_16x16x32_bf16 v[176:179], v[200:203], v[192:195], v[176:179]
	v_mfma_f32_16x16x32_bf16 v[200:203], v[200:203], v[196:199], v[88:91]
	v_mfma_f32_16x16x32_bf16 v[180:183], v[204:207], v[180:183], v[68:71]
	v_mfma_f32_16x16x32_bf16 v[192:195], v[204:207], v[196:199], v[84:87]
	s_setprio 0
	ds_read_b128 v[196:199], v134 offset:41024
	ds_read_b128 v[204:207], v134 offset:43584
	ds_read_b128 v[68:71], v135 offset:61504
	ds_read_b128 v[84:87], v135 offset:64064
	ds_read_b128 v[216:219], v134 offset:46144
	ds_read_b128 v[220:223], v134 offset:48704
	ds_read_b128 v[224:227], v161 offset:5120
	ds_read_b128 v[228:231], v161 offset:7680
	s_setprio 1
	s_waitcnt lgkmcnt(5)
	v_mfma_f32_16x16x32_bf16 v[124:127], v[68:71], v[196:199], v[96:99]
	v_mfma_f32_16x16x32_bf16 v[108:111], v[68:71], v[204:207], v[100:103]
	s_waitcnt lgkmcnt(3)
	v_mfma_f32_16x16x32_bf16 v[92:95], v[68:71], v[216:219], v[104:107]
	s_waitcnt lgkmcnt(2)
	v_mfma_f32_16x16x32_bf16 v[76:79], v[68:71], v[220:223], v[72:75]
	v_mfma_f32_16x16x32_bf16 v[120:123], v[84:87], v[196:199], v[184:187]
	v_mfma_f32_16x16x32_bf16 v[104:107], v[84:87], v[204:207], v[112:115]
	v_mfma_f32_16x16x32_bf16 v[88:91], v[84:87], v[216:219], v[116:119]
	v_mfma_f32_16x16x32_bf16 v[72:75], v[84:87], v[220:223], v[188:191]
	s_waitcnt lgkmcnt(1)
	v_mfma_f32_16x16x32_bf16 v[116:119], v[224:227], v[196:199], v[208:211]
	v_mfma_f32_16x16x32_bf16 v[100:103], v[224:227], v[204:207], v[212:215]
	v_mfma_f32_16x16x32_bf16 v[84:87], v[224:227], v[216:219], v[176:179]
	v_mfma_f32_16x16x32_bf16 v[68:71], v[224:227], v[220:223], v[200:203]
	s_waitcnt lgkmcnt(0)
	v_mfma_f32_16x16x32_bf16 v[112:115], v[228:231], v[196:199], v[64:67]
	v_mfma_f32_16x16x32_bf16 v[96:99], v[228:231], v[204:207], v[180:183]
	v_mfma_f32_16x16x32_bf16 v[80:83], v[228:231], v[216:219], v[80:83]
	v_mfma_f32_16x16x32_bf16 v[64:67], v[228:231], v[220:223], v[192:195]
	s_setprio 0
	v_add_u32_e32 v175, v150, v136
	s_branch .LBB0_845
	.p2alignl 6, 3212836864

.LBB0_873:
	s_waitcnt vmcnt(0)
	s_barrier
	s_mov_b64 s[0:1], exec
	v_readlane_b32 s2, v237, 1
	v_readlane_b32 s3, v237, 2
	s_and_b64 s[2:3], s[0:1], s[2:3]
	s_mov_b64 exec, s[2:3]
	s_cbranch_execz .LBB0_925
	v_mov_b32_e32 v0, 0x13ff0
	s_waitcnt vmcnt(0) expcnt(0) lgkmcnt(0)
	ds_read_b32 v2, v0
	v_mov_b32_e32 v0, 0x13ff4
	ds_read_b32 v0, v0
	s_waitcnt lgkmcnt(1)
	v_cmp_ne_u32_e32 vcc, 0, v2
	s_cbranch_vccnz .LBB0_889
	v_readlane_b32 s40, v237, 56
	v_readlane_b32 s43, v237, 59
	v_readlane_b32 s2, v237, 0
	v_readlane_b32 s41, v237, 57
	s_mul_i32 s16, s43, s2
	s_add_u32 s2, s40, 0x4100200
	s_addc_u32 s3, s41, 0
	s_add_u32 s4, s40, 0x4100400
	s_addc_u32 s5, s41, 0
	s_add_u32 s6, s40, 0x4100500
	s_addc_u32 s7, s41, 0
	s_add_u32 s8, s40, 0x4100600
	s_addc_u32 s9, s41, 0
	s_add_u32 s10, s40, 0x4100700
	s_addc_u32 s11, s41, 0
	s_add_u32 s12, s40, 0x4100800
	s_addc_u32 s13, s41, 0
	s_add_u32 s14, s40, 0x4100900
	s_addc_u32 s15, s41, 0
	s_add_u32 s18, s40, 0x4100a00
	s_addc_u32 s19, s41, 0
	s_add_u32 s20, s40, 0x4100b00
	s_addc_u32 s21, s41, 0
	s_add_u32 s22, s40, 0x4100c00
	s_addc_u32 s23, s41, 0
	s_add_u32 s24, s40, 0x4100d00
	s_addc_u32 s25, s41, 0
	s_add_u32 s26, s40, 0x4100e00
	s_addc_u32 s27, s41, 0
	s_add_u32 s28, s40, 0x4100f00
	s_addc_u32 s29, s41, 0
	s_add_u32 s30, s40, 0x4101000
	s_addc_u32 s31, s41, 0
	s_add_u32 s34, s40, 0x4101100
	s_addc_u32 s35, s41, 0
	s_add_u32 s36, s40, 0x4101200
	s_addc_u32 s37, s41, 0
	v_readlane_b32 s42, v237, 58
	s_add_u32 s38, s40, 0x4101300
	s_mul_i32 s16, s16, s42
	s_addc_u32 s39, s41, 0
	s_mov_b32 s17, 1
	v_mov_b32_e32 v16, 0
	s_branch .LBB0_877
	.p2alignl 6, 3212836864

.LBB0_925:
	s_or_b64 exec, exec, s[0:1]
	v_mov_b32_e32 v36, v128
	s_waitcnt lgkmcnt(0)
	v_mov_b32_e32 v0, v128
	s_barrier
	v_readlane_b32 s0, v237, 56
	v_ashrrev_i32_e32 v0, 6, v0
	v_readlane_b32 s0, v237, 36
	v_readlane_b32 s2, v237, 58
	s_mov_b32 s11, 0x8000
	v_add_u32_e32 v40, s0, v0
	v_readlane_b32 s3, v237, 59
	s_lshl_b32 s96, s2, 2
	v_cmp_gt_i32_e32 vcc, s11, v40
	v_readlane_b32 s1, v237, 57
	s_and_saveexec_b64 s[2:3], vcc
	s_cbranch_execz .LBB0_928
	v_ashrrev_i32_e32 v41, 31, v40
	v_readlane_b32 s0, v237, 40
	v_lshlrev_b32_e32 v2, 2, v36
	v_lshlrev_b64 v[38:39], 11, v[40:41]
	v_readlane_b32 s1, v237, 41
	v_and_b32_e32 v4, 0xfc, v2
	v_lshlrev_b32_e32 v34, 1, v4
	v_lshl_add_u64 v[0:1], s[0:1], 0, v[38:39]
	v_mov_b32_e32 v35, 0
	v_lshl_add_u64 v[2:3], s[76:77], 0, v[38:39]
	v_readlane_b32 s12, v237, 48
	v_lshl_add_u64 v[0:1], v[0:1], 0, v[34:35]
	v_lshl_add_u64 v[2:3], v[2:3], 0, v[34:35]
	v_lshlrev_b32_e32 v28, 2, v4
	v_readlane_b32 s14, v237, 50
	v_readlane_b32 s15, v237, 51
	global_load_dwordx2 v[42:43], v[0:1], off offset:1536 nt
	global_load_dwordx2 v[44:45], v[0:1], off offset:1024 nt
	global_load_dwordx2 v[48:49], v[0:1], off offset:512 nt
	global_load_dwordx2 v[52:53], v[0:1], off nt
	global_load_dwordx2 v[46:47], v[2:3], off offset:1536 nt
	global_load_dwordx2 v[50:51], v[2:3], off offset:1024 nt
	global_load_dwordx2 v[54:55], v[2:3], off offset:512 nt
	global_load_dwordx2 v[56:57], v[2:3], off nt
	v_readlane_b32 s16, v237, 52
	v_readlane_b32 s17, v237, 53
	global_load_dwordx4 v[0:3], v28, s[14:15]
	s_nop 3
	global_load_dwordx4 v[4:7], v28, s[16:17]
	global_load_dwordx4 v[8:11], v28, s[14:15] offset:1024
	global_load_dwordx4 v[12:15], v28, s[16:17] offset:1024
	global_load_dwordx4 v[16:19], v28, s[14:15] offset:2048
	global_load_dwordx4 v[20:23], v28, s[16:17] offset:2048
	global_load_dwordx4 v[24:27], v28, s[14:15] offset:3072
	s_nop 0
	global_load_dwordx4 v[28:31], v28, s[16:17] offset:3072
	v_readlane_b32 s13, v237, 49
	s_waitcnt vmcnt(17)
	v_lshlrev_b64 v[58:59], 12, v[40:41]
	v_and_b32_e32 v41, 63, v36
	v_readlane_b32 s12, v237, 56
	v_lshl_or_b32 v38, v41, 3, v38
	v_readlane_b32 s13, v237, 57
	v_readlane_b32 s18, v237, 54
	v_readlane_b32 s19, v237, 55
	v_lshl_add_u64 v[32:33], s[76:77], 0, v[34:35]
	v_lshl_add_u64 v[34:35], s[0:1], 0, v[34:35]
	v_lshl_or_b32 v58, v41, 4, v58
	s_ashr_i32 s97, s96, 31
	v_lshl_add_u64 v[38:39], s[12:13], 0, v[38:39]
	s_mov_b64 s[0:1], 0xa500000
	v_lshl_add_u64 v[36:37], s[18:19], 0, v[58:59]
	s_lshl_b64 s[4:5], s[96:97], 12
	v_lshl_add_u64 v[38:39], v[38:39], 0, s[0:1]
	s_lshl_b64 s[6:7], s[96:97], 11
	s_mov_b64 s[8:9], 0
	s_movk_i32 s12, 0x7fff
	s_mov_b32 s10, 0x3fb504f3
	v_mov_b32_e32 v41, 0x3727c5ac
	s_mov_b32 s13, 0x800000
	v_readlane_b32 s14, v237, 58
	v_readlane_b32 s15, v237, 59
	.p2alignl 6, 3212836864

.LBB0_928:
	s_or_b64 exec, exec, s[2:3]
	s_waitcnt vmcnt(0)
	s_barrier
	s_mov_b64 s[0:1], exec
	v_readlane_b32 s2, v237, 1
	v_readlane_b32 s3, v237, 2
	s_and_b64 s[2:3], s[0:1], s[2:3]
	s_mov_b64 exec, s[2:3]
	s_cbranch_execz .LBB0_980
	v_mov_b32_e32 v0, 0x13ff0
	s_waitcnt vmcnt(0) expcnt(0) lgkmcnt(0)
	ds_read_b32 v2, v0
	v_mov_b32_e32 v0, 0x13ff4
	ds_read_b32 v0, v0
	s_waitcnt lgkmcnt(1)
	v_cmp_ne_u32_e32 vcc, 0, v2
	s_cbranch_vccnz .LBB0_944
	v_readlane_b32 s40, v237, 56
	v_readlane_b32 s43, v237, 59
	v_readlane_b32 s2, v237, 0
	v_readlane_b32 s41, v237, 57
	s_mul_i32 s16, s43, s2
	s_add_u32 s2, s40, 0x4100200
	s_addc_u32 s3, s41, 0
	s_add_u32 s4, s40, 0x4100400
	s_addc_u32 s5, s41, 0
	s_add_u32 s6, s40, 0x4100500
	s_addc_u32 s7, s41, 0
	s_add_u32 s8, s40, 0x4100600
	s_addc_u32 s9, s41, 0
	s_add_u32 s10, s40, 0x4100700
	s_addc_u32 s11, s41, 0
	s_add_u32 s12, s40, 0x4100800
	s_addc_u32 s13, s41, 0
	s_add_u32 s14, s40, 0x4100900
	s_addc_u32 s15, s41, 0
	s_add_u32 s18, s40, 0x4100a00
	s_addc_u32 s19, s41, 0
	s_add_u32 s20, s40, 0x4100b00
	s_addc_u32 s21, s41, 0
	s_add_u32 s22, s40, 0x4100c00
	s_addc_u32 s23, s41, 0
	s_add_u32 s24, s40, 0x4100d00
	s_addc_u32 s25, s41, 0
	s_add_u32 s26, s40, 0x4100e00
	s_addc_u32 s27, s41, 0
	s_add_u32 s28, s40, 0x4100f00
	s_addc_u32 s29, s41, 0
	s_add_u32 s30, s40, 0x4101000
	s_addc_u32 s31, s41, 0
	s_add_u32 s34, s40, 0x4101100
	s_addc_u32 s35, s41, 0
	s_add_u32 s36, s40, 0x4101200
	s_addc_u32 s37, s41, 0
	v_readlane_b32 s42, v237, 58
	s_add_u32 s38, s40, 0x4101300
	s_mul_i32 s16, s16, s42
	s_addc_u32 s39, s41, 0
	s_mov_b32 s17, 1
	v_mov_b32_e32 v16, 0
	s_branch .LBB0_932
	.p2alignl 6, 3212836864

.LBB0_980:
	s_or_b64 exec, exec, s[0:1]
	v_readlane_b32 s0, v237, 56
	v_readlane_b32 s1, v237, 57
	s_add_u32 s4, s0, 0xa500000
	s_addc_u32 s5, s1, 0
	v_readlane_b32 s0, v237, 31
	s_waitcnt lgkmcnt(0)
	v_mov_b32_e32 v0, v128
	s_cmpk_gt_i32 s0, 0xbff
	v_readlane_b32 s2, v237, 58
	v_readlane_b32 s3, v237, 59
	s_barrier
	v_readlane_b32 s1, v237, 32
	s_cbranch_scc1 .LBB0_1015
	v_lshlrev_b32_e32 v0, 7, v0
	v_and_b32_e32 v129, 0xfffffc00, v0
	v_readlane_b32 s8, v237, 31
	v_readlane_b32 s0, v237, 56
	v_readlane_b32 s1, v237, 57
	v_lshl_add_u32 v0, s8, 17, v129
	v_readlane_b32 s2, v237, 58
	v_add_u32_e32 v134, 0x18100, v0
	s_lshl_b32 s12, s2, 17
	v_add_u32_e32 v135, 0x10100, v0
	v_add_u32_e32 v136, 0x8100, v0
	v_or_b32_e32 v137, 0x100, v0
	v_add_u32_e32 v138, 0x180c0, v0
	v_add_u32_e32 v139, 0x100c0, v0
	v_add_u32_e32 v140, 0x80c0, v0
	v_or_b32_e32 v141, 0xc0, v0
	s_mov_b64 s[6:7], -1
	s_movk_i32 s13, 0x50
	v_mov_b32_e32 v131, 0
	s_movk_i32 s14, 0xc00
	s_movk_i32 s15, 0xffc0
	s_movk_i32 s16, 0xa0
	s_movk_i32 s17, 0x110
	s_mov_b32 s1, 0
	v_readlane_b32 s9, v237, 32
	v_readlane_b32 s3, v237, 59
	s_branch .LBB0_983
	.p2alignl 6, 3212836864

.LBB0_987:
	v_readlane_b32 s24, v237, 56
	v_readlane_b32 s26, v237, 58
	s_add_i32 s19, s8, s26
	s_cmpk_gt_i32 s19, 0xbff
	s_cselect_b64 s[2:3], -1, 0
	s_cmpk_lt_i32 s19, 0xc00
	s_cselect_b64 s[6:7], -1, 0
	s_and_b64 s[10:11], s[6:7], exec
	s_cselect_b32 s8, s19, s8
	s_mul_hi_i32 s9, s8, 0x2aaaaaab
	s_lshr_b32 s10, s9, 31
	s_ashr_i32 s9, s9, 1
	s_add_i32 s9, s9, s10
	v_and_b32_e32 v66, 15, v142
	v_bfe_u32 v144, v142, 4, 2
	v_lshlrev_b32_e32 v67, 1, v143
	v_ashrrev_i32_e32 v68, 1, v142
	s_mul_i32 s10, s9, 0x7ff4
	v_lshl_add_u32 v146, v72, 1, v67
	v_lshl_add_u32 v147, v69, 1, v67
	v_lshl_add_u32 v148, v70, 1, v67
	v_lshl_add_u32 v149, v71, 1, v67
	v_or_b32_e32 v67, 0x3c0, v143
	v_and_or_b32 v145, v68, s15, v66
	v_lshlrev_b32_e32 v66, 4, v144
	v_and_b32_e32 v68, 0x4f, v142
	s_add_i32 s10, s10, s8
	s_lshl_b32 s21, s9, 17
	v_mad_u64_u32 v[132:133], s[8:9], v145, s16, v[66:67]
	v_mul_u32_u24_e32 v68, 0x50, v68
	v_lshl_add_u32 v133, v68, 1, v66
	v_add_u32_e32 v152, v67, v64
	v_add_u32_e32 v153, v67, v65
	s_mul_i32 s8, s0, 0x180000
	v_mov_b32_e32 v64, 0
	s_lshl_b32 s22, s10, 17
	v_add_u32_e32 v150, 0xf000, v133
	v_add_u32_e32 v151, 0xf040, v133
	v_add_u32_e32 v154, 0x8000, v152
	v_add_u32_e32 v155, 0x8000, v153
	v_add_u32_e32 v156, 0x10000, v152
	v_add_u32_e32 v157, 0x10000, v153
	v_add_u32_e32 v158, 0x18000, v152
	v_add_u32_e32 v159, 0x18000, v153
	v_add_u32_e32 v160, v129, v143
	v_subrev_u32_e32 v161, s8, v134
	v_subrev_u32_e32 v162, s8, v135
	v_subrev_u32_e32 v163, s8, v136
	v_subrev_u32_e32 v164, s8, v137
	v_subrev_u32_e32 v165, s8, v138
	v_subrev_u32_e32 v166, s8, v139
	v_subrev_u32_e32 v167, s8, v140
	v_subrev_u32_e32 v168, s8, v141
	s_mov_b32 s23, 0
	v_mov_b32_e32 v65, v64
	v_mov_b32_e32 v66, v64
	v_mov_b32_e32 v67, v64
	v_mov_b32_e32 v68, v64
	v_mov_b32_e32 v69, v64
	v_mov_b32_e32 v70, v64
	v_mov_b32_e32 v71, v64
	v_mov_b32_e32 v72, v64
	v_mov_b32_e32 v73, v64
	v_mov_b32_e32 v74, v64
	v_mov_b32_e32 v75, v64
	v_mov_b32_e32 v76, v64
	v_mov_b32_e32 v77, v64
	v_mov_b32_e32 v78, v64
	v_mov_b32_e32 v79, v64
	v_mov_b32_e32 v80, v64
	v_mov_b32_e32 v81, v64
	v_mov_b32_e32 v82, v64
	v_mov_b32_e32 v83, v64
	v_mov_b32_e32 v84, v64
	v_mov_b32_e32 v85, v64
	v_mov_b32_e32 v86, v64
	v_mov_b32_e32 v87, v64
	v_mov_b32_e32 v88, v64
	v_mov_b32_e32 v89, v64
	v_mov_b32_e32 v90, v64
	v_mov_b32_e32 v91, v64
	v_mov_b32_e32 v92, v64
	v_mov_b32_e32 v93, v64
	v_mov_b32_e32 v94, v64
	v_mov_b32_e32 v95, v64
	v_mov_b32_e32 v96, v64
	v_mov_b32_e32 v97, v64
	v_mov_b32_e32 v98, v64
	v_mov_b32_e32 v99, v64
	v_mov_b32_e32 v100, v64
	v_mov_b32_e32 v101, v64
	v_mov_b32_e32 v102, v64
	v_mov_b32_e32 v103, v64
	v_mov_b32_e32 v104, v64
	v_mov_b32_e32 v105, v64
	v_mov_b32_e32 v106, v64
	v_mov_b32_e32 v107, v64
	v_mov_b32_e32 v108, v64
	v_mov_b32_e32 v109, v64
	v_mov_b32_e32 v110, v64
	v_mov_b32_e32 v111, v64
	v_mov_b32_e32 v112, v64
	v_mov_b32_e32 v113, v64
	v_mov_b32_e32 v114, v64
	v_mov_b32_e32 v115, v64
	v_mov_b32_e32 v116, v64
	v_mov_b32_e32 v117, v64
	v_mov_b32_e32 v118, v64
	v_mov_b32_e32 v119, v64
	v_mov_b32_e32 v120, v64
	v_mov_b32_e32 v121, v64
	v_mov_b32_e32 v122, v64
	v_mov_b32_e32 v123, v64
	v_mov_b32_e32 v124, v64
	v_mov_b32_e32 v125, v64
	v_mov_b32_e32 v126, v64
	v_mov_b32_e32 v127, v64
	v_readlane_b32 s25, v237, 57
	v_readlane_b32 s27, v237, 59
	s_branch .LBB0_989
	.p2alignl 6, 3212836864

.LBB0_1015:
	s_waitcnt vmcnt(0)
	s_barrier
	s_mov_b64 s[0:1], exec
	v_readlane_b32 s2, v237, 1
	v_readlane_b32 s3, v237, 2
	s_and_b64 s[2:3], s[0:1], s[2:3]
	s_mov_b64 exec, s[2:3]
	s_cbranch_execz .LBB0_1067
	v_mov_b32_e32 v0, 0x13ff0
	s_waitcnt vmcnt(0) expcnt(0) lgkmcnt(0)
	ds_read_b32 v2, v0
	v_mov_b32_e32 v0, 0x13ff4
	ds_read_b32 v0, v0
	s_waitcnt lgkmcnt(1)
	v_cmp_ne_u32_e32 vcc, 0, v2
	s_cbranch_vccnz .LBB0_1031
	v_readlane_b32 s40, v237, 56
	v_readlane_b32 s43, v237, 59
	v_readlane_b32 s2, v237, 0
	v_readlane_b32 s41, v237, 57
	s_mul_i32 s16, s43, s2
	s_add_u32 s2, s40, 0x4100200
	s_addc_u32 s3, s41, 0
	s_add_u32 s6, s40, 0x4100400
	s_addc_u32 s7, s41, 0
	s_add_u32 s8, s40, 0x4100500
	s_addc_u32 s9, s41, 0
	s_add_u32 s10, s40, 0x4100600
	s_addc_u32 s11, s41, 0
	s_add_u32 s12, s40, 0x4100700
	s_addc_u32 s13, s41, 0
	s_add_u32 s14, s40, 0x4100800
	s_addc_u32 s15, s41, 0
	s_add_u32 s18, s40, 0x4100900
	s_addc_u32 s19, s41, 0
	s_add_u32 s20, s40, 0x4100a00
	s_addc_u32 s21, s41, 0
	s_add_u32 s22, s40, 0x4100b00
	s_addc_u32 s23, s41, 0
	s_add_u32 s24, s40, 0x4100c00
	s_addc_u32 s25, s41, 0
	s_add_u32 s26, s40, 0x4100d00
	s_addc_u32 s27, s41, 0
	s_add_u32 s28, s40, 0x4100e00
	s_addc_u32 s29, s41, 0
	s_add_u32 s30, s40, 0x4100f00
	s_addc_u32 s31, s41, 0
	s_add_u32 s34, s40, 0x4101000
	s_addc_u32 s35, s41, 0
	s_add_u32 s36, s40, 0x4101100
	s_addc_u32 s37, s41, 0
	s_add_u32 s38, s40, 0x4101200
	s_addc_u32 s39, s41, 0
	v_readlane_b32 s42, v237, 58
	s_add_u32 s40, s40, 0x4101300
	s_mul_i32 s16, s16, s42
	s_addc_u32 s41, s41, 0
	s_mov_b32 s17, 1
	v_mov_b32_e32 v16, 0
	s_branch .LBB0_1019
	.p2alignl 6, 3212836864

.LBB0_1019:
	global_load_dword v15, v16, s[6:7] sc1
	s_waitcnt lgkmcnt(0)
	global_load_dword v0, v16, s[8:9] sc1
	global_load_dword v1, v16, s[10:11] sc1
	global_load_dword v2, v16, s[12:13] sc1
	global_load_dword v3, v16, s[14:15] sc1
	global_load_dword v4, v16, s[18:19] sc1
	global_load_dword v5, v16, s[20:21] sc1
	global_load_dword v6, v16, s[22:23] sc1
	global_load_dword v7, v16, s[24:25] sc1
	global_load_dword v8, v16, s[26:27] sc1
	global_load_dword v9, v16, s[28:29] sc1
	global_load_dword v10, v16, s[30:31] sc1
	global_load_dword v11, v16, s[34:35] sc1
	global_load_dword v12, v16, s[36:37] sc1
	global_load_dword v13, v16, s[38:39] sc1
	global_load_dword v14, v16, s[40:41] sc1
	s_mov_b64 s[42:43], -1
	s_mov_b64 s[44:45], -1
	s_waitcnt vmcnt(14)
	v_add_u32_e32 v17, v0, v15
	s_waitcnt vmcnt(13)
	v_add_u32_e32 v17, v17, v1
	s_waitcnt vmcnt(12)
	v_add_u32_e32 v17, v17, v2
	s_waitcnt vmcnt(11)
	v_add_u32_e32 v17, v17, v3
	s_waitcnt vmcnt(10)
	v_add_u32_e32 v17, v17, v4
	s_waitcnt vmcnt(9)
	v_add_u32_e32 v17, v17, v5
	s_waitcnt vmcnt(8)
	v_add_u32_e32 v17, v17, v6
	s_waitcnt vmcnt(7)
	v_add_u32_e32 v17, v17, v7
	s_waitcnt vmcnt(6)
	v_add_u32_e32 v17, v17, v8
	s_waitcnt vmcnt(5)
	v_add_u32_e32 v17, v17, v9
	s_waitcnt vmcnt(4)
	v_add_u32_e32 v17, v17, v10
	s_waitcnt vmcnt(3)
	v_add_u32_e32 v17, v17, v11
	s_waitcnt vmcnt(2)
	v_add_u32_e32 v17, v17, v12
	s_waitcnt vmcnt(1)
	v_add_u32_e32 v17, v17, v13
	s_waitcnt vmcnt(0)
	v_add_u32_e32 v17, v17, v14
	v_cmp_eq_u32_e32 vcc, s16, v17
	s_cbranch_vccnz .LBB0_1018
	s_and_b32 s33, s17, 0xff
	s_cmp_eq_u32 s33, 0
	s_mov_b64 s[46:47], -1
	s_sleep 1
	s_cbranch_scc1 .LBB0_1023
	s_and_b64 vcc, exec, s[46:47]
	s_cbranch_vccz .LBB0_1018
	.p2alignl 6, 3212836864

.LBB0_1067:
	s_or_b64 exec, exec, s[0:1]
	v_readlane_b32 s0, v237, 31
	s_cmpk_gt_i32 s0, 0x10ff
	v_mbcnt_lo_u32_b32 v40, -1, 0
	s_waitcnt lgkmcnt(0)
	s_barrier
	v_readlane_b32 s1, v237, 32
	s_cbranch_scc1 .LBB0_1078
	v_readlane_b32 s0, v237, 56
	v_readlane_b32 s1, v237, 57
	s_add_u32 s8, s0, 0x3d4a000
	v_readlane_b32 s6, v237, 31
	s_addc_u32 s9, s1, 0
	s_lshl_b32 s0, s6, 7
	v_mbcnt_hi_u32_b32 v39, -1, v40
	v_readlane_b32 s2, v237, 58
	v_readlane_b32 s3, v237, 59
	s_add_i32 s10, s0, 0xfff80000
	v_readlane_b32 s0, v237, 39
	v_and_b32_e32 v0, 64, v39
	s_lshl_b32 s11, s2, 7
	s_add_i32 s12, s0, 0xfff00000
	s_lshl_b32 s13, s2, 8
	s_mov_b32 s3, 0
	s_movk_i32 s14, 0x80
	s_movk_i32 s15, 0xc00
	v_mov_b32_e32 v33, 0
	s_mov_b32 s16, 0x2aaaaaab
	s_movk_i32 s17, 0xffe8
	s_movk_i32 s18, 0xa0
	s_movk_i32 s19, 0x1a0
	s_movk_i32 s20, 0xffbe
	s_movk_i32 s21, 0xffbd
	s_movk_i32 s22, 0xffbc
	s_movk_i32 s23, 0xffaf
	s_movk_i32 s24, 0xffae
	s_movk_i32 s25, 0xffad
	s_movk_i32 s26, 0xffac
	s_movk_i32 s27, 0xff9f
	s_movk_i32 s28, 0xff9e
	s_movk_i32 s29, 0xff9d
	s_movk_i32 s30, 0xff9c
	s_movk_i32 s31, 0xff8f
	s_movk_i32 s33, 0xff8e
	s_movk_i32 s34, 0xff8d
	s_movk_i32 s35, 0xff8c
	s_mov_b32 s36, 0x3fb8aa3b
	v_mov_b32_e32 v38, 0xf149f2ca
	v_xor_b32_e32 v41, 16, v39
	v_add_u32_e32 v42, 64, v0
	v_xor_b32_e32 v43, 32, v39
	s_mov_b32 s37, s6
	v_readlane_b32 s7, v237, 32
	s_branch .LBB0_1070
	.p2alignl 6, 3212836864

.LBB0_1070:
	s_cmpk_gt_i32 s37, 0xfff
	s_mov_b64 s[0:1], -1
	s_cbranch_scc0 .LBB0_1076
	v_mov_b32_e32 v0, v128
	s_and_b32 s0, s10, 0x4000
	s_and_b32 s1, s12, 0x3f00
	s_or_b32 s2, s0, s1
	v_and_b32_e32 v2, 0xffffffc0, v0
	v_ashrrev_i32_e32 v3, 31, v2
	s_lshl_b32 s0, s37, 1
	v_and_b32_e32 v1, 63, v0
	v_lshl_add_u64 v[2:3], v[2:3], 0, s[2:3]
	s_and_b32 s6, s0, 0x80
	v_mad_u64_u32 v[4:5], s[0:1], v2, s15, 0
	v_lshlrev_b32_e32 v1, 1, v1
	v_readlane_b32 s40, v237, 56
	v_mad_i32_i24 v3, v3, s15, v5
	v_or3_b32 v2, v4, s6, v1
	v_readlane_b32 s41, v237, 57
	v_mov_b32_e32 v1, 0
	s_mov_b64 s[0:1], 0
	v_lshl_add_u64 v[2:3], s[40:41], 0, v[2:3]
	v_readlane_b32 s42, v237, 58
	v_readlane_b32 s43, v237, 59
	.p2alignl 6, 3212836864

.LBB0_1130:
	s_or_b64 exec, exec, s[0:1]
	v_readlane_b32 s0, v237, 37
	v_readlane_b32 s1, v237, 38
	s_and_b64 vcc, exec, s[0:1]
	s_waitcnt lgkmcnt(0)
	s_barrier
	s_cbranch_vccnz .LBB0_1396
	v_readlane_b32 s8, v237, 56
	v_readlane_b32 s9, v237, 57
	s_add_u32 s2, s8, 0x1c500000
	s_addc_u32 s3, s9, 0
	s_add_u32 s20, s8, 0x1c900000
	s_addc_u32 s21, s9, 0
	s_add_u32 s16, s8, 0x3d4a000
	s_addc_u32 s17, s9, 0
	v_mbcnt_hi_u32_b32 v31, -1, v40
	v_readlane_b32 s10, v237, 58
	s_add_u32 s33, s8, 0x3d00100
	v_readlane_b32 s0, v237, 31
	v_and_b32_e32 v0, 64, v31
	s_addc_u32 s36, s9, 0
	s_lshl_b32 s37, s0, 3
	s_lshl_b32 s38, s10, 3
	s_movk_i32 s39, 0xc00
	v_mov_b64_e32 v[16:17], s[76:77]
	s_mov_b32 s23, 0
	v_mov_b32_e32 v19, 0
	s_movk_i32 s40, 0xa0
	s_movk_i32 s41, 0x220
	v_mov_b32_e32 v30, 0xf149f2ca
	v_xor_b32_e32 v32, 16, v31
	v_add_u32_e32 v33, 64, v0
	v_xor_b32_e32 v34, 32, v31
	s_mov_b32 s42, 0xfe967699
	v_mov_b32_e32 v35, -1
	v_mov_b32_e32 v36, 1
	s_mov_b32 s43, 0x55555556
	v_mov_b32_e32 v37, 0x12c00
	v_mov_b32_e32 v38, 0xff61b1e6
	v_mov_b32_e32 v39, 0x12d00
	v_mov_b32_e32 v41, 0x12e00
	s_mov_b32 s44, s0
	v_readlane_b32 s11, v237, 59
	v_readlane_b32 s1, v237, 32
	s_branch .LBB0_1133
	.p2alignl 6, 3212836864

.LBB0_1158:
	s_or_b64 exec, exec, s[18:19]
	v_cmp_ne_u32_e64 s[0:1], v21, v45
	s_nop 1
	v_cndmask_b32_e64 v0, v38, v0, s[0:1]
	v_cmp_ne_u32_e64 s[0:1], v27, v45
	s_nop 1
	v_cndmask_b32_e64 v42, v38, v42, s[0:1]
	v_cmp_ne_u32_e64 s[0:1], v28, v45
	s_nop 1
	v_cndmask_b32_e64 v43, v38, v43, s[0:1]
	v_cmp_ne_u32_e64 s[0:1], v29, v45
	s_nop 1
	v_cndmask_b32_e64 v44, v38, v44, s[0:1]
	v_cmp_gt_f32_e64 s[0:1], v42, v0
	s_nop 1
	v_cndmask_b32_e64 v46, v0, v42, s[0:1]
	v_cndmask_b32_e64 v45, v21, v27, s[0:1]
	v_cmp_gt_f32_e64 s[0:1], v43, v46
	s_nop 1
	v_cndmask_b32_e64 v46, v46, v43, s[0:1]
	v_cndmask_b32_e64 v45, v45, v28, s[0:1]
	v_cmp_gt_f32_e64 s[0:1], v44, v46
	s_nop 1
	v_cndmask_b32_e64 v46, v46, v44, s[0:1]
	v_cndmask_b32_e64 v45, v45, v29, s[0:1]
	s_nop 4
	v_mov_b32_dpp v47, v46 row_ror:8 row_mask:0xf bank_mask:0xf
	v_mov_b32_dpp v48, v45 row_ror:8 row_mask:0xf bank_mask:0xf
	v_cmp_gt_f32_e64 s[30:31], v47, v46
	v_cmp_eq_f32_e64 s[0:1], v47, v46
	v_cmp_lt_i32_e64 s[18:19], v48, v45
	s_and_b64 s[0:1], s[0:1], s[18:19]
	s_or_b64 s[30:31], s[30:31], s[0:1]
	v_cndmask_b32_e64 v46, v46, v47, s[30:31]
	v_cndmask_b32_e64 v45, v45, v48, s[30:31]
	s_nop 4
	v_mov_b32_dpp v47, v46 row_ror:4 row_mask:0xf bank_mask:0xf
	v_mov_b32_dpp v48, v45 row_ror:4 row_mask:0xf bank_mask:0xf
	v_cmp_gt_f32_e64 s[30:31], v47, v46
	v_cmp_eq_f32_e64 s[0:1], v47, v46
	v_cmp_lt_i32_e64 s[18:19], v48, v45
	s_and_b64 s[0:1], s[0:1], s[18:19]
	s_or_b64 s[30:31], s[30:31], s[0:1]
	v_cndmask_b32_e64 v46, v46, v47, s[30:31]
	v_cndmask_b32_e64 v45, v45, v48, s[30:31]
	s_nop 4
	v_mov_b32_dpp v47, v46 row_ror:2 row_mask:0xf bank_mask:0xf
	v_mov_b32_dpp v48, v45 row_ror:2 row_mask:0xf bank_mask:0xf
	v_cmp_gt_f32_e64 s[30:31], v47, v46
	v_cmp_eq_f32_e64 s[0:1], v47, v46
	v_cmp_lt_i32_e64 s[18:19], v48, v45
	s_and_b64 s[0:1], s[0:1], s[18:19]
	s_or_b64 s[30:31], s[30:31], s[0:1]
	v_cndmask_b32_e64 v46, v46, v47, s[30:31]
	v_cndmask_b32_e64 v45, v45, v48, s[30:31]
	ds_bpermute_b32 v47, v12, v46
	s_waitcnt lgkmcnt(1)
	ds_bpermute_b32 v48, v12, v45
	s_waitcnt lgkmcnt(1)
	v_cmp_lt_f32_e64 s[30:31], v46, v47
	v_cmp_nlt_f32_e64 s[0:1], v46, v47
	s_and_saveexec_b64 s[34:35], s[0:1]
	s_cbranch_execz .LBB0_1173
	v_cmp_eq_f32_e64 s[0:1], v46, v47
	s_waitcnt lgkmcnt(0)
	v_cmp_lt_i32_e64 s[18:19], v48, v45
	s_and_b64 s[0:1], s[0:1], s[18:19]
	s_andn2_b64 s[18:19], s[30:31], exec
	s_and_b64 s[0:1], s[0:1], exec
	s_or_b64 s[30:31], s[18:19], s[0:1]
	s_or_b64 exec, exec, s[34:35]
	s_and_saveexec_b64 s[0:1], s[30:31]
	s_cbranch_execnz .LBB0_1174
	.p2alignl 6, 3212836864

.LBB0_1179:
	s_or_b64 exec, exec, s[18:19]
	v_cmp_ne_u32_e64 s[0:1], v21, v45
	s_nop 1
	v_cndmask_b32_e64 v0, v38, v0, s[0:1]
	v_cmp_ne_u32_e64 s[0:1], v27, v45
	s_nop 1
	v_cndmask_b32_e64 v42, v38, v42, s[0:1]
	v_cmp_ne_u32_e64 s[0:1], v28, v45
	s_nop 1
	v_cndmask_b32_e64 v43, v38, v43, s[0:1]
	v_cmp_ne_u32_e64 s[0:1], v29, v45
	s_nop 1
	v_cndmask_b32_e64 v44, v38, v44, s[0:1]
	v_cmp_gt_f32_e64 s[0:1], v42, v0
	s_nop 1
	v_cndmask_b32_e64 v0, v0, v42, s[0:1]
	v_cndmask_b32_e64 v45, v21, v27, s[0:1]
	v_cmp_gt_f32_e64 s[0:1], v43, v0
	s_nop 1
	v_cndmask_b32_e64 v43, v0, v43, s[0:1]
	v_cndmask_b32_e64 v42, v45, v28, s[0:1]
	v_cmp_gt_f32_e64 s[0:1], v44, v43
	s_nop 1
	v_cndmask_b32_e64 v0, v42, v29, s[0:1]
	v_cndmask_b32_e64 v42, v43, v44, s[0:1]
	s_nop 4
	v_mov_b32_dpp v43, v42 row_ror:8 row_mask:0xf bank_mask:0xf
	v_mov_b32_dpp v44, v0 row_ror:8 row_mask:0xf bank_mask:0xf
	v_cmp_gt_f32_e64 s[30:31], v43, v42
	v_cmp_eq_f32_e64 s[0:1], v43, v42
	v_cmp_lt_i32_e64 s[18:19], v44, v0
	s_and_b64 s[0:1], s[0:1], s[18:19]
	s_or_b64 s[30:31], s[30:31], s[0:1]
	v_cndmask_b32_e64 v42, v42, v43, s[30:31]
	v_cndmask_b32_e64 v0, v0, v44, s[30:31]
	s_nop 4
	v_mov_b32_dpp v43, v42 row_ror:4 row_mask:0xf bank_mask:0xf
	v_mov_b32_dpp v44, v0 row_ror:4 row_mask:0xf bank_mask:0xf
	v_cmp_gt_f32_e64 s[30:31], v43, v42
	v_cmp_eq_f32_e64 s[0:1], v43, v42
	v_cmp_lt_i32_e64 s[18:19], v44, v0
	s_and_b64 s[0:1], s[0:1], s[18:19]
	s_or_b64 s[30:31], s[30:31], s[0:1]
	v_cndmask_b32_e64 v42, v42, v43, s[30:31]
	v_cndmask_b32_e64 v0, v0, v44, s[30:31]
	s_nop 4
	v_mov_b32_dpp v43, v42 row_ror:2 row_mask:0xf bank_mask:0xf
	v_mov_b32_dpp v44, v0 row_ror:2 row_mask:0xf bank_mask:0xf
	v_cmp_gt_f32_e64 s[30:31], v43, v42
	v_cmp_eq_f32_e64 s[0:1], v43, v42
	v_cmp_lt_i32_e64 s[18:19], v44, v0
	s_and_b64 s[0:1], s[0:1], s[18:19]
	s_or_b64 s[30:31], s[30:31], s[0:1]
	v_cndmask_b32_e64 v42, v42, v43, s[30:31]
	v_cndmask_b32_e64 v0, v0, v44, s[30:31]
	ds_bpermute_b32 v43, v12, v42
	s_waitcnt lgkmcnt(1)
	ds_bpermute_b32 v44, v12, v0
	s_waitcnt lgkmcnt(1)
	v_cmp_lt_f32_e64 s[30:31], v42, v43
	v_cmp_nlt_f32_e64 s[0:1], v42, v43
	s_and_saveexec_b64 s[34:35], s[0:1]
	s_cbranch_execz .LBB0_1194
	v_cmp_eq_f32_e64 s[0:1], v42, v43
	s_waitcnt lgkmcnt(0)
	v_cmp_lt_i32_e64 s[18:19], v44, v0
	s_and_b64 s[0:1], s[0:1], s[18:19]
	s_andn2_b64 s[18:19], s[30:31], exec
	s_and_b64 s[0:1], s[0:1], exec
	s_or_b64 s[30:31], s[18:19], s[0:1]
	s_or_b64 exec, exec, s[34:35]
	s_and_saveexec_b64 s[0:1], s[30:31]
	s_cbranch_execnz .LBB0_1195
	.p2alignl 6, 3212836864

.LBB0_1221:
	s_or_b64 exec, exec, s[18:19]
	v_cmp_ne_u32_e64 s[0:1], v21, v42
	s_nop 1
	v_cndmask_b32_e64 v13, v38, v25, s[0:1]
	v_cmp_ne_u32_e64 s[0:1], v27, v42
	s_nop 1
	v_cndmask_b32_e64 v24, v38, v24, s[0:1]
	v_cmp_ne_u32_e64 s[0:1], v28, v42
	s_nop 1
	v_cndmask_b32_e64 v9, v38, v9, s[0:1]
	v_cmp_ne_u32_e64 s[0:1], v29, v42
	s_nop 1
	v_cndmask_b32_e64 v5, v38, v5, s[0:1]
	v_cmp_gt_f32_e64 s[0:1], v24, v13
	s_nop 1
	v_cndmask_b32_e64 v42, v13, v24, s[0:1]
	v_cndmask_b32_e64 v25, v21, v27, s[0:1]
	v_cmp_gt_f32_e64 s[0:1], v9, v42
	s_nop 1
	v_cndmask_b32_e64 v42, v42, v9, s[0:1]
	v_cndmask_b32_e64 v25, v25, v28, s[0:1]
	v_cmp_gt_f32_e64 s[0:1], v5, v42
	s_nop 1
	v_cndmask_b32_e64 v42, v42, v5, s[0:1]
	v_cndmask_b32_e64 v25, v25, v29, s[0:1]
	s_nop 4
	v_mov_b32_dpp v43, v42 row_ror:8 row_mask:0xf bank_mask:0xf
	v_mov_b32_dpp v44, v25 row_ror:8 row_mask:0xf bank_mask:0xf
	v_cmp_gt_f32_e64 s[30:31], v43, v42
	v_cmp_eq_f32_e64 s[0:1], v43, v42
	v_cmp_lt_i32_e64 s[18:19], v44, v25
	s_and_b64 s[0:1], s[0:1], s[18:19]
	s_or_b64 s[30:31], s[30:31], s[0:1]
	v_cndmask_b32_e64 v42, v42, v43, s[30:31]
	v_cndmask_b32_e64 v25, v25, v44, s[30:31]
	s_nop 4
	v_mov_b32_dpp v43, v42 row_ror:4 row_mask:0xf bank_mask:0xf
	v_mov_b32_dpp v44, v25 row_ror:4 row_mask:0xf bank_mask:0xf
	v_cmp_gt_f32_e64 s[30:31], v43, v42
	v_cmp_eq_f32_e64 s[0:1], v43, v42
	v_cmp_lt_i32_e64 s[18:19], v44, v25
	s_and_b64 s[0:1], s[0:1], s[18:19]
	s_or_b64 s[30:31], s[30:31], s[0:1]
	v_cndmask_b32_e64 v42, v42, v43, s[30:31]
	v_cndmask_b32_e64 v25, v25, v44, s[30:31]
	s_nop 4
	v_mov_b32_dpp v43, v42 row_ror:2 row_mask:0xf bank_mask:0xf
	v_mov_b32_dpp v44, v25 row_ror:2 row_mask:0xf bank_mask:0xf
	v_cmp_gt_f32_e64 s[30:31], v43, v42
	v_cmp_eq_f32_e64 s[0:1], v43, v42
	v_cmp_lt_i32_e64 s[18:19], v44, v25
	s_and_b64 s[0:1], s[0:1], s[18:19]
	s_or_b64 s[30:31], s[30:31], s[0:1]
	v_cndmask_b32_e64 v42, v42, v43, s[30:31]
	v_cndmask_b32_e64 v25, v25, v44, s[30:31]
	ds_bpermute_b32 v43, v12, v42
	s_waitcnt lgkmcnt(1)
	ds_bpermute_b32 v44, v12, v25
	s_waitcnt lgkmcnt(1)
	v_cmp_lt_f32_e64 s[30:31], v42, v43
	v_cmp_nlt_f32_e64 s[0:1], v42, v43
	s_and_saveexec_b64 s[34:35], s[0:1]
	s_cbranch_execz .LBB0_1236
	v_cmp_eq_f32_e64 s[0:1], v42, v43
	s_waitcnt lgkmcnt(0)
	v_cmp_lt_i32_e64 s[18:19], v44, v25
	s_and_b64 s[0:1], s[0:1], s[18:19]
	s_andn2_b64 s[18:19], s[30:31], exec
	s_and_b64 s[0:1], s[0:1], exec
	s_or_b64 s[30:31], s[18:19], s[0:1]
	s_or_b64 exec, exec, s[34:35]
	s_and_saveexec_b64 s[0:1], s[30:31]
	s_cbranch_execnz .LBB0_1237
	.p2alignl 6, 3212836864

.LBB0_1242:
	s_or_b64 exec, exec, s[18:19]
	v_cmp_ne_u32_e64 s[0:1], v21, v25
	s_nop 1
	v_cndmask_b32_e64 v13, v38, v13, s[0:1]
	v_cmp_ne_u32_e64 s[0:1], v27, v25
	s_nop 1
	v_cndmask_b32_e64 v24, v38, v24, s[0:1]
	v_cmp_ne_u32_e64 s[0:1], v28, v25
	s_nop 1
	v_cndmask_b32_e64 v9, v38, v9, s[0:1]
	v_cmp_ne_u32_e64 s[0:1], v29, v25
	s_nop 1
	v_cndmask_b32_e64 v25, v38, v5, s[0:1]
	v_cmp_gt_f32_e64 s[0:1], v24, v13
	s_nop 1
	v_cndmask_b32_e64 v13, v13, v24, s[0:1]
	v_cndmask_b32_e64 v5, v21, v27, s[0:1]
	v_cmp_gt_f32_e64 s[0:1], v9, v13
	s_nop 1
	v_cndmask_b32_e64 v9, v13, v9, s[0:1]
	v_cndmask_b32_e64 v5, v5, v28, s[0:1]
	v_cmp_gt_f32_e64 s[0:1], v25, v9
	s_nop 1
	v_cndmask_b32_e64 v9, v9, v25, s[0:1]
	v_cndmask_b32_e64 v5, v5, v29, s[0:1]
	s_nop 4
	v_mov_b32_dpp v13, v9 row_ror:8 row_mask:0xf bank_mask:0xf
	v_mov_b32_dpp v24, v5 row_ror:8 row_mask:0xf bank_mask:0xf
	v_cmp_gt_f32_e64 s[30:31], v13, v9
	v_cmp_eq_f32_e64 s[0:1], v13, v9
	v_cmp_lt_i32_e64 s[18:19], v24, v5
	s_and_b64 s[0:1], s[0:1], s[18:19]
	s_or_b64 s[30:31], s[30:31], s[0:1]
	v_cndmask_b32_e64 v9, v9, v13, s[30:31]
	v_cndmask_b32_e64 v5, v5, v24, s[30:31]
	s_nop 4
	v_mov_b32_dpp v13, v9 row_ror:4 row_mask:0xf bank_mask:0xf
	v_mov_b32_dpp v24, v5 row_ror:4 row_mask:0xf bank_mask:0xf
	v_cmp_gt_f32_e64 s[30:31], v13, v9
	v_cmp_eq_f32_e64 s[0:1], v13, v9
	v_cmp_lt_i32_e64 s[18:19], v24, v5
	s_and_b64 s[0:1], s[0:1], s[18:19]
	s_or_b64 s[30:31], s[30:31], s[0:1]
	v_cndmask_b32_e64 v9, v9, v13, s[30:31]
	v_cndmask_b32_e64 v5, v5, v24, s[30:31]
	s_nop 4
	v_mov_b32_dpp v13, v9 row_ror:2 row_mask:0xf bank_mask:0xf
	v_mov_b32_dpp v24, v5 row_ror:2 row_mask:0xf bank_mask:0xf
	v_cmp_gt_f32_e64 s[30:31], v13, v9
	v_cmp_eq_f32_e64 s[0:1], v13, v9
	v_cmp_lt_i32_e64 s[18:19], v24, v5
	s_and_b64 s[0:1], s[0:1], s[18:19]
	s_or_b64 s[30:31], s[30:31], s[0:1]
	v_cndmask_b32_e64 v9, v9, v13, s[30:31]
	v_cndmask_b32_e64 v5, v5, v24, s[30:31]
	ds_bpermute_b32 v13, v12, v9
	s_waitcnt lgkmcnt(1)
	ds_bpermute_b32 v24, v12, v5
	s_waitcnt lgkmcnt(1)
	v_cmp_lt_f32_e64 s[30:31], v9, v13
	v_cmp_nlt_f32_e64 s[0:1], v9, v13
	s_and_saveexec_b64 s[34:35], s[0:1]
	s_cbranch_execz .LBB0_1257
	v_cmp_eq_f32_e64 s[0:1], v9, v13
	s_waitcnt lgkmcnt(0)
	v_cmp_lt_i32_e64 s[18:19], v24, v5
	s_and_b64 s[0:1], s[0:1], s[18:19]
	s_andn2_b64 s[18:19], s[30:31], exec
	s_and_b64 s[0:1], s[0:1], exec
	s_or_b64 s[30:31], s[18:19], s[0:1]
	s_or_b64 exec, exec, s[34:35]
	s_and_saveexec_b64 s[0:1], s[30:31]
	s_cbranch_execnz .LBB0_1258
	.p2alignl 6, 3212836864

.LBB0_1284:
	s_or_b64 exec, exec, s[18:19]
	v_cmp_ne_u32_e64 s[0:1], v21, v10
	s_nop 1
	v_cndmask_b32_e64 v9, v38, v9, s[0:1]
	v_cmp_ne_u32_e64 s[0:1], v27, v10
	s_nop 1
	v_cndmask_b32_e64 v6, v38, v6, s[0:1]
	v_cmp_ne_u32_e64 s[0:1], v28, v10
	s_nop 1
	v_cndmask_b32_e64 v5, v38, v5, s[0:1]
	v_cmp_ne_u32_e64 s[0:1], v29, v10
	s_nop 1
	v_cndmask_b32_e64 v2, v38, v2, s[0:1]
	v_cmp_gt_f32_e64 s[0:1], v6, v9
	s_nop 1
	v_cndmask_b32_e64 v13, v9, v6, s[0:1]
	v_cndmask_b32_e64 v10, v21, v27, s[0:1]
	v_cmp_gt_f32_e64 s[0:1], v5, v13
	s_nop 1
	v_cndmask_b32_e64 v13, v13, v5, s[0:1]
	v_cndmask_b32_e64 v10, v10, v28, s[0:1]
	v_cmp_gt_f32_e64 s[0:1], v2, v13
	s_nop 1
	v_cndmask_b32_e64 v13, v13, v2, s[0:1]
	v_cndmask_b32_e64 v10, v10, v29, s[0:1]
	s_nop 4
	v_mov_b32_dpp v14, v13 row_ror:8 row_mask:0xf bank_mask:0xf
	v_mov_b32_dpp v24, v10 row_ror:8 row_mask:0xf bank_mask:0xf
	v_cmp_gt_f32_e64 s[30:31], v14, v13
	v_cmp_eq_f32_e64 s[0:1], v14, v13
	v_cmp_lt_i32_e64 s[18:19], v24, v10
	s_and_b64 s[0:1], s[0:1], s[18:19]
	s_or_b64 s[30:31], s[30:31], s[0:1]
	v_cndmask_b32_e64 v13, v13, v14, s[30:31]
	v_cndmask_b32_e64 v10, v10, v24, s[30:31]
	s_nop 4
	v_mov_b32_dpp v14, v13 row_ror:4 row_mask:0xf bank_mask:0xf
	v_mov_b32_dpp v24, v10 row_ror:4 row_mask:0xf bank_mask:0xf
	v_cmp_gt_f32_e64 s[30:31], v14, v13
	v_cmp_eq_f32_e64 s[0:1], v14, v13
	v_cmp_lt_i32_e64 s[18:19], v24, v10
	s_and_b64 s[0:1], s[0:1], s[18:19]
	s_or_b64 s[30:31], s[30:31], s[0:1]
	v_cndmask_b32_e64 v13, v13, v14, s[30:31]
	v_cndmask_b32_e64 v10, v10, v24, s[30:31]
	s_nop 4
	v_mov_b32_dpp v14, v13 row_ror:2 row_mask:0xf bank_mask:0xf
	v_mov_b32_dpp v24, v10 row_ror:2 row_mask:0xf bank_mask:0xf
	v_cmp_gt_f32_e64 s[30:31], v14, v13
	v_cmp_eq_f32_e64 s[0:1], v14, v13
	v_cmp_lt_i32_e64 s[18:19], v24, v10
	s_and_b64 s[0:1], s[0:1], s[18:19]
	s_or_b64 s[30:31], s[30:31], s[0:1]
	v_cndmask_b32_e64 v13, v13, v14, s[30:31]
	v_cndmask_b32_e64 v10, v10, v24, s[30:31]
	ds_bpermute_b32 v14, v12, v13
	s_waitcnt lgkmcnt(1)
	ds_bpermute_b32 v24, v12, v10
	s_waitcnt lgkmcnt(1)
	v_cmp_lt_f32_e64 s[30:31], v13, v14
	v_cmp_nlt_f32_e64 s[0:1], v13, v14
	s_and_saveexec_b64 s[34:35], s[0:1]
	s_cbranch_execz .LBB0_1299
	v_cmp_eq_f32_e64 s[0:1], v13, v14
	s_waitcnt lgkmcnt(0)
	v_cmp_lt_i32_e64 s[18:19], v24, v10
	s_and_b64 s[0:1], s[0:1], s[18:19]
	s_andn2_b64 s[18:19], s[30:31], exec
	s_and_b64 s[0:1], s[0:1], exec
	s_or_b64 s[30:31], s[18:19], s[0:1]
	s_or_b64 exec, exec, s[34:35]
	s_and_saveexec_b64 s[0:1], s[30:31]
	s_cbranch_execnz .LBB0_1300
	.p2alignl 6, 3212836864

.LBB0_1305:
	s_or_b64 exec, exec, s[18:19]
	v_cmp_ne_u32_e64 s[0:1], v21, v10
	s_nop 1
	v_cndmask_b32_e64 v9, v38, v9, s[0:1]
	v_cmp_ne_u32_e64 s[0:1], v27, v10
	s_nop 1
	v_cndmask_b32_e64 v6, v38, v6, s[0:1]
	v_cmp_ne_u32_e64 s[0:1], v28, v10
	s_nop 1
	v_cndmask_b32_e64 v5, v38, v5, s[0:1]
	v_cmp_ne_u32_e64 s[0:1], v29, v10
	s_nop 1
	v_cndmask_b32_e64 v10, v38, v2, s[0:1]
	v_cmp_gt_f32_e64 s[0:1], v6, v9
	s_nop 1
	v_cndmask_b32_e64 v6, v9, v6, s[0:1]
	v_cndmask_b32_e64 v2, v21, v27, s[0:1]
	v_cmp_gt_f32_e64 s[0:1], v5, v6
	s_nop 1
	v_cndmask_b32_e64 v5, v6, v5, s[0:1]
	v_cndmask_b32_e64 v2, v2, v28, s[0:1]
	v_cmp_gt_f32_e64 s[0:1], v10, v5
	s_nop 1
	v_cndmask_b32_e64 v5, v5, v10, s[0:1]
	v_cndmask_b32_e64 v2, v2, v29, s[0:1]
	s_nop 4
	v_mov_b32_dpp v6, v5 row_ror:8 row_mask:0xf bank_mask:0xf
	v_mov_b32_dpp v9, v2 row_ror:8 row_mask:0xf bank_mask:0xf
	v_cmp_gt_f32_e64 s[30:31], v6, v5
	v_cmp_eq_f32_e64 s[0:1], v6, v5
	v_cmp_lt_i32_e64 s[18:19], v9, v2
	s_and_b64 s[0:1], s[0:1], s[18:19]
	s_or_b64 s[30:31], s[30:31], s[0:1]
	v_cndmask_b32_e64 v5, v5, v6, s[30:31]
	v_cndmask_b32_e64 v2, v2, v9, s[30:31]
	s_nop 4
	v_mov_b32_dpp v6, v5 row_ror:4 row_mask:0xf bank_mask:0xf
	v_mov_b32_dpp v9, v2 row_ror:4 row_mask:0xf bank_mask:0xf
	v_cmp_gt_f32_e64 s[30:31], v6, v5
	v_cmp_eq_f32_e64 s[0:1], v6, v5
	v_cmp_lt_i32_e64 s[18:19], v9, v2
	s_and_b64 s[0:1], s[0:1], s[18:19]
	s_or_b64 s[30:31], s[30:31], s[0:1]
	v_cndmask_b32_e64 v5, v5, v6, s[30:31]
	v_cndmask_b32_e64 v2, v2, v9, s[30:31]
	s_nop 4
	v_mov_b32_dpp v6, v5 row_ror:2 row_mask:0xf bank_mask:0xf
	v_mov_b32_dpp v9, v2 row_ror:2 row_mask:0xf bank_mask:0xf
	v_cmp_gt_f32_e64 s[30:31], v6, v5
	v_cmp_eq_f32_e64 s[0:1], v6, v5
	v_cmp_lt_i32_e64 s[18:19], v9, v2
	s_and_b64 s[0:1], s[0:1], s[18:19]
	s_or_b64 s[30:31], s[30:31], s[0:1]
	v_cndmask_b32_e64 v5, v5, v6, s[30:31]
	v_cndmask_b32_e64 v2, v2, v9, s[30:31]
	ds_bpermute_b32 v6, v12, v5
	s_waitcnt lgkmcnt(1)
	ds_bpermute_b32 v9, v12, v2
	s_waitcnt lgkmcnt(1)
	v_cmp_lt_f32_e64 s[30:31], v5, v6
	v_cmp_nlt_f32_e64 s[0:1], v5, v6
	s_and_saveexec_b64 s[34:35], s[0:1]
	s_cbranch_execz .LBB0_1320
	v_cmp_eq_f32_e64 s[0:1], v5, v6
	s_waitcnt lgkmcnt(0)
	v_cmp_lt_i32_e64 s[18:19], v9, v2
	s_and_b64 s[0:1], s[0:1], s[18:19]
	s_andn2_b64 s[18:19], s[30:31], exec
	s_and_b64 s[0:1], s[0:1], exec
	s_or_b64 s[30:31], s[18:19], s[0:1]
	s_or_b64 exec, exec, s[34:35]
	s_and_saveexec_b64 s[0:1], s[30:31]
	s_cbranch_execnz .LBB0_1321
	.p2alignl 6, 3212836864

.LBB0_1347:
	s_or_b64 exec, exec, s[8:9]
	v_cmp_ne_u32_e64 s[0:1], v21, v7
	s_nop 1
	v_cndmask_b32_e64 v6, v38, v6, s[0:1]
	v_cmp_ne_u32_e64 s[0:1], v27, v7
	s_nop 1
	v_cndmask_b32_e64 v5, v38, v5, s[0:1]
	v_cmp_ne_u32_e64 s[0:1], v28, v7
	s_nop 1
	v_cndmask_b32_e64 v3, v38, v3, s[0:1]
	v_cmp_ne_u32_e64 s[0:1], v29, v7
	s_nop 1
	v_cndmask_b32_e64 v2, v38, v2, s[0:1]
	v_cmp_gt_f32_e64 s[0:1], v5, v6
	s_nop 1
	v_cndmask_b32_e64 v9, v6, v5, s[0:1]
	v_cndmask_b32_e64 v7, v21, v27, s[0:1]
	v_cmp_gt_f32_e64 s[0:1], v3, v9
	s_nop 1
	v_cndmask_b32_e64 v9, v9, v3, s[0:1]
	v_cndmask_b32_e64 v7, v7, v28, s[0:1]
	v_cmp_gt_f32_e64 s[0:1], v2, v9
	s_nop 1
	v_cndmask_b32_e64 v9, v9, v2, s[0:1]
	v_cndmask_b32_e64 v7, v7, v29, s[0:1]
	s_nop 4
	v_mov_b32_dpp v10, v9 row_ror:8 row_mask:0xf bank_mask:0xf
	v_mov_b32_dpp v11, v7 row_ror:8 row_mask:0xf bank_mask:0xf
	v_cmp_gt_f32_e64 s[10:11], v10, v9
	v_cmp_eq_f32_e64 s[0:1], v10, v9
	v_cmp_lt_i32_e64 s[8:9], v11, v7
	s_and_b64 s[0:1], s[0:1], s[8:9]
	s_or_b64 s[10:11], s[10:11], s[0:1]
	v_cndmask_b32_e64 v9, v9, v10, s[10:11]
	v_cndmask_b32_e64 v7, v7, v11, s[10:11]
	s_nop 4
	v_mov_b32_dpp v10, v9 row_ror:4 row_mask:0xf bank_mask:0xf
	v_mov_b32_dpp v11, v7 row_ror:4 row_mask:0xf bank_mask:0xf
	v_cmp_gt_f32_e64 s[10:11], v10, v9
	v_cmp_eq_f32_e64 s[0:1], v10, v9
	v_cmp_lt_i32_e64 s[8:9], v11, v7
	s_and_b64 s[0:1], s[0:1], s[8:9]
	s_or_b64 s[10:11], s[10:11], s[0:1]
	v_cndmask_b32_e64 v9, v9, v10, s[10:11]
	v_cndmask_b32_e64 v7, v7, v11, s[10:11]
	s_nop 4
	v_mov_b32_dpp v10, v9 row_ror:2 row_mask:0xf bank_mask:0xf
	v_mov_b32_dpp v11, v7 row_ror:2 row_mask:0xf bank_mask:0xf
	v_cmp_gt_f32_e64 s[10:11], v10, v9
	v_cmp_eq_f32_e64 s[0:1], v10, v9
	v_cmp_lt_i32_e64 s[8:9], v11, v7
	s_and_b64 s[0:1], s[0:1], s[8:9]
	s_or_b64 s[10:11], s[10:11], s[0:1]
	v_cndmask_b32_e64 v9, v9, v10, s[10:11]
	v_cndmask_b32_e64 v7, v7, v11, s[10:11]
	ds_bpermute_b32 v10, v12, v9
	s_waitcnt lgkmcnt(1)
	ds_bpermute_b32 v11, v12, v7
	s_waitcnt lgkmcnt(1)
	v_cmp_lt_f32_e64 s[10:11], v9, v10
	v_cmp_nlt_f32_e64 s[0:1], v9, v10
	s_and_saveexec_b64 s[12:13], s[0:1]
	s_cbranch_execz .LBB0_1362
	v_cmp_eq_f32_e64 s[0:1], v9, v10
	s_waitcnt lgkmcnt(0)
	v_cmp_lt_i32_e64 s[8:9], v11, v7
	s_and_b64 s[0:1], s[0:1], s[8:9]
	s_andn2_b64 s[8:9], s[10:11], exec
	s_and_b64 s[0:1], s[0:1], exec
	s_or_b64 s[10:11], s[8:9], s[0:1]
	s_or_b64 exec, exec, s[12:13]
	s_and_saveexec_b64 s[0:1], s[10:11]
	s_cbranch_execnz .LBB0_1363
	.p2alignl 6, 3212836864

.LBB0_1368:
	s_or_b64 exec, exec, s[8:9]
	v_cmp_ne_u32_e64 s[0:1], v21, v7
	s_nop 1
	v_cndmask_b32_e64 v6, v38, v6, s[0:1]
	v_cmp_ne_u32_e64 s[0:1], v27, v7
	s_nop 1
	v_cndmask_b32_e64 v5, v38, v5, s[0:1]
	v_cmp_ne_u32_e64 s[0:1], v28, v7
	s_nop 1
	v_cndmask_b32_e64 v3, v38, v3, s[0:1]
	v_cmp_ne_u32_e64 s[0:1], v29, v7
	s_nop 1
	v_cndmask_b32_e64 v7, v38, v2, s[0:1]
	v_cmp_gt_f32_e64 s[0:1], v5, v6
	s_nop 1
	v_cndmask_b32_e64 v5, v6, v5, s[0:1]
	v_cndmask_b32_e64 v2, v21, v27, s[0:1]
	v_cmp_gt_f32_e64 s[0:1], v3, v5
	s_nop 1
	v_cndmask_b32_e64 v3, v5, v3, s[0:1]
	v_cndmask_b32_e64 v2, v2, v28, s[0:1]
	v_cmp_gt_f32_e64 s[0:1], v7, v3
	s_nop 1
	v_cndmask_b32_e64 v3, v3, v7, s[0:1]
	v_cndmask_b32_e64 v2, v2, v29, s[0:1]
	s_nop 4
	v_mov_b32_dpp v5, v3 row_ror:8 row_mask:0xf bank_mask:0xf
	v_mov_b32_dpp v6, v2 row_ror:8 row_mask:0xf bank_mask:0xf
	v_cmp_gt_f32_e64 s[10:11], v5, v3
	v_cmp_eq_f32_e64 s[0:1], v5, v3
	v_cmp_lt_i32_e64 s[8:9], v6, v2
	s_and_b64 s[0:1], s[0:1], s[8:9]
	s_or_b64 s[10:11], s[10:11], s[0:1]
	v_cndmask_b32_e64 v3, v3, v5, s[10:11]
	v_cndmask_b32_e64 v2, v2, v6, s[10:11]
	s_nop 4
	v_mov_b32_dpp v5, v3 row_ror:4 row_mask:0xf bank_mask:0xf
	v_mov_b32_dpp v4, v2 row_ror:4 row_mask:0xf bank_mask:0xf
	v_cmp_gt_f32_e64 s[10:11], v5, v3
	v_cmp_eq_f32_e64 s[0:1], v5, v3
	v_cmp_lt_i32_e64 s[8:9], v4, v2
	s_and_b64 s[0:1], s[0:1], s[8:9]
	s_or_b64 s[10:11], s[10:11], s[0:1]
	v_cndmask_b32_e64 v3, v3, v5, s[10:11]
	v_cndmask_b32_e64 v2, v2, v4, s[10:11]
	s_waitcnt lgkmcnt(0)
	s_nop 4
	v_mov_b32_dpp v4, v3 row_ror:2 row_mask:0xf bank_mask:0xf
	v_mov_b32_dpp v5, v2 row_ror:2 row_mask:0xf bank_mask:0xf
	v_cmp_gt_f32_e64 s[10:11], v4, v3
	v_cmp_eq_f32_e64 s[0:1], v4, v3
	v_cmp_lt_i32_e64 s[8:9], v5, v2
	s_and_b64 s[0:1], s[0:1], s[8:9]
	s_or_b64 s[10:11], s[10:11], s[0:1]
	v_cndmask_b32_e64 v3, v3, v4, s[10:11]
	v_cndmask_b32_e64 v2, v2, v5, s[10:11]
	ds_bpermute_b32 v4, v12, v3
	s_waitcnt lgkmcnt(1)
	ds_bpermute_b32 v5, v12, v2
	s_waitcnt lgkmcnt(1)
	v_cmp_lt_f32_e64 s[10:11], v3, v4
	v_cmp_nlt_f32_e64 s[0:1], v3, v4
	s_and_saveexec_b64 s[12:13], s[0:1]
	s_cbranch_execz .LBB0_1383
	v_cmp_eq_f32_e64 s[0:1], v3, v4
	s_waitcnt lgkmcnt(0)
	v_cmp_lt_i32_e64 s[8:9], v5, v2
	s_and_b64 s[0:1], s[0:1], s[8:9]
	s_andn2_b64 s[8:9], s[10:11], exec
	s_and_b64 s[0:1], s[0:1], exec
	s_or_b64 s[10:11], s[8:9], s[0:1]
	s_or_b64 exec, exec, s[12:13]
	s_and_saveexec_b64 s[0:1], s[10:11]
	s_cbranch_execnz .LBB0_1384
	.p2alignl 6, 3212836864

.LBB0_1464:
	s_or_b64 exec, exec, s[2:3]
	s_waitcnt lgkmcnt(0)
	s_barrier
	ds_write_b32 v1, v2
	v_mov_b32_e32 v1, 0x12ffc
	s_waitcnt lgkmcnt(0)
	s_barrier
	ds_read_b32 v46, v1
	v_readlane_b32 s8, v237, 56
	v_readlane_b32 s9, v237, 57
	s_add_u32 s2, s8, 0x1c500000
	s_addc_u32 s3, s9, 0
	v_readlane_b32 s6, v237, 31
	s_add_u32 s8, s8, 0x1c900000
	s_addc_u32 s9, s9, 0
	s_waitcnt lgkmcnt(0)
	v_cmp_ge_i32_e32 vcc, s6, v46
	v_readlane_b32 s10, v237, 58
	v_readlane_b32 s11, v237, 59
	v_readlane_b32 s7, v237, 32
	s_cbranch_vccnz .LBB0_1477
	s_movk_i32 s6, 0xff
	s_mov_b32 s14, 0
	v_readlane_b32 s22, v237, 31
	v_readlane_b32 s23, v237, 32
	.p2alignl 6, 3212836864
.LBB0_1466:
	s_add_i32 s7, s6, s14
	s_ashr_i32 s7, s7, 1
	s_lshl_b32 s10, s7, 2
	s_add_i32 s10, s10, 0x12c00
	v_mov_b32_e32 v1, s10
	ds_read_b32 v1, v1
	s_add_i32 s10, s7, 1
	s_waitcnt lgkmcnt(0)
	v_readfirstlane_b32 s11, v1
	s_cmp_gt_i32 s11, s22
	s_cselect_b32 s6, s7, s6
	s_cselect_b32 s14, s14, s10
	s_cmp_lt_i32 s14, s6
	s_cbranch_scc1 .LBB0_1466
	s_ashr_i32 s15, s14, 31
	s_lshl_b64 s[6:7], s[14:15], 2
	s_add_u32 s6, s0, s6
	s_addc_u32 s7, s1, s7
	v_mov_b32_e32 v37, 0
	global_load_dword v45, v37, s[6:7]
	s_lshl_b32 s6, s14, 2
	s_ashr_i32 s7, s14, 6
	s_add_i32 s6, s6, 0x12c00
	s_mul_hi_i32 s10, s7, 0x7e0000
	s_mul_i32 s7, s7, 0x7e0000
	v_mov_b32_e32 v3, s6
	s_add_u32 s11, s4, s7
	ds_read_b32 v3, v3
	s_addc_u32 s10, s5, s10
	s_and_b32 s6, s14, 63
	s_add_i32 s12, s6, -1
	s_mul_i32 s7, s6, 63
	s_mul_i32 s6, s12, s6
	s_lshr_b32 s12, s6, 31
	s_add_i32 s6, s6, s12
	s_waitcnt lgkmcnt(0)
	v_sub_u32_e32 v3, s22, v3
	s_sext_i32_i16 s6, s6
	v_lshlrev_b32_e32 v3, 6, v3
	s_lshr_b32 s6, s6, 1
	s_sub_i32 s6, 0, s6
	v_ashrrev_i32_e32 v4, 2, v0
	s_sext_i32_i16 s6, s6
	v_and_b32_e32 v2, -16, v4
	s_add_i32 s7, s7, s6
	v_and_b32_e32 v1, 15, v0
	s_lshl_b32 s6, s7, 10
	s_ashr_i32 s7, s6, 31
	s_lshl_b64 s[6:7], s[6:7], 2
	s_add_u32 s6, s11, s6
	s_addc_u32 s7, s10, s7
	v_mbcnt_hi_u32_b32 v48, -1, v40
	v_bfi_b32 v47, -16, v4, v0
	v_and_b32_e32 v0, 64, v48
	s_movk_i32 s16, 0xc00
	v_mov_b64_e32 v[38:39], s[76:77]
	s_movk_i32 s17, 0xa0
	s_movk_i32 s18, 0x220
	s_mov_b32 s19, 0x3e38aa3b
	s_mov_b32 s20, 0xf149f2ca
	v_xor_b32_e32 v49, 16, v48
	v_add_u32_e32 v50, 64, v0
	v_xor_b32_e32 v51, 32, v48
	s_mov_b32 s21, s22
	s_waitcnt vmcnt(0)
	v_add_u32_e32 v3, v45, v3
	v_add_u32_e32 v3, 63, v3
	v_and_b32_e32 v55, 0xffffffc0, v3
	v_add_u32_e32 v2, v55, v2
	v_or_b32_e32 v1, v2, v1
	v_cmp_lt_i32_e32 vcc, v1, v45
	v_mov_b32_e32 v54, v55
	v_mov_b32_e32 v52, v45
	v_cndmask_b32_e32 v2, 0, v1, vcc
	v_ashrrev_i32_e32 v3, 31, v2
	v_lshl_add_u64 v[2:3], v[2:3], 2, s[6:7]
	global_load_dword v53, v[2:3], off
	s_waitcnt vmcnt(0)
	v_mov_b32_e32 v56, v53
	s_branch .LBB0_1470
	.p2alignl 6, 3212836864
.LBB0_1468:
	s_or_b64 exec, exec, s[12:13]
	v_mov_b32_e32 v17, v16
	v_pk_mul_f32 v[8:9], v[16:17], v[8:9]
	v_pk_mul_f32 v[10:11], v[16:17], v[10:11]
	v_pk_mul_f32 v[4:5], v[16:17], v[4:5]
	v_pk_mul_f32 v[6:7], v[16:17], v[6:7]
	v_pk_mul_f32 v[0:1], v[16:17], v[0:1]
	v_pk_mul_f32 v[2:3], v[16:17], v[2:3]
	v_cvt_pk_bf16_f32 v8, v8, v9
	v_cvt_pk_bf16_f32 v9, v10, v11
	v_cvt_pk_bf16_f32 v4, v4, v5
	v_cvt_pk_bf16_f32 v5, v6, v7
	v_cvt_pk_bf16_f32 v0, v0, v1
	v_cvt_pk_bf16_f32 v1, v2, v3
	global_store_dwordx2 v[12:13], v[8:9], off offset:32
	global_store_dwordx2 v[12:13], v[4:5], off offset:64
	global_store_dwordx2 v[12:13], v[0:1], off offset:96
	.p2alignl 6, 3212836864

.LBB0_1470:
	v_readlane_b32 s24, v237, 56
	v_readlane_b32 s26, v237, 58
	s_add_i32 s21, s21, s26
	v_cmp_ge_i32_e64 s[6:7], s21, v46
	s_and_b64 vcc, exec, s[6:7]
	s_mov_b32 s10, s14
	v_readlane_b32 s25, v237, 57
	v_readlane_b32 s27, v237, 59
	s_cbranch_vccnz .LBB0_1474
	s_movk_i32 s11, 0xff
	s_mov_b32 s10, 0
	.p2alignl 6, 3212836864

.LBB0_1477:
	s_waitcnt vmcnt(0)
	s_waitcnt lgkmcnt(0)
	s_barrier
	s_mov_b64 s[0:1], exec
	v_readlane_b32 s4, v237, 1
	v_readlane_b32 s5, v237, 2
	s_and_b64 s[4:5], s[0:1], s[4:5]
	s_mov_b64 exec, s[4:5]
	s_cbranch_execz .LBB0_1529
	v_mov_b32_e32 v0, 0x13ff0
	s_waitcnt vmcnt(0) expcnt(0) lgkmcnt(0)
	ds_read_b32 v2, v0
	v_mov_b32_e32 v0, 0x13ff4
	ds_read_b32 v0, v0
	s_waitcnt lgkmcnt(1)
	v_cmp_ne_u32_e32 vcc, 0, v2
	s_cbranch_vccnz .LBB0_1493
	v_readlane_b32 s44, v237, 56
	v_readlane_b32 s47, v237, 59
	v_readlane_b32 s4, v237, 0
	v_readlane_b32 s45, v237, 57
	s_mul_i32 s16, s47, s4
	s_add_u32 s4, s44, 0x4100200
	s_addc_u32 s5, s45, 0
	s_add_u32 s6, s44, 0x4100400
	s_addc_u32 s7, s45, 0
	s_add_u32 s10, s44, 0x4100500
	s_addc_u32 s11, s45, 0
	s_add_u32 s12, s44, 0x4100600
	s_addc_u32 s13, s45, 0
	s_add_u32 s14, s44, 0x4100700
	s_addc_u32 s15, s45, 0
	s_add_u32 s18, s44, 0x4100800
	s_addc_u32 s19, s45, 0
	s_add_u32 s20, s44, 0x4100900
	s_addc_u32 s21, s45, 0
	s_add_u32 s22, s44, 0x4100a00
	s_addc_u32 s23, s45, 0
	s_add_u32 s24, s44, 0x4100b00
	s_addc_u32 s25, s45, 0
	s_add_u32 s26, s44, 0x4100c00
	s_addc_u32 s27, s45, 0
	s_add_u32 s28, s44, 0x4100d00
	s_addc_u32 s29, s45, 0
	s_add_u32 s30, s44, 0x4100e00
	s_addc_u32 s31, s45, 0
	s_add_u32 s34, s44, 0x4100f00
	s_addc_u32 s35, s45, 0
	s_add_u32 s36, s44, 0x4101000
	s_addc_u32 s37, s45, 0
	s_add_u32 s38, s44, 0x4101100
	s_addc_u32 s39, s45, 0
	s_add_u32 s40, s44, 0x4101200
	s_addc_u32 s41, s45, 0
	v_readlane_b32 s46, v237, 58
	s_add_u32 s42, s44, 0x4101300
	s_mul_i32 s16, s16, s46
	s_addc_u32 s43, s45, 0
	s_mov_b32 s17, 1
	v_mov_b32_e32 v16, 0
	s_branch .LBB0_1481
	.p2alignl 6, 3212836864

.LBB0_1481:
	global_load_dword v15, v16, s[6:7] sc1
	s_waitcnt lgkmcnt(0)
	global_load_dword v0, v16, s[10:11] sc1
	global_load_dword v1, v16, s[12:13] sc1
	global_load_dword v2, v16, s[14:15] sc1
	global_load_dword v3, v16, s[18:19] sc1
	global_load_dword v4, v16, s[20:21] sc1
	global_load_dword v5, v16, s[22:23] sc1
	global_load_dword v6, v16, s[24:25] sc1
	global_load_dword v7, v16, s[26:27] sc1
	global_load_dword v8, v16, s[28:29] sc1
	global_load_dword v9, v16, s[30:31] sc1
	global_load_dword v10, v16, s[34:35] sc1
	global_load_dword v11, v16, s[36:37] sc1
	global_load_dword v12, v16, s[38:39] sc1
	global_load_dword v13, v16, s[40:41] sc1
	global_load_dword v14, v16, s[42:43] sc1
	s_mov_b64 s[44:45], -1
	s_mov_b64 s[46:47], -1
	s_waitcnt vmcnt(14)
	v_add_u32_e32 v17, v0, v15
	s_waitcnt vmcnt(13)
	v_add_u32_e32 v17, v17, v1
	s_waitcnt vmcnt(12)
	v_add_u32_e32 v17, v17, v2
	s_waitcnt vmcnt(11)
	v_add_u32_e32 v17, v17, v3
	s_waitcnt vmcnt(10)
	v_add_u32_e32 v17, v17, v4
	s_waitcnt vmcnt(9)
	v_add_u32_e32 v17, v17, v5
	s_waitcnt vmcnt(8)
	v_add_u32_e32 v17, v17, v6
	s_waitcnt vmcnt(7)
	v_add_u32_e32 v17, v17, v7
	s_waitcnt vmcnt(6)
	v_add_u32_e32 v17, v17, v8
	s_waitcnt vmcnt(5)
	v_add_u32_e32 v17, v17, v9
	s_waitcnt vmcnt(4)
	v_add_u32_e32 v17, v17, v10
	s_waitcnt vmcnt(3)
	v_add_u32_e32 v17, v17, v11
	s_waitcnt vmcnt(2)
	v_add_u32_e32 v17, v17, v12
	s_waitcnt vmcnt(1)
	v_add_u32_e32 v17, v17, v13
	s_waitcnt vmcnt(0)
	v_add_u32_e32 v17, v17, v14
	v_cmp_eq_u32_e32 vcc, s16, v17
	s_cbranch_vccnz .LBB0_1480
	s_and_b32 s33, s17, 0xff
	s_cmp_eq_u32 s33, 0
	s_mov_b64 s[48:49], -1
	s_sleep 1
	s_cbranch_scc1 .LBB0_1485
	s_and_b64 vcc, exec, s[48:49]
	s_cbranch_vccz .LBB0_1480
	.p2alignl 6, 3212836864

.LBB0_1529:
	s_or_b64 exec, exec, s[0:1]
	s_waitcnt lgkmcnt(0)
	v_mov_b32_e32 v0, v128
	v_readlane_b32 s0, v237, 29
	s_barrier
	v_readlane_b32 s1, v237, 30
	v_ashrrev_i32_e32 v1, 31, v0
	s_nop 0
	v_lshl_add_u64 v[8:9], s[0:1], 0, v[0:1]
	s_mov_b64 s[0:1], 0x200000
	v_cmp_gt_u64_e32 vcc, s[0:1], v[8:9]
	s_and_saveexec_b64 s[4:5], vcc
	s_cbranch_execz .LBB0_1538
	v_lshlrev_b32_e32 v2, 3, v0
	v_and_b32_e32 v2, 56, v2
	v_readlane_b32 s6, v237, 40
	v_mov_b32_e32 v11, 0
	v_lshlrev_b32_e32 v10, 1, v2
	v_readlane_b32 s7, v237, 41
	v_readlane_b32 s12, v237, 56
	v_readlane_b32 s14, v237, 58
	v_lshl_add_u64 v[12:13], s[6:7], 0, v[10:11]
	v_readlane_b32 s6, v237, 31
	v_readlane_b32 s7, v237, 32
	s_mov_b32 s1, 0
	v_readlane_b32 s13, v237, 57
	v_readlane_b32 s15, v237, 59
	s_mov_b32 s0, s14
	s_lshl_b64 s[6:7], s[6:7], 12
	s_lshl_b64 s[10:11], s[0:1], 8
	v_lshl_add_u64 v[14:15], v[0:1], 4, s[6:7]
	s_lshl_b64 s[12:13], s[0:1], 12
	s_mov_b64 s[14:15], 0
	v_lshlrev_b32_e32 v16, 1, v2
	v_mov_b32_e32 v17, v11
	s_mov_b64 s[18:19], 0x1fffff
	s_branch .LBB0_1532
	.p2alignl 6, 3212836864

.LBB0_1532:
	v_lshrrev_b64 v[18:19], 3, v[8:9]
	v_lshlrev_b64 v[0:1], 4, v[18:19]
	v_lshl_add_u64 v[2:3], s[2:3], 0, v[0:1]
	global_load_dwordx4 v[4:7], v[2:3], off
	v_lshlrev_b64 v[2:3], 9, v[18:19]
	v_lshl_add_u64 v[28:29], v[12:13], 0, v[2:3]
	v_lshl_add_u64 v[0:1], s[8:9], 0, v[0:1]
	global_load_dwordx4 v[20:23], v[28:29], off
	global_load_dwordx4 v[40:43], v[28:29], off offset:128
	global_load_dwordx4 v[44:47], v[28:29], off offset:256
	global_load_dwordx4 v[48:51], v[28:29], off offset:384
	s_waitcnt vmcnt(4)
	v_max_f32_e32 v10, v5, v5
	global_load_dwordx4 v[0:3], v[0:1], off
	v_max_f32_e32 v19, v4, v4
	v_max_f32_e32 v10, v19, v10
	v_max_f32_e32 v26, v6, v6
	v_max_f32_e32 v27, v7, v7
	s_waitcnt vmcnt(4)
	v_lshlrev_b32_e32 v24, 16, v20
	v_and_b32_e32 v25, 0xffff0000, v20
	v_lshlrev_b32_e32 v20, 16, v21
	v_and_b32_e32 v21, 0xffff0000, v21
	v_lshlrev_b32_e32 v30, 16, v22
	v_and_b32_e32 v31, 0xffff0000, v22
	v_lshlrev_b32_e32 v32, 16, v23
	v_and_b32_e32 v33, 0xffff0000, v23
	s_waitcnt vmcnt(0)
	v_cmp_lt_f32_e64 s[6:7], 0, v1
	s_nop 1
	v_cndmask_b32_e64 v10, v4, v10, s[6:7]
	v_max_f32_e32 v19, v10, v10
	v_max_f32_e32 v19, v19, v26
	v_cmp_lt_f32_e64 s[0:1], 0, v2
	v_cmp_lt_f32_e32 vcc, 0, v3
	s_nop 0
	v_cndmask_b32_e64 v19, v10, v19, s[0:1]
	v_max_f32_e32 v10, v19, v19
	v_max_f32_e32 v10, v10, v27
	v_cndmask_b32_e32 v19, v19, v10, vcc
	v_sub_f32_e32 v4, v4, v19
	v_mul_f32_e32 v4, 0x3fb8aa3b, v4
	v_exp_f32_e32 v34, v4
	s_nop 0
	v_mul_f32_e32 v4, v0, v34
	v_pk_fma_f32 v[26:27], v[4:5], v[24:25], 0 op_sel_hi:[0,1,0]
	v_pk_fma_f32 v[24:25], v[4:5], v[20:21], 0 op_sel_hi:[0,1,0]
	v_pk_fma_f32 v[22:23], v[4:5], v[30:31], 0 op_sel_hi:[0,1,0]
	v_pk_fma_f32 v[20:21], v[4:5], v[32:33], 0 op_sel_hi:[0,1,0]
	v_fma_f32 v0, v0, v34, 0
	s_and_saveexec_b64 s[20:21], s[6:7]
	s_cbranch_execz .LBB0_1535
	v_sub_f32_e32 v4, v5, v19
	v_mul_f32_e32 v4, 0x3fb8aa3b, v4
	v_exp_f32_e32 v5, v4
	v_lshlrev_b32_e32 v34, 16, v40
	v_mul_f32_e32 v4, v1, v5
	v_and_b32_e32 v35, 0xffff0000, v40
	v_lshlrev_b32_e32 v30, 16, v41
	v_and_b32_e32 v31, 0xffff0000, v41
	v_lshlrev_b32_e32 v36, 16, v42
	v_and_b32_e32 v37, 0xffff0000, v42
	v_lshlrev_b32_e32 v32, 16, v43
	v_and_b32_e32 v33, 0xffff0000, v43
	v_pk_fma_f32 v[20:21], v[4:5], v[32:33], v[20:21] op_sel_hi:[0,1,1]
	v_pk_fma_f32 v[22:23], v[4:5], v[36:37], v[22:23] op_sel_hi:[0,1,1]
	v_pk_fma_f32 v[24:25], v[4:5], v[30:31], v[24:25] op_sel_hi:[0,1,1]
	v_pk_fma_f32 v[26:27], v[4:5], v[34:35], v[26:27] op_sel_hi:[0,1,1]
	v_fmac_f32_e32 v0, v1, v5
	s_or_b64 exec, exec, s[20:21]
	s_and_saveexec_b64 s[6:7], s[0:1]
	s_cbranch_execnz .LBB0_1536
	.p2alignl 6, 3212836864

.LBB0_1538:
	s_or_b64 exec, exec, s[4:5]
	s_waitcnt vmcnt(0)
	s_barrier
	s_mov_b64 s[0:1], exec
	v_readlane_b32 s2, v237, 1
	v_readlane_b32 s3, v237, 2
	s_and_b64 s[2:3], s[0:1], s[2:3]
	s_mov_b64 exec, s[2:3]
	s_cbranch_execz .LBB0_1590
	v_mov_b32_e32 v0, 0x13ff0
	s_waitcnt vmcnt(0) expcnt(0) lgkmcnt(0)
	ds_read_b32 v2, v0
	v_mov_b32_e32 v0, 0x13ff4
	ds_read_b32 v0, v0
	s_waitcnt lgkmcnt(1)
	v_cmp_ne_u32_e32 vcc, 0, v2
	s_cbranch_vccnz .LBB0_1554
	v_readlane_b32 s40, v237, 56
	v_readlane_b32 s43, v237, 59
	v_readlane_b32 s2, v237, 0
	v_readlane_b32 s41, v237, 57
	s_mul_i32 s16, s43, s2
	s_add_u32 s2, s40, 0x4100200
	s_addc_u32 s3, s41, 0
	s_add_u32 s4, s40, 0x4100400
	s_addc_u32 s5, s41, 0
	s_add_u32 s6, s40, 0x4100500
	s_addc_u32 s7, s41, 0
	s_add_u32 s8, s40, 0x4100600
	s_addc_u32 s9, s41, 0
	s_add_u32 s10, s40, 0x4100700
	s_addc_u32 s11, s41, 0
	s_add_u32 s12, s40, 0x4100800
	s_addc_u32 s13, s41, 0
	s_add_u32 s14, s40, 0x4100900
	s_addc_u32 s15, s41, 0
	s_add_u32 s18, s40, 0x4100a00
	s_addc_u32 s19, s41, 0
	s_add_u32 s20, s40, 0x4100b00
	s_addc_u32 s21, s41, 0
	s_add_u32 s22, s40, 0x4100c00
	s_addc_u32 s23, s41, 0
	s_add_u32 s24, s40, 0x4100d00
	s_addc_u32 s25, s41, 0
	s_add_u32 s26, s40, 0x4100e00
	s_addc_u32 s27, s41, 0
	s_add_u32 s28, s40, 0x4100f00
	s_addc_u32 s29, s41, 0
	s_add_u32 s30, s40, 0x4101000
	s_addc_u32 s31, s41, 0
	s_add_u32 s34, s40, 0x4101100
	s_addc_u32 s35, s41, 0
	s_add_u32 s36, s40, 0x4101200
	s_addc_u32 s37, s41, 0
	v_readlane_b32 s42, v237, 58
	s_add_u32 s38, s40, 0x4101300
	s_mul_i32 s16, s16, s42
	s_addc_u32 s39, s41, 0
	s_mov_b32 s17, 1
	v_mov_b32_e32 v16, 0
	s_branch .LBB0_1542
	.p2alignl 6, 3212836864

.LBB0_1590:
	s_or_b64 exec, exec, s[0:1]
	v_readlane_b32 s0, v237, 34
	v_readlane_b32 s1, v237, 35
	s_waitcnt lgkmcnt(0)
	v_mov_b32_e32 v0, v128
	s_and_b64 vcc, exec, s[0:1]
	s_barrier
	s_cbranch_vccnz .LBB0_1617
	v_ashrrev_i32_e32 v129, 3, v0
	v_readlane_b32 s0, v237, 31
	v_lshlrev_b32_e32 v136, 10, v129
	s_mov_b64 s[2:3], -1
	s_movk_i32 s8, 0x50
	v_mov_b32_e32 v131, 0
	s_movk_i32 s9, 0xffc0
	s_movk_i32 s10, 0xa0
	s_mov_b32 s11, s0
	s_mov_b32 s4, s0
	v_readlane_b32 s1, v237, 32
	s_branch .LBB0_1593
	.p2alignl 6, 3212836864

.LBB0_1597:
	s_and_b32 s98, s11, 7
	s_lshl_b32 s98, s98, 5
	s_bfe_u32 s99, s11, 0x50005
	s_or_b32 s98, s98, s99
	s_lshl_b32 s98, s98, 3
	s_lshr_b32 s99, s11, 10
	s_lshl_b32 s99, s99, 2
	s_or_b32 s98, s98, s99
	s_bfe_u32 s99, s11, 0x20003
	s_or_b32 s98, s98, s99
	s_and_b32 s0, s98, 7
	v_lshl_add_u32 v140, s0, 17, v136
	v_readlane_b32 s0, v237, 56
	v_readlane_b32 s2, v237, 58
	s_add_i32 s14, s4, s2
	v_readlane_b32 s1, v237, 57
	s_cmpk_gt_i32 s14, 0x7ff
	v_readlane_b32 s3, v237, 59
	s_cselect_b64 s[0:1], -1, 0
	s_cmpk_lt_i32 s14, 0x800
	s_cselect_b64 s[2:3], -1, 0
	s_and_b64 s[6:7], s[2:3], exec
	s_cselect_b32 s4, s14, s4
	s_and_b32 s98, s4, 7
	s_lshl_b32 s98, s98, 5
	s_bfe_u32 s99, s4, 0x50005
	s_or_b32 s98, s98, s99
	s_lshl_b32 s98, s98, 3
	s_lshr_b32 s99, s4, 10
	s_lshl_b32 s99, s99, 2
	s_or_b32 s98, s98, s99
	s_bfe_u32 s99, s4, 0x20003
	s_or_b32 s4, s98, s99
	v_lshlrev_b32_e32 v10, 1, v139
	s_lshl_b32 s5, s4, 4
	s_lshl_b32 s4, s4, 7
	v_and_b32_e32 v9, 15, v137
	v_bfe_u32 v141, v137, 4, 2
	v_lshl_add_u32 v144, v70, 1, v10
	v_lshl_add_u32 v145, v67, 1, v10
	v_lshl_add_u32 v146, v68, 1, v10
	v_lshl_add_u32 v147, v69, 1, v10
	v_ashrrev_i32_e32 v10, 1, v137
	s_and_b32 s5, s5, 0x3fff80
	s_and_b32 s4, s4, 0x380
	v_and_or_b32 v148, v10, s9, v9
	v_lshlrev_b32_e32 v10, 4, v141
	v_and_b32_e32 v9, 0x4f, v137
	v_add_lshl_u32 v142, s5, v129, 10
	v_add_lshl_u32 v143, s4, v129, 10
	v_or_b32_e32 v65, 0x3c0, v139
	v_mad_u64_u32 v[134:135], s[4:5], v148, s10, v[10:11]
	v_mul_u32_u24_e32 v9, 0x50, v9
	v_lshl_add_u32 v135, v9, 1, v10
	v_add_u32_e32 v151, v65, v138
	v_add_u32_e32 v152, v65, v64
	v_mov_b32_e32 v64, 0
	v_add_u32_e32 v149, 0xf000, v135
	v_add_u32_e32 v150, 0xf040, v135
	v_add_u32_e32 v153, 0x8000, v151
	v_add_u32_e32 v154, 0x8000, v152
	v_add_u32_e32 v155, 0x10000, v151
	v_add_u32_e32 v156, 0x10000, v152
	v_add_u32_e32 v157, 0x18000, v151
	v_add_u32_e32 v158, 0x18000, v152
	s_mov_b32 s15, 0
	v_mov_b32_e32 v65, v64
	v_mov_b32_e32 v66, v64
	v_mov_b32_e32 v67, v64
	v_mov_b32_e32 v68, v64
	v_mov_b32_e32 v69, v64
	v_mov_b32_e32 v70, v64
	v_mov_b32_e32 v71, v64
	v_mov_b32_e32 v72, v64
	v_mov_b32_e32 v73, v64
	v_mov_b32_e32 v74, v64
	v_mov_b32_e32 v75, v64
	v_mov_b32_e32 v76, v64
	v_mov_b32_e32 v77, v64
	v_mov_b32_e32 v78, v64
	v_mov_b32_e32 v79, v64
	v_mov_b32_e32 v80, v64
	v_mov_b32_e32 v81, v64
	v_mov_b32_e32 v82, v64
	v_mov_b32_e32 v83, v64
	v_mov_b32_e32 v84, v64
	v_mov_b32_e32 v85, v64
	v_mov_b32_e32 v86, v64
	v_mov_b32_e32 v87, v64
	v_mov_b32_e32 v88, v64
	v_mov_b32_e32 v89, v64
	v_mov_b32_e32 v90, v64
	v_mov_b32_e32 v91, v64
	v_mov_b32_e32 v92, v64
	v_mov_b32_e32 v93, v64
	v_mov_b32_e32 v94, v64
	v_mov_b32_e32 v95, v64
	v_mov_b32_e32 v96, v64
	v_mov_b32_e32 v97, v64
	v_mov_b32_e32 v98, v64
	v_mov_b32_e32 v99, v64
	v_mov_b32_e32 v100, v64
	v_mov_b32_e32 v101, v64
	v_mov_b32_e32 v102, v64
	v_mov_b32_e32 v103, v64
	v_mov_b32_e32 v104, v64
	v_mov_b32_e32 v105, v64
	v_mov_b32_e32 v106, v64
	v_mov_b32_e32 v107, v64
	v_mov_b32_e32 v108, v64
	v_mov_b32_e32 v109, v64
	v_mov_b32_e32 v110, v64
	v_mov_b32_e32 v111, v64
	v_mov_b32_e32 v112, v64
	v_mov_b32_e32 v113, v64
	v_mov_b32_e32 v114, v64
	v_mov_b32_e32 v115, v64
	v_mov_b32_e32 v116, v64
	v_mov_b32_e32 v117, v64
	v_mov_b32_e32 v118, v64
	v_mov_b32_e32 v119, v64
	v_mov_b32_e32 v120, v64
	v_mov_b32_e32 v121, v64
	v_mov_b32_e32 v122, v64
	v_mov_b32_e32 v123, v64
	v_mov_b32_e32 v124, v64
	v_mov_b32_e32 v125, v64
	v_mov_b32_e32 v126, v64
	v_mov_b32_e32 v127, v64
	v_mov_b32_e32 v9, v132
	v_mov_b32_e32 v10, v133
	s_branch .LBB0_1599
	.p2alignl 6, 3212836864

.LBB0_1617:
	s_waitcnt vmcnt(0)
	s_barrier
	s_mov_b64 s[0:1], exec
	v_readlane_b32 s2, v237, 1
	v_readlane_b32 s3, v237, 2
	v_readlane_b32 s46, v237, 40
	s_and_b64 s[2:3], s[0:1], s[2:3]
	v_readlane_b32 s47, v237, 41
	s_mov_b64 exec, s[2:3]
	s_cbranch_execz .LBB0_1669
	v_mov_b32_e32 v0, 0x13ff0
	s_waitcnt vmcnt(0) expcnt(0) lgkmcnt(0)
	ds_read_b32 v2, v0
	v_mov_b32_e32 v0, 0x13ff4
	ds_read_b32 v0, v0
	s_waitcnt lgkmcnt(1)
	v_cmp_ne_u32_e32 vcc, 0, v2
	s_cbranch_vccnz .LBB0_1633
	v_readlane_b32 s40, v237, 56
	v_readlane_b32 s43, v237, 59
	v_readlane_b32 s2, v237, 0
	v_readlane_b32 s41, v237, 57
	s_mul_i32 s16, s43, s2
	s_add_u32 s2, s40, 0x4100200
	s_addc_u32 s3, s41, 0
	s_add_u32 s4, s40, 0x4100400
	s_addc_u32 s5, s41, 0
	s_add_u32 s6, s40, 0x4100500
	s_addc_u32 s7, s41, 0
	s_add_u32 s8, s40, 0x4100600
	s_addc_u32 s9, s41, 0
	s_add_u32 s10, s40, 0x4100700
	s_addc_u32 s11, s41, 0
	s_add_u32 s12, s40, 0x4100800
	s_addc_u32 s13, s41, 0
	s_add_u32 s14, s40, 0x4100900
	s_addc_u32 s15, s41, 0
	s_add_u32 s18, s40, 0x4100a00
	s_addc_u32 s19, s41, 0
	s_add_u32 s20, s40, 0x4100b00
	s_addc_u32 s21, s41, 0
	s_add_u32 s22, s40, 0x4100c00
	s_addc_u32 s23, s41, 0
	s_add_u32 s24, s40, 0x4100d00
	s_addc_u32 s25, s41, 0
	s_add_u32 s26, s40, 0x4100e00
	s_addc_u32 s27, s41, 0
	s_add_u32 s28, s40, 0x4100f00
	s_addc_u32 s29, s41, 0
	s_add_u32 s30, s40, 0x4101000
	s_addc_u32 s31, s41, 0
	s_add_u32 s34, s40, 0x4101100
	s_addc_u32 s35, s41, 0
	s_add_u32 s36, s40, 0x4101200
	s_addc_u32 s37, s41, 0
	v_readlane_b32 s42, v237, 58
	s_add_u32 s38, s40, 0x4101300
	s_mul_i32 s16, s16, s42
	s_addc_u32 s39, s41, 0
	s_mov_b32 s17, 1
	v_mov_b32_e32 v16, 0
	s_branch .LBB0_1621
	.p2alignl 6, 3212836864

.LBB0_1669:
	s_or_b64 exec, exec, s[0:1]
	s_add_u32 s0, s70, 0x10000
	s_waitcnt vmcnt(17)
	v_mov_b32_e32 v56, v128
	s_waitcnt lgkmcnt(0)
	s_barrier
	s_addc_u32 s1, s71, 0
	s_nop 0
	v_ashrrev_i32_e32 v57, 31, v56
	v_add_u32_e32 v66, 0x100, v56
	v_lshl_add_u64 v[8:9], v[56:57], 4, s[0:1]
	v_ashrrev_i32_e32 v67, 31, v66
	v_add_u32_e32 v68, 0x200, v56
	v_add_u32_e32 v70, 0x300, v56
	s_barrier
	v_lshl_add_u64 v[10:11], v[66:67], 4, s[0:1]
	global_load_dwordx4 v[0:3], v[8:9], off
	global_load_dwordx4 v[4:7], v[10:11], off
	v_ashrrev_i32_e32 v69, 31, v68
	v_ashrrev_i32_e32 v71, 31, v70
	v_lshl_add_u64 v[8:9], v[68:69], 4, s[0:1]
	v_lshl_add_u64 v[12:13], v[70:71], 4, s[0:1]
	v_add_u32_e32 v72, 0x400, v56
	global_load_dwordx4 v[8:11], v[8:9], off
	v_ashrrev_i32_e32 v73, 31, v72
	global_load_dwordx4 v[12:15], v[12:13], off nt
	v_lshl_add_u64 v[16:17], v[72:73], 4, s[0:1]
	v_add_u32_e32 v74, 0x500, v56
	global_load_dwordx4 v[16:19], v[16:17], off
	v_ashrrev_i32_e32 v75, 31, v74
	v_lshl_add_u64 v[20:21], v[74:75], 4, s[0:1]
	v_add_u32_e32 v76, 0x600, v56
	global_load_dwordx4 v[20:23], v[20:21], off
	v_ashrrev_i32_e32 v77, 31, v76
	v_lshl_add_u64 v[24:25], v[76:77], 4, s[0:1]
	v_add_u32_e32 v78, 0x700, v56
	global_load_dwordx4 v[24:27], v[24:25], off
	v_ashrrev_i32_e32 v79, 31, v78
	v_lshl_add_u64 v[28:29], v[78:79], 4, s[0:1]
	v_add_u32_e32 v80, 0x800, v56
	global_load_dwordx4 v[28:31], v[28:29], off
	v_ashrrev_i32_e32 v81, 31, v80
	v_lshl_add_u64 v[32:33], v[80:81], 4, s[0:1]
	v_add_u32_e32 v82, 0x900, v56
	global_load_dwordx4 v[32:35], v[32:33], off
	v_ashrrev_i32_e32 v83, 31, v82
	v_lshl_add_u64 v[36:37], v[82:83], 4, s[0:1]
	v_add_u32_e32 v84, 0xa00, v56
	global_load_dwordx4 v[36:39], v[36:37], off
	v_ashrrev_i32_e32 v85, 31, v84
	v_lshl_add_u64 v[40:41], v[84:85], 4, s[0:1]
	v_add_u32_e32 v86, 0xb00, v56
	global_load_dwordx4 v[40:43], v[40:41], off
	v_ashrrev_i32_e32 v87, 31, v86
	v_lshl_add_u64 v[44:45], v[86:87], 4, s[0:1]
	v_add_u32_e32 v88, 0xc00, v56
	global_load_dwordx4 v[44:47], v[44:45], off
	v_ashrrev_i32_e32 v89, 31, v88
	v_lshl_add_u64 v[48:49], v[88:89], 4, s[0:1]
	v_add_u32_e32 v90, 0xd00, v56
	global_load_dwordx4 v[48:51], v[48:49], off
	v_ashrrev_i32_e32 v91, 31, v90
	v_lshl_add_u64 v[52:53], v[90:91], 4, s[0:1]
	v_add_u32_e32 v92, 0xe00, v56
	global_load_dwordx4 v[52:55], v[52:53], off
	v_ashrrev_i32_e32 v93, 31, v92
	v_lshl_add_u64 v[58:59], v[92:93], 4, s[0:1]
	v_add_u32_e32 v94, 0xf00, v56
	global_load_dwordx4 v[58:61], v[58:59], off
	v_ashrrev_i32_e32 v95, 31, v94
	s_waitcnt vmcnt(31)
	v_lshl_add_u64 v[62:63], v[94:95], 4, s[0:1]
	global_load_dwordx4 v[62:65], v[62:63], off
	v_lshlrev_b32_e32 v67, 14, v56
	v_and_b32_e32 v69, -4, v56
	v_and_b32_e32 v67, 0xc000, v67
	v_and_b32_e32 v66, -4, v66
	v_and_b32_e32 v68, -4, v68
	v_add_u32_e32 v69, v67, v69
	v_add_u32_e32 v66, v67, v66
	v_add_u32_e32 v68, v67, v68
	v_readlane_b32 s0, v237, 46
	v_readlane_b32 s1, v237, 47
	s_andn2_b64 vcc, exec, s[0:1]
	s_waitcnt vmcnt(15)
	ds_write2st64_b32 v69, v0, v1 offset1:16
	ds_write2st64_b32 v69, v2, v3 offset0:32 offset1:48
	s_waitcnt vmcnt(14)
	ds_write2st64_b32 v66, v4, v5 offset1:16
	ds_write2st64_b32 v66, v6, v7 offset0:32 offset1:48
	s_waitcnt vmcnt(13)
	ds_write2st64_b32 v68, v8, v9 offset1:16
	ds_write2st64_b32 v68, v10, v11 offset0:32 offset1:48
	v_and_b32_e32 v0, -4, v70
	v_add_u32_e32 v0, v67, v0
	s_waitcnt vmcnt(12)
	ds_write2st64_b32 v0, v12, v13 offset1:16
	ds_write2st64_b32 v0, v14, v15 offset0:32 offset1:48
	v_and_b32_e32 v0, -4, v72
	v_add_u32_e32 v0, v67, v0
	s_waitcnt vmcnt(11)
	ds_write2st64_b32 v0, v16, v17 offset1:16
	ds_write2st64_b32 v0, v18, v19 offset0:32 offset1:48
	v_and_b32_e32 v0, -4, v74
	v_add_u32_e32 v0, v67, v0
	s_waitcnt vmcnt(10)
	ds_write2st64_b32 v0, v20, v21 offset1:16
	ds_write2st64_b32 v0, v22, v23 offset0:32 offset1:48
	v_and_b32_e32 v0, -4, v76
	v_add_u32_e32 v0, v67, v0
	s_waitcnt vmcnt(9)
	ds_write2st64_b32 v0, v24, v25 offset1:16
	ds_write2st64_b32 v0, v26, v27 offset0:32 offset1:48
	v_and_b32_e32 v0, -4, v78
	v_add_u32_e32 v0, v67, v0
	s_waitcnt vmcnt(8)
	ds_write2st64_b32 v0, v28, v29 offset1:16
	ds_write2st64_b32 v0, v30, v31 offset0:32 offset1:48
	v_and_b32_e32 v0, -4, v80
	v_add_u32_e32 v0, v67, v0
	s_waitcnt vmcnt(7)
	ds_write2st64_b32 v0, v32, v33 offset1:16
	ds_write2st64_b32 v0, v34, v35 offset0:32 offset1:48
	v_and_b32_e32 v0, -4, v82
	v_add_u32_e32 v0, v67, v0
	s_waitcnt vmcnt(6)
	ds_write2st64_b32 v0, v36, v37 offset1:16
	ds_write2st64_b32 v0, v38, v39 offset0:32 offset1:48
	v_and_b32_e32 v0, -4, v84
	v_add_u32_e32 v0, v67, v0
	s_waitcnt vmcnt(5)
	ds_write2st64_b32 v0, v40, v41 offset1:16
	ds_write2st64_b32 v0, v42, v43 offset0:32 offset1:48
	v_and_b32_e32 v0, -4, v86
	v_add_u32_e32 v0, v67, v0
	s_waitcnt vmcnt(4)
	ds_write2st64_b32 v0, v44, v45 offset1:16
	ds_write2st64_b32 v0, v46, v47 offset0:32 offset1:48
	v_and_b32_e32 v0, -4, v88
	v_add_u32_e32 v0, v67, v0
	s_waitcnt vmcnt(3)
	ds_write2st64_b32 v0, v48, v49 offset1:16
	ds_write2st64_b32 v0, v50, v51 offset0:32 offset1:48
	v_and_b32_e32 v0, -4, v90
	v_add_u32_e32 v0, v67, v0
	s_waitcnt vmcnt(2)
	ds_write2st64_b32 v0, v52, v53 offset1:16
	ds_write2st64_b32 v0, v54, v55 offset0:32 offset1:48
	v_and_b32_e32 v0, -4, v92
	v_add_u32_e32 v0, v67, v0
	s_waitcnt vmcnt(1)
	ds_write2st64_b32 v0, v58, v59 offset1:16
	ds_write2st64_b32 v0, v60, v61 offset0:32 offset1:48
	v_and_b32_e32 v0, -4, v94
	v_add_u32_e32 v0, v67, v0
	s_waitcnt vmcnt(0)
	ds_write2st64_b32 v0, v62, v63 offset1:16
	ds_write2st64_b32 v0, v64, v65 offset0:32 offset1:48
	s_waitcnt lgkmcnt(0)
	s_barrier
	s_cbranch_vccnz .LBB0_1718
	v_and_b32_e32 v5, 63, v56
	v_readlane_b32 s8, v237, 48
	v_lshlrev_b32_e32 v60, 4, v5
	v_mov_b32_e32 v61, 0
	v_readlane_b32 s12, v237, 52
	v_readlane_b32 s13, v237, 53
	v_readlane_b32 s14, v237, 54
	v_readlane_b32 s15, v237, 55
	v_lshl_add_u64 v[2:3], s[62:63], 0, v[60:61]
	s_mov_b64 s[0:1], 0x1000
	v_lshl_add_u64 v[62:63], s[14:15], 0, v[60:61]
	v_readlane_b32 s12, v237, 56
	v_lshl_add_u64 v[66:67], v[2:3], 0, s[0:1]
	v_lshl_add_u64 v[2:3], s[64:65], 0, v[60:61]
	v_readlane_b32 s13, v237, 57
	v_lshl_add_u64 v[68:69], v[2:3], 0, s[0:1]
	v_lshrrev_b32_e32 v250, 6, v56
	v_lshlrev_b32_e32 v250, 10, v250
	v_mov_b32_e32 v251, 0
	v_lshl_add_u64 v[252:253], v[66:67], 0, v[250:251]
	global_load_dwordx4 v[186:189], v[252:253], off
	v_lshl_add_u64 v[252:253], v[68:69], 0, v[250:251]
	global_load_dwordx4 v[190:193], v[252:253], off
	v_lshlrev_b32_e32 v250, 4, v56
	v_add_u32_e32 v250, 0x10400, v250
	s_waitcnt vmcnt(0)
	ds_write_b128 v250, v[186:189]
	ds_write_b128 v250, v[190:193] offset:4096
	v_add_u32_e32 v234, 0x10400, v60
	s_waitcnt lgkmcnt(0)
	s_mov_b64 s[0:1], 0x3d00080
	v_lshl_add_u64 v[2:3], v[56:57], 2, s[12:13]
	v_lshl_add_u64 v[70:71], v[2:3], 0, s[0:1]
	v_lshlrev_b32_e32 v2, 6, v5
	v_mov_b32_e32 v3, v61
	v_lshl_add_u64 v[2:3], s[66:67], 0, v[2:3]
	s_mov_b64 s[0:1], 0x4000
	v_lshl_add_u64 v[72:73], v[2:3], 0, s[0:1]
	s_mov_b64 s[0:1], 0x5000
	v_lshl_add_u64 v[74:75], v[2:3], 0, s[0:1]
	s_mov_b64 s[0:1], 0x6000
	v_lshl_add_u64 v[76:77], v[2:3], 0, s[0:1]
	s_mov_b64 s[0:1], 0x7000
	v_lshl_add_u64 v[78:79], v[2:3], 0, s[0:1]
	v_readlane_b32 s0, v237, 31
	v_ashrrev_i32_e32 v4, 2, v56
	v_lshlrev_b32_e32 v0, 3, v5
	v_mov_b32_e32 v1, v61
	v_readlane_b32 s1, v237, 32
	v_lshlrev_b32_e32 v6, 2, v56
	v_and_b32_e32 v58, -16, v4
	v_readlane_b32 s9, v237, 49
	v_lshl_add_u64 v[64:65], s[46:47], 0, v[0:1]
	v_readlane_b32 s14, v237, 58
	s_mov_b32 s2, s0
	s_lshl_b32 s18, s0, 6
	v_mov_b32_e32 v2, 0x10000
	v_lshl_add_u64 v[0:1], s[12:13], 0, v[0:1]
	s_mov_b64 s[0:1], 0x4500400
	v_cmp_gt_i32_e64 s[4:5], 24, v56
	v_add_u32_e32 v99, 0x10100, v6
	v_ashrrev_i32_e32 v59, 31, v58
	s_mov_b32 s3, 0
	v_cmp_eq_u32_e64 s[6:7], 0, v5
	v_cmp_gt_i32_e64 s[8:9], 64, v56
	v_add_u32_e32 v112, 0x10000, v6
	v_add_u32_e32 v113, 0x10200, v6
	v_add_u32_e32 v57, 0x10180, v6
	v_add_u32_e32 v114, s18, v4
	s_lshl_b32 s16, s14, 6
	v_lshl_add_u32 v115, v4, 2, v2
	v_lshl_add_u64 v[80:81], v[0:1], 0, s[0:1]
	s_mov_b32 s20, 0x3fb504f3
	v_mov_b32_e32 v116, 0x3727c5ac
	v_mov_b32_e32 v117, 1
	v_mov_b32_e32 v118, 0xff61b1e6
	v_mov_b32_e32 v119, 0x10100
	v_mov_b32_e32 v120, 0x10180
	s_mov_b32 s17, s2
	v_readlane_b32 s10, v237, 50
	v_readlane_b32 s11, v237, 51
	v_readlane_b32 s15, v237, 59
	s_branch .LBB0_1672
	.p2alignl 6, 3212836864

.LBB0_1672:
	s_barrier
	s_and_saveexec_b64 s[0:1], s[4:5]
	ds_write_b32 v99, v61
	s_or_b64 exec, exec, s[0:1]
	s_lshl_b32 s22, s17, 6
	s_ashr_i32 s23, s22, 31
	v_lshl_add_u64 v[82:83], s[22:23], 0, v[58:59]
	v_lshlrev_b64 v[0:1], 12, v[82:83]
	v_lshl_add_u64 v[0:1], v[62:63], 0, v[0:1]
	v_lshlrev_b64 v[2:3], 11, v[82:83]
	v_lshl_add_u64 v[2:3], v[64:65], 0, v[2:3]
	global_load_dwordx4 v[28:31], v[0:1], off
	global_load_dwordx4 v[20:23], v[0:1], off offset:1024
	global_load_dwordx4 v[24:27], v[0:1], off offset:2048
	global_load_dwordx4 v[16:19], v[0:1], off offset:3072
	global_load_dwordx2 v[84:85], v[2:3], off
	global_load_dwordx2 v[88:89], v[2:3], off offset:512
	global_load_dwordx2 v[90:91], v[2:3], off offset:1024
	global_load_dwordx2 v[92:93], v[2:3], off offset:1536
	global_load_dwordx4 v[182:185], v[72:73], off
	global_load_dwordx4 v[186:189], v[72:73], off offset:16
	global_load_dwordx4 v[190:193], v[72:73], off offset:32
	global_load_dwordx4 v[194:197], v[72:73], off offset:48
	global_load_dwordx4 v[198:201], v[74:75], off
	global_load_dwordx4 v[202:205], v[74:75], off offset:16
	global_load_dwordx4 v[206:209], v[74:75], off offset:32
	global_load_dwordx4 v[210:213], v[74:75], off offset:48
	global_load_dwordx4 v[214:217], v[76:77], off
	global_load_dwordx4 v[218:221], v[76:77], off offset:16
	global_load_dwordx4 v[222:225], v[76:77], off offset:32
	global_load_dwordx4 v[226:229], v[76:77], off offset:48
	global_load_dwordx4 v[230:233], v[78:79], off
	global_load_dwordx4 v[238:241], v[78:79], off offset:16
	global_load_dwordx4 v[242:245], v[78:79], off offset:32
	global_load_dwordx4 v[246:249], v[78:79], off offset:48
	global_load_dword v162, v61, s[72:73] offset:64
	global_load_dword v163, v61, s[72:73] offset:68
	global_load_dword v164, v61, s[72:73] offset:72
	global_load_dword v165, v61, s[72:73] offset:76
	global_load_dword v166, v61, s[72:73] offset:80
	global_load_dword v167, v61, s[72:73] offset:84
	global_load_dword v168, v61, s[72:73] offset:88
	global_load_dword v169, v61, s[72:73] offset:92
	global_load_dword v170, v61, s[72:73] offset:96
	global_load_dword v171, v61, s[72:73] offset:100
	global_load_dword v172, v61, s[72:73] offset:104
	global_load_dword v173, v61, s[72:73] offset:108
	global_load_dword v174, v61, s[72:73] offset:112
	global_load_dword v175, v61, s[72:73] offset:116
	global_load_dword v176, v61, s[72:73] offset:120
	global_load_dword v177, v61, s[72:73] offset:124
	global_load_dwordx4 v[178:181], v61, s[68:69] offset:16
	s_ashr_i32 s19, s18, 31
	v_lshl_add_u64 v[0:1], v[58:59], 0, s[18:19]
	v_lshlrev_b64 v[0:1], 11, v[0:1]
	v_lshl_add_u64 v[86:87], v[80:81], 0, v[0:1]
	s_mov_b32 s19, 0
	v_mov_b32_e32 v121, v115
	s_branch .LBB0_1676
	.p2alignl 6, 3212836864

.LBB0_1676:
	s_add_i32 s21, s19, 1
	s_waitcnt vmcnt(0)
	v_mov_b64_e32 v[38:39], v[84:85]
	v_mov_b64_e32 v[32:33], v[92:93]
	v_mov_b64_e32 v[34:35], v[90:91]
	v_mov_b64_e32 v[36:37], v[88:89]
	v_mov_b32_e32 v0, s21
	v_min_u32_e32 v0, 15, v0
	v_mov_b32_e32 v1, 0
	v_lshl_add_u64 v[0:1], v[82:83], 0, v[0:1]
	v_lshlrev_b64 v[2:3], 12, v[0:1]
	v_lshlrev_b64 v[0:1], 11, v[0:1]
	v_lshl_add_u64 v[12:13], v[62:63], 0, v[2:3]
	v_lshl_add_u64 v[92:93], v[64:65], 0, v[0:1]
	global_load_dwordx4 v[0:3], v[12:13], off nt
	global_load_dwordx2 v[84:85], v[92:93], off nt
	global_load_dwordx4 v[4:7], v[12:13], off offset:1024 nt
	global_load_dwordx2 v[88:89], v[92:93], off offset:512 nt
	global_load_dwordx4 v[8:11], v[12:13], off offset:2048 nt
	global_load_dwordx2 v[90:91], v[92:93], off offset:1024 nt
	s_nop 0
	global_load_dwordx4 v[12:15], v[12:13], off offset:3072 nt
	s_nop 0
	global_load_dwordx2 v[92:93], v[92:93], off offset:1536 nt
	v_lshlrev_b32_e32 v40, 16, v38
	v_and_b32_e32 v41, 0xffff0000, v38
	v_lshlrev_b32_e32 v38, 16, v39
	v_and_b32_e32 v39, 0xffff0000, v39
	v_lshlrev_b32_e32 v54, 16, v36
	v_and_b32_e32 v55, 0xffff0000, v36
	v_lshlrev_b32_e32 v94, 16, v37
	v_and_b32_e32 v95, 0xffff0000, v37
	v_lshlrev_b32_e32 v96, 16, v34
	v_and_b32_e32 v97, 0xffff0000, v34
	v_lshlrev_b32_e32 v100, 16, v35
	v_and_b32_e32 v101, 0xffff0000, v35
	v_lshlrev_b32_e32 v102, 16, v32
	v_and_b32_e32 v103, 0xffff0000, v32
	v_lshlrev_b32_e32 v104, 16, v33
	v_and_b32_e32 v105, 0xffff0000, v33
	v_pk_fma_f32 v[106:107], v[30:31], s[20:21], v[38:39] op_sel_hi:[1,0,1]
	ds_read_b128 v[30:33], v234
	ds_read_b128 v[34:37], v234 offset:4096
	v_pk_fma_f32 v[28:29], v[28:29], s[20:21], v[40:41] op_sel_hi:[1,0,1]
	v_pk_fma_f32 v[20:21], v[20:21], s[20:21], v[54:55] op_sel_hi:[1,0,1]
	v_add_f32_e32 v38, v28, v29
	v_add_f32_e32 v38, v38, v106
	v_pk_fma_f32 v[22:23], v[22:23], s[20:21], v[94:95] op_sel_hi:[1,0,1]
	v_add_f32_e32 v54, v20, v21
	v_pk_fma_f32 v[24:25], v[24:25], s[20:21], v[96:97] op_sel_hi:[1,0,1]
	v_add_f32_e32 v38, v107, v38
	v_add_f32_e32 v54, v54, v22
	v_pk_fma_f32 v[26:27], v[26:27], s[20:21], v[100:101] op_sel_hi:[1,0,1]
	v_add_f32_e32 v55, v24, v25
	v_add_f32_e32 v98, 0, v38
	v_add_f32_e32 v54, v23, v54
	v_add_f32_e32 v55, v55, v26
	v_add_f32_e32 v54, v98, v54
	v_add_f32_e32 v55, v27, v55
	v_pk_fma_f32 v[16:17], v[16:17], s[20:21], v[102:103] op_sel_hi:[1,0,1]
	v_add_f32_e32 v54, v54, v55
	v_pk_fma_f32 v[18:19], v[18:19], s[20:21], v[104:105] op_sel_hi:[1,0,1]
	v_add_f32_e32 v55, v16, v17
	v_add_f32_e32 v55, v55, v18
	v_add_f32_e32 v55, v19, v55
	v_add_f32_e32 v54, v54, v55
	ds_read_b128 v[38:41], v60
	ds_read_b128 v[42:45], v60 offset:4096
	ds_read_b128 v[46:49], v60 offset:8192
	ds_read_b128 v[50:53], v60 offset:12288
	ds_read_b128 v[108:111], v60 offset:16384
	ds_read_b128 v[122:125], v60 offset:20480
	ds_read_b128 v[130:133], v60 offset:24576
	ds_read_b128 v[134:137], v60 offset:28672
	ds_read_b128 v[138:141], v60 offset:32768
	ds_read_b128 v[142:145], v60 offset:36864
	ds_read_b128 v[146:149], v60 offset:40960
	ds_read_b128 v[150:153], v60 offset:45056
	ds_read_b128 v[154:157], v60 offset:49152
	v_add_f32_dpp v54, v54, v54 quad_perm:[1,0,3,2] row_mask:0xf bank_mask:0xf bound_ctrl:1
	s_nop 1
	v_add_f32_dpp v54, v54, v54 quad_perm:[2,3,0,1] row_mask:0xf bank_mask:0xf bound_ctrl:1
	s_nop 1
	v_add_f32_dpp v54, v54, v54 row_half_mirror row_mask:0xf bank_mask:0xf bound_ctrl:1
	s_nop 1
	v_add_f32_dpp v54, v54, v54 row_mirror row_mask:0xf bank_mask:0xf bound_ctrl:1
	s_nop 0
	v_readlane_b32 s2, v54, 16
	v_readlane_b32 s10, v54, 48
	v_readlane_b32 s0, v54, 0
	v_readlane_b32 s1, v54, 32
	v_mov_b32_e32 v54, s2
	v_mov_b32_e32 v55, s10
	v_pk_add_f32 v[54:55], s[0:1], v[54:55]
	s_nop 0
	v_add_f32_e32 v54, v54, v55
	v_mul_f32_e32 v54, 0x3a800000, v54
	v_pk_add_f32 v[28:29], v[28:29], v[54:55] op_sel_hi:[1,0] neg_lo:[0,1] neg_hi:[0,1]
	v_pk_add_f32 v[126:127], v[106:107], v[54:55] op_sel_hi:[1,0] neg_lo:[0,1] neg_hi:[0,1]
	v_pk_mul_f32 v[104:105], v[28:29], v[28:29]
	v_pk_mul_f32 v[106:107], v[126:127], v[126:127]
	v_pk_add_f32 v[158:159], v[20:21], v[54:55] op_sel_hi:[1,0] neg_lo:[0,1] neg_hi:[0,1]
	v_pk_add_f32 v[160:161], v[22:23], v[54:55] op_sel_hi:[1,0] neg_lo:[0,1] neg_hi:[0,1]
	v_pk_add_f32 v[100:101], v[24:25], v[54:55] op_sel_hi:[1,0] neg_lo:[0,1] neg_hi:[0,1]
	v_pk_add_f32 v[102:103], v[26:27], v[54:55] op_sel_hi:[1,0] neg_lo:[0,1] neg_hi:[0,1]
	v_pk_add_f32 v[94:95], v[16:17], v[54:55] op_sel_hi:[1,0] neg_lo:[0,1] neg_hi:[0,1]
	v_pk_add_f32 v[96:97], v[18:19], v[54:55] op_sel_hi:[1,0] neg_lo:[0,1] neg_hi:[0,1]
	v_add_f32_e32 v54, v104, v105
	v_add_f32_e32 v54, v106, v54
	v_pk_mul_f32 v[20:21], v[158:159], v[158:159]
	v_add_f32_e32 v54, v107, v54
	v_add_f32_e32 v20, v20, v54
	v_pk_mul_f32 v[22:23], v[160:161], v[160:161]
	v_add_f32_e32 v20, v21, v20
	v_add_f32_e32 v20, v22, v20
	v_pk_mul_f32 v[24:25], v[100:101], v[100:101]
	v_add_f32_e32 v20, v23, v20
	v_add_f32_e32 v20, v24, v20
	v_pk_mul_f32 v[26:27], v[102:103], v[102:103]
	v_add_f32_e32 v20, v25, v20
	v_add_f32_e32 v20, v26, v20
	v_pk_mul_f32 v[16:17], v[94:95], v[94:95]
	v_add_f32_e32 v20, v27, v20
	v_add_f32_e32 v16, v16, v20
	v_pk_mul_f32 v[18:19], v[96:97], v[96:97]
	v_add_f32_e32 v16, v17, v16
	v_add_f32_e32 v16, v18, v16
	v_add_f32_e32 v16, v19, v16
	s_nop 1
	v_add_f32_dpp v16, v16, v16 quad_perm:[1,0,3,2] row_mask:0xf bank_mask:0xf bound_ctrl:1
	s_nop 1
	v_add_f32_dpp v16, v16, v16 quad_perm:[2,3,0,1] row_mask:0xf bank_mask:0xf bound_ctrl:1
	s_nop 1
	v_add_f32_dpp v16, v16, v16 row_half_mirror row_mask:0xf bank_mask:0xf bound_ctrl:1
	s_nop 1
	v_add_f32_dpp v16, v16, v16 row_mirror row_mask:0xf bank_mask:0xf bound_ctrl:1
	s_nop 0
	v_readlane_b32 s2, v16, 16
	v_readlane_b32 s10, v16, 48
	v_readlane_b32 s0, v16, 0
	v_readlane_b32 s1, v16, 32
	v_mov_b32_e32 v16, s2
	v_mov_b32_e32 v17, s10
	v_pk_add_f32 v[16:17], s[0:1], v[16:17]
	s_mov_b32 s0, 0x800000
	v_add_f32_e32 v16, v16, v17
	v_fmamk_f32 v16, v16, 0x3a800000, v116
	v_cmp_gt_f32_e32 vcc, s0, v16
	v_mul_f32_e32 v17, 0x4b800000, v16
	s_nop 0
	v_cndmask_b32_e32 v16, v16, v17, vcc
	v_rsq_f32_e32 v54, v16
	ds_read_b128 v[16:19], v60 offset:53248
	s_waitcnt lgkmcnt(15)
	ds_read_b128 v[20:23], v60 offset:57344
	s_waitcnt lgkmcnt(15)
	ds_read_b128 v[24:27], v60 offset:61440
	s_waitcnt lgkmcnt(15)
	v_mul_f32_e32 v55, 0x45800000, v54
	v_cndmask_b32_e32 v98, v54, v55, vcc
	v_pk_mul_f32 v[28:29], v[28:29], v[98:99] op_sel_hi:[1,0]
	v_pk_fma_f32 v[106:107], v[30:31], v[28:29], v[34:35]
	v_pk_mul_f32 v[28:29], v[126:127], v[98:99] op_sel_hi:[1,0]
	s_waitcnt lgkmcnt(2)
	v_mul_f32_e32 v17, v107, v17
	v_pk_fma_f32 v[104:105], v[32:33], v[28:29], v[36:37]
	v_cvt_pk_bf16_f32 v28, v106, v107
	v_cvt_pk_bf16_f32 v29, v104, v105
	global_store_dwordx2 v[86:87], v[28:29], off offset:-1024
	v_mul_f32_e32 v54, v39, v107
	v_fmac_f32_e32 v54, v38, v106
	ds_read_b128 v[32:35], v234 offset:1024
	ds_read_b128 v[36:39], v234 offset:5120
	v_fmac_f32_e32 v54, v104, v40
	v_fmac_f32_e32 v54, v105, v41
	v_mul_f32_e32 v55, v107, v43
	v_fmac_f32_e32 v55, v106, v42
	v_fmac_f32_e32 v55, v104, v44
	v_fmac_f32_e32 v55, v105, v45
	v_mul_f32_e32 v28, v107, v47
	v_fmac_f32_e32 v28, v106, v46
	v_fmac_f32_e32 v28, v104, v48
	v_fmac_f32_e32 v28, v105, v49
	v_add_f32_e32 v46, 0, v28
	v_mul_f32_e32 v45, v107, v51
	v_fmac_f32_e32 v45, v106, v50
	v_fmac_f32_e32 v45, v104, v52
	v_fmac_f32_e32 v45, v105, v53
	v_mul_f32_e32 v44, v107, v109
	v_fmac_f32_e32 v44, v106, v108
	v_fmac_f32_e32 v44, v104, v110
	v_fmac_f32_e32 v44, v105, v111
	v_mul_f32_e32 v53, v107, v123
	v_fmac_f32_e32 v53, v106, v122
	v_fmac_f32_e32 v53, v104, v124
	v_fmac_f32_e32 v53, v105, v125
	v_mul_f32_e32 v52, v107, v131
	v_fmac_f32_e32 v52, v106, v130
	v_fmac_f32_e32 v52, v104, v132
	v_fmac_f32_e32 v52, v105, v133
	v_mul_f32_e32 v51, v107, v135
	v_fmac_f32_e32 v51, v106, v134
	v_fmac_f32_e32 v51, v104, v136
	v_fmac_f32_e32 v51, v105, v137
	v_mul_f32_e32 v50, v107, v139
	v_fmac_f32_e32 v50, v106, v138
	v_fmac_f32_e32 v50, v104, v140
	v_fmac_f32_e32 v50, v105, v141
	v_mul_f32_e32 v49, v107, v143
	v_fmac_f32_e32 v49, v106, v142
	v_fmac_f32_e32 v49, v104, v144
	v_fmac_f32_e32 v49, v105, v145
	v_mul_f32_e32 v48, v107, v147
	v_fmac_f32_e32 v48, v106, v146
	v_fmac_f32_e32 v48, v104, v148
	v_fmac_f32_e32 v48, v105, v149
	v_mul_f32_e32 v131, v107, v151
	v_fmac_f32_e32 v17, v106, v16
	s_waitcnt lgkmcnt(3)
	v_mul_f32_e32 v122, v107, v21
	v_fmac_f32_e32 v131, v106, v150
	v_fmac_f32_e32 v122, v106, v20
	v_fmac_f32_e32 v131, v104, v152
	v_fmac_f32_e32 v122, v104, v22
	v_fmac_f32_e32 v131, v105, v153
	v_fmac_f32_e32 v122, v105, v23
	v_mul_f32_e32 v125, v107, v155
	s_waitcnt lgkmcnt(2)
	v_mul_f32_e32 v123, v107, v25
	v_fmac_f32_e32 v125, v106, v154
	v_fmac_f32_e32 v123, v106, v24
	v_fmac_f32_e32 v125, v104, v156
	v_fmac_f32_e32 v17, v104, v18
	v_fmac_f32_e32 v123, v104, v26
	v_fmac_f32_e32 v125, v105, v157
	v_fmac_f32_e32 v17, v105, v19
	v_fmac_f32_e32 v123, v105, v27
	v_pk_mul_f32 v[40:41], v[158:159], v[98:99] op_sel_hi:[1,0]
	v_add_f32_e32 v124, 0, v17
	s_waitcnt lgkmcnt(0)
	v_pk_fma_f32 v[108:109], v[40:41], v[32:33], v[36:37]
	ds_read_b128 v[40:43], v60 offset:1024
	ds_read_b128 v[134:137], v60 offset:21504
	v_pk_mul_f32 v[32:33], v[160:161], v[98:99] op_sel_hi:[1,0]
	ds_read_b128 v[142:145], v60 offset:29696
	v_pk_fma_f32 v[110:111], v[32:33], v[34:35], v[38:39]
	s_waitcnt lgkmcnt(2)
	v_fma_f32 v126, v109, v41, v54
	v_cvt_pk_bf16_f32 v32, v108, v109
	v_cvt_pk_bf16_f32 v33, v110, v111
	v_fmac_f32_e32 v126, v108, v40
	global_store_dwordx2 v[86:87], v[32:33], off offset:-512
	ds_read_b128 v[32:35], v60 offset:5120
	v_fmac_f32_e32 v126, v110, v42
	v_fmac_f32_e32 v126, v111, v43
	s_waitcnt lgkmcnt(2)
	v_fma_f32 v133, v109, v135, v53
	s_waitcnt lgkmcnt(1)
	v_fma_f32 v135, v109, v143, v51
	v_fmac_f32_e32 v135, v108, v142
	v_fmac_f32_e32 v135, v110, v144
	v_fmac_f32_e32 v135, v111, v145
	ds_read_b128 v[144:147], v60 offset:50176
	s_waitcnt lgkmcnt(1)
	v_fma_f32 v127, v109, v33, v55
	v_fmac_f32_e32 v127, v108, v32
	v_fmac_f32_e32 v127, v110, v34
	v_fmac_f32_e32 v127, v111, v35
	ds_read_b128 v[36:39], v60 offset:9216
	ds_read_b128 v[32:35], v60 offset:13312
	ds_read_b128 v[40:43], v60 offset:17408
	ds_read_b128 v[138:141], v60 offset:25600
	v_fmac_f32_e32 v133, v108, v134
	v_fmac_f32_e32 v133, v110, v136
	s_waitcnt lgkmcnt(3)
	v_fma_f32 v129, v109, v37, v46
	s_waitcnt lgkmcnt(2)
	v_fma_f32 v130, v109, v33, v45
	v_fmac_f32_e32 v133, v111, v137
	v_fmac_f32_e32 v129, v108, v36
	v_fmac_f32_e32 v130, v108, v32
	s_waitcnt lgkmcnt(0)
	v_fma_f32 v134, v109, v139, v52
	v_fmac_f32_e32 v129, v110, v38
	v_fmac_f32_e32 v130, v110, v34
	v_fma_f32 v132, v109, v41, v44
	v_fmac_f32_e32 v134, v108, v138
	v_fmac_f32_e32 v129, v111, v39
	v_fmac_f32_e32 v130, v111, v35
	v_fmac_f32_e32 v132, v108, v40
	v_fmac_f32_e32 v134, v110, v140
	v_fmac_f32_e32 v132, v110, v42
	v_fmac_f32_e32 v134, v111, v141
	v_fmac_f32_e32 v132, v111, v43
	ds_read_b128 v[52:55], v60 offset:33792
	ds_read_b128 v[138:141], v60 offset:37888
	s_waitcnt lgkmcnt(1)
	v_fma_f32 v136, v109, v53, v50
	v_fmac_f32_e32 v136, v108, v52
	v_fmac_f32_e32 v136, v110, v54
	v_fmac_f32_e32 v136, v111, v55
	ds_read_b128 v[50:53], v60 offset:41984
	s_waitcnt lgkmcnt(1)
	v_fma_f32 v137, v109, v139, v49
	v_fmac_f32_e32 v137, v108, v138
	v_fmac_f32_e32 v137, v110, v140
	v_fmac_f32_e32 v137, v111, v141
	ds_read_b128 v[140:143], v60 offset:46080
	s_waitcnt lgkmcnt(1)
	v_fma_f32 v138, v109, v51, v48
	v_fmac_f32_e32 v138, v108, v50
	v_fmac_f32_e32 v138, v110, v52
	v_fmac_f32_e32 v138, v111, v53
	ds_read_b128 v[48:51], v234 offset:2048
	ds_read_b128 v[52:55], v234 offset:6144
	s_waitcnt lgkmcnt(2)
	v_fma_f32 v131, v109, v141, v131
	v_fmac_f32_e32 v131, v108, v140
	v_fmac_f32_e32 v131, v110, v142
	v_fmac_f32_e32 v131, v111, v143
	ds_read_b128 v[140:143], v60 offset:54272
	v_fma_f32 v139, v109, v145, v125
	v_fmac_f32_e32 v139, v108, v144
	v_fmac_f32_e32 v139, v110, v146
	v_fmac_f32_e32 v139, v111, v147
	ds_read_b128 v[144:147], v60 offset:58368
	s_waitcnt lgkmcnt(1)
	v_fma_f32 v148, v109, v141, v124
	v_fmac_f32_e32 v148, v108, v140
	v_fmac_f32_e32 v148, v110, v142
	v_fmac_f32_e32 v148, v111, v143
	ds_read_b128 v[140:143], v60 offset:62464
	s_waitcnt lgkmcnt(1)
	v_mul_f32_e32 v124, v109, v145
	v_fmac_f32_e32 v124, v108, v144
	v_fmac_f32_e32 v124, v110, v146
	v_fmac_f32_e32 v124, v111, v147
	v_add_f32_e32 v144, v122, v124
	s_waitcnt lgkmcnt(0)
	v_mul_f32_e32 v122, v109, v141
	v_fmac_f32_e32 v122, v108, v140
	v_fmac_f32_e32 v122, v110, v142
	v_fmac_f32_e32 v122, v111, v143
	v_add_f32_e32 v142, v123, v122
	v_mov_b32_e32 v122, v106
	v_mov_b32_e32 v123, v108
	v_mov_b32_e32 v108, v107
	v_mov_b32_e32 v106, v186
	v_mov_b32_e32 v124, v182
	v_mov_b32_e32 v140, v190
	v_mov_b32_e32 v125, v198
	v_mov_b32_e32 v107, v202
	v_pk_mul_f32 v[106:107], v[108:109], v[106:107]
	v_mov_b32_e32 v36, v187
	v_pk_fma_f32 v[106:107], v[122:123], v[124:125], v[106:107]
	v_mov_b32_e32 v124, v104
	v_mov_b32_e32 v125, v110
	v_mov_b32_e32 v110, v105
	v_mov_b32_e32 v104, v194
	v_mov_b32_e32 v141, v206
	v_pk_fma_f32 v[106:107], v[124:125], v[140:141], v[106:107]
	v_mov_b32_e32 v105, v210
	v_mov_b32_e32 v32, v183
	v_mov_b32_e32 v37, v203
	v_pk_mul_f32 v[24:25], v[108:109], v[36:37]
	v_pk_fma_f32 v[104:105], v[110:111], v[104:105], v[106:107]
	v_mov_b32_e32 v33, v199
	v_pk_fma_f32 v[24:25], v[122:123], v[32:33], v[24:25]
	v_mov_b32_e32 v40, v191
	v_add_f32_e32 v16, 0, v104
	v_mov_b32_e32 v41, v207
	v_pk_fma_f32 v[20:21], v[124:125], v[40:41], v[24:25]
	v_mov_b32_e32 v44, v195
	v_add_f32_e32 v107, v16, v105
	v_mov_b32_e32 v45, v211
	v_pk_fma_f32 v[16:17], v[110:111], v[44:45], v[20:21]
	v_mov_b32_e32 v20, v188
	v_add_f32_e32 v16, 0, v16
	v_mov_b32_e32 v21, v204
	v_add_f32_e32 v105, v16, v17
	v_mov_b32_e32 v16, v184
	v_mov_b32_e32 v17, v200
	v_pk_mul_f32 v[20:21], v[108:109], v[20:21]
	v_mov_b32_e32 v38, v189
	v_pk_fma_f32 v[16:17], v[122:123], v[16:17], v[20:21]
	v_mov_b32_e32 v20, v192
	v_mov_b32_e32 v21, v208
	v_pk_fma_f32 v[16:17], v[124:125], v[20:21], v[16:17]
	v_mov_b32_e32 v20, v196
	v_mov_b32_e32 v21, v212
	v_pk_fma_f32 v[16:17], v[110:111], v[20:21], v[16:17]
	v_mov_b32_e32 v34, v185
	v_add_f32_e32 v16, 0, v16
	v_add_f32_e32 v106, v16, v17
	v_mov_b32_e32 v39, v205
	v_pk_mul_f32 v[16:17], v[108:109], v[38:39]
	v_mov_b32_e32 v42, v193
	v_mov_b32_e32 v35, v201
	v_pk_fma_f32 v[16:17], v[122:123], v[34:35], v[16:17]
	v_mov_b32_e32 v46, v197
	v_mov_b32_e32 v43, v209
	v_pk_fma_f32 v[16:17], v[124:125], v[42:43], v[16:17]
	v_pk_mul_f32 v[20:21], v[102:103], v[98:99] op_sel_hi:[1,0]
	v_mov_b32_e32 v47, v213
	v_pk_fma_f32 v[16:17], v[110:111], v[46:47], v[16:17]
	v_pk_fma_f32 v[50:51], v[20:21], v[50:51], v[54:55]
	v_add_f32_e32 v16, 0, v16
	v_add_f32_e32 v104, v16, v17
	v_pk_mul_f32 v[16:17], v[100:101], v[98:99] op_sel_hi:[1,0]
	v_cvt_pk_bf16_f32 v21, v50, v51
	v_pk_fma_f32 v[48:49], v[16:17], v[48:49], v[52:53]
	ds_read_b128 v[16:19], v60 offset:2048
	v_cvt_pk_bf16_f32 v20, v48, v49
	global_store_dwordx2 v[86:87], v[20:21], off
	ds_read_b128 v[20:23], v60 offset:6144
	v_pk_mul_f32 v[46:47], v[94:95], v[98:99] op_sel_hi:[1,0]
	s_waitcnt lgkmcnt(1)
	v_fma_f32 v42, v49, v17, v126
	v_fmac_f32_e32 v42, v48, v16
	v_fmac_f32_e32 v42, v50, v18
	v_fmac_f32_e32 v42, v51, v19
	ds_read_b128 v[16:19], v60 offset:10240
	s_waitcnt lgkmcnt(1)
	v_fma_f32 v41, v49, v21, v127
	v_fmac_f32_e32 v41, v48, v20
	v_fmac_f32_e32 v41, v50, v22
	v_fmac_f32_e32 v41, v51, v23
	ds_read_b128 v[20:23], v60 offset:14336
	s_waitcnt lgkmcnt(1)
	v_fma_f32 v40, v49, v17, v129
	v_fmac_f32_e32 v40, v48, v16
	v_fmac_f32_e32 v40, v50, v18
	v_fmac_f32_e32 v40, v51, v19
	ds_read_b128 v[16:19], v60 offset:18432
	ds_read_b128 v[32:35], v234 offset:3072
	ds_read_b128 v[36:39], v234 offset:7168
	s_waitcnt lgkmcnt(3)
	v_fma_f32 v45, v49, v21, v130
	v_fmac_f32_e32 v45, v48, v20
	v_fmac_f32_e32 v45, v50, v22
	v_fmac_f32_e32 v45, v51, v23
	ds_read_b128 v[20:23], v60 offset:22528
	s_waitcnt lgkmcnt(3)
	v_fma_f32 v44, v49, v17, v132
	v_fmac_f32_e32 v44, v48, v16
	v_fmac_f32_e32 v44, v50, v18
	v_fmac_f32_e32 v44, v51, v19
	ds_read_b128 v[16:19], v60 offset:26624
	s_waitcnt lgkmcnt(1)
	v_fma_f32 v124, v49, v21, v133
	v_fmac_f32_e32 v124, v48, v20
	v_fmac_f32_e32 v124, v50, v22
	v_fmac_f32_e32 v124, v51, v23
	ds_read_b128 v[20:23], v60 offset:30720
	s_waitcnt lgkmcnt(1)
	v_fma_f32 v123, v49, v17, v134
	v_fmac_f32_e32 v123, v48, v16
	v_fmac_f32_e32 v123, v50, v18
	v_fmac_f32_e32 v123, v51, v19
	s_waitcnt lgkmcnt(0)
	v_fma_f32 v122, v49, v21, v135
	v_fmac_f32_e32 v122, v48, v20
	v_fmac_f32_e32 v122, v50, v22
	ds_read_b128 v[16:19], v60 offset:34816
	v_fmac_f32_e32 v122, v51, v23
	ds_read_b128 v[20:23], v60 offset:38912
	s_waitcnt lgkmcnt(1)
	v_fma_f32 v111, v49, v17, v136
	v_fmac_f32_e32 v111, v48, v16
	v_fmac_f32_e32 v111, v50, v18
	s_waitcnt lgkmcnt(0)
	v_fma_f32 v110, v49, v21, v137
	v_fmac_f32_e32 v110, v48, v20
	v_fmac_f32_e32 v111, v51, v19
	v_fmac_f32_e32 v110, v50, v22
	ds_read_b128 v[16:19], v60 offset:43008
	v_fmac_f32_e32 v110, v51, v23
	ds_read_b128 v[20:23], v60 offset:47104
	s_waitcnt lgkmcnt(1)
	v_fma_f32 v109, v49, v17, v138
	v_fmac_f32_e32 v109, v48, v16
	v_fmac_f32_e32 v109, v50, v18
	s_waitcnt lgkmcnt(0)
	v_fma_f32 v108, v49, v21, v131
	v_fmac_f32_e32 v108, v48, v20
	v_fmac_f32_e32 v109, v51, v19
	v_fmac_f32_e32 v108, v50, v22
	ds_read_b128 v[16:19], v60 offset:51200
	v_fmac_f32_e32 v108, v51, v23
	ds_read_b128 v[20:23], v60 offset:55296
	s_waitcnt lgkmcnt(1)
	v_fma_f32 v103, v49, v17, v139
	v_fmac_f32_e32 v103, v48, v16
	v_fmac_f32_e32 v103, v50, v18
	s_waitcnt lgkmcnt(0)
	v_fma_f32 v102, v49, v21, v148
	v_fmac_f32_e32 v102, v48, v20
	v_fmac_f32_e32 v103, v51, v19
	v_fmac_f32_e32 v102, v50, v22
	ds_read_b128 v[16:19], v60 offset:59392
	v_fmac_f32_e32 v102, v51, v23
	ds_read_b128 v[20:23], v60 offset:63488
	s_waitcnt lgkmcnt(1)
	v_fma_f32 v100, v49, v17, v144
	v_fmac_f32_e32 v100, v48, v16
	v_fmac_f32_e32 v100, v50, v18
	s_waitcnt lgkmcnt(0)
	v_fma_f32 v101, v49, v21, v142
	v_fmac_f32_e32 v101, v48, v20
	v_fmac_f32_e32 v101, v50, v22
	v_fmac_f32_e32 v100, v51, v19
	v_fmac_f32_e32 v101, v51, v23
	v_pk_fma_f32 v[52:53], v[46:47], v[32:33], v[36:37]
	v_pk_mul_f32 v[32:33], v[96:97], v[98:99] op_sel_hi:[1,0]
	ds_read_b128 v[94:97], v60 offset:3072
	v_pk_fma_f32 v[54:55], v[32:33], v[34:35], v[38:39]
	v_cvt_pk_bf16_f32 v32, v52, v53
	v_cvt_pk_bf16_f32 v33, v54, v55
	global_store_dwordx2 v[86:87], v[32:33], off offset:512
	ds_read_b128 v[32:35], v60 offset:7168
	s_waitcnt lgkmcnt(1)
	v_mul_f32_e32 v36, v53, v95
	v_fmac_f32_e32 v36, v52, v94
	v_fmac_f32_e32 v36, v54, v96
	v_fmac_f32_e32 v36, v55, v97
	v_add_f32_e32 v94, v42, v36
	ds_read_b128 v[36:39], v60 offset:11264
	ds_read_b128 v[130:133], v60 offset:15360
	s_waitcnt lgkmcnt(2)
	v_fma_f32 v95, v53, v33, v41
	v_fmac_f32_e32 v95, v52, v32
	v_fmac_f32_e32 v95, v54, v34
	s_waitcnt lgkmcnt(1)
	v_fma_f32 v96, v53, v37, v40
	v_fmac_f32_e32 v96, v52, v36
	v_fmac_f32_e32 v96, v54, v38
	v_fmac_f32_e32 v95, v55, v35
	v_fmac_f32_e32 v96, v55, v39
	ds_read_b128 v[40:43], v60 offset:19456
	s_waitcnt lgkmcnt(1)
	v_fma_f32 v97, v53, v131, v45
	v_fmac_f32_e32 v97, v52, v130
	v_fmac_f32_e32 v97, v54, v132
	v_fmac_f32_e32 v97, v55, v133
	ds_read_b128 v[130:133], v60 offset:23552
	s_waitcnt lgkmcnt(1)
	v_fma_f32 v125, v53, v41, v44
	v_fmac_f32_e32 v125, v52, v40
	v_fmac_f32_e32 v125, v54, v42
	v_fmac_f32_e32 v125, v55, v43
	ds_read_b128 v[134:137], v60 offset:27648
	s_waitcnt lgkmcnt(1)
	v_fma_f32 v124, v53, v131, v124
	v_fmac_f32_e32 v124, v52, v130
	v_fmac_f32_e32 v124, v54, v132
	v_fmac_f32_e32 v124, v55, v133
	ds_read_b128 v[130:133], v60 offset:31744
	s_waitcnt lgkmcnt(1)
	v_fma_f32 v98, v53, v135, v123
	v_fmac_f32_e32 v98, v52, v134
	v_fmac_f32_e32 v98, v54, v136
	v_fmac_f32_e32 v98, v55, v137
	ds_read_b128 v[134:137], v60 offset:35840
	s_waitcnt lgkmcnt(1)
	v_fma_f32 v122, v53, v131, v122
	v_fmac_f32_e32 v122, v52, v130
	v_fmac_f32_e32 v122, v54, v132
	v_fmac_f32_e32 v122, v55, v133
	ds_read_b128 v[130:133], v60 offset:39936
	s_waitcnt lgkmcnt(1)
	v_fma_f32 v111, v53, v135, v111
	v_fmac_f32_e32 v111, v52, v134
	v_fmac_f32_e32 v111, v54, v136
	v_fmac_f32_e32 v111, v55, v137
	ds_read_b128 v[134:137], v60 offset:44032
	s_waitcnt lgkmcnt(1)
	v_fma_f32 v110, v53, v131, v110
	v_fmac_f32_e32 v110, v52, v130
	v_fmac_f32_e32 v110, v54, v132
	v_fmac_f32_e32 v110, v55, v133
	ds_read_b128 v[130:133], v60 offset:48128
	s_waitcnt lgkmcnt(1)
	v_fma_f32 v109, v53, v135, v109
	v_fmac_f32_e32 v109, v52, v134
	v_fmac_f32_e32 v109, v54, v136
	v_fmac_f32_e32 v109, v55, v137
	ds_read_b128 v[134:137], v60 offset:52224
	s_waitcnt lgkmcnt(1)
	v_fma_f32 v108, v53, v131, v108
	v_fmac_f32_e32 v108, v52, v130
	v_fmac_f32_e32 v108, v54, v132
	v_fmac_f32_e32 v108, v55, v133
	ds_read_b128 v[130:133], v60 offset:56320
	s_waitcnt lgkmcnt(1)
	v_fma_f32 v103, v53, v135, v103
	v_fmac_f32_e32 v103, v52, v134
	v_fmac_f32_e32 v103, v54, v136
	v_fmac_f32_e32 v103, v55, v137
	ds_read_b128 v[134:137], v60 offset:60416
	s_waitcnt lgkmcnt(1)
	v_fma_f32 v102, v53, v131, v102
	v_fmac_f32_e32 v102, v52, v130
	v_fmac_f32_e32 v102, v54, v132
	v_fmac_f32_e32 v102, v55, v133
	ds_read_b128 v[130:133], v60 offset:64512
	s_waitcnt lgkmcnt(1)
	v_fma_f32 v123, v53, v135, v100
	v_fmac_f32_e32 v123, v52, v134
	v_fmac_f32_e32 v123, v54, v136
	v_fmac_f32_e32 v123, v55, v137
	s_waitcnt lgkmcnt(0)
	v_fma_f32 v129, v53, v131, v101
	v_fmac_f32_e32 v129, v52, v130
	v_fmac_f32_e32 v129, v54, v132
	v_fmac_f32_e32 v129, v55, v133
	v_mov_b32_e32 v100, v48
	v_mov_b32_e32 v101, v52
	v_mov_b32_e32 v52, v49
	v_mov_b32_e32 v48, v218
	v_mov_b32_e32 v126, v214
	v_mov_b32_e32 v130, v222
	v_mov_b32_e32 v127, v230
	v_mov_b32_e32 v49, v238
	v_pk_mul_f32 v[48:49], v[52:53], v[48:49]
	v_mov_b32_e32 v36, v219
	v_pk_fma_f32 v[48:49], v[100:101], v[126:127], v[48:49]
	v_mov_b32_e32 v126, v50
	v_mov_b32_e32 v127, v54
	v_mov_b32_e32 v131, v242
	v_pk_fma_f32 v[48:49], v[126:127], v[130:131], v[48:49]
	v_mov_b32_e32 v54, v51
	v_mov_b32_e32 v50, v226
	v_mov_b32_e32 v51, v246
	v_mov_b32_e32 v32, v215
	v_mov_b32_e32 v37, v239
	v_pk_mul_f32 v[24:25], v[52:53], v[36:37]
	v_pk_fma_f32 v[48:49], v[54:55], v[50:51], v[48:49]
	v_mov_b32_e32 v33, v231
	v_pk_fma_f32 v[24:25], v[100:101], v[32:33], v[24:25]
	v_mov_b32_e32 v40, v223
	v_add_f32_e32 v16, v107, v48
	v_mov_b32_e32 v41, v243
	v_pk_fma_f32 v[20:21], v[126:127], v[40:41], v[24:25]
	v_mov_b32_e32 v44, v227
	v_add_f32_e32 v28, v16, v49
	v_mov_b32_e32 v45, v247
	v_pk_fma_f32 v[16:17], v[54:55], v[44:45], v[20:21]
	v_mov_b32_e32 v20, v220
	v_add_f32_e32 v16, v105, v16
	v_mov_b32_e32 v21, v240
	v_add_f32_e32 v24, v16, v17
	v_mov_b32_e32 v16, v216
	v_mov_b32_e32 v17, v232
	v_pk_mul_f32 v[20:21], v[52:53], v[20:21]
	v_mov_b32_e32 v38, v221
	v_pk_fma_f32 v[16:17], v[100:101], v[16:17], v[20:21]
	v_mov_b32_e32 v20, v224
	v_mov_b32_e32 v21, v244
	v_pk_fma_f32 v[16:17], v[126:127], v[20:21], v[16:17]
	v_mov_b32_e32 v20, v228
	v_mov_b32_e32 v21, v248
	v_pk_fma_f32 v[16:17], v[54:55], v[20:21], v[16:17]
	v_mov_b32_e32 v34, v217
	v_add_f32_e32 v16, v106, v16
	v_add_f32_e32 v20, v16, v17
	v_mov_b32_e32 v39, v241
	v_pk_mul_f32 v[16:17], v[52:53], v[38:39]
	v_mov_b32_e32 v42, v225
	v_mov_b32_e32 v35, v233
	v_pk_fma_f32 v[16:17], v[100:101], v[34:35], v[16:17]
	v_mov_b32_e32 v46, v229
	v_mov_b32_e32 v43, v245
	v_pk_fma_f32 v[16:17], v[126:127], v[42:43], v[16:17]
	v_mov_b32_e32 v47, v249
	v_pk_fma_f32 v[16:17], v[54:55], v[46:47], v[16:17]
	v_add_f32_e32 v16, v104, v16
	v_add_f32_e32 v22, v16, v17
	v_add_f32_dpp v250, v24, v24 row_mirror row_mask:0xf bank_mask:0xf bound_ctrl:1
	v_add_f32_dpp v94, v94, v94 row_mirror row_mask:0xf bank_mask:0xf bound_ctrl:1
	v_add_f32_dpp v125, v125, v125 row_mirror row_mask:0xf bank_mask:0xf bound_ctrl:1
	v_add_f32_dpp v111, v111, v111 row_mirror row_mask:0xf bank_mask:0xf bound_ctrl:1
	v_add_f32_dpp v103, v103, v103 row_mirror row_mask:0xf bank_mask:0xf bound_ctrl:1
	v_add_f32_dpp v250, v20, v20 row_mirror row_mask:0xf bank_mask:0xc bound_ctrl:1
	v_add_f32_dpp v94, v95, v95 row_mirror row_mask:0xf bank_mask:0xc bound_ctrl:1
	v_add_f32_dpp v125, v124, v124 row_mirror row_mask:0xf bank_mask:0xc bound_ctrl:1
	v_add_f32_dpp v111, v110, v110 row_mirror row_mask:0xf bank_mask:0xc bound_ctrl:1
	v_add_f32_dpp v103, v102, v102 row_mirror row_mask:0xf bank_mask:0xc bound_ctrl:1
	v_add_f32_dpp v251, v28, v28 row_mirror row_mask:0xf bank_mask:0xf bound_ctrl:1
	v_add_f32_dpp v96, v96, v96 row_mirror row_mask:0xf bank_mask:0xf bound_ctrl:1
	v_add_f32_dpp v98, v98, v98 row_mirror row_mask:0xf bank_mask:0xf bound_ctrl:1
	v_add_f32_dpp v109, v109, v109 row_mirror row_mask:0xf bank_mask:0xf bound_ctrl:1
	v_add_f32_dpp v123, v123, v123 row_mirror row_mask:0xf bank_mask:0xf bound_ctrl:1
	v_add_f32_dpp v251, v22, v22 row_mirror row_mask:0xf bank_mask:0xc bound_ctrl:1
	v_add_f32_dpp v96, v97, v97 row_mirror row_mask:0xf bank_mask:0xc bound_ctrl:1
	v_add_f32_dpp v98, v122, v122 row_mirror row_mask:0xf bank_mask:0xc bound_ctrl:1
	v_add_f32_dpp v109, v108, v108 row_mirror row_mask:0xf bank_mask:0xc bound_ctrl:1
	v_add_f32_dpp v123, v129, v129 row_mirror row_mask:0xf bank_mask:0xc bound_ctrl:1
	v_add_f32_dpp v250, v250, v250 row_half_mirror row_mask:0xf bank_mask:0xf bound_ctrl:1
	v_add_f32_dpp v94, v94, v94 row_half_mirror row_mask:0xf bank_mask:0xf bound_ctrl:1
	v_add_f32_dpp v125, v125, v125 row_half_mirror row_mask:0xf bank_mask:0xf bound_ctrl:1
	v_add_f32_dpp v111, v111, v111 row_half_mirror row_mask:0xf bank_mask:0xf bound_ctrl:1
	v_add_f32_dpp v103, v103, v103 row_half_mirror row_mask:0xf bank_mask:0xf bound_ctrl:1
	v_add_f32_dpp v250, v251, v251 row_half_mirror row_mask:0xf bank_mask:0xa bound_ctrl:1
	v_add_f32_dpp v94, v96, v96 row_half_mirror row_mask:0xf bank_mask:0xa bound_ctrl:1
	v_add_f32_dpp v125, v98, v98 row_half_mirror row_mask:0xf bank_mask:0xa bound_ctrl:1
	v_add_f32_dpp v111, v109, v109 row_half_mirror row_mask:0xf bank_mask:0xa bound_ctrl:1
	v_add_f32_dpp v103, v123, v123 row_half_mirror row_mask:0xf bank_mask:0xa bound_ctrl:1
	v_add_f32_dpp v250, v250, v250 quad_perm:[1,0,3,2] row_mask:0xf bank_mask:0xf bound_ctrl:1
	v_add_f32_dpp v94, v94, v94 quad_perm:[1,0,3,2] row_mask:0xf bank_mask:0xf bound_ctrl:1
	v_add_f32_dpp v125, v125, v125 quad_perm:[1,0,3,2] row_mask:0xf bank_mask:0xf bound_ctrl:1
	v_add_f32_dpp v111, v111, v111 quad_perm:[1,0,3,2] row_mask:0xf bank_mask:0xf bound_ctrl:1
	v_add_f32_dpp v103, v103, v103 quad_perm:[1,0,3,2] row_mask:0xf bank_mask:0xf bound_ctrl:1
	v_add_f32_dpp v250, v250, v250 quad_perm:[2,3,0,1] row_mask:0xf bank_mask:0xf bound_ctrl:1
	v_add_f32_dpp v94, v94, v94 quad_perm:[2,3,0,1] row_mask:0xf bank_mask:0xf bound_ctrl:1
	v_add_f32_dpp v125, v125, v125 quad_perm:[2,3,0,1] row_mask:0xf bank_mask:0xf bound_ctrl:1
	v_add_f32_dpp v111, v111, v111 quad_perm:[2,3,0,1] row_mask:0xf bank_mask:0xf bound_ctrl:1
	v_add_f32_dpp v103, v103, v103 quad_perm:[2,3,0,1] row_mask:0xf bank_mask:0xf bound_ctrl:1
	v_readlane_b32 s2, v250, 20
	v_readlane_b32 s10, v250, 52
	v_readlane_b32 s0, v250, 4
	v_readlane_b32 s1, v250, 36
	v_mov_b32_e32 v16, s2
	v_mov_b32_e32 v17, s10
	v_readlane_b32 s2, v250, 16
	v_readlane_b32 s10, v250, 48
	v_pk_add_f32 v[16:17], s[0:1], v[16:17]
	v_readlane_b32 s0, v250, 0
	v_readlane_b32 s1, v250, 32
	v_mov_b32_e32 v18, s2
	v_mov_b32_e32 v19, s10
	v_readlane_b32 s2, v250, 24
	v_readlane_b32 s10, v250, 56
	v_pk_add_f32 v[18:19], s[0:1], v[18:19]
	v_readlane_b32 s0, v250, 8
	v_readlane_b32 s1, v250, 40
	v_mov_b32_e32 v20, s2
	v_mov_b32_e32 v21, s10
	v_pk_add_f32 v[20:21], s[0:1], v[20:21]
	v_mov_b32_e32 v25, v18
	v_add_f32_e32 v26, v20, v21
	v_mov_b32_e32 v18, v17
	v_readlane_b32 s2, v250, 28
	v_readlane_b32 s10, v250, 60
	v_readlane_b32 s0, v250, 12
	v_readlane_b32 s1, v250, 44
	v_mov_b32_e32 v20, s2
	v_mov_b32_e32 v21, s10
	v_pk_add_f32 v[20:21], s[0:1], v[20:21]
	v_add_f32_e32 v27, v20, v21
	v_readlane_b32 s14, v94, 0
	v_readlane_b32 s94, v94, 16
	v_readlane_b32 s15, v94, 32
	v_readlane_b32 s95, v94, 48
	v_readlane_b32 s87, v94, 8
	v_readlane_b32 s91, v94, 24
	v_readlane_b32 s90, v94, 40
	v_readlane_b32 s92, v94, 56
	v_readlane_b32 s65, v94, 4
	v_readlane_b32 s75, v94, 20
	v_readlane_b32 s66, v94, 36
	v_readlane_b32 s78, v94, 52
	v_readlane_b32 s51, v94, 12
	v_readlane_b32 s53, v94, 28
	v_readlane_b32 s52, v94, 44
	v_readlane_b32 s54, v94, 60
	v_readlane_b32 s35, v125, 0
	v_readlane_b32 s37, v125, 16
	v_readlane_b32 s36, v125, 32
	v_readlane_b32 s38, v125, 48
	v_readlane_b32 s23, v125, 8
	v_readlane_b32 s27, v125, 24
	v_readlane_b32 s26, v125, 40
	v_readlane_b32 s93, v125, 56
	v_readlane_b32 s81, v125, 4
	v_readlane_b32 s83, v125, 20
	v_readlane_b32 s82, v125, 36
	v_readlane_b32 s84, v125, 52
	v_readlane_b32 s63, v125, 12
	v_readlane_b32 s67, v125, 28
	v_readlane_b32 s64, v125, 44
	v_readlane_b32 s70, v125, 60
	v_readlane_b32 s59, v111, 0
	v_readlane_b32 s61, v111, 16
	v_readlane_b32 s60, v111, 32
	v_readlane_b32 s62, v111, 48
	v_readlane_b32 s55, v111, 8
	v_readlane_b32 s57, v111, 24
	v_readlane_b32 s56, v111, 40
	v_readlane_b32 s58, v111, 56
	v_readlane_b32 s47, v111, 4
	v_readlane_b32 s49, v111, 20
	v_readlane_b32 s48, v111, 36
	v_readlane_b32 s50, v111, 52
	v_readlane_b32 s43, v111, 12
	v_readlane_b32 s45, v111, 28
	v_readlane_b32 s44, v111, 44
	v_readlane_b32 s46, v111, 60
	v_readlane_b32 s39, v103, 0
	v_readlane_b32 s41, v103, 16
	v_readlane_b32 s40, v103, 32
	v_readlane_b32 s42, v103, 48
	v_readlane_b32 s30, v103, 8
	v_readlane_b32 s33, v103, 24
	v_readlane_b32 s31, v103, 40
	v_readlane_b32 s34, v103, 56
	v_readlane_b32 s28, v103, 4
	v_readlane_b32 s29, v103, 20
	v_readlane_b32 s85, v103, 36
	v_readlane_b32 s86, v103, 52
	v_mov_b32_e32 v24, v16
	v_pk_add_f32 v[16:17], v[24:25], v[18:19]
	v_mov_b32_e32 v20, v178
	v_mov_b32_e32 v21, v179
	v_mov_b32_e32 v22, v180
	v_mov_b32_e32 v23, v181
	v_add_f32_e32 v19, v26, v22
	v_pk_add_f32 v[16:17], v[16:17], v[20:21]
	v_add_f32_e32 v18, v27, v23
	v_cmp_gt_f32_e32 vcc, v17, v16
	v_mov_b32_e32 v22, 0
	v_readlane_b32 s71, v103, 12
	v_cndmask_b32_e32 v20, v16, v17, vcc
	v_cmp_gt_f32_e64 s[12:13], v19, v20
	v_cndmask_b32_e64 v21, 0, 1, vcc
	s_and_b64 s[10:11], s[12:13], exec
	v_cndmask_b32_e64 v20, v20, v19, s[12:13]
	v_cmp_ngt_f32_e64 s[0:1], v18, v20
	v_readfirstlane_b32 s2, v21
	s_cselect_b32 s2, 2, s2
	s_and_b64 s[10:11], s[0:1], exec
	s_cselect_b32 s2, s2, 3
	s_cmp_eq_u32 s2, 0
	s_cselect_b64 s[24:25], -1, 0
	s_cmp_lg_u32 s2, 0
	v_mov_b32_e32 v21, 0
	v_readlane_b32 s79, v103, 28
	v_readlane_b32 s74, v103, 44
	v_readlane_b32 s80, v103, 60
	v_cmp_gt_f32_e64 s[10:11], v18, v20
	s_waitcnt lgkmcnt(0)
	s_cbranch_scc0 .LBB0_1684
	v_cndmask_b32_e64 v23, 0, 1, s[24:25]
	v_cmp_ne_u32_e64 s[14:15], 1, v23
	s_andn2_b64 vcc, exec, s[24:25]
	s_cbranch_vccz .LBB0_1685
	.p2alignl 6, 3212836864
.LBB0_1678:
	v_mov_b32_e32 v23, 0
	s_and_b64 vcc, exec, s[14:15]
	v_mov_b32_e32 v24, 0
	s_cbranch_vccz .LBB0_1686
	.p2alignl 6, 3212836864
.LBB0_1679:
	s_and_b64 vcc, exec, s[14:15]
	s_cbranch_vccz .LBB0_1687
	.p2alignl 6, 3212836864
.LBB0_1680:
	s_cmp_eq_u32 s2, 1
	s_cselect_b64 s[24:25], -1, 0
	s_cmp_lg_u32 s2, 1
	s_cbranch_scc1 .LBB0_1688
	.p2alignl 6, 3212836864
.LBB0_1681:
	v_mov_b32_e32 v22, s37
	v_mov_b32_e32 v25, s38
	v_add_f32_e32 v22, s35, v22
	v_add_f32_e32 v25, s36, v25
	v_add_f32_e32 v22, v22, v25
	v_mov_b32_e32 v25, v166
	v_add_f32_e32 v22, v22, v25
	v_cndmask_b32_e64 v25, 0, 1, s[24:25]
	v_cmp_ne_u32_e64 s[14:15], 1, v25
	s_andn2_b64 vcc, exec, s[24:25]
	s_cbranch_vccz .LBB0_1689
	.p2alignl 6, 3212836864
.LBB0_1682:
	s_and_b64 vcc, exec, s[14:15]
	s_cbranch_vccnz .LBB0_1690
	.p2alignl 6, 3212836864

.LBB0_1692:
	s_and_b64 s[14:15], s[12:13], s[0:1]
	v_cndmask_b32_e64 v25, 0, 1, s[14:15]
	v_cmp_ne_u32_e64 s[12:13], 1, v25
	s_andn2_b64 vcc, exec, s[14:15]
	s_cbranch_vccnz .LBB0_1701
	v_mov_b32_e32 v22, v170
	v_mov_b32_e32 v25, s61
	v_mov_b32_e32 v26, s62
	v_add_f32_e32 v25, s59, v25
	v_add_f32_e32 v26, s60, v26
	v_add_f32_e32 v25, v25, v26
	v_add_f32_e32 v22, v25, v22
	s_and_b64 vcc, exec, s[12:13]
	s_cbranch_vccz .LBB0_1702
	.p2alignl 6, 3212836864
.LBB0_1694:
	s_and_b64 vcc, exec, s[12:13]
	s_cbranch_vccnz .LBB0_1703
	.p2alignl 6, 3212836864
.LBB0_1695:
	v_mov_b32_e32 v24, v172
	v_mov_b32_e32 v25, s49
	v_mov_b32_e32 v26, s50
	v_add_f32_e32 v25, s47, v25
	v_add_f32_e32 v26, s48, v26
	v_add_f32_e32 v25, v25, v26
	v_add_f32_e32 v24, v25, v24
	s_and_b64 vcc, exec, s[12:13]
	s_cbranch_vccz .LBB0_1704
	.p2alignl 6, 3212836864
.LBB0_1696:
	v_cndmask_b32_e64 v25, 0, 1, s[10:11]
	v_cmp_ne_u32_e64 s[12:13], 1, v25
	s_andn2_b64 vcc, exec, s[10:11]
	s_cbranch_vccnz .LBB0_1705
	.p2alignl 6, 3212836864
.LBB0_1697:
	v_mov_b32_e32 v22, v174
	v_mov_b32_e32 v25, s41
	v_mov_b32_e32 v26, s42
	v_add_f32_e32 v25, s39, v25
	v_add_f32_e32 v26, s40, v26
	v_add_f32_e32 v25, v25, v26
	v_add_f32_e32 v22, v25, v22
	s_and_b64 vcc, exec, s[12:13]
	s_cbranch_vccz .LBB0_1706
	.p2alignl 6, 3212836864

.LBB0_1699:
	v_mov_b32_e32 v24, v176
	v_mov_b32_e32 v25, s29
	v_mov_b32_e32 v26, s86
	v_add_f32_e32 v25, s28, v25
	v_add_f32_e32 v26, s85, v26
	v_add_f32_e32 v25, v25, v26
	v_add_f32_e32 v24, v25, v24
	s_and_b64 vcc, exec, s[12:13]
	s_cbranch_vccz .LBB0_1708
	.p2alignl 6, 3212836864

.LBB0_1796:
	v_ashrrev_i32_e32 v143, 3, v12
	v_add_u32_e32 v8, v140, v143
	v_cmp_lt_i32_e32 vcc, v8, v141
	v_add_u32_e32 v4, 32, v8
	v_add_u32_e32 v6, 64, v8
	v_cndmask_b32_e32 v2, 0, v8, vcc
	v_cmp_lt_i32_e32 vcc, v4, v141
	v_add_u32_e32 v8, 0x60, v8
	v_readlane_b32 s0, v237, 42
	v_cndmask_b32_e32 v4, 0, v4, vcc
	v_cmp_lt_i32_e32 vcc, v6, v141
	v_lshlrev_b64 v[0:1], 17, v[130:131]
	v_readlane_b32 s1, v237, 43
	v_cndmask_b32_e32 v6, 0, v6, vcc
	v_cmp_lt_i32_e32 vcc, v8, v141
	v_lshl_add_u64 v[0:1], s[0:1], 0, v[0:1]
	v_ashrrev_i32_e32 v3, 31, v2
	v_cndmask_b32_e32 v8, 0, v8, vcc
	v_ashrrev_i32_e32 v5, 31, v4
	v_ashrrev_i32_e32 v7, 31, v6
	v_ashrrev_i32_e32 v9, 31, v8
	v_lshl_add_u64 v[2:3], v[2:3], 2, v[0:1]
	v_lshl_add_u64 v[4:5], v[4:5], 2, v[0:1]
	v_lshl_add_u64 v[6:7], v[6:7], 2, v[0:1]
	v_lshl_add_u64 v[0:1], v[8:9], 2, v[0:1]
	global_load_dword v2, v[2:3], off
	s_nop 0
	global_load_dword v3, v[4:5], off
	s_nop 0
	global_load_dword v4, v[6:7], off
	s_nop 0
	global_load_dword v0, v[0:1], off
	s_movk_i32 s75, 0xab
	v_mul_lo_u32 v1, v130, s75
	v_bfe_u32 v1, v1, 10, 6
	v_readlane_b32 s4, v237, 56
	v_mul_lo_u32 v5, v1, -6
	v_readlane_b32 s5, v237, 57
	s_add_u32 s92, s4, 0x1d00000
	v_readlane_b32 s0, v237, 31
	v_add_u32_e32 v5, v5, v130
	s_addc_u32 s93, s5, 0
	s_mov_b32 s4, s0
	s_and_b32 s0, s0, 7
	v_cmp_gt_i32_e32 vcc, 5, v5
	v_min_i32_e32 v8, 4, v5
	s_cmp_lt_u32 s0, 4
	v_cndmask_b32_e64 v6, 2, 1, vcc
	v_add_u32_e32 v7, 1, v5
	v_add_u32_e32 v8, -1, v8
	v_cmp_gt_i32_e32 vcc, 3, v5
	v_lshlrev_b32_e32 v1, 2, v1
	s_mov_b32 s95, 0
	v_cndmask_b32_e64 v5, v6, 0, vcc
	v_cndmask_b32_e32 v6, v8, v7, vcc
	s_cselect_b64 vcc, -1, 0
	s_lshl_b32 s0, s4, 7
	v_or_b32_e32 v5, v5, v1
	v_add_u32_e32 v1, v6, v1
	s_and_b32 s0, s0, 0x180
	v_cndmask_b32_e32 v1, v1, v5, vcc
	v_add_lshl_u32 v5, v143, s0, 10
	s_mov_b64 s[58:59], -1
	s_movk_i32 s85, 0x50
	s_movk_i32 s33, 0xfcc0
	s_movk_i32 s96, 0xc0
	s_movk_i32 s97, 0xfd00
	s_movk_i32 s16, 0x100
	v_mov_b32_e32 v132, v130
	v_lshl_add_u32 v148, v1, 19, v5
	s_mov_b32 s60, s4
	v_readlane_b32 s6, v237, 58
	v_readlane_b32 s7, v237, 59
	v_readlane_b32 s1, v237, 32
	s_waitcnt vmcnt(3)
	v_lshlrev_b32_e32 v147, 10, v2
	s_waitcnt vmcnt(2)
	v_lshlrev_b32_e32 v146, 10, v3
	s_waitcnt vmcnt(1)
	v_lshlrev_b32_e32 v145, 10, v4
	s_waitcnt vmcnt(0)
	v_lshlrev_b32_e32 v144, 10, v0
	s_branch .LBB0_1798
	.p2alignl 6, 3212836864

.LBB0_1827:
	v_mul_lo_u32 v69, v134, s75
	v_bfe_u32 v69, v69, 10, 6
	v_mul_lo_u32 v70, v69, -6
	v_add_u32_e32 v70, v70, v134
	v_cmp_gt_i32_e32 vcc, 5, v70
	v_min_i32_e32 v77, 4, v70
	s_and_b32 s0, s61, 7
	v_cndmask_b32_e64 v71, 2, 1, vcc
	v_add_u32_e32 v76, 1, v70
	v_add_u32_e32 v77, -1, v77
	v_cmp_gt_i32_e32 vcc, 3, v70
	s_cmp_lt_u32 s0, 4
	v_lshlrev_b32_e32 v69, 2, v69
	v_cndmask_b32_e64 v70, v71, 0, vcc
	v_cndmask_b32_e32 v71, v77, v76, vcc
	s_cselect_b64 vcc, -1, 0
	s_lshl_b32 s0, s61, 7
	v_or_b32_e32 v70, v70, v69
	v_add_u32_e32 v69, v71, v69
	s_and_b32 s0, s0, 0x180
	s_waitcnt vmcnt(3)
	v_lshlrev_b32_e32 v135, 10, v65
	s_waitcnt vmcnt(2)
	v_lshlrev_b32_e32 v152, 10, v66
	v_cndmask_b32_e32 v65, v69, v70, vcc
	v_add_lshl_u32 v66, s0, v143, 10
	v_lshl_add_u32 v155, v65, 19, v66
	v_bfe_u32 v138, v64, 6, 1
	v_and_b32_e32 v65, 15, v64
	v_bfe_u32 v139, v64, 4, 2
	v_ashrrev_i32_e32 v64, 1, v64
	s_movk_i32 s0, 0xffc0
	v_and_or_b32 v156, v64, s0, v65
	v_lshlrev_b32_e32 v64, 4, v139
	v_lshl_or_b32 v65, v138, 6, v65
	s_movk_i32 s0, 0xa0
	v_mad_u64_u32 v[136:137], s[0:1], v156, s0, v[64:65]
	v_mul_u32_u24_e32 v65, 0x50, v65
	v_lshlrev_b32_e32 v66, 1, v133
	v_lshlrev_b32_e32 v65, 1, v65
	s_waitcnt vmcnt(1)
	v_lshlrev_b32_e32 v153, 10, v67
	s_waitcnt vmcnt(0)
	v_lshlrev_b32_e32 v154, 10, v68
	v_lshl_add_u32 v157, v75, 1, v66
	v_lshl_add_u32 v158, v72, 1, v66
	v_lshl_add_u32 v159, v73, 1, v66
	v_lshl_add_u32 v160, v74, 1, v66
	v_or_b32_e32 v66, 0x3c0, v133
	v_add_u32_e32 v137, v64, v65
	v_or_b32_e32 v67, 0xf000, v64
	v_add_u32_e32 v68, 0x1400, v65
	v_add_u32_e32 v65, 0x1e00, v65
	v_or_b32_e32 v64, 0xf040, v64
	v_add_u32_e32 v163, v64, v68
	v_add_u32_e32 v164, v64, v65
	v_add_u32_e32 v166, v66, v148
	v_mov_b32_e32 v64, 0
	s_mov_b32 s10, 0
	v_add_u32_e32 v161, v67, v68
	v_add_u32_e32 v162, v67, v65
	v_add_u32_e32 v165, v66, v147
	v_add_u32_e32 v167, v66, v146
	v_add_u32_e32 v168, 0x8000, v166
	v_add_u32_e32 v169, v66, v145
	v_add_u32_e32 v170, 0x10000, v166
	v_add_u32_e32 v171, v66, v144
	v_add_u32_e32 v172, 0x18000, v166
	v_mov_b32_e32 v173, v147
	v_mov_b32_e32 v174, v148
	v_mov_b32_e32 v175, v146
	v_mov_b32_e32 v176, v145
	v_mov_b32_e32 v177, v144
	v_mov_b32_e32 v178, v135
	v_mov_b32_e32 v179, v155
	v_mov_b32_e32 v180, v152
	v_mov_b32_e32 v181, v153
	v_mov_b32_e32 v182, v154
	v_mov_b32_e32 v65, v64
	v_mov_b32_e32 v66, v64
	v_mov_b32_e32 v67, v64
	v_mov_b32_e32 v80, v64
	v_mov_b32_e32 v81, v64
	v_mov_b32_e32 v82, v64
	v_mov_b32_e32 v83, v64
	v_mov_b32_e32 v96, v64
	v_mov_b32_e32 v97, v64
	v_mov_b32_e32 v98, v64
	v_mov_b32_e32 v99, v64
	v_mov_b32_e32 v112, v64
	v_mov_b32_e32 v113, v64
	v_mov_b32_e32 v114, v64
	v_mov_b32_e32 v115, v64
	v_mov_b32_e32 v68, v64
	v_mov_b32_e32 v69, v64
	v_mov_b32_e32 v70, v64
	v_mov_b32_e32 v71, v64
	v_mov_b32_e32 v84, v64
	v_mov_b32_e32 v85, v64
	v_mov_b32_e32 v86, v64
	v_mov_b32_e32 v87, v64
	v_mov_b32_e32 v100, v64
	v_mov_b32_e32 v101, v64
	v_mov_b32_e32 v102, v64
	v_mov_b32_e32 v103, v64
	v_mov_b32_e32 v116, v64
	v_mov_b32_e32 v117, v64
	v_mov_b32_e32 v118, v64
	v_mov_b32_e32 v119, v64
	v_mov_b32_e32 v72, v64
	v_mov_b32_e32 v73, v64
	v_mov_b32_e32 v74, v64
	v_mov_b32_e32 v75, v64
	v_mov_b32_e32 v88, v64
	v_mov_b32_e32 v89, v64
	v_mov_b32_e32 v90, v64
	v_mov_b32_e32 v91, v64
	v_mov_b32_e32 v104, v64
	v_mov_b32_e32 v105, v64
	v_mov_b32_e32 v106, v64
	v_mov_b32_e32 v107, v64
	v_mov_b32_e32 v120, v64
	v_mov_b32_e32 v121, v64
	v_mov_b32_e32 v122, v64
	v_mov_b32_e32 v123, v64
	v_mov_b32_e32 v76, v64
	v_mov_b32_e32 v77, v64
	v_mov_b32_e32 v78, v64
	v_mov_b32_e32 v79, v64
	v_mov_b32_e32 v92, v64
	v_mov_b32_e32 v93, v64
	v_mov_b32_e32 v94, v64
	v_mov_b32_e32 v95, v64
	v_mov_b32_e32 v108, v64
	v_mov_b32_e32 v109, v64
	v_mov_b32_e32 v110, v64
	v_mov_b32_e32 v111, v64
	v_mov_b32_e32 v124, v64
	v_mov_b32_e32 v125, v64
	v_mov_b32_e32 v126, v64
	v_mov_b32_e32 v127, v64
	s_branch .LBB0_1829
	.p2alignl 6, 3212836864

.LBB0_1858:
	s_waitcnt vmcnt(0)
	s_barrier
	s_mov_b64 s[0:1], exec
	v_readlane_b32 s4, v237, 1
	v_readlane_b32 s5, v237, 2
	s_and_b64 s[4:5], s[0:1], s[4:5]
	s_mov_b64 exec, s[4:5]
	s_cbranch_execz .LBB0_1910
	s_waitcnt vmcnt(8)
	v_mov_b32_e32 v0, 0x13ff0
	s_waitcnt vmcnt(0) expcnt(0) lgkmcnt(0)
	ds_read_b32 v2, v0
	v_mov_b32_e32 v0, 0x13ff4
	ds_read_b32 v0, v0
	s_waitcnt lgkmcnt(1)
	v_cmp_ne_u32_e32 vcc, 0, v2
	s_cbranch_vccnz .LBB0_1874
	v_readlane_b32 s40, v237, 56
	v_readlane_b32 s43, v237, 59
	v_readlane_b32 s4, v237, 0
	v_readlane_b32 s41, v237, 57
	s_mul_i32 s33, s43, s4
	s_add_u32 s4, s40, 0x4100200
	s_addc_u32 s5, s41, 0
	s_add_u32 s6, s40, 0x4100400
	s_addc_u32 s7, s41, 0
	s_add_u32 s8, s40, 0x4100500
	s_addc_u32 s9, s41, 0
	s_add_u32 s10, s40, 0x4100600
	s_addc_u32 s11, s41, 0
	s_add_u32 s12, s40, 0x4100700
	s_addc_u32 s13, s41, 0
	s_add_u32 s14, s40, 0x4100800
	s_addc_u32 s15, s41, 0
	s_add_u32 s16, s40, 0x4100900
	s_addc_u32 s17, s41, 0
	s_add_u32 s18, s40, 0x4100a00
	s_addc_u32 s19, s41, 0
	s_add_u32 s20, s40, 0x4100b00
	s_addc_u32 s21, s41, 0
	s_add_u32 s22, s40, 0x4100c00
	s_addc_u32 s23, s41, 0
	s_add_u32 s24, s40, 0x4100d00
	s_addc_u32 s25, s41, 0
	s_add_u32 s26, s40, 0x4100e00
	s_addc_u32 s27, s41, 0
	s_add_u32 s28, s40, 0x4100f00
	s_addc_u32 s29, s41, 0
	s_add_u32 s30, s40, 0x4101000
	s_addc_u32 s31, s41, 0
	s_add_u32 s34, s40, 0x4101100
	s_addc_u32 s35, s41, 0
	s_add_u32 s36, s40, 0x4101200
	s_addc_u32 s37, s41, 0
	v_readlane_b32 s42, v237, 58
	s_add_u32 s38, s40, 0x4101300
	s_mul_i32 s33, s33, s42
	s_addc_u32 s39, s41, 0
	s_mov_b32 s46, 1
	v_mov_b32_e32 v16, 0
	s_branch .LBB0_1862
	.p2alignl 6, 3212836864

.LBB0_1862:
	global_load_dword v15, v16, s[6:7] sc1
	s_waitcnt lgkmcnt(0)
	global_load_dword v0, v16, s[8:9] sc1
	global_load_dword v1, v16, s[10:11] sc1
	global_load_dword v2, v16, s[12:13] sc1
	global_load_dword v3, v16, s[14:15] sc1
	global_load_dword v4, v16, s[16:17] sc1
	global_load_dword v5, v16, s[18:19] sc1
	global_load_dword v6, v16, s[20:21] sc1
	global_load_dword v7, v16, s[22:23] sc1
	global_load_dword v8, v16, s[24:25] sc1
	global_load_dword v9, v16, s[26:27] sc1
	global_load_dword v10, v16, s[28:29] sc1
	global_load_dword v11, v16, s[30:31] sc1
	global_load_dword v12, v16, s[34:35] sc1
	global_load_dword v13, v16, s[36:37] sc1
	global_load_dword v14, v16, s[38:39] sc1
	s_mov_b64 s[40:41], -1
	s_mov_b64 s[42:43], -1
	s_waitcnt vmcnt(14)
	v_add_u32_e32 v17, v0, v15
	s_waitcnt vmcnt(13)
	v_add_u32_e32 v17, v17, v1
	s_waitcnt vmcnt(12)
	v_add_u32_e32 v17, v17, v2
	s_waitcnt vmcnt(11)
	v_add_u32_e32 v17, v17, v3
	s_waitcnt vmcnt(10)
	v_add_u32_e32 v17, v17, v4
	s_waitcnt vmcnt(9)
	v_add_u32_e32 v17, v17, v5
	s_waitcnt vmcnt(8)
	v_add_u32_e32 v17, v17, v6
	s_waitcnt vmcnt(7)
	v_add_u32_e32 v17, v17, v7
	s_waitcnt vmcnt(6)
	v_add_u32_e32 v17, v17, v8
	s_waitcnt vmcnt(5)
	v_add_u32_e32 v17, v17, v9
	s_waitcnt vmcnt(4)
	v_add_u32_e32 v17, v17, v10
	s_waitcnt vmcnt(3)
	v_add_u32_e32 v17, v17, v11
	s_waitcnt vmcnt(2)
	v_add_u32_e32 v17, v17, v12
	s_waitcnt vmcnt(1)
	v_add_u32_e32 v17, v17, v13
	s_waitcnt vmcnt(0)
	v_add_u32_e32 v17, v17, v14
	v_cmp_eq_u32_e32 vcc, s33, v17
	s_cbranch_vccnz .LBB0_1861
	s_and_b32 s40, s46, 0xff
	s_cmp_eq_u32 s40, 0
	s_mov_b64 s[40:41], -1
	s_mov_b64 s[44:45], -1
	s_sleep 1
	s_cbranch_scc1 .LBB0_1866
	s_and_b64 vcc, exec, s[44:45]
	s_cbranch_vccz .LBB0_1861
	.p2alignl 6, 3212836864

.LBB0_1936:
	s_movk_i32 s33, 0xab
	v_mul_lo_u32 v1, v130, s33
	v_bfe_u32 v1, v1, 10, 6
	v_mul_lo_u32 v2, v1, -6
	v_add_u32_e32 v2, v2, v130
	v_cmp_gt_i32_e32 vcc, 5, v2
	v_readlane_b32 s4, v237, 56
	v_readlane_b32 s5, v237, 57
	v_cndmask_b32_e64 v3, 2, 1, vcc
	v_cmp_gt_i32_e32 vcc, 3, v2
	s_add_u32 s16, s4, 0x3500000
	v_ashrrev_i32_e32 v140, 3, v8
	v_add_u32_e32 v4, 1, v2
	v_min_i32_e32 v5, 4, v2
	v_cndmask_b32_e64 v2, v3, 0, vcc
	v_add_u32_e32 v0, v0, v138
	v_readlane_b32 s0, v237, 31
	s_addc_u32 s17, s5, 0
	v_add_lshl_u32 v142, v0, v140, 9
	s_lshl_b32 s0, s0, 15
	v_lshlrev_b32_e32 v0, 20, v1
	v_lshlrev_b32_e32 v1, 18, v2
	v_add_u32_e32 v5, -1, v5
	s_and_b32 s0, s0, 0x38000
	v_or_b32_e32 v0, v1, v0
	v_cndmask_b32_e32 v3, v5, v4, vcc
	v_lshlrev_b32_e32 v141, 8, v140
	v_or_b32_e32 v0, s0, v0
	v_add_u32_e32 v144, v0, v141
	v_sub_u32_e32 v0, v3, v2
	s_mov_b32 s93, 0
	v_lshlrev_b32_e32 v143, 18, v0
	s_mov_b64 s[58:59], -1
	s_movk_i32 s60, 0x50
	v_readlane_b32 s6, v237, 58
	v_readlane_b32 s7, v237, 59
	v_readlane_b32 s1, v237, 32
	s_branch .LBB0_1938
	.p2alignl 6, 3212836864

.LBB0_1967:
	v_lshlrev_b32_e32 v65, 1, v136
	v_lshl_add_u32 v155, v74, 1, v65
	v_lshl_add_u32 v156, v71, 1, v65
	v_lshl_add_u32 v157, v72, 1, v65
	v_lshl_add_u32 v158, v73, 1, v65
	v_or_b32_e32 v65, 0xc0, v136
	s_waitcnt lgkmcnt(0)
	s_barrier
	s_waitcnt vmcnt(15)
	ds_write_b128 v155, v[0:3] offset:40960
	s_waitcnt vmcnt(14)
	ds_write_b128 v155, v[8:11] offset:61440
	s_waitcnt vmcnt(13)
	ds_write_b128 v156, v[16:19] offset:40960
	s_waitcnt vmcnt(12)
	ds_write_b128 v156, v[24:27] offset:61440
	s_waitcnt vmcnt(11)
	ds_write_b128 v157, v[28:31] offset:40960
	s_waitcnt vmcnt(10)
	ds_write_b128 v157, v[36:39] offset:61440
	s_waitcnt vmcnt(9)
	ds_write_b128 v158, v[44:47] offset:40960
	s_waitcnt vmcnt(8)
	ds_write_b128 v158, v[56:59] offset:61440
	v_add_u32_e32 v44, v65, v142
	v_mov_b32_e32 v132, v44
	v_mul_lo_u32 v66, v146, s33
	v_lshl_add_u64 v[0:1], v[132:133], 1, s[88:89]
	v_add_u32_e32 v132, v65, v144
	global_load_dwordx4 v[0:3], v[0:1], off
	v_bfe_u32 v66, v66, 10, 6
	v_lshl_add_u64 v[8:9], v[132:133], 1, s[16:17]
	v_add_u32_e32 v132, 0x4000, v44
	global_load_dwordx4 v[8:11], v[8:9], off
	v_mul_lo_u32 v67, v66, -6
	v_lshl_add_u64 v[16:17], v[132:133], 1, s[88:89]
	v_add_u32_e32 v132, v65, v137
	global_load_dwordx4 v[16:19], v[16:17], off
	v_add_u32_e32 v151, v67, v146
	v_lshl_add_u64 v[24:25], v[132:133], 1, s[16:17]
	v_add_u32_e32 v132, 0x8000, v44
	global_load_dwordx4 v[24:27], v[24:25], off
	v_cmp_gt_i32_e32 vcc, 5, v151
	v_lshl_add_u64 v[28:29], v[132:133], 1, s[88:89]
	v_add_u32_e32 v132, v65, v148
	global_load_dwordx4 v[28:31], v[28:29], off
	v_cndmask_b32_e64 v67, 2, 1, vcc
	v_lshl_add_u64 v[36:37], v[132:133], 1, s[16:17]
	v_add_u32_e32 v132, 0xc000, v44
	global_load_dwordx4 v[36:39], v[36:37], off
	v_cmp_gt_i32_e64 s[8:9], 3, v151
	v_lshl_add_u64 v[44:45], v[132:133], 1, s[88:89]
	v_add_u32_e32 v132, v65, v149
	global_load_dwordx4 v[44:47], v[44:45], off
	v_cndmask_b32_e64 v152, v67, 0, s[8:9]
	v_lshl_add_u64 v[56:57], v[132:133], 1, s[16:17]
	global_load_dwordx4 v[56:59], v[56:57], off
	v_add_u32_e32 v64, v64, v145
	v_add_lshl_u32 v150, v64, v140, 9
	s_lshl_b32 s0, s92, 15
	v_lshlrev_b32_e32 v64, 20, v66
	v_lshlrev_b32_e32 v66, 18, v152
	s_and_b32 s0, s0, 0x38000
	v_or_b32_e32 v64, v66, v64
	v_or_b32_e32 v64, s0, v64
	v_add_u32_e32 v153, v64, v141
	v_and_b32_e32 v64, 15, v131
	v_bfe_u32 v159, v131, 4, 2
	v_ashrrev_i32_e32 v66, 1, v131
	s_movk_i32 s0, 0xffc0
	v_and_or_b32 v154, v66, s0, v64
	v_lshlrev_b32_e32 v64, 4, v159
	v_and_b32_e32 v66, 0x4f, v131
	s_movk_i32 s0, 0xa0
	v_mad_u64_u32 v[134:135], s[0:1], v154, s0, v[64:65]
	v_mul_u32_u24_e32 v66, 0x50, v66
	v_lshl_add_u32 v135, v66, 1, v64
	v_add_u32_e32 v64, v144, v143
	v_add_u32_e32 v164, v65, v64
	v_add_u32_e32 v166, v136, v64
	ds_read_b128 v[64:67], v134
	ds_read_b128 v[68:71], v134 offset:2560
	ds_read_b128 v[72:75], v135 offset:20480
	ds_read_b128 v[76:79], v135 offset:23040
	ds_read_b128 v[80:83], v134 offset:5120
	ds_read_b128 v[84:87], v134 offset:7680
	ds_read_b128 v[88:91], v135 offset:25600
	ds_read_b128 v[92:95], v135 offset:28160
	v_add_u32_e32 v162, v142, v136
	s_mov_b32 s12, 2
	s_mov_b32 s13, 0
	v_add_u32_e32 v160, 0xf000, v135
	v_add_u32_e32 v161, 0xf040, v135
	v_add_u32_e32 v163, 0x1c0, v162
	v_add_u32_e32 v165, 0x41c0, v162
	v_add_u32_e32 v167, 0x20c0, v166
	v_add_u32_e32 v168, 0x81c0, v162
	v_add_u32_e32 v169, 0x40c0, v166
	v_add_u32_e32 v170, 0xc1c0, v162
	v_add_u32_e32 v171, 0x60c0, v166
	v_add_u32_e32 v172, 0x2000, v153
	v_add_u32_e32 v173, 0x4000, v153
	v_add_u32_e32 v174, 0x6000, v153
	s_setprio 1
	s_waitcnt lgkmcnt(5)
	v_mfma_f32_16x16x32_bf16 v[96:99], v[72:75], v[64:67], 0
	v_mfma_f32_16x16x32_bf16 v[100:103], v[72:75], v[68:71], 0
	s_waitcnt lgkmcnt(3)
	v_mfma_f32_16x16x32_bf16 v[104:107], v[72:75], v[80:83], 0
	s_waitcnt lgkmcnt(2)
	v_mfma_f32_16x16x32_bf16 v[72:75], v[72:75], v[84:87], 0
	v_mfma_f32_16x16x32_bf16 v[108:111], v[76:79], v[64:67], 0
	v_mfma_f32_16x16x32_bf16 v[112:115], v[76:79], v[68:71], 0
	v_mfma_f32_16x16x32_bf16 v[116:119], v[76:79], v[80:83], 0
	v_mfma_f32_16x16x32_bf16 v[76:79], v[76:79], v[84:87], 0
	s_waitcnt lgkmcnt(1)
	v_mfma_f32_16x16x32_bf16 v[120:123], v[88:91], v[64:67], 0
	v_mfma_f32_16x16x32_bf16 v[124:127], v[88:91], v[68:71], 0
	v_mfma_f32_16x16x32_bf16 v[176:179], v[88:91], v[80:83], 0
	v_mfma_f32_16x16x32_bf16 v[88:91], v[88:91], v[84:87], 0
	s_waitcnt lgkmcnt(0)
	v_mfma_f32_16x16x32_bf16 v[64:67], v[92:95], v[64:67], 0
	v_mfma_f32_16x16x32_bf16 v[68:71], v[92:95], v[68:71], 0
	v_mfma_f32_16x16x32_bf16 v[80:83], v[92:95], v[80:83], 0
	v_mfma_f32_16x16x32_bf16 v[84:87], v[92:95], v[84:87], 0
	s_setprio 0
	ds_read_b128 v[92:95], v134 offset:64
	ds_read_b128 v[180:183], v134 offset:2624
	ds_read_b128 v[184:187], v135 offset:20544
	ds_read_b128 v[188:191], v135 offset:23104
	ds_read_b128 v[192:195], v134 offset:5184
	ds_read_b128 v[196:199], v134 offset:7744
	ds_read_b128 v[200:203], v135 offset:25664
	ds_read_b128 v[204:207], v135 offset:28224
	s_setprio 1
	s_waitcnt lgkmcnt(5)
	v_mfma_f32_16x16x32_bf16 v[96:99], v[184:187], v[92:95], v[96:99]
	v_mfma_f32_16x16x32_bf16 v[100:103], v[184:187], v[180:183], v[100:103]
	s_waitcnt lgkmcnt(3)
	v_mfma_f32_16x16x32_bf16 v[104:107], v[184:187], v[192:195], v[104:107]
	s_waitcnt lgkmcnt(2)
	v_mfma_f32_16x16x32_bf16 v[72:75], v[184:187], v[196:199], v[72:75]
	v_mfma_f32_16x16x32_bf16 v[108:111], v[188:191], v[92:95], v[108:111]
	v_mfma_f32_16x16x32_bf16 v[112:115], v[188:191], v[180:183], v[112:115]
	v_mfma_f32_16x16x32_bf16 v[116:119], v[188:191], v[192:195], v[116:119]
	v_mfma_f32_16x16x32_bf16 v[76:79], v[188:191], v[196:199], v[76:79]
	s_waitcnt lgkmcnt(1)
	v_mfma_f32_16x16x32_bf16 v[120:123], v[200:203], v[92:95], v[120:123]
	v_mfma_f32_16x16x32_bf16 v[124:127], v[200:203], v[180:183], v[124:127]
	v_mfma_f32_16x16x32_bf16 v[88:91], v[200:203], v[196:199], v[88:91]
	s_waitcnt lgkmcnt(0)
	v_mfma_f32_16x16x32_bf16 v[64:67], v[204:207], v[92:95], v[64:67]
	v_mfma_f32_16x16x32_bf16 v[68:71], v[204:207], v[180:183], v[68:71]
	v_mfma_f32_16x16x32_bf16 v[80:83], v[204:207], v[192:195], v[80:83]
	v_mfma_f32_16x16x32_bf16 v[84:87], v[204:207], v[196:199], v[84:87]
	v_mfma_f32_16x16x32_bf16 v[176:179], v[200:203], v[192:195], v[176:179]
	s_setprio 0
	v_add_u32_e32 v132, 0x100, v162
	s_barrier
	s_waitcnt vmcnt(15)
	ds_write_b128 v155, v[4:7]
	s_waitcnt vmcnt(14)
	ds_write_b128 v155, v[12:15] offset:20480
	s_waitcnt vmcnt(13)
	ds_write_b128 v156, v[20:23]
	s_waitcnt vmcnt(12)
	ds_write_b128 v156, v[32:35] offset:20480
	s_waitcnt vmcnt(11)
	ds_write_b128 v157, v[40:43]
	s_waitcnt vmcnt(10)
	ds_write_b128 v157, v[48:51] offset:20480
	s_waitcnt vmcnt(9)
	ds_write_b128 v158, v[52:55]
	s_waitcnt vmcnt(8)
	ds_write_b128 v158, v[60:63] offset:20480
	s_nop 0
	v_lshl_add_u64 v[4:5], v[132:133], 1, s[88:89]
	v_mov_b32_e32 v132, v166
	global_load_dwordx4 v[4:7], v[4:5], off
	s_nop 0
	v_lshl_add_u64 v[12:13], v[132:133], 1, s[16:17]
	v_add_u32_e32 v132, 0x4100, v162
	global_load_dwordx4 v[12:15], v[12:13], off
	s_nop 0
	v_lshl_add_u64 v[20:21], v[132:133], 1, s[88:89]
	v_add_u32_e32 v132, 0x2000, v166
	global_load_dwordx4 v[20:23], v[20:21], off
	s_nop 0
	v_lshl_add_u64 v[32:33], v[132:133], 1, s[16:17]
	v_add_u32_e32 v132, 0x8100, v162
	global_load_dwordx4 v[32:35], v[32:33], off
	s_nop 0
	v_lshl_add_u64 v[40:41], v[132:133], 1, s[88:89]
	v_add_u32_e32 v132, 0x4000, v166
	global_load_dwordx4 v[40:43], v[40:41], off
	s_nop 0
	v_lshl_add_u64 v[48:49], v[132:133], 1, s[16:17]
	v_add_u32_e32 v132, 0xc100, v162
	global_load_dwordx4 v[48:51], v[48:49], off
	s_nop 0
	v_lshl_add_u64 v[52:53], v[132:133], 1, s[88:89]
	v_add_u32_e32 v132, 0x6000, v166
	global_load_dwordx4 v[52:55], v[52:53], off
	s_nop 0
	v_lshl_add_u64 v[60:61], v[132:133], 1, s[16:17]
	global_load_dwordx4 v[60:63], v[60:61], off
	ds_read_b128 v[92:95], v134 offset:40960
	ds_read_b128 v[180:183], v134 offset:43520
	ds_read_b128 v[184:187], v135 offset:61440
	ds_read_b128 v[188:191], v135 offset:64000
	ds_read_b128 v[192:195], v134 offset:46080
	ds_read_b128 v[196:199], v134 offset:48640
	ds_read_b128 v[200:203], v160 offset:5120
	ds_read_b128 v[204:207], v160 offset:7680
	s_setprio 1
	s_waitcnt lgkmcnt(5)
	v_mfma_f32_16x16x32_bf16 v[96:99], v[184:187], v[92:95], v[96:99]
	v_mfma_f32_16x16x32_bf16 v[100:103], v[184:187], v[180:183], v[100:103]
	s_waitcnt lgkmcnt(3)
	v_mfma_f32_16x16x32_bf16 v[104:107], v[184:187], v[192:195], v[104:107]
	s_waitcnt lgkmcnt(2)
	v_mfma_f32_16x16x32_bf16 v[72:75], v[184:187], v[196:199], v[72:75]
	v_mfma_f32_16x16x32_bf16 v[112:115], v[188:191], v[180:183], v[112:115]
	v_mfma_f32_16x16x32_bf16 v[116:119], v[188:191], v[192:195], v[116:119]
	s_waitcnt lgkmcnt(0)
	v_mfma_f32_16x16x32_bf16 v[64:67], v[204:207], v[92:95], v[64:67]
	v_mfma_f32_16x16x32_bf16 v[80:83], v[204:207], v[192:195], v[80:83]
	v_mfma_f32_16x16x32_bf16 v[184:187], v[188:191], v[92:95], v[108:111]
	v_mfma_f32_16x16x32_bf16 v[188:191], v[188:191], v[196:199], v[76:79]
	v_mfma_f32_16x16x32_bf16 v[208:211], v[200:203], v[92:95], v[120:123]
	v_mfma_f32_16x16x32_bf16 v[212:215], v[200:203], v[180:183], v[124:127]
	v_mfma_f32_16x16x32_bf16 v[176:179], v[200:203], v[192:195], v[176:179]
	v_mfma_f32_16x16x32_bf16 v[200:203], v[200:203], v[196:199], v[88:91]
	v_mfma_f32_16x16x32_bf16 v[180:183], v[204:207], v[180:183], v[68:71]
	v_mfma_f32_16x16x32_bf16 v[192:195], v[204:207], v[196:199], v[84:87]
	s_setprio 0
	ds_read_b128 v[196:199], v134 offset:41024
	ds_read_b128 v[204:207], v134 offset:43584
	ds_read_b128 v[68:71], v135 offset:61504
	ds_read_b128 v[84:87], v135 offset:64064
	ds_read_b128 v[216:219], v134 offset:46144
	ds_read_b128 v[220:223], v134 offset:48704
	ds_read_b128 v[224:227], v161 offset:5120
	ds_read_b128 v[228:231], v161 offset:7680
	s_setprio 1
	s_waitcnt lgkmcnt(5)
	v_mfma_f32_16x16x32_bf16 v[124:127], v[68:71], v[196:199], v[96:99]
	v_mfma_f32_16x16x32_bf16 v[108:111], v[68:71], v[204:207], v[100:103]
	s_waitcnt lgkmcnt(3)
	v_mfma_f32_16x16x32_bf16 v[92:95], v[68:71], v[216:219], v[104:107]
	s_waitcnt lgkmcnt(2)
	v_mfma_f32_16x16x32_bf16 v[76:79], v[68:71], v[220:223], v[72:75]
	v_mfma_f32_16x16x32_bf16 v[120:123], v[84:87], v[196:199], v[184:187]
	v_mfma_f32_16x16x32_bf16 v[104:107], v[84:87], v[204:207], v[112:115]
	v_mfma_f32_16x16x32_bf16 v[88:91], v[84:87], v[216:219], v[116:119]
	v_mfma_f32_16x16x32_bf16 v[72:75], v[84:87], v[220:223], v[188:191]
	s_waitcnt lgkmcnt(1)
	v_mfma_f32_16x16x32_bf16 v[116:119], v[224:227], v[196:199], v[208:211]
	v_mfma_f32_16x16x32_bf16 v[100:103], v[224:227], v[204:207], v[212:215]
	v_mfma_f32_16x16x32_bf16 v[84:87], v[224:227], v[216:219], v[176:179]
	v_mfma_f32_16x16x32_bf16 v[68:71], v[224:227], v[220:223], v[200:203]
	s_waitcnt lgkmcnt(0)
	v_mfma_f32_16x16x32_bf16 v[112:115], v[228:231], v[196:199], v[64:67]
	v_mfma_f32_16x16x32_bf16 v[96:99], v[228:231], v[204:207], v[180:183]
	v_mfma_f32_16x16x32_bf16 v[80:83], v[228:231], v[216:219], v[80:83]
	v_mfma_f32_16x16x32_bf16 v[64:67], v[228:231], v[220:223], v[192:195]
	s_setprio 0
	v_add_u32_e32 v175, v150, v136
	s_branch .LBB0_1969
	.p2alignl 6, 3212836864

.LBB0_1997:
	s_waitcnt vmcnt(0)
	s_barrier
	s_mov_b64 s[0:1], exec
	v_readlane_b32 s2, v237, 1
	v_readlane_b32 s3, v237, 2
	v_readlane_b32 s44, v237, 48
	v_readlane_b32 s52, v237, 56
	v_readlane_b32 s56, v237, 40
	s_and_b64 s[2:3], s[0:1], s[2:3]
	v_readlane_b32 s46, v237, 50
	v_readlane_b32 s47, v237, 51
	v_readlane_b32 s48, v237, 52
	v_readlane_b32 s49, v237, 53
	v_readlane_b32 s50, v237, 54
	v_readlane_b32 s51, v237, 55
	v_readlane_b32 s53, v237, 57
	v_readlane_b32 s54, v237, 58
	v_readlane_b32 s55, v237, 59
	v_readlane_b32 s57, v237, 41
	v_readlane_b32 s45, v237, 49
	s_mov_b64 exec, s[2:3]
	s_cbranch_execz .LBB0_2049
	v_mov_b32_e32 v0, 0x13ff0
	s_waitcnt vmcnt(0) expcnt(0) lgkmcnt(0)
	ds_read_b32 v2, v0
	v_mov_b32_e32 v0, 0x13ff4
	ds_read_b32 v0, v0
	s_waitcnt lgkmcnt(1)
	v_cmp_ne_u32_e32 vcc, 0, v2
	s_cbranch_vccnz .LBB0_2013
	v_readlane_b32 s2, v237, 0
	s_mul_i32 s33, s55, s2
	s_add_u32 s2, s52, 0x4100200
	s_addc_u32 s3, s53, 0
	s_add_u32 s4, s52, 0x4100400
	s_addc_u32 s5, s53, 0
	s_add_u32 s6, s52, 0x4100500
	s_addc_u32 s7, s53, 0
	s_add_u32 s8, s52, 0x4100600
	s_addc_u32 s9, s53, 0
	s_add_u32 s10, s52, 0x4100700
	s_addc_u32 s11, s53, 0
	s_add_u32 s12, s52, 0x4100800
	s_addc_u32 s13, s53, 0
	s_add_u32 s14, s52, 0x4100900
	s_addc_u32 s15, s53, 0
	s_add_u32 s16, s52, 0x4100a00
	s_addc_u32 s17, s53, 0
	s_add_u32 s18, s52, 0x4100b00
	s_addc_u32 s19, s53, 0
	s_add_u32 s20, s52, 0x4100c00
	s_addc_u32 s21, s53, 0
	s_add_u32 s22, s52, 0x4100d00
	s_addc_u32 s23, s53, 0
	s_add_u32 s24, s52, 0x4100e00
	s_addc_u32 s25, s53, 0
	s_add_u32 s26, s52, 0x4100f00
	s_addc_u32 s27, s53, 0
	s_add_u32 s28, s52, 0x4101000
	s_addc_u32 s29, s53, 0
	s_add_u32 s30, s52, 0x4101100
	s_addc_u32 s31, s53, 0
	s_add_u32 s34, s52, 0x4101200
	s_addc_u32 s35, s53, 0
	s_add_u32 s36, s52, 0x4101300
	s_mul_i32 s33, s33, s54
	s_addc_u32 s37, s53, 0
	s_mov_b32 s44, 1
	v_mov_b32_e32 v16, 0
	s_branch .LBB0_2001
	.p2alignl 6, 3212836864

.LBB0_2001:
	global_load_dword v15, v16, s[4:5] sc1
	s_waitcnt lgkmcnt(0)
	global_load_dword v0, v16, s[6:7] sc1
	global_load_dword v1, v16, s[8:9] sc1
	global_load_dword v2, v16, s[10:11] sc1
	global_load_dword v3, v16, s[12:13] sc1
	global_load_dword v4, v16, s[14:15] sc1
	global_load_dword v5, v16, s[16:17] sc1
	global_load_dword v6, v16, s[18:19] sc1
	global_load_dword v7, v16, s[20:21] sc1
	global_load_dword v8, v16, s[22:23] sc1
	global_load_dword v9, v16, s[24:25] sc1
	global_load_dword v10, v16, s[26:27] sc1
	global_load_dword v11, v16, s[28:29] sc1
	global_load_dword v12, v16, s[30:31] sc1
	global_load_dword v13, v16, s[34:35] sc1
	global_load_dword v14, v16, s[36:37] sc1
	s_mov_b64 s[38:39], -1
	s_mov_b64 s[40:41], -1
	s_waitcnt vmcnt(14)
	v_add_u32_e32 v17, v0, v15
	s_waitcnt vmcnt(13)
	v_add_u32_e32 v17, v17, v1
	s_waitcnt vmcnt(12)
	v_add_u32_e32 v17, v17, v2
	s_waitcnt vmcnt(11)
	v_add_u32_e32 v17, v17, v3
	s_waitcnt vmcnt(10)
	v_add_u32_e32 v17, v17, v4
	s_waitcnt vmcnt(9)
	v_add_u32_e32 v17, v17, v5
	s_waitcnt vmcnt(8)
	v_add_u32_e32 v17, v17, v6
	s_waitcnt vmcnt(7)
	v_add_u32_e32 v17, v17, v7
	s_waitcnt vmcnt(6)
	v_add_u32_e32 v17, v17, v8
	s_waitcnt vmcnt(5)
	v_add_u32_e32 v17, v17, v9
	s_waitcnt vmcnt(4)
	v_add_u32_e32 v17, v17, v10
	s_waitcnt vmcnt(3)
	v_add_u32_e32 v17, v17, v11
	s_waitcnt vmcnt(2)
	v_add_u32_e32 v17, v17, v12
	s_waitcnt vmcnt(1)
	v_add_u32_e32 v17, v17, v13
	s_waitcnt vmcnt(0)
	v_add_u32_e32 v17, v17, v14
	v_cmp_eq_u32_e32 vcc, s33, v17
	s_cbranch_vccnz .LBB0_2000
	s_and_b32 s38, s44, 0xff
	s_cmp_eq_u32 s38, 0
	s_mov_b64 s[38:39], -1
	s_mov_b64 s[42:43], -1
	s_sleep 1
	s_cbranch_scc1 .LBB0_2005
	s_and_b64 vcc, exec, s[42:43]
	s_cbranch_vccz .LBB0_2000
	.p2alignl 6, 3212836864

.LBB0_2049:
	s_or_b64 exec, exec, s[0:1]
	v_mov_b32_e32 v36, v128
	s_waitcnt lgkmcnt(0)
	s_barrier
	v_readlane_b32 s0, v237, 36
	v_ashrrev_i32_e32 v0, 6, v128
	s_mov_b32 s7, 0x8000
	v_add_u32_e32 v38, s0, v0
	v_cmp_gt_i32_e32 vcc, s7, v38
	s_and_saveexec_b64 s[0:1], vcc
	s_cbranch_execz .LBB0_2052
	v_ashrrev_i32_e32 v39, 31, v38
	v_lshlrev_b32_e32 v4, 2, v36
	v_lshlrev_b64 v[0:1], 11, v[38:39]
	v_and_b32_e32 v6, 0xfc, v4
	v_lshl_add_u64 v[2:3], s[56:57], 0, v[0:1]
	v_lshlrev_b32_e32 v4, 1, v6
	v_mov_b32_e32 v5, 0
	v_lshl_add_u64 v[0:1], s[76:77], 0, v[0:1]
	v_lshl_add_u64 v[2:3], v[2:3], 0, v[4:5]
	v_lshl_add_u64 v[0:1], v[0:1], 0, v[4:5]
	v_lshl_add_u64 v[32:33], s[76:77], 0, v[4:5]
	v_lshl_add_u64 v[34:35], s[56:57], 0, v[4:5]
	v_lshlrev_b32_e32 v4, 2, v6
	global_load_dwordx2 v[40:41], v[2:3], off offset:1536 nt
	global_load_dwordx2 v[42:43], v[2:3], off offset:1024 nt
	global_load_dwordx2 v[46:47], v[2:3], off offset:512 nt
	global_load_dwordx2 v[50:51], v[2:3], off nt
	global_load_dwordx2 v[44:45], v[0:1], off offset:1536 nt
	global_load_dwordx2 v[48:49], v[0:1], off offset:1024 nt
	global_load_dwordx2 v[52:53], v[0:1], off offset:512 nt
	global_load_dwordx2 v[54:55], v[0:1], off nt
	v_lshl_add_u64 v[0:1], s[46:47], 0, v[4:5]
	s_mov_b64 s[0:1], 0x1000
	v_lshl_add_u64 v[4:5], s[48:49], 0, v[4:5]
	s_waitcnt vmcnt(9)
	v_lshl_add_u64 v[56:57], v[0:1], 0, s[0:1]
	v_lshl_add_u64 v[58:59], v[4:5], 0, s[0:1]
	s_movk_i32 s0, 0x1000
	v_add_co_u32_e32 v0, vcc, s0, v0
	v_and_b32_e32 v36, 63, v36
	s_nop 0
	v_addc_co_u32_e32 v1, vcc, 0, v1, vcc
	s_waitcnt vmcnt(8)
	v_add_co_u32_e32 v60, vcc, s0, v4
	global_load_dwordx4 v[0:3], v[0:1], off nt
	s_nop 0
	v_addc_co_u32_e32 v61, vcc, 0, v5, vcc
	global_load_dwordx4 v[4:7], v[60:61], off nt
	global_load_dwordx4 v[8:11], v[56:57], off offset:1024 nt
	global_load_dwordx4 v[12:15], v[56:57], off offset:2048 nt
	global_load_dwordx4 v[16:19], v[58:59], off offset:1024 nt
	global_load_dwordx4 v[20:23], v[58:59], off offset:2048 nt
	global_load_dwordx4 v[24:27], v[56:57], off offset:3072 nt
	global_load_dwordx4 v[28:31], v[58:59], off offset:3072 nt
	v_lshlrev_b64 v[56:57], 12, v[38:39]
	v_lshl_or_b32 v56, v36, 4, v56
	s_ashr_i32 s97, s96, 31
	v_lshl_add_u64 v[36:37], s[50:51], 0, v[56:57]
	s_lshl_b64 s[2:3], s[96:97], 12
	s_mov_b64 s[4:5], 0
	s_movk_i32 s8, 0x7fff
	s_mov_b32 s6, 0x3fb504f3
	v_mov_b32_e32 v39, 0x3727c5ac
	s_mov_b32 s9, 0x800000
	.p2alignl 6, 3212836864
